# v18: v17 plus nt cache policy on the A-operand LDS-DMA loads of every GEMM K-loop
# baseline (speedup 1.0000x reference)
.LBB0_278:
	ds_read_b128 v[130:133], v158
	ds_read_b128 v[134:137], v158 offset:1024
	ds_read_b128 v[162:165], v158 offset:2048
	ds_read_b128 v[166:169], v158 offset:3072
	s_add_u32 s0, s30, 0xfffc0080
	s_addc_u32 s1, s31, -1
	s_cmp_eq_u32 s60, 12
	s_cselect_b32 s37, s23, s1
	s_cselect_b32 s36, s56, s0
	s_cselect_b32 s35, s21, s59
	s_cselect_b32 s34, s57, s58
	v_lshl_add_u64 v[154:155], s[30:31], 0, v[148:149]
	s_add_i32 m0, s29, 0xc000
	ds_read_b128 v[170:173], v159
	ds_read_b128 v[174:177], v159 offset:1024
	ds_read_b128 v[178:181], v159 offset:2048
	ds_read_b128 v[182:185], v159 offset:3072
	ds_read_b128 v[186:189], v159 offset:4096
	ds_read_b128 v[190:193], v159 offset:5120
	ds_read_b128 v[194:197], v159 offset:6144
	ds_read_b128 v[198:201], v159 offset:7168
	global_load_lds_dwordx4 v[154:155], off nt
	v_lshl_add_u64 v[154:155], s[30:31], 0, v[146:147]
	s_add_i32 m0, s29, 0xe000
	s_nop 0
	global_load_lds_dwordx4 v[154:155], off nt
	s_waitcnt lgkmcnt(8)
	s_waitcnt vmcnt(10)
	s_barrier
	s_waitcnt lgkmcnt(0)
	s_waitcnt lgkmcnt(0)
	v_mfma_f32_16x16x32_bf16 v[126:129], v[130:133], v[170:173], v[126:129]
	v_mfma_f32_16x16x32_bf16 v[122:125], v[162:165], v[170:173], v[122:125]
	v_mfma_f32_16x16x32_bf16 v[118:121], v[130:133], v[178:181], v[118:121]
	v_mfma_f32_16x16x32_bf16 v[110:113], v[162:165], v[178:181], v[110:113]
	v_mfma_f32_16x16x32_bf16 v[102:105], v[130:133], v[186:189], v[102:105]
	v_mfma_f32_16x16x32_bf16 v[94:97], v[162:165], v[186:189], v[94:97]
	v_mfma_f32_16x16x32_bf16 v[86:89], v[130:133], v[194:197], v[86:89]
	v_mfma_f32_16x16x32_bf16 v[78:81], v[162:165], v[194:197], v[78:81]
	v_mfma_f32_16x16x32_bf16 v[126:129], v[134:137], v[174:177], v[126:129]
	v_mfma_f32_16x16x32_bf16 v[122:125], v[166:169], v[174:177], v[122:125]
	v_mfma_f32_16x16x32_bf16 v[118:121], v[134:137], v[182:185], v[118:121]
	v_mfma_f32_16x16x32_bf16 v[110:113], v[166:169], v[182:185], v[110:113]
	v_mfma_f32_16x16x32_bf16 v[102:105], v[134:137], v[190:193], v[102:105]
	v_mfma_f32_16x16x32_bf16 v[94:97], v[166:169], v[190:193], v[94:97]
	v_mfma_f32_16x16x32_bf16 v[86:89], v[134:137], v[198:201], v[86:89]
	v_mfma_f32_16x16x32_bf16 v[78:81], v[166:169], v[198:201], v[78:81]
	s_barrier
	s_add_i32 s0, s52, s41
	v_lshl_add_u64 v[154:155], s[34:35], 0, v[142:143]
	s_mov_b32 m0, s0
	ds_read_b128 v[202:205], v160
	ds_read_b128 v[206:209], v160 offset:1024
	ds_read_b128 v[210:213], v160 offset:2048
	ds_read_b128 v[214:217], v160 offset:3072
	global_load_lds_dwordx4 v[154:155], off
	v_lshl_add_u64 v[218:219], s[34:35], 0, v[138:139]
	s_add_i32 m0, s0, 0x2000
	s_nop 0
	global_load_lds_dwordx4 v[218:219], off
	s_waitcnt vmcnt(10)
	s_barrier
	s_waitcnt lgkmcnt(0)
	s_waitcnt lgkmcnt(0)
	v_mfma_f32_16x16x32_bf16 v[114:117], v[202:205], v[170:173], v[114:117]
	v_mfma_f32_16x16x32_bf16 v[106:109], v[210:213], v[170:173], v[106:109]
	v_mfma_f32_16x16x32_bf16 v[98:101], v[202:205], v[178:181], v[98:101]
	v_mfma_f32_16x16x32_bf16 v[90:93], v[210:213], v[178:181], v[90:93]
	v_mfma_f32_16x16x32_bf16 v[82:85], v[202:205], v[186:189], v[82:85]
	v_mfma_f32_16x16x32_bf16 v[74:77], v[210:213], v[186:189], v[74:77]
	v_mfma_f32_16x16x32_bf16 v[70:73], v[202:205], v[194:197], v[70:73]
	v_mfma_f32_16x16x32_bf16 v[66:69], v[210:213], v[194:197], v[66:69]
	v_mfma_f32_16x16x32_bf16 v[114:117], v[206:209], v[174:177], v[114:117]
	v_mfma_f32_16x16x32_bf16 v[106:109], v[214:217], v[174:177], v[106:109]
	v_mfma_f32_16x16x32_bf16 v[98:101], v[206:209], v[182:185], v[98:101]
	v_mfma_f32_16x16x32_bf16 v[90:93], v[214:217], v[182:185], v[90:93]
	v_mfma_f32_16x16x32_bf16 v[82:85], v[206:209], v[190:193], v[82:85]
	v_mfma_f32_16x16x32_bf16 v[74:77], v[214:217], v[190:193], v[74:77]
	v_mfma_f32_16x16x32_bf16 v[70:73], v[206:209], v[198:201], v[70:73]
	v_mfma_f32_16x16x32_bf16 v[66:69], v[214:217], v[198:201], v[66:69]
	s_mov_b32 m0, s29
	v_lshl_add_u64 v[220:221], s[36:37], 0, v[144:145]
	s_barrier
	ds_read_b128 v[170:173], v159 offset:16384
	ds_read_b128 v[174:177], v159 offset:17408
	ds_read_b128 v[178:181], v159 offset:18432
	ds_read_b128 v[182:185], v159 offset:19456
	ds_read_b128 v[186:189], v159 offset:20480
	ds_read_b128 v[190:193], v159 offset:21504
	ds_read_b128 v[194:197], v159 offset:22528
	ds_read_b128 v[198:201], v159 offset:23552
	global_load_lds_dwordx4 v[220:221], off nt
	v_lshl_add_u64 v[222:223], s[36:37], 0, v[140:141]
	s_mov_b32 m0, s43
	s_nop 0
	global_load_lds_dwordx4 v[222:223], off nt
	s_waitcnt vmcnt(10)
	s_barrier
	s_waitcnt lgkmcnt(0)
	s_waitcnt lgkmcnt(0)
	v_mfma_f32_16x16x32_bf16 v[62:65], v[130:133], v[170:173], v[62:65]
	v_mfma_f32_16x16x32_bf16 v[58:61], v[162:165], v[170:173], v[58:61]
	v_mfma_f32_16x16x32_bf16 v[54:57], v[130:133], v[178:181], v[54:57]
	v_mfma_f32_16x16x32_bf16 v[46:49], v[162:165], v[178:181], v[46:49]
	v_mfma_f32_16x16x32_bf16 v[38:41], v[130:133], v[186:189], v[38:41]
	v_mfma_f32_16x16x32_bf16 v[30:33], v[162:165], v[186:189], v[30:33]
	v_mfma_f32_16x16x32_bf16 v[22:25], v[130:133], v[194:197], v[22:25]
	v_mfma_f32_16x16x32_bf16 v[14:17], v[162:165], v[194:197], v[14:17]
	v_mfma_f32_16x16x32_bf16 v[62:65], v[134:137], v[174:177], v[62:65]
	v_mfma_f32_16x16x32_bf16 v[58:61], v[166:169], v[174:177], v[58:61]
	v_mfma_f32_16x16x32_bf16 v[54:57], v[134:137], v[182:185], v[54:57]
	v_mfma_f32_16x16x32_bf16 v[46:49], v[166:169], v[182:185], v[46:49]
	v_mfma_f32_16x16x32_bf16 v[38:41], v[134:137], v[190:193], v[38:41]
	v_mfma_f32_16x16x32_bf16 v[30:33], v[166:169], v[190:193], v[30:33]
	v_mfma_f32_16x16x32_bf16 v[22:25], v[134:137], v[198:201], v[22:25]
	v_mfma_f32_16x16x32_bf16 v[14:17], v[166:169], v[198:201], v[14:17]
	s_barrier
	s_add_u32 s0, s34, 0x40000
	s_addc_u32 s1, s35, 0
	s_add_i32 s61, s53, s41
	v_lshl_add_u64 v[130:131], s[0:1], 0, v[142:143]
	s_mov_b32 m0, s61
	s_nop 0
	global_load_lds_dwordx4 v[130:131], off
	v_lshl_add_u64 v[130:131], s[0:1], 0, v[138:139]
	s_add_i32 m0, s61, 0x2000
	s_nop 0
	global_load_lds_dwordx4 v[130:131], off
	s_waitcnt vmcnt(10)
	s_barrier
	v_mfma_f32_16x16x32_bf16 v[50:53], v[202:205], v[170:173], v[50:53]
	v_mfma_f32_16x16x32_bf16 v[42:45], v[210:213], v[170:173], v[42:45]
	v_mfma_f32_16x16x32_bf16 v[34:37], v[202:205], v[178:181], v[34:37]
	v_mfma_f32_16x16x32_bf16 v[26:29], v[210:213], v[178:181], v[26:29]
	v_mfma_f32_16x16x32_bf16 v[18:21], v[202:205], v[186:189], v[18:21]
	v_mfma_f32_16x16x32_bf16 v[10:13], v[210:213], v[186:189], v[10:13]
	v_mfma_f32_16x16x32_bf16 v[6:9], v[202:205], v[194:197], v[6:9]
	v_mfma_f32_16x16x32_bf16 v[2:5], v[210:213], v[194:197], v[2:5]
	v_mfma_f32_16x16x32_bf16 v[50:53], v[206:209], v[174:177], v[50:53]
	v_mfma_f32_16x16x32_bf16 v[42:45], v[214:217], v[174:177], v[42:45]
	v_mfma_f32_16x16x32_bf16 v[34:37], v[206:209], v[182:185], v[34:37]
	v_mfma_f32_16x16x32_bf16 v[26:29], v[214:217], v[182:185], v[26:29]
	v_mfma_f32_16x16x32_bf16 v[18:21], v[206:209], v[190:193], v[18:21]
	v_mfma_f32_16x16x32_bf16 v[10:13], v[214:217], v[190:193], v[10:13]
	v_mfma_f32_16x16x32_bf16 v[6:9], v[206:209], v[198:201], v[6:9]
	v_mfma_f32_16x16x32_bf16 v[2:5], v[214:217], v[198:201], v[2:5]
	s_add_i32 s61, 0, 0x18000
	v_add_u32_e32 v166, s61, v157
	s_barrier
	ds_read_b128 v[130:133], v166
	ds_read_b128 v[134:137], v166 offset:1024
	ds_read_b128 v[162:165], v166 offset:2048
	ds_read_b128 v[166:169], v166 offset:3072
	s_add_u32 s0, s36, 0x40000
	s_addc_u32 s1, s37, 0
	s_mov_b32 m0, s44
	v_lshl_add_u64 v[202:203], s[0:1], 0, v[144:145]
	ds_read_b128 v[170:173], v159 offset:32768
	ds_read_b128 v[174:177], v159 offset:33792
	ds_read_b128 v[178:181], v159 offset:34816
	ds_read_b128 v[182:185], v159 offset:35840
	ds_read_b128 v[186:189], v159 offset:36864
	ds_read_b128 v[190:193], v159 offset:37888
	ds_read_b128 v[194:197], v159 offset:38912
	ds_read_b128 v[198:201], v159 offset:39936
	global_load_lds_dwordx4 v[202:203], off nt
	v_lshl_add_u64 v[202:203], s[0:1], 0, v[140:141]
	s_mov_b32 m0, s45
	s_nop 0
	global_load_lds_dwordx4 v[202:203], off nt
	s_waitcnt lgkmcnt(8)
	s_waitcnt vmcnt(10)
	s_barrier
	s_waitcnt lgkmcnt(0)
	s_waitcnt lgkmcnt(0)
	v_mfma_f32_16x16x32_bf16 v[126:129], v[130:133], v[170:173], v[126:129]
	v_mfma_f32_16x16x32_bf16 v[122:125], v[162:165], v[170:173], v[122:125]
	v_mfma_f32_16x16x32_bf16 v[118:121], v[130:133], v[178:181], v[118:121]
	v_mfma_f32_16x16x32_bf16 v[110:113], v[162:165], v[178:181], v[110:113]
	v_mfma_f32_16x16x32_bf16 v[102:105], v[130:133], v[186:189], v[102:105]
	v_mfma_f32_16x16x32_bf16 v[94:97], v[162:165], v[186:189], v[94:97]
	v_mfma_f32_16x16x32_bf16 v[86:89], v[130:133], v[194:197], v[86:89]
	v_mfma_f32_16x16x32_bf16 v[78:81], v[162:165], v[194:197], v[78:81]
	v_mfma_f32_16x16x32_bf16 v[126:129], v[134:137], v[174:177], v[126:129]
	v_mfma_f32_16x16x32_bf16 v[122:125], v[166:169], v[174:177], v[122:125]
	v_mfma_f32_16x16x32_bf16 v[118:121], v[134:137], v[182:185], v[118:121]
	v_mfma_f32_16x16x32_bf16 v[110:113], v[166:169], v[182:185], v[110:113]
	v_mfma_f32_16x16x32_bf16 v[102:105], v[134:137], v[190:193], v[102:105]
	v_mfma_f32_16x16x32_bf16 v[94:97], v[166:169], v[190:193], v[94:97]
	v_mfma_f32_16x16x32_bf16 v[86:89], v[134:137], v[198:201], v[86:89]
	v_mfma_f32_16x16x32_bf16 v[78:81], v[166:169], v[198:201], v[78:81]
	s_barrier
	s_add_i32 s36, 0, 0x1c000
	s_add_i32 s0, s61, s41
	v_add_u32_e32 v214, s36, v157
	v_lshl_add_u64 v[154:155], v[154:155], 0, s[16:17]
	s_mov_b32 m0, s0
	ds_read_b128 v[202:205], v214
	ds_read_b128 v[206:209], v214 offset:1024
	ds_read_b128 v[210:213], v214 offset:2048
	ds_read_b128 v[214:217], v214 offset:3072
	global_load_lds_dwordx4 v[154:155], off
	v_lshl_add_u64 v[154:155], v[218:219], 0, s[16:17]
	s_add_i32 m0, s0, 0x2000
	s_nop 0
	global_load_lds_dwordx4 v[154:155], off
	s_waitcnt vmcnt(10)
	s_barrier
	s_waitcnt lgkmcnt(0)
	s_waitcnt lgkmcnt(0)
	v_mfma_f32_16x16x32_bf16 v[114:117], v[202:205], v[170:173], v[114:117]
	v_mfma_f32_16x16x32_bf16 v[106:109], v[210:213], v[170:173], v[106:109]
	v_mfma_f32_16x16x32_bf16 v[98:101], v[202:205], v[178:181], v[98:101]
	v_mfma_f32_16x16x32_bf16 v[90:93], v[210:213], v[178:181], v[90:93]
	v_mfma_f32_16x16x32_bf16 v[82:85], v[202:205], v[186:189], v[82:85]
	v_mfma_f32_16x16x32_bf16 v[74:77], v[210:213], v[186:189], v[74:77]
	v_mfma_f32_16x16x32_bf16 v[70:73], v[202:205], v[194:197], v[70:73]
	v_mfma_f32_16x16x32_bf16 v[66:69], v[210:213], v[194:197], v[66:69]
	v_mfma_f32_16x16x32_bf16 v[114:117], v[206:209], v[174:177], v[114:117]
	v_mfma_f32_16x16x32_bf16 v[106:109], v[214:217], v[174:177], v[106:109]
	v_mfma_f32_16x16x32_bf16 v[98:101], v[206:209], v[182:185], v[98:101]
	v_mfma_f32_16x16x32_bf16 v[90:93], v[214:217], v[182:185], v[90:93]
	v_mfma_f32_16x16x32_bf16 v[82:85], v[206:209], v[190:193], v[82:85]
	v_mfma_f32_16x16x32_bf16 v[74:77], v[214:217], v[190:193], v[74:77]
	v_mfma_f32_16x16x32_bf16 v[70:73], v[206:209], v[198:201], v[70:73]
	v_mfma_f32_16x16x32_bf16 v[66:69], v[214:217], v[198:201], v[66:69]
	s_mov_b32 m0, s49
	v_lshl_add_u64 v[154:155], v[220:221], 0, s[16:17]
	s_barrier
	ds_read_b128 v[170:173], v159 offset:49152
	ds_read_b128 v[174:177], v159 offset:50176
	ds_read_b128 v[178:181], v159 offset:51200
	ds_read_b128 v[182:185], v159 offset:52224
	ds_read_b128 v[186:189], v159 offset:53248
	ds_read_b128 v[190:193], v159 offset:54272
	ds_read_b128 v[194:197], v159 offset:55296
	ds_read_b128 v[198:201], v159 offset:56320
	global_load_lds_dwordx4 v[154:155], off nt
	v_lshl_add_u64 v[154:155], v[222:223], 0, s[16:17]
	s_mov_b32 m0, s51
	s_nop 0
	global_load_lds_dwordx4 v[154:155], off nt
	s_waitcnt vmcnt(10)
	s_barrier
	s_waitcnt lgkmcnt(0)
	s_waitcnt lgkmcnt(0)
	v_mfma_f32_16x16x32_bf16 v[62:65], v[130:133], v[170:173], v[62:65]
	v_mfma_f32_16x16x32_bf16 v[58:61], v[162:165], v[170:173], v[58:61]
	v_mfma_f32_16x16x32_bf16 v[54:57], v[130:133], v[178:181], v[54:57]
	v_mfma_f32_16x16x32_bf16 v[46:49], v[162:165], v[178:181], v[46:49]
	v_mfma_f32_16x16x32_bf16 v[38:41], v[130:133], v[186:189], v[38:41]
	v_mfma_f32_16x16x32_bf16 v[30:33], v[162:165], v[186:189], v[30:33]
	v_mfma_f32_16x16x32_bf16 v[22:25], v[130:133], v[194:197], v[22:25]
	v_mfma_f32_16x16x32_bf16 v[14:17], v[162:165], v[194:197], v[14:17]
	v_mfma_f32_16x16x32_bf16 v[62:65], v[134:137], v[174:177], v[62:65]
	v_mfma_f32_16x16x32_bf16 v[58:61], v[166:169], v[174:177], v[58:61]
	v_mfma_f32_16x16x32_bf16 v[54:57], v[134:137], v[182:185], v[54:57]
	v_mfma_f32_16x16x32_bf16 v[46:49], v[166:169], v[182:185], v[46:49]
	v_mfma_f32_16x16x32_bf16 v[38:41], v[134:137], v[190:193], v[38:41]
	v_mfma_f32_16x16x32_bf16 v[30:33], v[166:169], v[190:193], v[30:33]
	v_mfma_f32_16x16x32_bf16 v[22:25], v[134:137], v[198:201], v[22:25]
	v_mfma_f32_16x16x32_bf16 v[14:17], v[166:169], v[198:201], v[14:17]
	s_barrier
	s_add_u32 s0, s34, 0x40080
	s_addc_u32 s1, s35, 0
	s_add_i32 s34, s36, s41
	v_lshl_add_u64 v[130:131], s[0:1], 0, v[142:143]
	s_mov_b32 m0, s34
	s_nop 0
	global_load_lds_dwordx4 v[130:131], off
	v_lshl_add_u64 v[130:131], s[0:1], 0, v[138:139]
	s_add_i32 m0, s34, 0x2000
	s_nop 0
	global_load_lds_dwordx4 v[130:131], off
	s_waitcnt vmcnt(10)
	s_barrier
	v_mfma_f32_16x16x32_bf16 v[50:53], v[202:205], v[170:173], v[50:53]
	v_mfma_f32_16x16x32_bf16 v[42:45], v[210:213], v[170:173], v[42:45]
	v_mfma_f32_16x16x32_bf16 v[34:37], v[202:205], v[178:181], v[34:37]
	v_mfma_f32_16x16x32_bf16 v[26:29], v[210:213], v[178:181], v[26:29]
	v_mfma_f32_16x16x32_bf16 v[18:21], v[202:205], v[186:189], v[18:21]
	v_mfma_f32_16x16x32_bf16 v[10:13], v[210:213], v[186:189], v[10:13]
	v_mfma_f32_16x16x32_bf16 v[6:9], v[202:205], v[194:197], v[6:9]
	v_mfma_f32_16x16x32_bf16 v[2:5], v[210:213], v[194:197], v[2:5]
	v_mfma_f32_16x16x32_bf16 v[50:53], v[206:209], v[174:177], v[50:53]
	v_mfma_f32_16x16x32_bf16 v[42:45], v[214:217], v[174:177], v[42:45]
	v_mfma_f32_16x16x32_bf16 v[34:37], v[206:209], v[182:185], v[34:37]
	v_mfma_f32_16x16x32_bf16 v[26:29], v[214:217], v[182:185], v[26:29]
	v_mfma_f32_16x16x32_bf16 v[18:21], v[206:209], v[190:193], v[18:21]
	v_mfma_f32_16x16x32_bf16 v[10:13], v[214:217], v[190:193], v[10:13]
	v_mfma_f32_16x16x32_bf16 v[6:9], v[206:209], v[198:201], v[6:9]
	v_mfma_f32_16x16x32_bf16 v[2:5], v[214:217], v[198:201], v[2:5]
	s_add_i32 s60, s60, 2
	s_add_u32 s58, s58, 0x100
	s_addc_u32 s59, s59, 0
	s_add_u32 s30, s30, 0x100
	s_addc_u32 s31, s31, 0
	s_cmp_gt_u32 s60, 13
	s_barrier
	s_cbranch_scc0 .LBB0_278
	v_mov_b32_e32 v162, v1
	v_mov_b32_e32 v163, v156
	s_cmp_gt_i32 s55, 11
	s_mov_b64 s[30:31], -1
	s_cbranch_scc0 .LBB0_286
	s_cmp_eq_u32 s55, 12
	s_cselect_b64 s[0:1], -1, 0
	s_and_b64 s[0:1], s[0:1], s[18:19]
	v_cmp_gt_i32_e32 vcc, 2, v163
	s_and_b64 s[0:1], s[0:1], vcc
	s_and_saveexec_b64 s[30:31], s[0:1]
	s_cbranch_execz .LBB0_285
	v_lshlrev_b32_e32 v154, 3, v163
	s_andn2_b64 vcc, exec, s[12:13]
	v_ashrrev_i32_e32 v155, 31, v154
	s_cbranch_vccnz .LBB0_283
	v_lshl_add_u64 v[134:135], v[154:155], 2, s[8:9]
	global_load_dwordx4 v[130:133], v[134:135], off
	s_nop 0
	global_load_dwordx4 v[134:137], v[134:135], off offset:16
	s_branch .LBB0_284

.LBB0_688:
	s_add_u32 s10, s34, 0x100
	s_addc_u32 s11, s35, 0
	s_add_u32 s30, s29, s34
	s_addc_u32 s31, s55, s35
	s_cmpk_eq_i32 s34, 0x300
	s_cselect_b64 vcc, -1, 0
	s_and_b64 s[0:1], vcc, exec
	s_cselect_b32 s1, 0, s10
	s_cselect_b32 s0, 0, s11
	s_cselect_b32 s30, s27, s30
	s_cselect_b32 s31, s25, s31
	s_add_u32 s36, s14, s1
	s_addc_u32 s37, s15, s0
	s_add_i32 s1, 0, 0x10000
	v_add_u32_e32 v14, s1, v197
	ds_read_b128 v[2:5], v14
	ds_read_b128 v[6:9], v14 offset:1024
	ds_read_b128 v[10:13], v14 offset:2048
	ds_read_b128 v[14:17], v14 offset:3072
	v_cndmask_b32_e32 v162, v168, v171, vcc
	v_cndmask_b32_e32 v184, v170, v198, vcc
	v_cndmask_b32_e32 v175, v172, v199, vcc
	v_cndmask_b32_e32 v173, v174, v200, vcc
	v_lshl_add_u64 v[18:19], v[178:179], 0, s[34:35]
	s_add_i32 m0, s45, 0xc000
	ds_read_b128 v[202:205], v169
	ds_read_b128 v[206:209], v169 offset:1024
	ds_read_b128 v[210:213], v169 offset:2048
	ds_read_b128 v[214:217], v169 offset:3072
	ds_read_b128 v[218:221], v169 offset:4096
	ds_read_b128 v[222:225], v169 offset:5120
	ds_read_b128 v[226:229], v169 offset:6144
	ds_read_b128 v[230:233], v169 offset:7168
	global_load_lds_dwordx4 v[18:19], off nt
	v_lshl_add_u64 v[18:19], v[176:177], 0, s[34:35]
	s_add_i32 m0, s45, 0xe000
	s_nop 0
	global_load_lds_dwordx4 v[18:19], off nt
	s_waitcnt lgkmcnt(8)
	s_waitcnt vmcnt(10)
	s_barrier
	s_waitcnt lgkmcnt(0)
	s_waitcnt lgkmcnt(0)
	v_mfma_scale_f32_16x16x128_f8f6f4 v[158:161], v[2:9], v[202:209], v[158:161], v188, v188 op_sel_hi:[0,0,0]
	v_mfma_scale_f32_16x16x128_f8f6f4 v[150:153], v[10:17], v[202:209], v[150:153], v188, v188 op_sel_hi:[0,0,0]
	v_mfma_scale_f32_16x16x128_f8f6f4 v[142:145], v[2:9], v[210:217], v[142:145], v188, v188 op_sel_hi:[0,0,0]
	v_mfma_scale_f32_16x16x128_f8f6f4 v[134:137], v[10:17], v[210:217], v[134:137], v188, v188 op_sel_hi:[0,0,0]
	v_mfma_scale_f32_16x16x128_f8f6f4 v[126:129], v[2:9], v[218:225], v[126:129], v188, v188 op_sel_hi:[0,0,0]
	v_mfma_scale_f32_16x16x128_f8f6f4 v[118:121], v[10:17], v[218:225], v[118:121], v188, v188 op_sel_hi:[0,0,0]
	v_mfma_scale_f32_16x16x128_f8f6f4 v[110:113], v[2:9], v[226:233], v[110:113], v188, v188 op_sel_hi:[0,0,0]
	v_mfma_scale_f32_16x16x128_f8f6f4 v[102:105], v[10:17], v[226:233], v[102:105], v188, v188 op_sel_hi:[0,0,0]
	s_barrier
	s_add_i32 s0, 0, 0x14000
	s_add_i32 s1, s1, s43
	v_add_u32_e32 v30, s0, v197
	v_lshl_add_u64 v[180:181], s[30:31], 0, v[164:165]
	s_mov_b32 m0, s1
	ds_read_b128 v[18:21], v30
	ds_read_b128 v[22:25], v30 offset:1024
	ds_read_b128 v[26:29], v30 offset:2048
	ds_read_b128 v[30:33], v30 offset:3072
	global_load_lds_dwordx4 v[180:181], off
	v_lshl_add_u64 v[182:183], s[30:31], 0, v[166:167]
	s_add_i32 m0, s1, 0x2000
	s_nop 0
	global_load_lds_dwordx4 v[182:183], off
	s_waitcnt vmcnt(10)
	s_barrier
	s_waitcnt lgkmcnt(0)
	s_waitcnt lgkmcnt(0)
	v_mfma_scale_f32_16x16x128_f8f6f4 v[154:157], v[18:25], v[202:209], v[154:157], v188, v188 op_sel_hi:[0,0,0]
	v_mfma_scale_f32_16x16x128_f8f6f4 v[146:149], v[26:33], v[202:209], v[146:149], v188, v188 op_sel_hi:[0,0,0]
	v_mfma_scale_f32_16x16x128_f8f6f4 v[138:141], v[18:25], v[210:217], v[138:141], v188, v188 op_sel_hi:[0,0,0]
	v_mfma_scale_f32_16x16x128_f8f6f4 v[130:133], v[26:33], v[210:217], v[130:133], v188, v188 op_sel_hi:[0,0,0]
	v_mfma_scale_f32_16x16x128_f8f6f4 v[122:125], v[18:25], v[218:225], v[122:125], v188, v188 op_sel_hi:[0,0,0]
	v_mfma_scale_f32_16x16x128_f8f6f4 v[114:117], v[26:33], v[218:225], v[114:117], v188, v188 op_sel_hi:[0,0,0]
	v_mfma_scale_f32_16x16x128_f8f6f4 v[106:109], v[18:25], v[226:233], v[106:109], v188, v188 op_sel_hi:[0,0,0]
	v_mfma_scale_f32_16x16x128_f8f6f4 v[98:101], v[26:33], v[226:233], v[98:101], v188, v188 op_sel_hi:[0,0,0]
	s_mov_b32 m0, s45
	s_barrier
	ds_read_b128 v[202:205], v169 offset:16384
	ds_read_b128 v[206:209], v169 offset:17408
	ds_read_b128 v[210:213], v169 offset:18432
	ds_read_b128 v[214:217], v169 offset:19456
	ds_read_b128 v[218:221], v169 offset:20480
	ds_read_b128 v[222:225], v169 offset:21504
	ds_read_b128 v[226:229], v169 offset:22528
	ds_read_b128 v[230:233], v169 offset:23552
	global_load_lds_dwordx4 v162, s[36:37] nt
	s_mov_b32 m0, s46
	v_mov_b32_e32 v185, v163
	global_load_lds_dwordx4 v184, s[36:37] nt
	s_waitcnt vmcnt(10)
	s_barrier
	s_waitcnt lgkmcnt(0)
	v_lshl_add_u64 v[186:187], s[36:37], 0, v[162:163]
	v_lshl_add_u64 v[184:185], s[36:37], 0, v[184:185]
	s_waitcnt lgkmcnt(0)
	v_mfma_scale_f32_16x16x128_f8f6f4 v[94:97], v[2:9], v[202:209], v[94:97], v188, v188 op_sel_hi:[0,0,0]
	v_mfma_scale_f32_16x16x128_f8f6f4 v[86:89], v[10:17], v[202:209], v[86:89], v188, v188 op_sel_hi:[0,0,0]
	v_mfma_scale_f32_16x16x128_f8f6f4 v[78:81], v[2:9], v[210:217], v[78:81], v188, v188 op_sel_hi:[0,0,0]
	v_mfma_scale_f32_16x16x128_f8f6f4 v[70:73], v[10:17], v[210:217], v[70:73], v188, v188 op_sel_hi:[0,0,0]
	v_mfma_scale_f32_16x16x128_f8f6f4 v[62:65], v[2:9], v[218:225], v[62:65], v188, v188 op_sel_hi:[0,0,0]
	v_mfma_scale_f32_16x16x128_f8f6f4 v[54:57], v[10:17], v[218:225], v[54:57], v188, v188 op_sel_hi:[0,0,0]
	v_mfma_scale_f32_16x16x128_f8f6f4 v[46:49], v[2:9], v[226:233], v[46:49], v188, v188 op_sel_hi:[0,0,0]
	v_mfma_scale_f32_16x16x128_f8f6f4 v[38:41], v[10:17], v[226:233], v[38:41], v188, v188 op_sel_hi:[0,0,0]
	s_barrier
	s_add_u32 s34, s30, 0x20000
	s_addc_u32 s35, s31, 0
	s_add_i32 s0, s0, s43
	v_lshl_add_u64 v[2:3], s[34:35], 0, v[164:165]
	s_mov_b32 m0, s0
	s_nop 0
	global_load_lds_dwordx4 v[2:3], off
	v_lshl_add_u64 v[2:3], s[34:35], 0, v[166:167]
	s_add_i32 m0, s0, 0x2000
	s_nop 0
	global_load_lds_dwordx4 v[2:3], off
	s_waitcnt vmcnt(10)
	s_barrier
	v_mfma_scale_f32_16x16x128_f8f6f4 v[90:93], v[18:25], v[202:209], v[90:93], v188, v188 op_sel_hi:[0,0,0]
	v_mfma_scale_f32_16x16x128_f8f6f4 v[82:85], v[26:33], v[202:209], v[82:85], v188, v188 op_sel_hi:[0,0,0]
	v_mfma_scale_f32_16x16x128_f8f6f4 v[74:77], v[18:25], v[210:217], v[74:77], v188, v188 op_sel_hi:[0,0,0]
	v_mfma_scale_f32_16x16x128_f8f6f4 v[66:69], v[26:33], v[210:217], v[66:69], v188, v188 op_sel_hi:[0,0,0]
	v_mfma_scale_f32_16x16x128_f8f6f4 v[58:61], v[18:25], v[218:225], v[58:61], v188, v188 op_sel_hi:[0,0,0]
	v_mfma_scale_f32_16x16x128_f8f6f4 v[50:53], v[26:33], v[218:225], v[50:53], v188, v188 op_sel_hi:[0,0,0]
	v_mfma_scale_f32_16x16x128_f8f6f4 v[42:45], v[18:25], v[226:233], v[42:45], v188, v188 op_sel_hi:[0,0,0]
	v_mfma_scale_f32_16x16x128_f8f6f4 v[34:37], v[26:33], v[226:233], v[34:37], v188, v188 op_sel_hi:[0,0,0]
	s_add_i32 s0, 0, 0x18000
	v_add_u32_e32 v14, s0, v197
	s_barrier
	ds_read_b128 v[2:5], v14
	ds_read_b128 v[6:9], v14 offset:1024
	ds_read_b128 v[10:13], v14 offset:2048
	ds_read_b128 v[14:17], v14 offset:3072
	s_mov_b32 m0, s47
	ds_read_b128 v[18:21], v169 offset:32768
	ds_read_b128 v[22:25], v169 offset:33792
	ds_read_b128 v[26:29], v169 offset:34816
	ds_read_b128 v[30:33], v169 offset:35840
	ds_read_b128 v[202:205], v169 offset:36864
	ds_read_b128 v[206:209], v169 offset:37888
	ds_read_b128 v[210:213], v169 offset:38912
	ds_read_b128 v[214:217], v169 offset:39936
	global_load_lds_dwordx4 v175, s[36:37] nt
	s_mov_b32 m0, s48
	s_nop 0
	global_load_lds_dwordx4 v173, s[36:37] nt
	s_waitcnt lgkmcnt(8)
	s_waitcnt vmcnt(10)
	s_barrier
	s_waitcnt lgkmcnt(0)
	s_waitcnt lgkmcnt(0)
	v_mfma_scale_f32_16x16x128_f8f6f4 v[158:161], v[2:9], v[18:25], v[158:161], v188, v188 op_sel_hi:[0,0,0]
	v_mfma_scale_f32_16x16x128_f8f6f4 v[150:153], v[10:17], v[18:25], v[150:153], v188, v188 op_sel_hi:[0,0,0]
	v_mfma_scale_f32_16x16x128_f8f6f4 v[142:145], v[2:9], v[26:33], v[142:145], v188, v188 op_sel_hi:[0,0,0]
	v_mfma_scale_f32_16x16x128_f8f6f4 v[134:137], v[10:17], v[26:33], v[134:137], v188, v188 op_sel_hi:[0,0,0]
	v_mfma_scale_f32_16x16x128_f8f6f4 v[126:129], v[2:9], v[202:209], v[126:129], v188, v188 op_sel_hi:[0,0,0]
	v_mfma_scale_f32_16x16x128_f8f6f4 v[118:121], v[10:17], v[202:209], v[118:121], v188, v188 op_sel_hi:[0,0,0]
	v_mfma_scale_f32_16x16x128_f8f6f4 v[110:113], v[2:9], v[210:217], v[110:113], v188, v188 op_sel_hi:[0,0,0]
	v_mfma_scale_f32_16x16x128_f8f6f4 v[102:105], v[10:17], v[210:217], v[102:105], v188, v188 op_sel_hi:[0,0,0]
	s_barrier
	s_add_i32 s34, 0, 0x1c000
	s_add_i32 s0, s0, s43
	v_add_u32_e32 v162, s34, v197
	v_lshl_add_u64 v[180:181], v[180:181], 0, s[20:21]
	s_mov_b32 m0, s0
	ds_read_b128 v[218:221], v162
	ds_read_b128 v[222:225], v162 offset:1024
	ds_read_b128 v[226:229], v162 offset:2048
	ds_read_b128 v[230:233], v162 offset:3072
	global_load_lds_dwordx4 v[180:181], off
	v_lshl_add_u64 v[180:181], v[182:183], 0, s[20:21]
	s_add_i32 m0, s0, 0x2000
	s_nop 0
	global_load_lds_dwordx4 v[180:181], off
	s_waitcnt vmcnt(10)
	s_barrier
	s_waitcnt lgkmcnt(0)
	s_waitcnt lgkmcnt(0)
	v_mfma_scale_f32_16x16x128_f8f6f4 v[154:157], v[218:225], v[18:25], v[154:157], v188, v188 op_sel_hi:[0,0,0]
	v_mfma_scale_f32_16x16x128_f8f6f4 v[146:149], v[226:233], v[18:25], v[146:149], v188, v188 op_sel_hi:[0,0,0]
	v_mfma_scale_f32_16x16x128_f8f6f4 v[138:141], v[218:225], v[26:33], v[138:141], v188, v188 op_sel_hi:[0,0,0]
	v_mfma_scale_f32_16x16x128_f8f6f4 v[130:133], v[226:233], v[26:33], v[130:133], v188, v188 op_sel_hi:[0,0,0]
	v_mfma_scale_f32_16x16x128_f8f6f4 v[122:125], v[218:225], v[202:209], v[122:125], v188, v188 op_sel_hi:[0,0,0]
	v_mfma_scale_f32_16x16x128_f8f6f4 v[114:117], v[226:233], v[202:209], v[114:117], v188, v188 op_sel_hi:[0,0,0]
	v_mfma_scale_f32_16x16x128_f8f6f4 v[106:109], v[218:225], v[210:217], v[106:109], v188, v188 op_sel_hi:[0,0,0]
	v_mfma_scale_f32_16x16x128_f8f6f4 v[98:101], v[226:233], v[210:217], v[98:101], v188, v188 op_sel_hi:[0,0,0]
	s_mov_b32 m0, s51
	v_lshl_add_u64 v[180:181], v[186:187], 0, s[20:21]
	s_barrier
	ds_read_b128 v[18:21], v169 offset:49152
	ds_read_b128 v[22:25], v169 offset:50176
	ds_read_b128 v[26:29], v169 offset:51200
	ds_read_b128 v[30:33], v169 offset:52224
	ds_read_b128 v[202:205], v169 offset:53248
	ds_read_b128 v[206:209], v169 offset:54272
	ds_read_b128 v[210:213], v169 offset:55296
	ds_read_b128 v[214:217], v169 offset:56320
	global_load_lds_dwordx4 v[180:181], off nt
	v_lshl_add_u64 v[180:181], v[184:185], 0, s[20:21]
	s_mov_b32 m0, s52
	s_nop 0
	global_load_lds_dwordx4 v[180:181], off nt
	s_waitcnt vmcnt(10)
	s_barrier
	s_waitcnt lgkmcnt(0)
	s_waitcnt lgkmcnt(0)
	v_mfma_scale_f32_16x16x128_f8f6f4 v[94:97], v[2:9], v[18:25], v[94:97], v188, v188 op_sel_hi:[0,0,0]
	v_mfma_scale_f32_16x16x128_f8f6f4 v[86:89], v[10:17], v[18:25], v[86:89], v188, v188 op_sel_hi:[0,0,0]
	v_mfma_scale_f32_16x16x128_f8f6f4 v[78:81], v[2:9], v[26:33], v[78:81], v188, v188 op_sel_hi:[0,0,0]
	v_mfma_scale_f32_16x16x128_f8f6f4 v[70:73], v[10:17], v[26:33], v[70:73], v188, v188 op_sel_hi:[0,0,0]
	v_mfma_scale_f32_16x16x128_f8f6f4 v[62:65], v[2:9], v[202:209], v[62:65], v188, v188 op_sel_hi:[0,0,0]
	v_mfma_scale_f32_16x16x128_f8f6f4 v[54:57], v[10:17], v[202:209], v[54:57], v188, v188 op_sel_hi:[0,0,0]
	v_mfma_scale_f32_16x16x128_f8f6f4 v[46:49], v[2:9], v[210:217], v[46:49], v188, v188 op_sel_hi:[0,0,0]
	v_mfma_scale_f32_16x16x128_f8f6f4 v[38:41], v[10:17], v[210:217], v[38:41], v188, v188 op_sel_hi:[0,0,0]
	s_barrier
	s_add_u32 s0, s30, 0x20080
	s_addc_u32 s1, s31, 0
	s_add_i32 s30, s34, s43
	v_lshl_add_u64 v[2:3], s[0:1], 0, v[164:165]
	s_mov_b32 m0, s30
	s_nop 0
	global_load_lds_dwordx4 v[2:3], off
	v_lshl_add_u64 v[2:3], s[0:1], 0, v[166:167]
	s_add_i32 m0, s30, 0x2000
	s_nop 0
	global_load_lds_dwordx4 v[2:3], off
	s_waitcnt vmcnt(10)
	s_barrier
	v_mfma_scale_f32_16x16x128_f8f6f4 v[90:93], v[218:225], v[18:25], v[90:93], v188, v188 op_sel_hi:[0,0,0]
	v_mfma_scale_f32_16x16x128_f8f6f4 v[82:85], v[226:233], v[18:25], v[82:85], v188, v188 op_sel_hi:[0,0,0]
	v_mfma_scale_f32_16x16x128_f8f6f4 v[74:77], v[218:225], v[26:33], v[74:77], v188, v188 op_sel_hi:[0,0,0]
	v_mfma_scale_f32_16x16x128_f8f6f4 v[66:69], v[226:233], v[26:33], v[66:69], v188, v188 op_sel_hi:[0,0,0]
	v_mfma_scale_f32_16x16x128_f8f6f4 v[58:61], v[218:225], v[202:209], v[58:61], v188, v188 op_sel_hi:[0,0,0]
	v_mfma_scale_f32_16x16x128_f8f6f4 v[50:53], v[226:233], v[202:209], v[50:53], v188, v188 op_sel_hi:[0,0,0]
	v_mfma_scale_f32_16x16x128_f8f6f4 v[42:45], v[218:225], v[210:217], v[42:45], v188, v188 op_sel_hi:[0,0,0]
	v_mfma_scale_f32_16x16x128_f8f6f4 v[34:37], v[226:233], v[210:217], v[34:37], v188, v188 op_sel_hi:[0,0,0]
	s_add_i32 s56, s56, 2
	s_cmp_gt_u32 s56, 5
	s_mov_b64 s[34:35], s[10:11]
	s_barrier
	s_cbranch_scc0 .LBB0_688
	v_mul_f32_e32 v5, 0x3c800000, v158
	v_mul_f32_e32 v6, 0xbfb8aa3b, v5
	v_exp_f32_e32 v6, v6
	s_ashr_i32 s29, s28, 31
	s_ashr_i32 s27, s26, 31
	s_lshl_b64 s[10:11], s[28:29], 18
	v_add_f32_e32 v6, 1.0, v6
	v_rcp_f32_e32 v6, v6
	s_lshl_b64 s[26:27], s[26:27], 15
	v_mov_b32_e32 v3, v195
	s_add_u32 s0, s6, s10
	v_mul_f32_e32 v5, v5, v6
	v_mul_f32_e32 v6, 0x3c800000, v159
	v_mul_f32_e32 v7, 0xbfb8aa3b, v6
	v_exp_f32_e32 v7, v7
	v_mul_f32_e32 v5, v5, v154
	v_mul_f32_e32 v5, 0x3e000000, v5
	v_med3_f32 v5, v5, s40, v190
	v_add_f32_e32 v7, 1.0, v7
	v_rcp_f32_e32 v7, v7
	s_nop 15
	s_nop 15
	v_mov_b32_e32 v2, v196
	v_mul_f32_e32 v6, v6, v7
	v_mul_f32_e32 v7, 0x3c800000, v160
	v_mul_f32_e32 v8, 0xbfb8aa3b, v7
	v_exp_f32_e32 v8, v8
	v_mul_f32_e32 v6, v6, v155
	v_mul_f32_e32 v6, 0x3e000000, v6
	v_add_u32_e32 v4, s49, v3
	v_add_f32_e32 v8, 1.0, v8
	v_rcp_f32_e32 v8, v8
	s_addc_u32 s1, s7, s11
	s_add_u32 s10, s0, s26
	v_mul_f32_e32 v7, v7, v8
	v_mul_f32_e32 v8, 0x3c800000, v161
	v_mul_f32_e32 v9, 0xbfb8aa3b, v8
	v_exp_f32_e32 v9, v9
	v_mul_f32_e32 v7, v7, v156
	v_mul_f32_e32 v7, 0x3e000000, v7
	v_lshl_add_u32 v2, v2, 3, s50
	v_add_f32_e32 v9, 1.0, v9
	v_rcp_f32_e32 v9, v9
	s_addc_u32 s11, s1, s27
	v_ashrrev_i32_e32 v3, 31, v2
	s_and_b64 vcc, exec, s[8:9]
	v_mul_f32_e32 v8, v8, v9
	v_mul_f32_e32 v9, 0x3c800000, v150
	v_mul_f32_e32 v10, 0xbfb8aa3b, v9
	v_exp_f32_e32 v10, v10
	v_mul_f32_e32 v8, v8, v157
	v_mul_f32_e32 v8, 0x3e000000, v8
	v_mov_b32_e32 v174, v200
	v_add_f32_e32 v10, 1.0, v10
	v_rcp_f32_e32 v10, v10
	v_mov_b32_e32 v172, v199
	v_mov_b32_e32 v170, v198
	v_mov_b32_e32 v168, v171
	v_mul_f32_e32 v9, v9, v10
	v_mul_f32_e32 v10, 0x3c800000, v151
	v_mul_f32_e32 v11, 0xbfb8aa3b, v10
	v_exp_f32_e32 v11, v11
	v_mul_f32_e32 v9, v9, v146
	v_mul_f32_e32 v9, 0x3e000000, v9
	s_mov_b32 s26, s24
	v_add_f32_e32 v11, 1.0, v11
	v_rcp_f32_e32 v11, v11
	s_mov_b32 s28, s54
	s_mov_b64 s[30:31], s[12:13]
	v_mul_f32_e32 v10, v10, v11
	v_mul_f32_e32 v11, 0x3c800000, v152
	v_mul_f32_e32 v12, 0xbfb8aa3b, v11
	v_exp_f32_e32 v12, v12
	v_mul_f32_e32 v10, v10, v147
	v_mul_f32_e32 v10, 0x3e000000, v10
	v_add_f32_e32 v12, 1.0, v12
	v_rcp_f32_e32 v12, v12
	s_nop 0
	v_mul_f32_e32 v11, v11, v12
	v_mul_f32_e32 v12, 0x3c800000, v153
	v_mul_f32_e32 v13, 0xbfb8aa3b, v12
	v_exp_f32_e32 v13, v13
	v_mul_f32_e32 v11, v11, v148
	v_mul_f32_e32 v11, 0x3e000000, v11
	v_add_f32_e32 v13, 1.0, v13
	v_rcp_f32_e32 v13, v13
	s_nop 0
	v_mul_f32_e32 v12, v12, v13
	v_med3_f32 v13, v6, s40, v190
	v_mov_b32_e32 v6, v163
	v_cvt_pk_fp8_f32 v6, v5, v13
	v_med3_f32 v5, v7, s40, v190
	v_med3_f32 v7, v8, s40, v190
	v_med3_f32 v8, v10, s40, v190
	v_cvt_pk_fp8_f32 v6, v5, v7 op_sel:[0,0,1]
	v_med3_f32 v5, v9, s40, v190
	v_mov_b32_e32 v7, v163
	v_cvt_pk_fp8_f32 v7, v5, v8
	v_mul_f32_e32 v12, v12, v149
	v_mul_f32_e32 v12, 0x3e000000, v12
	v_med3_f32 v5, v11, s40, v190
	v_med3_f32 v8, v12, s40, v190
	v_cvt_pk_fp8_f32 v7, v5, v8 op_sel:[0,0,1]
	v_ashrrev_i32_e32 v5, 31, v4
	v_lshlrev_b64 v[8:9], 7, v[4:5]
	v_lshl_add_u64 v[8:9], s[10:11], 0, v[8:9]
	v_lshl_add_u64 v[8:9], v[8:9], 0, v[2:3]
	v_mul_f32_e32 v5, 0x3c800000, v142
	global_store_dwordx2 v[8:9], v[6:7], off
	v_mul_f32_e32 v6, 0xbfb8aa3b, v5
	v_exp_f32_e32 v6, v6
	s_nop 0
	v_add_f32_e32 v6, 1.0, v6
	v_rcp_f32_e32 v6, v6
	s_nop 0
	v_mul_f32_e32 v5, v5, v6
	v_mul_f32_e32 v6, 0x3c800000, v143
	v_mul_f32_e32 v7, 0xbfb8aa3b, v6
	v_exp_f32_e32 v7, v7
	v_mul_f32_e32 v5, v5, v138
	v_mul_f32_e32 v5, 0x3e000000, v5
	v_med3_f32 v5, v5, s40, v190
	v_add_f32_e32 v7, 1.0, v7
	v_rcp_f32_e32 v7, v7
	s_nop 0
	v_mul_f32_e32 v6, v6, v7
	v_mul_f32_e32 v6, v6, v139
	v_mul_f32_e32 v7, 0x3e000000, v6
	v_mul_f32_e32 v6, 0x3c800000, v144
	v_mul_f32_e32 v8, 0xbfb8aa3b, v6
	v_exp_f32_e32 v8, v8
	v_med3_f32 v7, v7, s40, v190
	v_add_f32_e32 v8, 1.0, v8
	v_rcp_f32_e32 v8, v8
	s_nop 0
	v_mul_f32_e32 v6, v6, v8
	v_mul_f32_e32 v6, v6, v140
	v_mul_f32_e32 v9, 0x3e000000, v6
	v_mul_f32_e32 v6, 0x3c800000, v145
	v_mul_f32_e32 v8, 0xbfb8aa3b, v6
	v_exp_f32_e32 v8, v8
	s_nop 0
	v_add_f32_e32 v8, 1.0, v8
	v_rcp_f32_e32 v8, v8
	s_nop 0
	v_mul_f32_e32 v6, v6, v8
	v_mul_f32_e32 v6, v6, v141
	v_mul_f32_e32 v10, 0x3e000000, v6
	v_mul_f32_e32 v6, 0x3c800000, v134
	v_mul_f32_e32 v8, 0xbfb8aa3b, v6
	v_exp_f32_e32 v8, v8
	s_nop 0
	v_add_f32_e32 v8, 1.0, v8
	v_rcp_f32_e32 v8, v8
	s_nop 0
	v_mul_f32_e32 v6, v6, v8
	v_mul_f32_e32 v6, v6, v130
	v_mul_f32_e32 v11, 0x3e000000, v6
	v_mul_f32_e32 v6, 0x3c800000, v135
	v_mul_f32_e32 v8, 0xbfb8aa3b, v6
	v_exp_f32_e32 v8, v8
	s_nop 0
	v_add_f32_e32 v8, 1.0, v8
	v_rcp_f32_e32 v8, v8
	s_nop 0
	v_mul_f32_e32 v6, v6, v8
	v_mul_f32_e32 v6, v6, v131
	v_mul_f32_e32 v12, 0x3e000000, v6
	v_mul_f32_e32 v6, 0x3c800000, v136
	v_mul_f32_e32 v8, 0xbfb8aa3b, v6
	v_exp_f32_e32 v8, v8
	s_nop 0
	v_add_f32_e32 v8, 1.0, v8
	v_rcp_f32_e32 v8, v8
	s_nop 0
	v_mul_f32_e32 v6, v6, v8
	v_mul_f32_e32 v6, v6, v132
	v_mul_f32_e32 v13, 0x3e000000, v6
	v_mul_f32_e32 v6, 0x3c800000, v137
	v_mul_f32_e32 v8, 0xbfb8aa3b, v6
	v_exp_f32_e32 v8, v8
	s_nop 0
	v_add_f32_e32 v8, 1.0, v8
	v_rcp_f32_e32 v8, v8
	s_nop 0
	v_mul_f32_e32 v6, v6, v8
	v_mov_b32_e32 v8, v163
	v_cvt_pk_fp8_f32 v8, v5, v7
	v_med3_f32 v5, v9, s40, v190
	v_med3_f32 v7, v10, s40, v190
	v_mov_b32_e32 v9, v163
	v_cvt_pk_fp8_f32 v8, v5, v7 op_sel:[0,0,1]
	v_med3_f32 v5, v11, s40, v190
	v_med3_f32 v7, v12, s40, v190
	v_cvt_pk_fp8_f32 v9, v5, v7
	v_mul_f32_e32 v6, v6, v133
	v_mul_f32_e32 v14, 0x3e000000, v6
	v_add_u32_e32 v6, 16, v4
	v_med3_f32 v5, v13, s40, v190
	v_med3_f32 v7, v14, s40, v190
	v_cvt_pk_fp8_f32 v9, v5, v7 op_sel:[0,0,1]
	v_ashrrev_i32_e32 v7, 31, v6
	v_lshlrev_b64 v[6:7], 7, v[6:7]
	v_lshl_add_u64 v[6:7], s[10:11], 0, v[6:7]
	v_lshl_add_u64 v[6:7], v[6:7], 0, v[2:3]
	v_mul_f32_e32 v5, 0x3c800000, v126
	global_store_dwordx2 v[6:7], v[8:9], off
	v_mul_f32_e32 v6, 0xbfb8aa3b, v5
	v_exp_f32_e32 v6, v6
	s_nop 0
	v_add_f32_e32 v6, 1.0, v6
	v_rcp_f32_e32 v6, v6
	s_nop 0
	v_mul_f32_e32 v5, v5, v6
	v_mul_f32_e32 v6, 0x3c800000, v127
	v_mul_f32_e32 v7, 0xbfb8aa3b, v6
	v_exp_f32_e32 v7, v7
	v_mul_f32_e32 v5, v5, v122
	v_mul_f32_e32 v5, 0x3e000000, v5
	v_med3_f32 v5, v5, s40, v190
	v_add_f32_e32 v7, 1.0, v7
	v_rcp_f32_e32 v7, v7
	s_nop 0
	v_mul_f32_e32 v6, v6, v7
	v_mul_f32_e32 v6, v6, v123
	v_mul_f32_e32 v7, 0x3e000000, v6
	v_mul_f32_e32 v6, 0x3c800000, v128
	v_mul_f32_e32 v8, 0xbfb8aa3b, v6
	v_exp_f32_e32 v8, v8
	v_med3_f32 v7, v7, s40, v190
	v_add_f32_e32 v8, 1.0, v8
	v_rcp_f32_e32 v8, v8
	s_nop 0
	v_mul_f32_e32 v6, v6, v8
	v_mul_f32_e32 v6, v6, v124
	v_mul_f32_e32 v9, 0x3e000000, v6
	v_mul_f32_e32 v6, 0x3c800000, v129
	v_mul_f32_e32 v8, 0xbfb8aa3b, v6
	v_exp_f32_e32 v8, v8
	s_nop 0
	v_add_f32_e32 v8, 1.0, v8
	v_rcp_f32_e32 v8, v8
	s_nop 0
	v_mul_f32_e32 v6, v6, v8
	v_mul_f32_e32 v6, v6, v125
	v_mul_f32_e32 v10, 0x3e000000, v6
	v_mul_f32_e32 v6, 0x3c800000, v118
	v_mul_f32_e32 v8, 0xbfb8aa3b, v6
	v_exp_f32_e32 v8, v8
	s_nop 0
	v_add_f32_e32 v8, 1.0, v8
	v_rcp_f32_e32 v8, v8
	s_nop 0
	v_mul_f32_e32 v6, v6, v8
	v_mul_f32_e32 v6, v6, v114
	v_mul_f32_e32 v11, 0x3e000000, v6
	v_mul_f32_e32 v6, 0x3c800000, v119
	v_mul_f32_e32 v8, 0xbfb8aa3b, v6
	v_exp_f32_e32 v8, v8
	s_nop 0
	v_add_f32_e32 v8, 1.0, v8
	v_rcp_f32_e32 v8, v8
	s_nop 0
	v_mul_f32_e32 v6, v6, v8
	v_mul_f32_e32 v6, v6, v115
	v_mul_f32_e32 v12, 0x3e000000, v6
	v_mul_f32_e32 v6, 0x3c800000, v120
	v_mul_f32_e32 v8, 0xbfb8aa3b, v6
	v_exp_f32_e32 v8, v8
	s_nop 0
	v_add_f32_e32 v8, 1.0, v8
	v_rcp_f32_e32 v8, v8
	s_nop 0
	v_mul_f32_e32 v6, v6, v8
	v_mul_f32_e32 v6, v6, v116
	v_mul_f32_e32 v13, 0x3e000000, v6
	v_mul_f32_e32 v6, 0x3c800000, v121
	v_mul_f32_e32 v8, 0xbfb8aa3b, v6
	v_exp_f32_e32 v8, v8
	s_nop 0
	v_add_f32_e32 v8, 1.0, v8
	v_rcp_f32_e32 v8, v8
	s_nop 0
	v_mul_f32_e32 v6, v6, v8
	v_mov_b32_e32 v8, v163
	v_cvt_pk_fp8_f32 v8, v5, v7
	v_med3_f32 v5, v9, s40, v190
	v_med3_f32 v7, v10, s40, v190
	v_mov_b32_e32 v9, v163
	v_cvt_pk_fp8_f32 v8, v5, v7 op_sel:[0,0,1]
	v_med3_f32 v5, v11, s40, v190
	v_med3_f32 v7, v12, s40, v190
	v_cvt_pk_fp8_f32 v9, v5, v7
	v_mul_f32_e32 v6, v6, v117
	v_mul_f32_e32 v14, 0x3e000000, v6
	v_add_u32_e32 v6, 32, v4
	v_med3_f32 v5, v13, s40, v190
	v_med3_f32 v7, v14, s40, v190
	v_cvt_pk_fp8_f32 v9, v5, v7 op_sel:[0,0,1]
	v_ashrrev_i32_e32 v7, 31, v6
	v_lshlrev_b64 v[6:7], 7, v[6:7]
	v_lshl_add_u64 v[6:7], s[10:11], 0, v[6:7]
	v_lshl_add_u64 v[6:7], v[6:7], 0, v[2:3]
	v_mul_f32_e32 v5, 0x3c800000, v110
	global_store_dwordx2 v[6:7], v[8:9], off
	v_mul_f32_e32 v6, 0xbfb8aa3b, v5
	v_exp_f32_e32 v6, v6
	s_nop 0
	v_add_f32_e32 v6, 1.0, v6
	v_rcp_f32_e32 v6, v6
	s_nop 0
	v_mul_f32_e32 v5, v5, v6
	v_mul_f32_e32 v6, 0x3c800000, v111
	v_mul_f32_e32 v7, 0xbfb8aa3b, v6
	v_exp_f32_e32 v7, v7
	v_mul_f32_e32 v5, v5, v106
	v_mul_f32_e32 v5, 0x3e000000, v5
	v_med3_f32 v5, v5, s40, v190
	v_add_f32_e32 v7, 1.0, v7
	v_rcp_f32_e32 v7, v7
	s_nop 0
	v_mul_f32_e32 v6, v6, v7
	v_mul_f32_e32 v6, v6, v107
	v_mul_f32_e32 v7, 0x3e000000, v6
	v_mul_f32_e32 v6, 0x3c800000, v112
	v_mul_f32_e32 v8, 0xbfb8aa3b, v6
	v_exp_f32_e32 v8, v8
	v_med3_f32 v7, v7, s40, v190
	v_add_f32_e32 v8, 1.0, v8
	v_rcp_f32_e32 v8, v8
	s_nop 0
	v_mul_f32_e32 v6, v6, v8
	v_mul_f32_e32 v6, v6, v108
	v_mul_f32_e32 v9, 0x3e000000, v6
	v_mul_f32_e32 v6, 0x3c800000, v113
	v_mul_f32_e32 v8, 0xbfb8aa3b, v6
	v_exp_f32_e32 v8, v8
	s_nop 0
	v_add_f32_e32 v8, 1.0, v8
	v_rcp_f32_e32 v8, v8
	s_nop 0
	v_mul_f32_e32 v6, v6, v8
	v_mul_f32_e32 v6, v6, v109
	v_mul_f32_e32 v10, 0x3e000000, v6
	v_mul_f32_e32 v6, 0x3c800000, v102
	v_mul_f32_e32 v8, 0xbfb8aa3b, v6
	v_exp_f32_e32 v8, v8
	s_nop 0
	v_add_f32_e32 v8, 1.0, v8
	v_rcp_f32_e32 v8, v8
	s_nop 0
	v_mul_f32_e32 v6, v6, v8
	v_mul_f32_e32 v6, v6, v98
	v_mul_f32_e32 v11, 0x3e000000, v6
	v_mul_f32_e32 v6, 0x3c800000, v103
	v_mul_f32_e32 v8, 0xbfb8aa3b, v6
	v_exp_f32_e32 v8, v8
	s_nop 0
	v_add_f32_e32 v8, 1.0, v8
	v_rcp_f32_e32 v8, v8
	s_nop 0
	v_mul_f32_e32 v6, v6, v8
	v_mul_f32_e32 v6, v6, v99
	v_mul_f32_e32 v12, 0x3e000000, v6
	v_mul_f32_e32 v6, 0x3c800000, v104
	v_mul_f32_e32 v8, 0xbfb8aa3b, v6
	v_exp_f32_e32 v8, v8
	s_nop 0
	v_add_f32_e32 v8, 1.0, v8
	v_rcp_f32_e32 v8, v8
	s_nop 0
	v_mul_f32_e32 v6, v6, v8
	v_mul_f32_e32 v6, v6, v100
	v_mul_f32_e32 v13, 0x3e000000, v6
	v_mul_f32_e32 v6, 0x3c800000, v105
	v_mul_f32_e32 v8, 0xbfb8aa3b, v6
	v_exp_f32_e32 v8, v8
	s_nop 0
	v_add_f32_e32 v8, 1.0, v8
	v_rcp_f32_e32 v8, v8
	s_nop 0
	v_mul_f32_e32 v6, v6, v8
	v_mov_b32_e32 v8, v163
	v_cvt_pk_fp8_f32 v8, v5, v7
	v_med3_f32 v5, v9, s40, v190
	v_med3_f32 v7, v10, s40, v190
	v_mov_b32_e32 v9, v163
	v_cvt_pk_fp8_f32 v8, v5, v7 op_sel:[0,0,1]
	v_med3_f32 v5, v11, s40, v190
	v_med3_f32 v7, v12, s40, v190
	v_cvt_pk_fp8_f32 v9, v5, v7
	v_mul_f32_e32 v6, v6, v101
	v_mul_f32_e32 v14, 0x3e000000, v6
	v_add_u32_e32 v6, 48, v4
	v_med3_f32 v5, v13, s40, v190
	v_med3_f32 v7, v14, s40, v190
	v_cvt_pk_fp8_f32 v9, v5, v7 op_sel:[0,0,1]
	v_ashrrev_i32_e32 v7, 31, v6
	v_lshlrev_b64 v[6:7], 7, v[6:7]
	v_lshl_add_u64 v[6:7], s[10:11], 0, v[6:7]
	v_lshl_add_u64 v[6:7], v[6:7], 0, v[2:3]
	v_mul_f32_e32 v5, 0x3c800000, v94
	global_store_dwordx2 v[6:7], v[8:9], off
	v_mul_f32_e32 v7, 0xbfb8aa3b, v5
	v_exp_f32_e32 v7, v7
	v_add_u32_e32 v6, 0x80, v4
	v_add_f32_e32 v7, 1.0, v7
	v_rcp_f32_e32 v7, v7
	s_nop 0
	v_mul_f32_e32 v5, v5, v7
	v_mul_f32_e32 v7, 0x3c800000, v95
	v_mul_f32_e32 v8, 0xbfb8aa3b, v7
	v_exp_f32_e32 v8, v8
	v_mul_f32_e32 v5, v5, v90
	v_mul_f32_e32 v5, 0x3e000000, v5
	v_med3_f32 v5, v5, s40, v190
	v_add_f32_e32 v8, 1.0, v8
	v_rcp_f32_e32 v8, v8
	s_nop 0
	v_mul_f32_e32 v7, v7, v8
	v_mul_f32_e32 v8, 0x3c800000, v96
	v_mul_f32_e32 v9, 0xbfb8aa3b, v8
	v_exp_f32_e32 v9, v9
	v_mul_f32_e32 v7, v7, v91
	v_mul_f32_e32 v7, 0x3e000000, v7
	v_med3_f32 v7, v7, s40, v190
	v_add_f32_e32 v9, 1.0, v9
	v_rcp_f32_e32 v9, v9
	s_nop 0
	v_mul_f32_e32 v8, v8, v9
	v_mul_f32_e32 v8, v8, v92
	v_mul_f32_e32 v9, 0x3e000000, v8
	v_mul_f32_e32 v8, 0x3c800000, v97
	v_mul_f32_e32 v10, 0xbfb8aa3b, v8
	v_exp_f32_e32 v10, v10
	s_nop 0
	v_add_f32_e32 v10, 1.0, v10
	v_rcp_f32_e32 v10, v10
	s_nop 0
	v_mul_f32_e32 v8, v8, v10
	v_mul_f32_e32 v8, v8, v93
	v_mul_f32_e32 v10, 0x3e000000, v8
	v_mul_f32_e32 v8, 0x3c800000, v86
	v_mul_f32_e32 v11, 0xbfb8aa3b, v8
	v_exp_f32_e32 v11, v11
	s_nop 0
	v_add_f32_e32 v11, 1.0, v11
	v_rcp_f32_e32 v11, v11
	s_nop 0
	v_mul_f32_e32 v8, v8, v11
	v_mul_f32_e32 v8, v8, v82
	v_mul_f32_e32 v11, 0x3e000000, v8
	v_mul_f32_e32 v8, 0x3c800000, v87
	v_mul_f32_e32 v12, 0xbfb8aa3b, v8
	v_exp_f32_e32 v12, v12
	s_nop 0
	v_add_f32_e32 v12, 1.0, v12
	v_rcp_f32_e32 v12, v12
	s_nop 0
	v_mul_f32_e32 v8, v8, v12
	v_mul_f32_e32 v8, v8, v83
	v_mul_f32_e32 v12, 0x3e000000, v8
	v_mul_f32_e32 v8, 0x3c800000, v88
	v_mul_f32_e32 v13, 0xbfb8aa3b, v8
	v_exp_f32_e32 v13, v13
	s_nop 0
	v_add_f32_e32 v13, 1.0, v13
	v_rcp_f32_e32 v13, v13
	s_nop 0
	v_mul_f32_e32 v8, v8, v13
	v_mul_f32_e32 v8, v8, v84
	v_mul_f32_e32 v13, 0x3e000000, v8
	v_mul_f32_e32 v8, 0x3c800000, v89
	v_mul_f32_e32 v14, 0xbfb8aa3b, v8
	v_exp_f32_e32 v14, v14
	s_nop 0
	v_add_f32_e32 v14, 1.0, v14
	v_rcp_f32_e32 v14, v14
	s_nop 0
	v_mul_f32_e32 v8, v8, v14
	v_mul_f32_e32 v8, v8, v85
	v_mul_f32_e32 v14, 0x3e000000, v8
	v_mov_b32_e32 v8, v163
	v_cvt_pk_fp8_f32 v8, v5, v7
	v_med3_f32 v5, v9, s40, v190
	v_med3_f32 v7, v10, s40, v190
	v_mov_b32_e32 v9, v163
	v_cvt_pk_fp8_f32 v8, v5, v7 op_sel:[0,0,1]
	v_med3_f32 v5, v11, s40, v190
	v_med3_f32 v7, v12, s40, v190
	v_cvt_pk_fp8_f32 v9, v5, v7
	v_med3_f32 v5, v13, s40, v190
	v_med3_f32 v7, v14, s40, v190
	v_cvt_pk_fp8_f32 v9, v5, v7 op_sel:[0,0,1]
	v_ashrrev_i32_e32 v7, 31, v6
	v_lshlrev_b64 v[6:7], 7, v[6:7]
	v_lshl_add_u64 v[6:7], s[10:11], 0, v[6:7]
	v_lshl_add_u64 v[6:7], v[6:7], 0, v[2:3]
	v_mul_f32_e32 v5, 0x3c800000, v78
	global_store_dwordx2 v[6:7], v[8:9], off
	v_mul_f32_e32 v6, 0xbfb8aa3b, v5
	v_exp_f32_e32 v6, v6
	s_nop 0
	v_add_f32_e32 v6, 1.0, v6
	v_rcp_f32_e32 v6, v6
	s_nop 0
	v_mul_f32_e32 v5, v5, v6
	v_mul_f32_e32 v6, 0x3c800000, v79
	v_mul_f32_e32 v7, 0xbfb8aa3b, v6
	v_exp_f32_e32 v7, v7
	v_mul_f32_e32 v5, v5, v74
	v_mul_f32_e32 v5, 0x3e000000, v5
	v_med3_f32 v5, v5, s40, v190
	v_add_f32_e32 v7, 1.0, v7
	v_rcp_f32_e32 v7, v7
	s_nop 0
	v_mul_f32_e32 v6, v6, v7
	v_mul_f32_e32 v6, v6, v75
	v_mul_f32_e32 v7, 0x3e000000, v6
	v_mul_f32_e32 v6, 0x3c800000, v80
	v_mul_f32_e32 v8, 0xbfb8aa3b, v6
	v_exp_f32_e32 v8, v8
	v_med3_f32 v7, v7, s40, v190
	v_add_f32_e32 v8, 1.0, v8
	v_rcp_f32_e32 v8, v8
	s_nop 0
	v_mul_f32_e32 v6, v6, v8
	v_mul_f32_e32 v6, v6, v76
	v_mul_f32_e32 v9, 0x3e000000, v6
	v_mul_f32_e32 v6, 0x3c800000, v81
	v_mul_f32_e32 v8, 0xbfb8aa3b, v6
	v_exp_f32_e32 v8, v8
	s_nop 0
	v_add_f32_e32 v8, 1.0, v8
	v_rcp_f32_e32 v8, v8
	s_nop 0
	v_mul_f32_e32 v6, v6, v8
	v_mul_f32_e32 v6, v6, v77
	v_mul_f32_e32 v10, 0x3e000000, v6
	v_mul_f32_e32 v6, 0x3c800000, v70
	v_mul_f32_e32 v8, 0xbfb8aa3b, v6
	v_exp_f32_e32 v8, v8
	s_nop 0
	v_add_f32_e32 v8, 1.0, v8
	v_rcp_f32_e32 v8, v8
	s_nop 0
	v_mul_f32_e32 v6, v6, v8
	v_mul_f32_e32 v6, v6, v66
	v_mul_f32_e32 v11, 0x3e000000, v6
	v_mul_f32_e32 v6, 0x3c800000, v71
	v_mul_f32_e32 v8, 0xbfb8aa3b, v6
	v_exp_f32_e32 v8, v8
	s_nop 0
	v_add_f32_e32 v8, 1.0, v8
	v_rcp_f32_e32 v8, v8
	s_nop 0
	v_mul_f32_e32 v6, v6, v8
	v_mul_f32_e32 v6, v6, v67
	v_mul_f32_e32 v12, 0x3e000000, v6
	v_mul_f32_e32 v6, 0x3c800000, v72
	v_mul_f32_e32 v8, 0xbfb8aa3b, v6
	v_exp_f32_e32 v8, v8
	s_nop 0
	v_add_f32_e32 v8, 1.0, v8
	v_rcp_f32_e32 v8, v8
	s_nop 0
	v_mul_f32_e32 v6, v6, v8
	v_mul_f32_e32 v6, v6, v68
	v_mul_f32_e32 v13, 0x3e000000, v6
	v_mul_f32_e32 v6, 0x3c800000, v73
	v_mul_f32_e32 v8, 0xbfb8aa3b, v6
	v_exp_f32_e32 v8, v8
	s_nop 0
	v_add_f32_e32 v8, 1.0, v8
	v_rcp_f32_e32 v8, v8
	s_nop 0
	v_mul_f32_e32 v6, v6, v8
	v_mov_b32_e32 v8, v163
	v_cvt_pk_fp8_f32 v8, v5, v7
	v_med3_f32 v5, v9, s40, v190
	v_med3_f32 v7, v10, s40, v190
	v_mov_b32_e32 v9, v163
	v_cvt_pk_fp8_f32 v8, v5, v7 op_sel:[0,0,1]
	v_med3_f32 v5, v11, s40, v190
	v_med3_f32 v7, v12, s40, v190
	v_cvt_pk_fp8_f32 v9, v5, v7
	v_mul_f32_e32 v6, v6, v69
	v_mul_f32_e32 v14, 0x3e000000, v6
	v_add_u32_e32 v6, 0x90, v4
	v_med3_f32 v5, v13, s40, v190
	v_med3_f32 v7, v14, s40, v190
	v_cvt_pk_fp8_f32 v9, v5, v7 op_sel:[0,0,1]
	v_ashrrev_i32_e32 v7, 31, v6
	v_lshlrev_b64 v[6:7], 7, v[6:7]
	v_lshl_add_u64 v[6:7], s[10:11], 0, v[6:7]
	v_lshl_add_u64 v[6:7], v[6:7], 0, v[2:3]
	v_mul_f32_e32 v5, 0x3c800000, v62
	global_store_dwordx2 v[6:7], v[8:9], off
	v_mul_f32_e32 v6, 0xbfb8aa3b, v5
	v_exp_f32_e32 v6, v6
	s_nop 0
	v_add_f32_e32 v6, 1.0, v6
	v_rcp_f32_e32 v6, v6
	s_nop 0
	v_mul_f32_e32 v5, v5, v6
	v_mul_f32_e32 v6, 0x3c800000, v63
	v_mul_f32_e32 v7, 0xbfb8aa3b, v6
	v_exp_f32_e32 v7, v7
	v_mul_f32_e32 v5, v5, v58
	v_mul_f32_e32 v5, 0x3e000000, v5
	v_med3_f32 v5, v5, s40, v190
	v_add_f32_e32 v7, 1.0, v7
	v_rcp_f32_e32 v7, v7
	s_nop 0
	v_mul_f32_e32 v6, v6, v7
	v_mul_f32_e32 v6, v6, v59
	v_mul_f32_e32 v7, 0x3e000000, v6
	v_mul_f32_e32 v6, 0x3c800000, v64
	v_mul_f32_e32 v8, 0xbfb8aa3b, v6
	v_exp_f32_e32 v8, v8
	v_med3_f32 v7, v7, s40, v190
	v_add_f32_e32 v8, 1.0, v8
	v_rcp_f32_e32 v8, v8
	s_nop 0
	v_mul_f32_e32 v6, v6, v8
	v_mul_f32_e32 v6, v6, v60
	v_mul_f32_e32 v9, 0x3e000000, v6
	v_mul_f32_e32 v6, 0x3c800000, v65
	v_mul_f32_e32 v8, 0xbfb8aa3b, v6
	v_exp_f32_e32 v8, v8
	s_nop 0
	v_add_f32_e32 v8, 1.0, v8
	v_rcp_f32_e32 v8, v8
	s_nop 0
	v_mul_f32_e32 v6, v6, v8
	v_mul_f32_e32 v6, v6, v61
	v_mul_f32_e32 v10, 0x3e000000, v6
	v_mul_f32_e32 v6, 0x3c800000, v54
	v_mul_f32_e32 v8, 0xbfb8aa3b, v6
	v_exp_f32_e32 v8, v8
	s_nop 0
	v_add_f32_e32 v8, 1.0, v8
	v_rcp_f32_e32 v8, v8
	s_nop 0
	v_mul_f32_e32 v6, v6, v8
	v_mul_f32_e32 v6, v6, v50
	v_mul_f32_e32 v11, 0x3e000000, v6
	v_mul_f32_e32 v6, 0x3c800000, v55
	v_mul_f32_e32 v8, 0xbfb8aa3b, v6
	v_exp_f32_e32 v8, v8
	s_nop 0
	v_add_f32_e32 v8, 1.0, v8
	v_rcp_f32_e32 v8, v8
	s_nop 0
	v_mul_f32_e32 v6, v6, v8
	v_mul_f32_e32 v6, v6, v51
	v_mul_f32_e32 v12, 0x3e000000, v6
	v_mul_f32_e32 v6, 0x3c800000, v56
	v_mul_f32_e32 v8, 0xbfb8aa3b, v6
	v_exp_f32_e32 v8, v8
	s_nop 0
	v_add_f32_e32 v8, 1.0, v8
	v_rcp_f32_e32 v8, v8
	s_nop 0
	v_mul_f32_e32 v6, v6, v8
	v_mul_f32_e32 v6, v6, v52
	v_mul_f32_e32 v13, 0x3e000000, v6
	v_mul_f32_e32 v6, 0x3c800000, v57
	v_mul_f32_e32 v8, 0xbfb8aa3b, v6
	v_exp_f32_e32 v8, v8
	s_nop 0
	v_add_f32_e32 v8, 1.0, v8
	v_rcp_f32_e32 v8, v8
	s_nop 0
	v_mul_f32_e32 v6, v6, v8
	v_mov_b32_e32 v8, v163
	v_cvt_pk_fp8_f32 v8, v5, v7
	v_med3_f32 v5, v9, s40, v190
	v_med3_f32 v7, v10, s40, v190
	v_mov_b32_e32 v9, v163
	v_cvt_pk_fp8_f32 v8, v5, v7 op_sel:[0,0,1]
	v_med3_f32 v5, v11, s40, v190
	v_med3_f32 v7, v12, s40, v190
	v_cvt_pk_fp8_f32 v9, v5, v7
	v_mul_f32_e32 v6, v6, v53
	v_mul_f32_e32 v14, 0x3e000000, v6
	v_add_u32_e32 v6, 0xa0, v4
	v_med3_f32 v5, v13, s40, v190
	v_med3_f32 v7, v14, s40, v190
	v_cvt_pk_fp8_f32 v9, v5, v7 op_sel:[0,0,1]
	v_ashrrev_i32_e32 v7, 31, v6
	v_lshlrev_b64 v[6:7], 7, v[6:7]
	v_lshl_add_u64 v[6:7], s[10:11], 0, v[6:7]
	v_lshl_add_u64 v[6:7], v[6:7], 0, v[2:3]
	v_mul_f32_e32 v5, 0x3c800000, v46
	global_store_dwordx2 v[6:7], v[8:9], off
	v_mul_f32_e32 v6, 0xbfb8aa3b, v5
	v_exp_f32_e32 v6, v6
	v_add_u32_e32 v4, 0xb0, v4
	v_add_f32_e32 v6, 1.0, v6
	v_rcp_f32_e32 v6, v6
	s_nop 0
	v_mul_f32_e32 v5, v5, v6
	v_mul_f32_e32 v6, 0x3c800000, v47
	v_mul_f32_e32 v7, 0xbfb8aa3b, v6
	v_exp_f32_e32 v7, v7
	v_mul_f32_e32 v5, v5, v42
	v_mul_f32_e32 v5, 0x3e000000, v5
	v_med3_f32 v5, v5, s40, v190
	v_add_f32_e32 v7, 1.0, v7
	v_rcp_f32_e32 v7, v7
	s_nop 0
	v_mul_f32_e32 v6, v6, v7
	v_mul_f32_e32 v7, 0x3c800000, v48
	v_mul_f32_e32 v8, 0xbfb8aa3b, v7
	v_exp_f32_e32 v8, v8
	v_mul_f32_e32 v6, v6, v43
	v_mul_f32_e32 v6, 0x3e000000, v6
	v_add_f32_e32 v8, 1.0, v8
	v_rcp_f32_e32 v8, v8
	s_nop 0
	v_mul_f32_e32 v7, v7, v8
	v_mul_f32_e32 v8, 0x3c800000, v49
	v_mul_f32_e32 v9, 0xbfb8aa3b, v8
	v_exp_f32_e32 v9, v9
	v_mul_f32_e32 v7, v7, v44
	v_mul_f32_e32 v7, 0x3e000000, v7
	v_add_f32_e32 v9, 1.0, v9
	v_rcp_f32_e32 v9, v9
	s_nop 0
	v_mul_f32_e32 v8, v8, v9
	v_mul_f32_e32 v9, 0x3c800000, v38
	v_mul_f32_e32 v10, 0xbfb8aa3b, v9
	v_exp_f32_e32 v10, v10
	v_mul_f32_e32 v8, v8, v45
	v_mul_f32_e32 v8, 0x3e000000, v8
	v_add_f32_e32 v10, 1.0, v10
	v_rcp_f32_e32 v10, v10
	s_nop 0
	v_mul_f32_e32 v9, v9, v10
	v_mul_f32_e32 v10, 0x3c800000, v39
	v_mul_f32_e32 v11, 0xbfb8aa3b, v10
	v_exp_f32_e32 v11, v11
	v_mul_f32_e32 v9, v9, v34
	v_mul_f32_e32 v9, 0x3e000000, v9
	v_add_f32_e32 v11, 1.0, v11
	v_rcp_f32_e32 v11, v11
	s_nop 0
	v_mul_f32_e32 v10, v10, v11
	v_mul_f32_e32 v11, 0x3c800000, v40
	v_mul_f32_e32 v12, 0xbfb8aa3b, v11
	v_exp_f32_e32 v12, v12
	v_mul_f32_e32 v10, v10, v35
	v_mul_f32_e32 v10, 0x3e000000, v10
	v_add_f32_e32 v12, 1.0, v12
	v_rcp_f32_e32 v12, v12
	s_nop 0
	v_mul_f32_e32 v11, v11, v12
	v_mul_f32_e32 v12, 0x3c800000, v41
	v_mul_f32_e32 v13, 0xbfb8aa3b, v12
	v_exp_f32_e32 v13, v13
	v_mul_f32_e32 v11, v11, v36
	v_mul_f32_e32 v11, 0x3e000000, v11
	v_add_f32_e32 v13, 1.0, v13
	v_rcp_f32_e32 v13, v13
	s_nop 0
	v_mul_f32_e32 v12, v12, v13
	v_med3_f32 v13, v6, s40, v190
	v_mov_b32_e32 v6, v163
	v_cvt_pk_fp8_f32 v6, v5, v13
	v_med3_f32 v5, v7, s40, v190
	v_med3_f32 v7, v8, s40, v190
	v_med3_f32 v8, v10, s40, v190
	v_cvt_pk_fp8_f32 v6, v5, v7 op_sel:[0,0,1]
	v_med3_f32 v5, v9, s40, v190
	v_mov_b32_e32 v7, v163
	v_cvt_pk_fp8_f32 v7, v5, v8
	v_mul_f32_e32 v12, v12, v37
	v_mul_f32_e32 v12, 0x3e000000, v12
	v_med3_f32 v5, v11, s40, v190
	v_med3_f32 v8, v12, s40, v190
	v_cvt_pk_fp8_f32 v7, v5, v8 op_sel:[0,0,1]
	v_ashrrev_i32_e32 v5, 31, v4
	v_lshlrev_b64 v[4:5], 7, v[4:5]
	v_lshl_add_u64 v[4:5], s[10:11], 0, v[4:5]
	v_lshl_add_u64 v[2:3], v[4:5], 0, v[2:3]
	global_store_dwordx2 v[2:3], v[6:7], off
	s_cbranch_vccz .LBB0_677
	s_waitcnt vmcnt(0)
	s_cmpk_gt_u32 s42, 0xff
	s_cbranch_scc1 .LBB0_623
	s_barrier
	s_branch .LBB0_623

.LBB0_755:
	ds_read_b128 v[2:5], v169
	ds_read_b128 v[6:9], v169 offset:1024
	ds_read_b128 v[10:13], v169 offset:2048
	ds_read_b128 v[14:17], v169 offset:3072
	s_add_u32 s0, s26, 0x4000
	s_addc_u32 s1, s27, 0
	s_cmp_eq_u32 s53, 4
	s_cselect_b32 s34, s49, s0
	s_cselect_b32 s35, s19, s1
	s_cselect_b32 s28, s50, s51
	s_cselect_b32 s29, s17, s52
	s_add_u32 s30, s34, 0x8000
	s_addc_u32 s31, s35, 0
	v_lshl_add_u64 v[162:163], s[26:27], 0, v[156:157]
	s_add_i32 m0, s25, 0xc000
	ds_read_b128 v[174:177], v170
	ds_read_b128 v[178:181], v170 offset:1024
	ds_read_b128 v[182:185], v170 offset:2048
	ds_read_b128 v[186:189], v170 offset:3072
	ds_read_b128 v[190:193], v170 offset:4096
	ds_read_b128 v[194:197], v170 offset:5120
	ds_read_b128 v[198:201], v170 offset:6144
	ds_read_b128 v[202:205], v170 offset:7168
	global_load_lds_dwordx4 v[162:163], off nt
	v_lshl_add_u64 v[162:163], s[26:27], 0, v[154:155]
	s_add_i32 m0, s25, 0xe000
	s_nop 0
	global_load_lds_dwordx4 v[162:163], off nt
	s_waitcnt lgkmcnt(8)
	s_waitcnt vmcnt(10)
	s_barrier
	s_waitcnt lgkmcnt(0)
	s_waitcnt lgkmcnt(0)
	v_mfma_scale_f32_16x16x128_f8f6f4 v[142:145], v[2:9], v[174:181], v[142:145], v171, v171 op_sel_hi:[0,0,0]
	v_mfma_scale_f32_16x16x128_f8f6f4 v[138:141], v[10:17], v[174:181], v[138:141], v171, v171 op_sel_hi:[0,0,0]
	v_mfma_scale_f32_16x16x128_f8f6f4 v[126:129], v[2:9], v[182:189], v[126:129], v171, v171 op_sel_hi:[0,0,0]
	v_mfma_scale_f32_16x16x128_f8f6f4 v[122:125], v[10:17], v[182:189], v[122:125], v171, v171 op_sel_hi:[0,0,0]
	v_mfma_scale_f32_16x16x128_f8f6f4 v[110:113], v[2:9], v[190:197], v[110:113], v171, v171 op_sel_hi:[0,0,0]
	v_mfma_scale_f32_16x16x128_f8f6f4 v[106:109], v[10:17], v[190:197], v[106:109], v171, v171 op_sel_hi:[0,0,0]
	v_mfma_scale_f32_16x16x128_f8f6f4 v[94:97], v[2:9], v[198:205], v[94:97], v171, v171 op_sel_hi:[0,0,0]
	v_mfma_scale_f32_16x16x128_f8f6f4 v[90:93], v[10:17], v[198:205], v[90:93], v171, v171 op_sel_hi:[0,0,0]
	s_barrier
	s_add_i32 s0, s45, s36
	v_lshl_add_u64 v[162:163], s[28:29], 0, v[150:151]
	s_mov_b32 m0, s0
	ds_read_b128 v[206:209], v172
	ds_read_b128 v[210:213], v172 offset:1024
	ds_read_b128 v[214:217], v172 offset:2048
	ds_read_b128 v[218:221], v172 offset:3072
	global_load_lds_dwordx4 v[162:163], off
	v_lshl_add_u64 v[164:165], s[28:29], 0, v[146:147]
	s_add_i32 m0, s0, 0x2000
	s_nop 0
	global_load_lds_dwordx4 v[164:165], off
	s_waitcnt vmcnt(10)
	s_barrier
	s_waitcnt lgkmcnt(0)
	s_waitcnt lgkmcnt(0)
	v_mfma_scale_f32_16x16x128_f8f6f4 v[134:137], v[206:213], v[174:181], v[134:137], v171, v171 op_sel_hi:[0,0,0]
	v_mfma_scale_f32_16x16x128_f8f6f4 v[130:133], v[214:221], v[174:181], v[130:133], v171, v171 op_sel_hi:[0,0,0]
	v_mfma_scale_f32_16x16x128_f8f6f4 v[118:121], v[206:213], v[182:189], v[118:121], v171, v171 op_sel_hi:[0,0,0]
	v_mfma_scale_f32_16x16x128_f8f6f4 v[114:117], v[214:221], v[182:189], v[114:117], v171, v171 op_sel_hi:[0,0,0]
	v_mfma_scale_f32_16x16x128_f8f6f4 v[102:105], v[206:213], v[190:197], v[102:105], v171, v171 op_sel_hi:[0,0,0]
	v_mfma_scale_f32_16x16x128_f8f6f4 v[98:101], v[214:221], v[190:197], v[98:101], v171, v171 op_sel_hi:[0,0,0]
	v_mfma_scale_f32_16x16x128_f8f6f4 v[86:89], v[206:213], v[198:205], v[86:89], v171, v171 op_sel_hi:[0,0,0]
	v_mfma_scale_f32_16x16x128_f8f6f4 v[82:85], v[214:221], v[198:205], v[82:85], v171, v171 op_sel_hi:[0,0,0]
	s_mov_b32 m0, s25
	v_lshl_add_u64 v[222:223], s[34:35], 0, v[152:153]
	s_barrier
	ds_read_b128 v[174:177], v170 offset:16384
	ds_read_b128 v[178:181], v170 offset:17408
	ds_read_b128 v[182:185], v170 offset:18432
	ds_read_b128 v[186:189], v170 offset:19456
	ds_read_b128 v[190:193], v170 offset:20480
	ds_read_b128 v[194:197], v170 offset:21504
	ds_read_b128 v[198:201], v170 offset:22528
	ds_read_b128 v[202:205], v170 offset:23552
	global_load_lds_dwordx4 v[222:223], off nt
	v_lshl_add_u64 v[222:223], s[34:35], 0, v[148:149]
	s_mov_b32 m0, s37
	s_nop 0
	global_load_lds_dwordx4 v[222:223], off nt
	s_waitcnt vmcnt(10)
	s_barrier
	s_waitcnt lgkmcnt(0)
	s_waitcnt lgkmcnt(0)
	v_mfma_scale_f32_16x16x128_f8f6f4 v[78:81], v[2:9], v[174:181], v[78:81], v171, v171 op_sel_hi:[0,0,0]
	v_mfma_scale_f32_16x16x128_f8f6f4 v[74:77], v[10:17], v[174:181], v[74:77], v171, v171 op_sel_hi:[0,0,0]
	v_mfma_scale_f32_16x16x128_f8f6f4 v[62:65], v[2:9], v[182:189], v[62:65], v171, v171 op_sel_hi:[0,0,0]
	v_mfma_scale_f32_16x16x128_f8f6f4 v[58:61], v[10:17], v[182:189], v[58:61], v171, v171 op_sel_hi:[0,0,0]
	v_mfma_scale_f32_16x16x128_f8f6f4 v[46:49], v[2:9], v[190:197], v[46:49], v171, v171 op_sel_hi:[0,0,0]
	v_mfma_scale_f32_16x16x128_f8f6f4 v[42:45], v[10:17], v[190:197], v[42:45], v171, v171 op_sel_hi:[0,0,0]
	v_mfma_scale_f32_16x16x128_f8f6f4 v[30:33], v[2:9], v[198:205], v[30:33], v171, v171 op_sel_hi:[0,0,0]
	v_mfma_scale_f32_16x16x128_f8f6f4 v[26:29], v[10:17], v[198:205], v[26:29], v171, v171 op_sel_hi:[0,0,0]
	s_barrier
	s_add_u32 s0, s28, 0x20000
	s_addc_u32 s1, s29, 0
	s_add_i32 s54, s46, s36
	v_lshl_add_u64 v[2:3], s[0:1], 0, v[150:151]
	s_mov_b32 m0, s54
	s_nop 0
	global_load_lds_dwordx4 v[2:3], off
	v_lshl_add_u64 v[2:3], s[0:1], 0, v[146:147]
	s_add_i32 m0, s54, 0x2000
	s_nop 0
	global_load_lds_dwordx4 v[2:3], off
	s_waitcnt vmcnt(10)
	s_barrier
	v_mfma_scale_f32_16x16x128_f8f6f4 v[70:73], v[206:213], v[174:181], v[70:73], v171, v171 op_sel_hi:[0,0,0]
	v_mfma_scale_f32_16x16x128_f8f6f4 v[66:69], v[214:221], v[174:181], v[66:69], v171, v171 op_sel_hi:[0,0,0]
	v_mfma_scale_f32_16x16x128_f8f6f4 v[54:57], v[206:213], v[182:189], v[54:57], v171, v171 op_sel_hi:[0,0,0]
	v_mfma_scale_f32_16x16x128_f8f6f4 v[50:53], v[214:221], v[182:189], v[50:53], v171, v171 op_sel_hi:[0,0,0]
	v_mfma_scale_f32_16x16x128_f8f6f4 v[38:41], v[206:213], v[190:197], v[38:41], v171, v171 op_sel_hi:[0,0,0]
	v_mfma_scale_f32_16x16x128_f8f6f4 v[34:37], v[214:221], v[190:197], v[34:37], v171, v171 op_sel_hi:[0,0,0]
	v_mfma_scale_f32_16x16x128_f8f6f4 v[22:25], v[206:213], v[198:205], v[22:25], v171, v171 op_sel_hi:[0,0,0]
	v_mfma_scale_f32_16x16x128_f8f6f4 v[18:21], v[214:221], v[198:205], v[18:21], v171, v171 op_sel_hi:[0,0,0]
	s_add_i32 s54, 0, 0x18000
	v_add_u32_e32 v14, s54, v168
	s_barrier
	ds_read_b128 v[2:5], v14
	ds_read_b128 v[6:9], v14 offset:1024
	ds_read_b128 v[10:13], v14 offset:2048
	ds_read_b128 v[14:17], v14 offset:3072
	s_add_u32 s0, s34, 0x4000
	s_addc_u32 s1, s35, 0
	s_mov_b32 m0, s38
	v_lshl_add_u64 v[206:207], s[0:1], 0, v[152:153]
	ds_read_b128 v[174:177], v170 offset:32768
	ds_read_b128 v[178:181], v170 offset:33792
	ds_read_b128 v[182:185], v170 offset:34816
	ds_read_b128 v[186:189], v170 offset:35840
	ds_read_b128 v[190:193], v170 offset:36864
	ds_read_b128 v[194:197], v170 offset:37888
	ds_read_b128 v[198:201], v170 offset:38912
	ds_read_b128 v[202:205], v170 offset:39936
	global_load_lds_dwordx4 v[206:207], off nt
	v_lshl_add_u64 v[206:207], s[0:1], 0, v[148:149]
	s_mov_b32 m0, s39
	s_nop 0
	global_load_lds_dwordx4 v[206:207], off nt
	s_waitcnt lgkmcnt(8)
	s_waitcnt vmcnt(10)
	s_barrier
	s_waitcnt lgkmcnt(0)
	s_waitcnt lgkmcnt(0)
	v_mfma_scale_f32_16x16x128_f8f6f4 v[142:145], v[2:9], v[174:181], v[142:145], v171, v171 op_sel_hi:[0,0,0]
	v_mfma_scale_f32_16x16x128_f8f6f4 v[138:141], v[10:17], v[174:181], v[138:141], v171, v171 op_sel_hi:[0,0,0]
	v_mfma_scale_f32_16x16x128_f8f6f4 v[126:129], v[2:9], v[182:189], v[126:129], v171, v171 op_sel_hi:[0,0,0]
	v_mfma_scale_f32_16x16x128_f8f6f4 v[122:125], v[10:17], v[182:189], v[122:125], v171, v171 op_sel_hi:[0,0,0]
	v_mfma_scale_f32_16x16x128_f8f6f4 v[110:113], v[2:9], v[190:197], v[110:113], v171, v171 op_sel_hi:[0,0,0]
	v_mfma_scale_f32_16x16x128_f8f6f4 v[106:109], v[10:17], v[190:197], v[106:109], v171, v171 op_sel_hi:[0,0,0]
	v_mfma_scale_f32_16x16x128_f8f6f4 v[94:97], v[2:9], v[198:205], v[94:97], v171, v171 op_sel_hi:[0,0,0]
	v_mfma_scale_f32_16x16x128_f8f6f4 v[90:93], v[10:17], v[198:205], v[90:93], v171, v171 op_sel_hi:[0,0,0]
	s_barrier
	s_add_i32 s34, 0, 0x1c000
	s_add_i32 s0, s54, s36
	v_add_u32_e32 v218, s34, v168
	v_lshl_add_u64 v[162:163], v[162:163], 0, s[12:13]
	s_mov_b32 m0, s0
	ds_read_b128 v[206:209], v218
	ds_read_b128 v[210:213], v218 offset:1024
	ds_read_b128 v[214:217], v218 offset:2048
	ds_read_b128 v[218:221], v218 offset:3072
	global_load_lds_dwordx4 v[162:163], off
	v_lshl_add_u64 v[162:163], v[164:165], 0, s[12:13]
	s_add_i32 m0, s0, 0x2000
	s_nop 0
	global_load_lds_dwordx4 v[162:163], off
	s_waitcnt vmcnt(10)
	s_barrier
	s_waitcnt lgkmcnt(0)
	s_waitcnt lgkmcnt(0)
	v_mfma_scale_f32_16x16x128_f8f6f4 v[134:137], v[206:213], v[174:181], v[134:137], v171, v171 op_sel_hi:[0,0,0]
	v_mfma_scale_f32_16x16x128_f8f6f4 v[130:133], v[214:221], v[174:181], v[130:133], v171, v171 op_sel_hi:[0,0,0]
	v_mfma_scale_f32_16x16x128_f8f6f4 v[118:121], v[206:213], v[182:189], v[118:121], v171, v171 op_sel_hi:[0,0,0]
	v_mfma_scale_f32_16x16x128_f8f6f4 v[114:117], v[214:221], v[182:189], v[114:117], v171, v171 op_sel_hi:[0,0,0]
	v_mfma_scale_f32_16x16x128_f8f6f4 v[102:105], v[206:213], v[190:197], v[102:105], v171, v171 op_sel_hi:[0,0,0]
	v_mfma_scale_f32_16x16x128_f8f6f4 v[98:101], v[214:221], v[190:197], v[98:101], v171, v171 op_sel_hi:[0,0,0]
	v_mfma_scale_f32_16x16x128_f8f6f4 v[86:89], v[206:213], v[198:205], v[86:89], v171, v171 op_sel_hi:[0,0,0]
	v_mfma_scale_f32_16x16x128_f8f6f4 v[82:85], v[214:221], v[198:205], v[82:85], v171, v171 op_sel_hi:[0,0,0]
	s_mov_b32 m0, s43
	v_lshl_add_u64 v[162:163], s[30:31], 0, v[152:153]
	s_barrier
	ds_read_b128 v[174:177], v170 offset:49152
	ds_read_b128 v[178:181], v170 offset:50176
	ds_read_b128 v[182:185], v170 offset:51200
	ds_read_b128 v[186:189], v170 offset:52224
	ds_read_b128 v[190:193], v170 offset:53248
	ds_read_b128 v[194:197], v170 offset:54272
	ds_read_b128 v[198:201], v170 offset:55296
	ds_read_b128 v[202:205], v170 offset:56320
	global_load_lds_dwordx4 v[162:163], off nt
	v_lshl_add_u64 v[162:163], s[30:31], 0, v[148:149]
	s_mov_b32 m0, s44
	s_nop 0
	global_load_lds_dwordx4 v[162:163], off nt
	s_waitcnt vmcnt(10)
	s_barrier
	s_waitcnt lgkmcnt(0)
	s_waitcnt lgkmcnt(0)
	v_mfma_scale_f32_16x16x128_f8f6f4 v[78:81], v[2:9], v[174:181], v[78:81], v171, v171 op_sel_hi:[0,0,0]
	v_mfma_scale_f32_16x16x128_f8f6f4 v[74:77], v[10:17], v[174:181], v[74:77], v171, v171 op_sel_hi:[0,0,0]
	v_mfma_scale_f32_16x16x128_f8f6f4 v[62:65], v[2:9], v[182:189], v[62:65], v171, v171 op_sel_hi:[0,0,0]
	v_mfma_scale_f32_16x16x128_f8f6f4 v[58:61], v[10:17], v[182:189], v[58:61], v171, v171 op_sel_hi:[0,0,0]
	v_mfma_scale_f32_16x16x128_f8f6f4 v[46:49], v[2:9], v[190:197], v[46:49], v171, v171 op_sel_hi:[0,0,0]
	v_mfma_scale_f32_16x16x128_f8f6f4 v[42:45], v[10:17], v[190:197], v[42:45], v171, v171 op_sel_hi:[0,0,0]
	v_mfma_scale_f32_16x16x128_f8f6f4 v[30:33], v[2:9], v[198:205], v[30:33], v171, v171 op_sel_hi:[0,0,0]
	v_mfma_scale_f32_16x16x128_f8f6f4 v[26:29], v[10:17], v[198:205], v[26:29], v171, v171 op_sel_hi:[0,0,0]
	s_barrier
	s_add_u32 s0, s28, 0x20080
	s_addc_u32 s1, s29, 0
	s_add_i32 s28, s34, s36
	v_lshl_add_u64 v[2:3], s[0:1], 0, v[150:151]
	s_mov_b32 m0, s28
	s_nop 0
	global_load_lds_dwordx4 v[2:3], off
	v_lshl_add_u64 v[2:3], s[0:1], 0, v[146:147]
	s_add_i32 m0, s28, 0x2000
	s_nop 0
	global_load_lds_dwordx4 v[2:3], off
	s_waitcnt vmcnt(10)
	s_barrier
	v_mfma_scale_f32_16x16x128_f8f6f4 v[70:73], v[206:213], v[174:181], v[70:73], v171, v171 op_sel_hi:[0,0,0]
	v_mfma_scale_f32_16x16x128_f8f6f4 v[66:69], v[214:221], v[174:181], v[66:69], v171, v171 op_sel_hi:[0,0,0]
	v_mfma_scale_f32_16x16x128_f8f6f4 v[54:57], v[206:213], v[182:189], v[54:57], v171, v171 op_sel_hi:[0,0,0]
	v_mfma_scale_f32_16x16x128_f8f6f4 v[50:53], v[214:221], v[182:189], v[50:53], v171, v171 op_sel_hi:[0,0,0]
	v_mfma_scale_f32_16x16x128_f8f6f4 v[38:41], v[206:213], v[190:197], v[38:41], v171, v171 op_sel_hi:[0,0,0]
	v_mfma_scale_f32_16x16x128_f8f6f4 v[34:37], v[214:221], v[190:197], v[34:37], v171, v171 op_sel_hi:[0,0,0]
	v_mfma_scale_f32_16x16x128_f8f6f4 v[22:25], v[206:213], v[198:205], v[22:25], v171, v171 op_sel_hi:[0,0,0]
	v_mfma_scale_f32_16x16x128_f8f6f4 v[18:21], v[214:221], v[198:205], v[18:21], v171, v171 op_sel_hi:[0,0,0]
	s_add_i32 s53, s53, 2
	s_add_u32 s51, s51, 0x100
	s_addc_u32 s52, s52, 0
	s_add_u32 s26, s26, 0x10000
	s_addc_u32 s27, s27, 0
	s_cmp_gt_u32 s53, 5
	s_barrier
	s_cbranch_scc0 .LBB0_755
	v_pk_mul_f32 v[10:11], v[142:143], s[14:15] op_sel_hi:[1,0]
	v_pk_mul_f32 v[8:9], v[144:145], s[14:15] op_sel_hi:[1,0]
	v_med3_f32 v5, v10, s47, v173
	v_med3_f32 v11, v11, s47, v173
	v_mov_b32_e32 v10, 0
	v_cvt_pk_fp8_f32 v10, v5, v11
	v_mov_b32_e32 v3, v166
	v_mov_b32_e32 v2, v167
	s_lshl_b32 s0, s48, 8
	v_pk_mul_f32 v[14:15], v[138:139], s[14:15] op_sel_hi:[1,0]
	v_med3_f32 v5, v8, s47, v173
	v_med3_f32 v8, v9, s47, v173
	s_nop 15
	s_nop 15
	s_or_b32 s0, s0, s42
	v_cvt_pk_fp8_f32 v10, v5, v8 op_sel:[0,0,1]
	v_med3_f32 v5, v14, s47, v173
	v_med3_f32 v8, v15, s47, v173
	v_mov_b32_e32 v11, 0
	v_lshl_add_u32 v2, v2, 3, s0
	s_lshl_b32 s0, s24, 8
	v_cvt_pk_fp8_f32 v11, v5, v8
	s_add_i32 s0, s0, s41
	v_add_u32_e32 v4, s0, v3
	v_pk_mul_f32 v[12:13], v[140:141], s[14:15] op_sel_hi:[1,0]
	v_mov_b32_e32 v6, v4
	v_med3_f32 v5, v12, s47, v173
	v_med3_f32 v8, v13, s47, v173
	v_cvt_pk_fp8_f32 v11, v5, v8 op_sel:[0,0,1]
	v_ashrrev_i32_e32 v7, 31, v6
	v_lshlrev_b64 v[6:7], 10, v[6:7]
	v_ashrrev_i32_e32 v3, 31, v2
	v_lshl_add_u64 v[6:7], s[10:11], 0, v[6:7]
	v_lshl_add_u64 v[6:7], v[6:7], 0, v[2:3]
	global_store_dwordx2 v[6:7], v[10:11], off
	v_pk_mul_f32 v[10:11], v[134:135], s[14:15] op_sel_hi:[1,0]
	v_pk_mul_f32 v[8:9], v[136:137], s[14:15] op_sel_hi:[1,0]
	v_med3_f32 v5, v10, s47, v173
	v_med3_f32 v11, v11, s47, v173
	v_mov_b32_e32 v10, 0
	v_cvt_pk_fp8_f32 v10, v5, v11
	v_pk_mul_f32 v[14:15], v[130:131], s[14:15] op_sel_hi:[1,0]
	v_med3_f32 v5, v8, s47, v173
	v_med3_f32 v8, v9, s47, v173
	v_cvt_pk_fp8_f32 v10, v5, v8 op_sel:[0,0,1]
	v_med3_f32 v5, v14, s47, v173
	v_med3_f32 v8, v15, s47, v173
	v_mov_b32_e32 v11, 0
	v_cvt_pk_fp8_f32 v11, v5, v8
	v_pk_mul_f32 v[12:13], v[132:133], s[14:15] op_sel_hi:[1,0]
	v_pk_mul_f32 v[14:15], v[122:123], s[14:15] op_sel_hi:[1,0]
	v_med3_f32 v5, v12, s47, v173
	v_med3_f32 v8, v13, s47, v173
	v_cvt_pk_fp8_f32 v11, v5, v8 op_sel:[0,0,1]
	v_pk_mul_f32 v[8:9], v[128:129], s[14:15] op_sel_hi:[1,0]
	v_pk_mul_f32 v[12:13], v[124:125], s[14:15] op_sel_hi:[1,0]
	s_and_b64 vcc, exec, s[8:9]
	global_store_dwordx2 v[6:7], v[10:11], off offset:128
	v_pk_mul_f32 v[10:11], v[126:127], s[14:15] op_sel_hi:[1,0]
	v_add_u32_e32 v6, 16, v4
	v_med3_f32 v5, v10, s47, v173
	v_med3_f32 v11, v11, s47, v173
	v_mov_b32_e32 v10, 0
	v_cvt_pk_fp8_f32 v10, v5, v11
	v_med3_f32 v5, v8, s47, v173
	v_med3_f32 v8, v9, s47, v173
	v_mov_b32_e32 v11, 0
	v_cvt_pk_fp8_f32 v10, v5, v8 op_sel:[0,0,1]
	v_med3_f32 v5, v14, s47, v173
	v_med3_f32 v8, v15, s47, v173
	v_cvt_pk_fp8_f32 v11, v5, v8
	v_med3_f32 v5, v12, s47, v173
	v_med3_f32 v8, v13, s47, v173
	v_cvt_pk_fp8_f32 v11, v5, v8 op_sel:[0,0,1]
	v_ashrrev_i32_e32 v7, 31, v6
	v_lshlrev_b64 v[6:7], 10, v[6:7]
	v_lshl_add_u64 v[6:7], s[10:11], 0, v[6:7]
	v_lshl_add_u64 v[6:7], v[6:7], 0, v[2:3]
	global_store_dwordx2 v[6:7], v[10:11], off
	v_pk_mul_f32 v[10:11], v[118:119], s[14:15] op_sel_hi:[1,0]
	v_pk_mul_f32 v[8:9], v[120:121], s[14:15] op_sel_hi:[1,0]
	v_med3_f32 v5, v10, s47, v173
	v_med3_f32 v11, v11, s47, v173
	v_mov_b32_e32 v10, 0
	v_cvt_pk_fp8_f32 v10, v5, v11
	v_pk_mul_f32 v[14:15], v[114:115], s[14:15] op_sel_hi:[1,0]
	v_med3_f32 v5, v8, s47, v173
	v_med3_f32 v8, v9, s47, v173
	v_cvt_pk_fp8_f32 v10, v5, v8 op_sel:[0,0,1]
	v_med3_f32 v5, v14, s47, v173
	v_med3_f32 v8, v15, s47, v173
	v_mov_b32_e32 v11, 0
	v_cvt_pk_fp8_f32 v11, v5, v8
	v_pk_mul_f32 v[12:13], v[116:117], s[14:15] op_sel_hi:[1,0]
	v_pk_mul_f32 v[14:15], v[106:107], s[14:15] op_sel_hi:[1,0]
	v_med3_f32 v5, v12, s47, v173
	v_med3_f32 v8, v13, s47, v173
	v_cvt_pk_fp8_f32 v11, v5, v8 op_sel:[0,0,1]
	v_pk_mul_f32 v[8:9], v[112:113], s[14:15] op_sel_hi:[1,0]
	v_pk_mul_f32 v[12:13], v[108:109], s[14:15] op_sel_hi:[1,0]
	s_mov_b32 s48, s16
	global_store_dwordx2 v[6:7], v[10:11], off offset:128
	v_pk_mul_f32 v[10:11], v[110:111], s[14:15] op_sel_hi:[1,0]
	v_add_u32_e32 v6, 32, v4
	v_med3_f32 v5, v10, s47, v173
	v_med3_f32 v11, v11, s47, v173
	v_mov_b32_e32 v10, 0
	v_cvt_pk_fp8_f32 v10, v5, v11
	v_med3_f32 v5, v8, s47, v173
	v_med3_f32 v8, v9, s47, v173
	v_mov_b32_e32 v11, 0
	v_cvt_pk_fp8_f32 v10, v5, v8 op_sel:[0,0,1]
	v_med3_f32 v5, v14, s47, v173
	v_med3_f32 v8, v15, s47, v173
	v_cvt_pk_fp8_f32 v11, v5, v8
	v_med3_f32 v5, v12, s47, v173
	v_med3_f32 v8, v13, s47, v173
	v_cvt_pk_fp8_f32 v11, v5, v8 op_sel:[0,0,1]
	v_ashrrev_i32_e32 v7, 31, v6
	v_lshlrev_b64 v[6:7], 10, v[6:7]
	v_lshl_add_u64 v[6:7], s[10:11], 0, v[6:7]
	v_lshl_add_u64 v[6:7], v[6:7], 0, v[2:3]
	global_store_dwordx2 v[6:7], v[10:11], off
	v_pk_mul_f32 v[10:11], v[102:103], s[14:15] op_sel_hi:[1,0]
	v_pk_mul_f32 v[8:9], v[104:105], s[14:15] op_sel_hi:[1,0]
	v_med3_f32 v5, v10, s47, v173
	v_med3_f32 v11, v11, s47, v173
	v_mov_b32_e32 v10, 0
	v_cvt_pk_fp8_f32 v10, v5, v11
	v_pk_mul_f32 v[14:15], v[98:99], s[14:15] op_sel_hi:[1,0]
	v_med3_f32 v5, v8, s47, v173
	v_med3_f32 v8, v9, s47, v173
	v_cvt_pk_fp8_f32 v10, v5, v8 op_sel:[0,0,1]
	v_med3_f32 v5, v14, s47, v173
	v_med3_f32 v8, v15, s47, v173
	v_mov_b32_e32 v11, 0
	v_cvt_pk_fp8_f32 v11, v5, v8
	v_pk_mul_f32 v[12:13], v[100:101], s[14:15] op_sel_hi:[1,0]
	v_pk_mul_f32 v[14:15], v[90:91], s[14:15] op_sel_hi:[1,0]
	v_med3_f32 v5, v12, s47, v173
	v_med3_f32 v8, v13, s47, v173
	v_cvt_pk_fp8_f32 v11, v5, v8 op_sel:[0,0,1]
	v_pk_mul_f32 v[8:9], v[96:97], s[14:15] op_sel_hi:[1,0]
	v_pk_mul_f32 v[12:13], v[92:93], s[14:15] op_sel_hi:[1,0]
	s_mov_b32 s24, s18
	global_store_dwordx2 v[6:7], v[10:11], off offset:128
	v_pk_mul_f32 v[10:11], v[94:95], s[14:15] op_sel_hi:[1,0]
	v_add_u32_e32 v6, 48, v4
	v_med3_f32 v5, v10, s47, v173
	v_med3_f32 v11, v11, s47, v173
	v_mov_b32_e32 v10, 0
	v_cvt_pk_fp8_f32 v10, v5, v11
	v_med3_f32 v5, v8, s47, v173
	v_med3_f32 v8, v9, s47, v173
	v_mov_b32_e32 v11, 0
	v_cvt_pk_fp8_f32 v10, v5, v8 op_sel:[0,0,1]
	v_med3_f32 v5, v14, s47, v173
	v_med3_f32 v8, v15, s47, v173
	v_cvt_pk_fp8_f32 v11, v5, v8
	v_med3_f32 v5, v12, s47, v173
	v_med3_f32 v8, v13, s47, v173
	v_cvt_pk_fp8_f32 v11, v5, v8 op_sel:[0,0,1]
	v_ashrrev_i32_e32 v7, 31, v6
	v_lshlrev_b64 v[6:7], 10, v[6:7]
	v_lshl_add_u64 v[6:7], s[10:11], 0, v[6:7]
	v_lshl_add_u64 v[6:7], v[6:7], 0, v[2:3]
	global_store_dwordx2 v[6:7], v[10:11], off
	v_pk_mul_f32 v[10:11], v[86:87], s[14:15] op_sel_hi:[1,0]
	v_pk_mul_f32 v[8:9], v[88:89], s[14:15] op_sel_hi:[1,0]
	v_med3_f32 v5, v10, s47, v173
	v_med3_f32 v11, v11, s47, v173
	v_mov_b32_e32 v10, 0
	v_cvt_pk_fp8_f32 v10, v5, v11
	v_pk_mul_f32 v[14:15], v[82:83], s[14:15] op_sel_hi:[1,0]
	v_med3_f32 v5, v8, s47, v173
	v_med3_f32 v8, v9, s47, v173
	v_cvt_pk_fp8_f32 v10, v5, v8 op_sel:[0,0,1]
	v_med3_f32 v5, v14, s47, v173
	v_med3_f32 v8, v15, s47, v173
	v_mov_b32_e32 v11, 0
	v_cvt_pk_fp8_f32 v11, v5, v8
	v_pk_mul_f32 v[12:13], v[84:85], s[14:15] op_sel_hi:[1,0]
	v_pk_mul_f32 v[14:15], v[74:75], s[14:15] op_sel_hi:[1,0]
	v_med3_f32 v5, v12, s47, v173
	v_med3_f32 v8, v13, s47, v173
	v_cvt_pk_fp8_f32 v11, v5, v8 op_sel:[0,0,1]
	v_pk_mul_f32 v[8:9], v[80:81], s[14:15] op_sel_hi:[1,0]
	v_pk_mul_f32 v[12:13], v[76:77], s[14:15] op_sel_hi:[1,0]
	s_mov_b64 s[26:27], s[22:23]
	global_store_dwordx2 v[6:7], v[10:11], off offset:128
	v_pk_mul_f32 v[10:11], v[78:79], s[14:15] op_sel_hi:[1,0]
	v_add_u32_e32 v6, 0x80, v4
	v_med3_f32 v5, v10, s47, v173
	v_med3_f32 v11, v11, s47, v173
	v_mov_b32_e32 v10, 0
	v_cvt_pk_fp8_f32 v10, v5, v11
	v_med3_f32 v5, v8, s47, v173
	v_med3_f32 v8, v9, s47, v173
	v_mov_b32_e32 v11, 0
	v_cvt_pk_fp8_f32 v10, v5, v8 op_sel:[0,0,1]
	v_med3_f32 v5, v14, s47, v173
	v_med3_f32 v8, v15, s47, v173
	v_cvt_pk_fp8_f32 v11, v5, v8
	v_med3_f32 v5, v12, s47, v173
	v_med3_f32 v8, v13, s47, v173
	v_cvt_pk_fp8_f32 v11, v5, v8 op_sel:[0,0,1]
	v_ashrrev_i32_e32 v7, 31, v6
	v_lshlrev_b64 v[6:7], 10, v[6:7]
	v_lshl_add_u64 v[6:7], s[10:11], 0, v[6:7]
	v_lshl_add_u64 v[6:7], v[6:7], 0, v[2:3]
	global_store_dwordx2 v[6:7], v[10:11], off
	v_pk_mul_f32 v[10:11], v[70:71], s[14:15] op_sel_hi:[1,0]
	v_pk_mul_f32 v[8:9], v[72:73], s[14:15] op_sel_hi:[1,0]
	v_med3_f32 v5, v10, s47, v173
	v_med3_f32 v11, v11, s47, v173
	v_mov_b32_e32 v10, 0
	v_cvt_pk_fp8_f32 v10, v5, v11
	v_pk_mul_f32 v[14:15], v[66:67], s[14:15] op_sel_hi:[1,0]
	v_med3_f32 v5, v8, s47, v173
	v_med3_f32 v8, v9, s47, v173
	v_cvt_pk_fp8_f32 v10, v5, v8 op_sel:[0,0,1]
	v_med3_f32 v5, v14, s47, v173
	v_med3_f32 v8, v15, s47, v173
	v_mov_b32_e32 v11, 0
	v_cvt_pk_fp8_f32 v11, v5, v8
	v_pk_mul_f32 v[12:13], v[68:69], s[14:15] op_sel_hi:[1,0]
	v_pk_mul_f32 v[14:15], v[58:59], s[14:15] op_sel_hi:[1,0]
	v_med3_f32 v5, v12, s47, v173
	v_med3_f32 v8, v13, s47, v173
	v_cvt_pk_fp8_f32 v11, v5, v8 op_sel:[0,0,1]
	v_pk_mul_f32 v[8:9], v[64:65], s[14:15] op_sel_hi:[1,0]
	v_pk_mul_f32 v[12:13], v[60:61], s[14:15] op_sel_hi:[1,0]
	s_mov_b64 s[28:29], s[20:21]
	global_store_dwordx2 v[6:7], v[10:11], off offset:128
	v_pk_mul_f32 v[10:11], v[62:63], s[14:15] op_sel_hi:[1,0]
	v_add_u32_e32 v6, 0x90, v4
	v_med3_f32 v5, v10, s47, v173
	v_med3_f32 v11, v11, s47, v173
	v_mov_b32_e32 v10, 0
	v_cvt_pk_fp8_f32 v10, v5, v11
	v_med3_f32 v5, v8, s47, v173
	v_med3_f32 v8, v9, s47, v173
	v_mov_b32_e32 v11, 0
	v_cvt_pk_fp8_f32 v10, v5, v8 op_sel:[0,0,1]
	v_med3_f32 v5, v14, s47, v173
	v_med3_f32 v8, v15, s47, v173
	v_cvt_pk_fp8_f32 v11, v5, v8
	v_med3_f32 v5, v12, s47, v173
	v_med3_f32 v8, v13, s47, v173
	v_cvt_pk_fp8_f32 v11, v5, v8 op_sel:[0,0,1]
	v_ashrrev_i32_e32 v7, 31, v6
	v_lshlrev_b64 v[6:7], 10, v[6:7]
	v_lshl_add_u64 v[6:7], s[10:11], 0, v[6:7]
	v_lshl_add_u64 v[6:7], v[6:7], 0, v[2:3]
	global_store_dwordx2 v[6:7], v[10:11], off
	v_pk_mul_f32 v[10:11], v[54:55], s[14:15] op_sel_hi:[1,0]
	v_pk_mul_f32 v[8:9], v[56:57], s[14:15] op_sel_hi:[1,0]
	v_med3_f32 v5, v10, s47, v173
	v_med3_f32 v11, v11, s47, v173
	v_mov_b32_e32 v10, 0
	v_cvt_pk_fp8_f32 v10, v5, v11
	v_pk_mul_f32 v[14:15], v[50:51], s[14:15] op_sel_hi:[1,0]
	v_med3_f32 v5, v8, s47, v173
	v_med3_f32 v8, v9, s47, v173
	v_cvt_pk_fp8_f32 v10, v5, v8 op_sel:[0,0,1]
	v_med3_f32 v5, v14, s47, v173
	v_med3_f32 v8, v15, s47, v173
	v_mov_b32_e32 v11, 0
	v_cvt_pk_fp8_f32 v11, v5, v8
	v_pk_mul_f32 v[12:13], v[52:53], s[14:15] op_sel_hi:[1,0]
	v_pk_mul_f32 v[14:15], v[42:43], s[14:15] op_sel_hi:[1,0]
	v_med3_f32 v5, v12, s47, v173
	v_med3_f32 v8, v13, s47, v173
	v_cvt_pk_fp8_f32 v11, v5, v8 op_sel:[0,0,1]
	v_pk_mul_f32 v[8:9], v[48:49], s[14:15] op_sel_hi:[1,0]
	v_pk_mul_f32 v[12:13], v[44:45], s[14:15] op_sel_hi:[1,0]
	global_store_dwordx2 v[6:7], v[10:11], off offset:128
	v_pk_mul_f32 v[10:11], v[46:47], s[14:15] op_sel_hi:[1,0]
	v_add_u32_e32 v6, 0xa0, v4
	v_med3_f32 v5, v10, s47, v173
	v_med3_f32 v11, v11, s47, v173
	v_mov_b32_e32 v10, 0
	v_cvt_pk_fp8_f32 v10, v5, v11
	v_med3_f32 v5, v8, s47, v173
	v_med3_f32 v8, v9, s47, v173
	v_mov_b32_e32 v11, 0
	v_cvt_pk_fp8_f32 v10, v5, v8 op_sel:[0,0,1]
	v_med3_f32 v5, v14, s47, v173
	v_med3_f32 v8, v15, s47, v173
	v_cvt_pk_fp8_f32 v11, v5, v8
	v_med3_f32 v5, v12, s47, v173
	v_med3_f32 v8, v13, s47, v173
	v_cvt_pk_fp8_f32 v11, v5, v8 op_sel:[0,0,1]
	v_ashrrev_i32_e32 v7, 31, v6
	v_lshlrev_b64 v[6:7], 10, v[6:7]
	v_lshl_add_u64 v[6:7], s[10:11], 0, v[6:7]
	v_lshl_add_u64 v[6:7], v[6:7], 0, v[2:3]
	global_store_dwordx2 v[6:7], v[10:11], off
	v_pk_mul_f32 v[10:11], v[38:39], s[14:15] op_sel_hi:[1,0]
	v_pk_mul_f32 v[8:9], v[40:41], s[14:15] op_sel_hi:[1,0]
	v_med3_f32 v5, v10, s47, v173
	v_med3_f32 v11, v11, s47, v173
	v_mov_b32_e32 v10, 0
	v_cvt_pk_fp8_f32 v10, v5, v11
	v_pk_mul_f32 v[14:15], v[34:35], s[14:15] op_sel_hi:[1,0]
	v_med3_f32 v5, v8, s47, v173
	v_med3_f32 v8, v9, s47, v173
	v_cvt_pk_fp8_f32 v10, v5, v8 op_sel:[0,0,1]
	v_med3_f32 v5, v14, s47, v173
	v_med3_f32 v8, v15, s47, v173
	v_mov_b32_e32 v11, 0
	v_cvt_pk_fp8_f32 v11, v5, v8
	v_pk_mul_f32 v[12:13], v[36:37], s[14:15] op_sel_hi:[1,0]
	v_add_u32_e32 v4, 0xb0, v4
	v_med3_f32 v5, v12, s47, v173
	v_med3_f32 v8, v13, s47, v173
	v_cvt_pk_fp8_f32 v11, v5, v8 op_sel:[0,0,1]
	v_pk_mul_f32 v[8:9], v[28:29], s[14:15] op_sel_hi:[1,0]
	global_store_dwordx2 v[6:7], v[10:11], off offset:128
	v_pk_mul_f32 v[6:7], v[30:31], s[14:15] op_sel_hi:[1,0]
	v_pk_mul_f32 v[10:11], v[26:27], s[14:15] op_sel_hi:[1,0]
	v_ashrrev_i32_e32 v5, 31, v4
	v_med3_f32 v12, v6, s47, v173
	v_med3_f32 v7, v7, s47, v173
	v_mov_b32_e32 v6, 0
	v_lshlrev_b64 v[4:5], 10, v[4:5]
	v_cvt_pk_fp8_f32 v6, v12, v7
	v_lshl_add_u64 v[4:5], s[10:11], 0, v[4:5]
	v_lshl_add_u64 v[2:3], v[4:5], 0, v[2:3]
	v_pk_mul_f32 v[4:5], v[32:33], s[14:15] op_sel_hi:[1,0]
	v_mov_b32_e32 v7, 0
	v_med3_f32 v4, v4, s47, v173
	v_med3_f32 v5, v5, s47, v173
	v_cvt_pk_fp8_f32 v6, v4, v5 op_sel:[0,0,1]
	v_med3_f32 v4, v10, s47, v173
	v_med3_f32 v5, v11, s47, v173
	v_cvt_pk_fp8_f32 v7, v4, v5
	v_med3_f32 v4, v8, s47, v173
	v_med3_f32 v5, v9, s47, v173
	v_pk_mul_f32 v[10:11], v[18:19], s[14:15] op_sel_hi:[1,0]
	v_cvt_pk_fp8_f32 v7, v4, v5 op_sel:[0,0,1]
	v_pk_mul_f32 v[4:5], v[24:25], s[14:15] op_sel_hi:[1,0]
	v_pk_mul_f32 v[8:9], v[20:21], s[14:15] op_sel_hi:[1,0]
	v_med3_f32 v4, v4, s47, v173
	global_store_dwordx2 v[2:3], v[6:7], off
	v_pk_mul_f32 v[6:7], v[22:23], s[14:15] op_sel_hi:[1,0]
	v_med3_f32 v5, v5, s47, v173
	v_med3_f32 v12, v6, s47, v173
	v_med3_f32 v7, v7, s47, v173
	v_mov_b32_e32 v6, 0
	v_cvt_pk_fp8_f32 v6, v12, v7
	v_mov_b32_e32 v7, 0
	v_cvt_pk_fp8_f32 v6, v4, v5 op_sel:[0,0,1]
	v_med3_f32 v4, v10, s47, v173
	v_med3_f32 v5, v11, s47, v173
	v_cvt_pk_fp8_f32 v7, v4, v5
	v_med3_f32 v4, v8, s47, v173
	v_med3_f32 v5, v9, s47, v173
	v_cvt_pk_fp8_f32 v7, v4, v5 op_sel:[0,0,1]
	global_store_dwordx2 v[2:3], v[6:7], off offset:128
	s_cbranch_vccz .LBB0_748
	s_waitcnt vmcnt(0)
	s_cmpk_gt_u32 s4, 0xff
	s_cbranch_scc1 .LBB0_759
	s_barrier

.LBB0_895:
	ds_read_b128 v[156:159], v152
	ds_read_b128 v[160:163], v152 offset:1024
	ds_read_b128 v[164:167], v152 offset:2048
	ds_read_b128 v[168:171], v152 offset:3072
	s_add_u32 s0, s30, 0xfffc0080
	s_addc_u32 s1, s31, -1
	s_cmp_eq_u32 s55, 12
	s_cselect_b32 s37, s23, s1
	s_cselect_b32 s36, s51, s0
	s_cselect_b32 s35, s21, s54
	s_cselect_b32 s34, s52, s53
	v_lshl_add_u64 v[148:149], s[30:31], 0, v[140:141]
	s_add_i32 m0, s25, 0xc000
	ds_read_b128 v[172:175], v153
	ds_read_b128 v[176:179], v153 offset:1024
	ds_read_b128 v[180:183], v153 offset:2048
	ds_read_b128 v[184:187], v153 offset:3072
	ds_read_b128 v[188:191], v153 offset:4096
	ds_read_b128 v[192:195], v153 offset:5120
	ds_read_b128 v[196:199], v153 offset:6144
	ds_read_b128 v[200:203], v153 offset:7168
	global_load_lds_dwordx4 v[148:149], off nt
	v_lshl_add_u64 v[148:149], s[30:31], 0, v[138:139]
	s_add_i32 m0, s25, 0xe000
	s_nop 0
	global_load_lds_dwordx4 v[148:149], off nt
	s_waitcnt lgkmcnt(8)
	s_waitcnt vmcnt(10)
	s_barrier
	s_waitcnt lgkmcnt(0)
	s_waitcnt lgkmcnt(0)
	v_mfma_f32_16x16x32_bf16 v[126:129], v[156:159], v[172:175], v[126:129]
	v_mfma_f32_16x16x32_bf16 v[122:125], v[164:167], v[172:175], v[122:125]
	v_mfma_f32_16x16x32_bf16 v[118:121], v[156:159], v[180:183], v[118:121]
	v_mfma_f32_16x16x32_bf16 v[110:113], v[164:167], v[180:183], v[110:113]
	v_mfma_f32_16x16x32_bf16 v[102:105], v[156:159], v[188:191], v[102:105]
	v_mfma_f32_16x16x32_bf16 v[94:97], v[164:167], v[188:191], v[94:97]
	v_mfma_f32_16x16x32_bf16 v[86:89], v[156:159], v[196:199], v[86:89]
	v_mfma_f32_16x16x32_bf16 v[78:81], v[164:167], v[196:199], v[78:81]
	v_mfma_f32_16x16x32_bf16 v[126:129], v[160:163], v[176:179], v[126:129]
	v_mfma_f32_16x16x32_bf16 v[122:125], v[168:171], v[176:179], v[122:125]
	v_mfma_f32_16x16x32_bf16 v[118:121], v[160:163], v[184:187], v[118:121]
	v_mfma_f32_16x16x32_bf16 v[110:113], v[168:171], v[184:187], v[110:113]
	v_mfma_f32_16x16x32_bf16 v[102:105], v[160:163], v[192:195], v[102:105]
	v_mfma_f32_16x16x32_bf16 v[94:97], v[168:171], v[192:195], v[94:97]
	v_mfma_f32_16x16x32_bf16 v[86:89], v[160:163], v[200:203], v[86:89]
	v_mfma_f32_16x16x32_bf16 v[78:81], v[168:171], v[200:203], v[78:81]
	s_barrier
	s_add_i32 s0, s47, s11
	v_lshl_add_u64 v[148:149], s[34:35], 0, v[134:135]
	s_mov_b32 m0, s0
	ds_read_b128 v[204:207], v154
	ds_read_b128 v[208:211], v154 offset:1024
	ds_read_b128 v[212:215], v154 offset:2048
	ds_read_b128 v[216:219], v154 offset:3072
	global_load_lds_dwordx4 v[148:149], off
	v_lshl_add_u64 v[220:221], s[34:35], 0, v[130:131]
	s_add_i32 m0, s0, 0x2000
	s_nop 0
	global_load_lds_dwordx4 v[220:221], off
	s_waitcnt vmcnt(10)
	s_barrier
	s_waitcnt lgkmcnt(0)
	s_waitcnt lgkmcnt(0)
	v_mfma_f32_16x16x32_bf16 v[114:117], v[204:207], v[172:175], v[114:117]
	v_mfma_f32_16x16x32_bf16 v[106:109], v[212:215], v[172:175], v[106:109]
	v_mfma_f32_16x16x32_bf16 v[98:101], v[204:207], v[180:183], v[98:101]
	v_mfma_f32_16x16x32_bf16 v[90:93], v[212:215], v[180:183], v[90:93]
	v_mfma_f32_16x16x32_bf16 v[82:85], v[204:207], v[188:191], v[82:85]
	v_mfma_f32_16x16x32_bf16 v[74:77], v[212:215], v[188:191], v[74:77]
	v_mfma_f32_16x16x32_bf16 v[70:73], v[204:207], v[196:199], v[70:73]
	v_mfma_f32_16x16x32_bf16 v[66:69], v[212:215], v[196:199], v[66:69]
	v_mfma_f32_16x16x32_bf16 v[114:117], v[208:211], v[176:179], v[114:117]
	v_mfma_f32_16x16x32_bf16 v[106:109], v[216:219], v[176:179], v[106:109]
	v_mfma_f32_16x16x32_bf16 v[98:101], v[208:211], v[184:187], v[98:101]
	v_mfma_f32_16x16x32_bf16 v[90:93], v[216:219], v[184:187], v[90:93]
	v_mfma_f32_16x16x32_bf16 v[82:85], v[208:211], v[192:195], v[82:85]
	v_mfma_f32_16x16x32_bf16 v[74:77], v[216:219], v[192:195], v[74:77]
	v_mfma_f32_16x16x32_bf16 v[70:73], v[208:211], v[200:203], v[70:73]
	v_mfma_f32_16x16x32_bf16 v[66:69], v[216:219], v[200:203], v[66:69]
	s_mov_b32 m0, s25
	v_lshl_add_u64 v[222:223], s[36:37], 0, v[136:137]
	s_barrier
	ds_read_b128 v[172:175], v153 offset:16384
	ds_read_b128 v[176:179], v153 offset:17408
	ds_read_b128 v[180:183], v153 offset:18432
	ds_read_b128 v[184:187], v153 offset:19456
	ds_read_b128 v[188:191], v153 offset:20480
	ds_read_b128 v[192:195], v153 offset:21504
	ds_read_b128 v[196:199], v153 offset:22528
	ds_read_b128 v[200:203], v153 offset:23552
	global_load_lds_dwordx4 v[222:223], off nt
	v_lshl_add_u64 v[224:225], s[36:37], 0, v[132:133]
	s_mov_b32 m0, s39
	s_nop 0
	global_load_lds_dwordx4 v[224:225], off nt
	s_waitcnt vmcnt(10)
	s_barrier
	s_waitcnt lgkmcnt(0)
	s_waitcnt lgkmcnt(0)
	v_mfma_f32_16x16x32_bf16 v[62:65], v[156:159], v[172:175], v[62:65]
	v_mfma_f32_16x16x32_bf16 v[58:61], v[164:167], v[172:175], v[58:61]
	v_mfma_f32_16x16x32_bf16 v[54:57], v[156:159], v[180:183], v[54:57]
	v_mfma_f32_16x16x32_bf16 v[46:49], v[164:167], v[180:183], v[46:49]
	v_mfma_f32_16x16x32_bf16 v[38:41], v[156:159], v[188:191], v[38:41]
	v_mfma_f32_16x16x32_bf16 v[30:33], v[164:167], v[188:191], v[30:33]
	v_mfma_f32_16x16x32_bf16 v[22:25], v[156:159], v[196:199], v[22:25]
	v_mfma_f32_16x16x32_bf16 v[14:17], v[164:167], v[196:199], v[14:17]
	v_mfma_f32_16x16x32_bf16 v[62:65], v[160:163], v[176:179], v[62:65]
	v_mfma_f32_16x16x32_bf16 v[58:61], v[168:171], v[176:179], v[58:61]
	v_mfma_f32_16x16x32_bf16 v[54:57], v[160:163], v[184:187], v[54:57]
	v_mfma_f32_16x16x32_bf16 v[46:49], v[168:171], v[184:187], v[46:49]
	v_mfma_f32_16x16x32_bf16 v[38:41], v[160:163], v[192:195], v[38:41]
	v_mfma_f32_16x16x32_bf16 v[30:33], v[168:171], v[192:195], v[30:33]
	v_mfma_f32_16x16x32_bf16 v[22:25], v[160:163], v[200:203], v[22:25]
	v_mfma_f32_16x16x32_bf16 v[14:17], v[168:171], v[200:203], v[14:17]
	s_barrier
	s_add_u32 s0, s34, 0x40000
	s_addc_u32 s1, s35, 0
	s_add_i32 s56, s48, s11
	v_lshl_add_u64 v[156:157], s[0:1], 0, v[134:135]
	s_mov_b32 m0, s56
	s_nop 0
	global_load_lds_dwordx4 v[156:157], off
	v_lshl_add_u64 v[156:157], s[0:1], 0, v[130:131]
	s_add_i32 m0, s56, 0x2000
	s_nop 0
	global_load_lds_dwordx4 v[156:157], off
	s_waitcnt vmcnt(10)
	s_barrier
	v_mfma_f32_16x16x32_bf16 v[50:53], v[204:207], v[172:175], v[50:53]
	v_mfma_f32_16x16x32_bf16 v[42:45], v[212:215], v[172:175], v[42:45]
	v_mfma_f32_16x16x32_bf16 v[34:37], v[204:207], v[180:183], v[34:37]
	v_mfma_f32_16x16x32_bf16 v[26:29], v[212:215], v[180:183], v[26:29]
	v_mfma_f32_16x16x32_bf16 v[18:21], v[204:207], v[188:191], v[18:21]
	v_mfma_f32_16x16x32_bf16 v[10:13], v[212:215], v[188:191], v[10:13]
	v_mfma_f32_16x16x32_bf16 v[6:9], v[204:207], v[196:199], v[6:9]
	v_mfma_f32_16x16x32_bf16 v[2:5], v[212:215], v[196:199], v[2:5]
	v_mfma_f32_16x16x32_bf16 v[50:53], v[208:211], v[176:179], v[50:53]
	v_mfma_f32_16x16x32_bf16 v[42:45], v[216:219], v[176:179], v[42:45]
	v_mfma_f32_16x16x32_bf16 v[34:37], v[208:211], v[184:187], v[34:37]
	v_mfma_f32_16x16x32_bf16 v[26:29], v[216:219], v[184:187], v[26:29]
	v_mfma_f32_16x16x32_bf16 v[18:21], v[208:211], v[192:195], v[18:21]
	v_mfma_f32_16x16x32_bf16 v[10:13], v[216:219], v[192:195], v[10:13]
	v_mfma_f32_16x16x32_bf16 v[6:9], v[208:211], v[200:203], v[6:9]
	v_mfma_f32_16x16x32_bf16 v[2:5], v[216:219], v[200:203], v[2:5]
	s_add_i32 s56, 0, 0x18000
	v_add_u32_e32 v146, s56, v151
	s_barrier
	ds_read_b128 v[156:159], v146
	ds_read_b128 v[160:163], v146 offset:1024
	ds_read_b128 v[164:167], v146 offset:2048
	ds_read_b128 v[168:171], v146 offset:3072
	s_add_u32 s0, s36, 0x40000
	s_addc_u32 s1, s37, 0
	s_mov_b32 m0, s40
	v_lshl_add_u64 v[204:205], s[0:1], 0, v[136:137]
	ds_read_b128 v[172:175], v153 offset:32768
	ds_read_b128 v[176:179], v153 offset:33792
	ds_read_b128 v[180:183], v153 offset:34816
	ds_read_b128 v[184:187], v153 offset:35840
	ds_read_b128 v[188:191], v153 offset:36864
	ds_read_b128 v[192:195], v153 offset:37888
	ds_read_b128 v[196:199], v153 offset:38912
	ds_read_b128 v[200:203], v153 offset:39936
	global_load_lds_dwordx4 v[204:205], off nt
	v_lshl_add_u64 v[204:205], s[0:1], 0, v[132:133]
	s_mov_b32 m0, s41
	s_nop 0
	global_load_lds_dwordx4 v[204:205], off nt
	s_waitcnt lgkmcnt(8)
	s_waitcnt vmcnt(10)
	s_barrier
	s_waitcnt lgkmcnt(0)
	s_waitcnt lgkmcnt(0)
	v_mfma_f32_16x16x32_bf16 v[126:129], v[156:159], v[172:175], v[126:129]
	v_mfma_f32_16x16x32_bf16 v[122:125], v[164:167], v[172:175], v[122:125]
	v_mfma_f32_16x16x32_bf16 v[118:121], v[156:159], v[180:183], v[118:121]
	v_mfma_f32_16x16x32_bf16 v[110:113], v[164:167], v[180:183], v[110:113]
	v_mfma_f32_16x16x32_bf16 v[102:105], v[156:159], v[188:191], v[102:105]
	v_mfma_f32_16x16x32_bf16 v[94:97], v[164:167], v[188:191], v[94:97]
	v_mfma_f32_16x16x32_bf16 v[86:89], v[156:159], v[196:199], v[86:89]
	v_mfma_f32_16x16x32_bf16 v[78:81], v[164:167], v[196:199], v[78:81]
	v_mfma_f32_16x16x32_bf16 v[126:129], v[160:163], v[176:179], v[126:129]
	v_mfma_f32_16x16x32_bf16 v[122:125], v[168:171], v[176:179], v[122:125]
	v_mfma_f32_16x16x32_bf16 v[118:121], v[160:163], v[184:187], v[118:121]
	v_mfma_f32_16x16x32_bf16 v[110:113], v[168:171], v[184:187], v[110:113]
	v_mfma_f32_16x16x32_bf16 v[102:105], v[160:163], v[192:195], v[102:105]
	v_mfma_f32_16x16x32_bf16 v[94:97], v[168:171], v[192:195], v[94:97]
	v_mfma_f32_16x16x32_bf16 v[86:89], v[160:163], v[200:203], v[86:89]
	v_mfma_f32_16x16x32_bf16 v[78:81], v[168:171], v[200:203], v[78:81]
	s_barrier
	s_add_i32 s36, 0, 0x1c000
	s_add_i32 s0, s56, s11
	v_add_u32_e32 v146, s36, v151
	v_lshl_add_u64 v[148:149], v[148:149], 0, s[16:17]
	s_mov_b32 m0, s0
	ds_read_b128 v[204:207], v146
	ds_read_b128 v[208:211], v146 offset:1024
	ds_read_b128 v[212:215], v146 offset:2048
	ds_read_b128 v[216:219], v146 offset:3072
	global_load_lds_dwordx4 v[148:149], off
	v_lshl_add_u64 v[148:149], v[220:221], 0, s[16:17]
	s_add_i32 m0, s0, 0x2000
	s_nop 0
	global_load_lds_dwordx4 v[148:149], off
	s_waitcnt vmcnt(10)
	s_barrier
	s_waitcnt lgkmcnt(0)
	s_waitcnt lgkmcnt(0)
	v_mfma_f32_16x16x32_bf16 v[114:117], v[204:207], v[172:175], v[114:117]
	v_mfma_f32_16x16x32_bf16 v[106:109], v[212:215], v[172:175], v[106:109]
	v_mfma_f32_16x16x32_bf16 v[98:101], v[204:207], v[180:183], v[98:101]
	v_mfma_f32_16x16x32_bf16 v[90:93], v[212:215], v[180:183], v[90:93]
	v_mfma_f32_16x16x32_bf16 v[82:85], v[204:207], v[188:191], v[82:85]
	v_mfma_f32_16x16x32_bf16 v[74:77], v[212:215], v[188:191], v[74:77]
	v_mfma_f32_16x16x32_bf16 v[70:73], v[204:207], v[196:199], v[70:73]
	v_mfma_f32_16x16x32_bf16 v[66:69], v[212:215], v[196:199], v[66:69]
	v_mfma_f32_16x16x32_bf16 v[114:117], v[208:211], v[176:179], v[114:117]
	v_mfma_f32_16x16x32_bf16 v[106:109], v[216:219], v[176:179], v[106:109]
	v_mfma_f32_16x16x32_bf16 v[98:101], v[208:211], v[184:187], v[98:101]
	v_mfma_f32_16x16x32_bf16 v[90:93], v[216:219], v[184:187], v[90:93]
	v_mfma_f32_16x16x32_bf16 v[82:85], v[208:211], v[192:195], v[82:85]
	v_mfma_f32_16x16x32_bf16 v[74:77], v[216:219], v[192:195], v[74:77]
	v_mfma_f32_16x16x32_bf16 v[70:73], v[208:211], v[200:203], v[70:73]
	v_mfma_f32_16x16x32_bf16 v[66:69], v[216:219], v[200:203], v[66:69]
	s_mov_b32 m0, s45
	v_lshl_add_u64 v[148:149], v[222:223], 0, s[16:17]
	s_barrier
	ds_read_b128 v[172:175], v153 offset:49152
	ds_read_b128 v[176:179], v153 offset:50176
	ds_read_b128 v[180:183], v153 offset:51200
	ds_read_b128 v[184:187], v153 offset:52224
	ds_read_b128 v[188:191], v153 offset:53248
	ds_read_b128 v[192:195], v153 offset:54272
	ds_read_b128 v[196:199], v153 offset:55296
	ds_read_b128 v[200:203], v153 offset:56320
	global_load_lds_dwordx4 v[148:149], off nt
	v_lshl_add_u64 v[148:149], v[224:225], 0, s[16:17]
	s_mov_b32 m0, s46
	s_nop 0
	global_load_lds_dwordx4 v[148:149], off nt
	s_waitcnt vmcnt(10)
	s_barrier
	s_waitcnt lgkmcnt(0)
	s_waitcnt lgkmcnt(0)
	v_mfma_f32_16x16x32_bf16 v[62:65], v[156:159], v[172:175], v[62:65]
	v_mfma_f32_16x16x32_bf16 v[58:61], v[164:167], v[172:175], v[58:61]
	v_mfma_f32_16x16x32_bf16 v[54:57], v[156:159], v[180:183], v[54:57]
	v_mfma_f32_16x16x32_bf16 v[46:49], v[164:167], v[180:183], v[46:49]
	v_mfma_f32_16x16x32_bf16 v[38:41], v[156:159], v[188:191], v[38:41]
	v_mfma_f32_16x16x32_bf16 v[30:33], v[164:167], v[188:191], v[30:33]
	v_mfma_f32_16x16x32_bf16 v[22:25], v[156:159], v[196:199], v[22:25]
	v_mfma_f32_16x16x32_bf16 v[14:17], v[164:167], v[196:199], v[14:17]
	v_mfma_f32_16x16x32_bf16 v[62:65], v[160:163], v[176:179], v[62:65]
	v_mfma_f32_16x16x32_bf16 v[58:61], v[168:171], v[176:179], v[58:61]
	v_mfma_f32_16x16x32_bf16 v[54:57], v[160:163], v[184:187], v[54:57]
	v_mfma_f32_16x16x32_bf16 v[46:49], v[168:171], v[184:187], v[46:49]
	v_mfma_f32_16x16x32_bf16 v[38:41], v[160:163], v[192:195], v[38:41]
	v_mfma_f32_16x16x32_bf16 v[30:33], v[168:171], v[192:195], v[30:33]
	v_mfma_f32_16x16x32_bf16 v[22:25], v[160:163], v[200:203], v[22:25]
	v_mfma_f32_16x16x32_bf16 v[14:17], v[168:171], v[200:203], v[14:17]
	s_barrier
	s_add_u32 s0, s34, 0x40080
	s_addc_u32 s1, s35, 0
	s_add_i32 s34, s36, s11
	v_lshl_add_u64 v[148:149], s[0:1], 0, v[134:135]
	s_mov_b32 m0, s34
	s_nop 0
	global_load_lds_dwordx4 v[148:149], off
	v_lshl_add_u64 v[148:149], s[0:1], 0, v[130:131]
	s_add_i32 m0, s34, 0x2000
	s_nop 0
	global_load_lds_dwordx4 v[148:149], off
	s_waitcnt vmcnt(10)
	s_barrier
	v_mfma_f32_16x16x32_bf16 v[50:53], v[204:207], v[172:175], v[50:53]
	v_mfma_f32_16x16x32_bf16 v[42:45], v[212:215], v[172:175], v[42:45]
	v_mfma_f32_16x16x32_bf16 v[34:37], v[204:207], v[180:183], v[34:37]
	v_mfma_f32_16x16x32_bf16 v[26:29], v[212:215], v[180:183], v[26:29]
	v_mfma_f32_16x16x32_bf16 v[18:21], v[204:207], v[188:191], v[18:21]
	v_mfma_f32_16x16x32_bf16 v[10:13], v[212:215], v[188:191], v[10:13]
	v_mfma_f32_16x16x32_bf16 v[6:9], v[204:207], v[196:199], v[6:9]
	v_mfma_f32_16x16x32_bf16 v[2:5], v[212:215], v[196:199], v[2:5]
	v_mfma_f32_16x16x32_bf16 v[50:53], v[208:211], v[176:179], v[50:53]
	v_mfma_f32_16x16x32_bf16 v[42:45], v[216:219], v[176:179], v[42:45]
	v_mfma_f32_16x16x32_bf16 v[34:37], v[208:211], v[184:187], v[34:37]
	v_mfma_f32_16x16x32_bf16 v[26:29], v[216:219], v[184:187], v[26:29]
	v_mfma_f32_16x16x32_bf16 v[18:21], v[208:211], v[192:195], v[18:21]
	v_mfma_f32_16x16x32_bf16 v[10:13], v[216:219], v[192:195], v[10:13]
	v_mfma_f32_16x16x32_bf16 v[6:9], v[208:211], v[200:203], v[6:9]
	v_mfma_f32_16x16x32_bf16 v[2:5], v[216:219], v[200:203], v[2:5]
	s_add_i32 s55, s55, 2
	s_add_u32 s53, s53, 0x100
	s_addc_u32 s54, s54, 0
	s_add_u32 s30, s30, 0x100
	s_addc_u32 s31, s31, 0
	s_cmp_gt_u32 s55, 13
	s_barrier
	s_cbranch_scc0 .LBB0_895
	v_mov_b32_e32 v156, v147
	v_mov_b32_e32 v146, v150
	s_cmp_gt_i32 s50, 11
	s_mov_b64 s[30:31], -1
	s_cbranch_scc0 .LBB0_900
	s_cmp_eq_u32 s50, 12
	s_cselect_b64 s[0:1], -1, 0
	s_and_b64 s[0:1], s[0:1], s[18:19]
	v_cmp_gt_i32_e32 vcc, 4, v146
	s_and_b64 s[0:1], s[0:1], vcc
	s_and_saveexec_b64 s[30:31], s[0:1]
	s_cbranch_execz .LBB0_899
	s_lshl_b32 s0, s24, 8
	s_add_i32 s0, s0, s43
	v_add_u32_e32 v157, s0, v156
	v_mov_b32_e32 v158, v157
	v_lshlrev_b32_e32 v148, 3, v146
	v_ashrrev_i32_e32 v149, 31, v148
	v_ashrrev_i32_e32 v159, 31, v158
	v_lshlrev_b64 v[158:159], 7, v[158:159]
	v_lshl_add_u64 v[158:159], s[14:15], 0, v[158:159]
	v_lshlrev_b64 v[148:149], 2, v[148:149]
	v_lshl_add_u64 v[162:163], v[158:159], 0, v[148:149]
	v_pk_add_f32 v[160:161], v[128:129], 0 op_sel_hi:[1,0]
	v_pk_add_f32 v[158:159], v[126:127], 0 op_sel_hi:[1,0]
	global_store_dwordx4 v[162:163], v[158:161], off
	s_nop 1
	v_pk_add_f32 v[160:161], v[124:125], 0 op_sel_hi:[1,0]
	v_pk_add_f32 v[158:159], v[122:123], 0 op_sel_hi:[1,0]
	global_store_dwordx4 v[162:163], v[158:161], off offset:16
	s_nop 1
	v_add_u32_e32 v158, 16, v157
	v_pk_add_f32 v[160:161], v[120:121], 0 op_sel_hi:[1,0]
	v_ashrrev_i32_e32 v159, 31, v158
	v_lshlrev_b64 v[158:159], 7, v[158:159]
	v_lshl_add_u64 v[158:159], s[14:15], 0, v[158:159]
	v_lshl_add_u64 v[162:163], v[158:159], 0, v[148:149]
	v_pk_add_f32 v[158:159], v[118:119], 0 op_sel_hi:[1,0]
	global_store_dwordx4 v[162:163], v[158:161], off
	s_nop 1
	v_pk_add_f32 v[160:161], v[112:113], 0 op_sel_hi:[1,0]
	v_pk_add_f32 v[158:159], v[110:111], 0 op_sel_hi:[1,0]
	global_store_dwordx4 v[162:163], v[158:161], off offset:16
	s_nop 1
	v_add_u32_e32 v158, 32, v157
	v_pk_add_f32 v[160:161], v[104:105], 0 op_sel_hi:[1,0]
	v_ashrrev_i32_e32 v159, 31, v158
	v_lshlrev_b64 v[158:159], 7, v[158:159]
	v_lshl_add_u64 v[158:159], s[14:15], 0, v[158:159]
	v_lshl_add_u64 v[162:163], v[158:159], 0, v[148:149]
	v_pk_add_f32 v[158:159], v[102:103], 0 op_sel_hi:[1,0]
	global_store_dwordx4 v[162:163], v[158:161], off
	s_nop 1
	v_pk_add_f32 v[160:161], v[96:97], 0 op_sel_hi:[1,0]
	v_pk_add_f32 v[158:159], v[94:95], 0 op_sel_hi:[1,0]
	global_store_dwordx4 v[162:163], v[158:161], off offset:16
	s_nop 1
	v_add_u32_e32 v158, 48, v157
	v_pk_add_f32 v[160:161], v[88:89], 0 op_sel_hi:[1,0]
	v_ashrrev_i32_e32 v159, 31, v158
	v_lshlrev_b64 v[158:159], 7, v[158:159]
	v_lshl_add_u64 v[158:159], s[14:15], 0, v[158:159]
	v_lshl_add_u64 v[162:163], v[158:159], 0, v[148:149]
	v_pk_add_f32 v[158:159], v[86:87], 0 op_sel_hi:[1,0]
	global_store_dwordx4 v[162:163], v[158:161], off
	s_nop 1
	v_pk_add_f32 v[160:161], v[80:81], 0 op_sel_hi:[1,0]
	v_pk_add_f32 v[158:159], v[78:79], 0 op_sel_hi:[1,0]
	global_store_dwordx4 v[162:163], v[158:161], off offset:16
	s_nop 1
	v_add_u32_e32 v158, 0x80, v157
	v_pk_add_f32 v[160:161], v[64:65], 0 op_sel_hi:[1,0]
	v_ashrrev_i32_e32 v159, 31, v158
	v_lshlrev_b64 v[158:159], 7, v[158:159]
	v_lshl_add_u64 v[158:159], s[14:15], 0, v[158:159]
	v_lshl_add_u64 v[162:163], v[158:159], 0, v[148:149]
	v_pk_add_f32 v[158:159], v[62:63], 0 op_sel_hi:[1,0]
	global_store_dwordx4 v[162:163], v[158:161], off
	s_nop 1
	v_pk_add_f32 v[160:161], v[60:61], 0 op_sel_hi:[1,0]
	v_pk_add_f32 v[158:159], v[58:59], 0 op_sel_hi:[1,0]
	global_store_dwordx4 v[162:163], v[158:161], off offset:16
	s_nop 1
	v_add_u32_e32 v158, 0x90, v157
	v_pk_add_f32 v[160:161], v[56:57], 0 op_sel_hi:[1,0]
	v_ashrrev_i32_e32 v159, 31, v158
	v_lshlrev_b64 v[158:159], 7, v[158:159]
	v_lshl_add_u64 v[158:159], s[14:15], 0, v[158:159]
	v_lshl_add_u64 v[162:163], v[158:159], 0, v[148:149]
	v_pk_add_f32 v[158:159], v[54:55], 0 op_sel_hi:[1,0]
	global_store_dwordx4 v[162:163], v[158:161], off
	s_nop 1
	v_pk_add_f32 v[160:161], v[48:49], 0 op_sel_hi:[1,0]
	v_pk_add_f32 v[158:159], v[46:47], 0 op_sel_hi:[1,0]
	global_store_dwordx4 v[162:163], v[158:161], off offset:16
	s_nop 1
	v_add_u32_e32 v158, 0xa0, v157
	v_pk_add_f32 v[160:161], v[40:41], 0 op_sel_hi:[1,0]
	v_ashrrev_i32_e32 v159, 31, v158
	v_lshlrev_b64 v[158:159], 7, v[158:159]
	v_lshl_add_u64 v[158:159], s[14:15], 0, v[158:159]
	v_lshl_add_u64 v[162:163], v[158:159], 0, v[148:149]
	v_pk_add_f32 v[158:159], v[38:39], 0 op_sel_hi:[1,0]
	global_store_dwordx4 v[162:163], v[158:161], off
	s_nop 1
	v_pk_add_f32 v[160:161], v[32:33], 0 op_sel_hi:[1,0]
	v_pk_add_f32 v[158:159], v[30:31], 0 op_sel_hi:[1,0]
	global_store_dwordx4 v[162:163], v[158:161], off offset:16
	s_nop 1
	v_add_u32_e32 v158, 0xb0, v157
	v_pk_add_f32 v[160:161], v[24:25], 0 op_sel_hi:[1,0]
	v_ashrrev_i32_e32 v159, 31, v158
	v_lshlrev_b64 v[158:159], 7, v[158:159]
	v_lshl_add_u64 v[158:159], s[14:15], 0, v[158:159]
	v_lshl_add_u64 v[148:149], v[158:159], 0, v[148:149]
	v_pk_add_f32 v[158:159], v[22:23], 0 op_sel_hi:[1,0]
	global_store_dwordx4 v[148:149], v[158:161], off
	s_nop 1
	v_pk_add_f32 v[160:161], v[16:17], 0 op_sel_hi:[1,0]
	v_pk_add_f32 v[158:159], v[14:15], 0 op_sel_hi:[1,0]
	global_store_dwordx4 v[148:149], v[158:161], off offset:16

.LBB0_1302:
	s_add_u32 s12, s36, 0x100
	s_addc_u32 s13, s37, 0
	s_add_u32 s34, s31, s36
	s_addc_u32 s35, s55, s37
	s_cmpk_eq_i32 s36, 0x300
	s_cselect_b64 vcc, -1, 0
	s_and_b64 s[0:1], vcc, exec
	s_cselect_b32 s1, 0, s12
	s_cselect_b32 s0, 0, s13
	s_cselect_b32 s34, s29, s34
	s_cselect_b32 s35, s27, s35
	s_add_u32 s38, s16, s1
	s_addc_u32 s39, s17, s0
	s_add_i32 s1, 0, 0x10000
	v_add_u32_e32 v14, s1, v197
	ds_read_b128 v[2:5], v14
	ds_read_b128 v[6:9], v14 offset:1024
	ds_read_b128 v[10:13], v14 offset:2048
	ds_read_b128 v[14:17], v14 offset:3072
	v_cndmask_b32_e32 v162, v168, v171, vcc
	v_cndmask_b32_e32 v184, v170, v198, vcc
	v_cndmask_b32_e32 v175, v172, v199, vcc
	v_cndmask_b32_e32 v173, v174, v200, vcc
	v_lshl_add_u64 v[18:19], v[178:179], 0, s[36:37]
	s_add_i32 m0, s45, 0xc000
	ds_read_b128 v[202:205], v169
	ds_read_b128 v[206:209], v169 offset:1024
	ds_read_b128 v[210:213], v169 offset:2048
	ds_read_b128 v[214:217], v169 offset:3072
	ds_read_b128 v[218:221], v169 offset:4096
	ds_read_b128 v[222:225], v169 offset:5120
	ds_read_b128 v[226:229], v169 offset:6144
	ds_read_b128 v[230:233], v169 offset:7168
	global_load_lds_dwordx4 v[18:19], off nt
	v_lshl_add_u64 v[18:19], v[176:177], 0, s[36:37]
	s_add_i32 m0, s45, 0xe000
	s_nop 0
	global_load_lds_dwordx4 v[18:19], off nt
	s_waitcnt lgkmcnt(8)
	s_waitcnt vmcnt(10)
	s_barrier
	s_waitcnt lgkmcnt(0)
	s_waitcnt lgkmcnt(0)
	v_mfma_scale_f32_16x16x128_f8f6f4 v[158:161], v[2:9], v[202:209], v[158:161], v188, v188 op_sel_hi:[0,0,0]
	v_mfma_scale_f32_16x16x128_f8f6f4 v[150:153], v[10:17], v[202:209], v[150:153], v188, v188 op_sel_hi:[0,0,0]
	v_mfma_scale_f32_16x16x128_f8f6f4 v[142:145], v[2:9], v[210:217], v[142:145], v188, v188 op_sel_hi:[0,0,0]
	v_mfma_scale_f32_16x16x128_f8f6f4 v[134:137], v[10:17], v[210:217], v[134:137], v188, v188 op_sel_hi:[0,0,0]
	v_mfma_scale_f32_16x16x128_f8f6f4 v[126:129], v[2:9], v[218:225], v[126:129], v188, v188 op_sel_hi:[0,0,0]
	v_mfma_scale_f32_16x16x128_f8f6f4 v[118:121], v[10:17], v[218:225], v[118:121], v188, v188 op_sel_hi:[0,0,0]
	v_mfma_scale_f32_16x16x128_f8f6f4 v[110:113], v[2:9], v[226:233], v[110:113], v188, v188 op_sel_hi:[0,0,0]
	v_mfma_scale_f32_16x16x128_f8f6f4 v[102:105], v[10:17], v[226:233], v[102:105], v188, v188 op_sel_hi:[0,0,0]
	s_barrier
	s_add_i32 s0, 0, 0x14000
	s_add_i32 s1, s1, s43
	v_add_u32_e32 v30, s0, v197
	v_lshl_add_u64 v[180:181], s[34:35], 0, v[164:165]
	s_mov_b32 m0, s1
	ds_read_b128 v[18:21], v30
	ds_read_b128 v[22:25], v30 offset:1024
	ds_read_b128 v[26:29], v30 offset:2048
	ds_read_b128 v[30:33], v30 offset:3072
	global_load_lds_dwordx4 v[180:181], off
	v_lshl_add_u64 v[182:183], s[34:35], 0, v[166:167]
	s_add_i32 m0, s1, 0x2000
	s_nop 0
	global_load_lds_dwordx4 v[182:183], off
	s_waitcnt vmcnt(10)
	s_barrier
	s_waitcnt lgkmcnt(0)
	s_waitcnt lgkmcnt(0)
	v_mfma_scale_f32_16x16x128_f8f6f4 v[154:157], v[18:25], v[202:209], v[154:157], v188, v188 op_sel_hi:[0,0,0]
	v_mfma_scale_f32_16x16x128_f8f6f4 v[146:149], v[26:33], v[202:209], v[146:149], v188, v188 op_sel_hi:[0,0,0]
	v_mfma_scale_f32_16x16x128_f8f6f4 v[138:141], v[18:25], v[210:217], v[138:141], v188, v188 op_sel_hi:[0,0,0]
	v_mfma_scale_f32_16x16x128_f8f6f4 v[130:133], v[26:33], v[210:217], v[130:133], v188, v188 op_sel_hi:[0,0,0]
	v_mfma_scale_f32_16x16x128_f8f6f4 v[122:125], v[18:25], v[218:225], v[122:125], v188, v188 op_sel_hi:[0,0,0]
	v_mfma_scale_f32_16x16x128_f8f6f4 v[114:117], v[26:33], v[218:225], v[114:117], v188, v188 op_sel_hi:[0,0,0]
	v_mfma_scale_f32_16x16x128_f8f6f4 v[106:109], v[18:25], v[226:233], v[106:109], v188, v188 op_sel_hi:[0,0,0]
	v_mfma_scale_f32_16x16x128_f8f6f4 v[98:101], v[26:33], v[226:233], v[98:101], v188, v188 op_sel_hi:[0,0,0]
	s_mov_b32 m0, s45
	s_barrier
	ds_read_b128 v[202:205], v169 offset:16384
	ds_read_b128 v[206:209], v169 offset:17408
	ds_read_b128 v[210:213], v169 offset:18432
	ds_read_b128 v[214:217], v169 offset:19456
	ds_read_b128 v[218:221], v169 offset:20480
	ds_read_b128 v[222:225], v169 offset:21504
	ds_read_b128 v[226:229], v169 offset:22528
	ds_read_b128 v[230:233], v169 offset:23552
	global_load_lds_dwordx4 v162, s[38:39] nt
	s_mov_b32 m0, s46
	v_mov_b32_e32 v185, v163
	global_load_lds_dwordx4 v184, s[38:39] nt
	s_waitcnt vmcnt(10)
	s_barrier
	s_waitcnt lgkmcnt(0)
	v_lshl_add_u64 v[186:187], s[38:39], 0, v[162:163]
	v_lshl_add_u64 v[184:185], s[38:39], 0, v[184:185]
	s_waitcnt lgkmcnt(0)
	v_mfma_scale_f32_16x16x128_f8f6f4 v[94:97], v[2:9], v[202:209], v[94:97], v188, v188 op_sel_hi:[0,0,0]
	v_mfma_scale_f32_16x16x128_f8f6f4 v[86:89], v[10:17], v[202:209], v[86:89], v188, v188 op_sel_hi:[0,0,0]
	v_mfma_scale_f32_16x16x128_f8f6f4 v[78:81], v[2:9], v[210:217], v[78:81], v188, v188 op_sel_hi:[0,0,0]
	v_mfma_scale_f32_16x16x128_f8f6f4 v[70:73], v[10:17], v[210:217], v[70:73], v188, v188 op_sel_hi:[0,0,0]
	v_mfma_scale_f32_16x16x128_f8f6f4 v[62:65], v[2:9], v[218:225], v[62:65], v188, v188 op_sel_hi:[0,0,0]
	v_mfma_scale_f32_16x16x128_f8f6f4 v[54:57], v[10:17], v[218:225], v[54:57], v188, v188 op_sel_hi:[0,0,0]
	v_mfma_scale_f32_16x16x128_f8f6f4 v[46:49], v[2:9], v[226:233], v[46:49], v188, v188 op_sel_hi:[0,0,0]
	v_mfma_scale_f32_16x16x128_f8f6f4 v[38:41], v[10:17], v[226:233], v[38:41], v188, v188 op_sel_hi:[0,0,0]
	s_barrier
	s_add_u32 s36, s34, 0x20000
	s_addc_u32 s37, s35, 0
	s_add_i32 s0, s0, s43
	v_lshl_add_u64 v[2:3], s[36:37], 0, v[164:165]
	s_mov_b32 m0, s0
	s_nop 0
	global_load_lds_dwordx4 v[2:3], off
	v_lshl_add_u64 v[2:3], s[36:37], 0, v[166:167]
	s_add_i32 m0, s0, 0x2000
	s_nop 0
	global_load_lds_dwordx4 v[2:3], off
	s_waitcnt vmcnt(10)
	s_barrier
	v_mfma_scale_f32_16x16x128_f8f6f4 v[90:93], v[18:25], v[202:209], v[90:93], v188, v188 op_sel_hi:[0,0,0]
	v_mfma_scale_f32_16x16x128_f8f6f4 v[82:85], v[26:33], v[202:209], v[82:85], v188, v188 op_sel_hi:[0,0,0]
	v_mfma_scale_f32_16x16x128_f8f6f4 v[74:77], v[18:25], v[210:217], v[74:77], v188, v188 op_sel_hi:[0,0,0]
	v_mfma_scale_f32_16x16x128_f8f6f4 v[66:69], v[26:33], v[210:217], v[66:69], v188, v188 op_sel_hi:[0,0,0]
	v_mfma_scale_f32_16x16x128_f8f6f4 v[58:61], v[18:25], v[218:225], v[58:61], v188, v188 op_sel_hi:[0,0,0]
	v_mfma_scale_f32_16x16x128_f8f6f4 v[50:53], v[26:33], v[218:225], v[50:53], v188, v188 op_sel_hi:[0,0,0]
	v_mfma_scale_f32_16x16x128_f8f6f4 v[42:45], v[18:25], v[226:233], v[42:45], v188, v188 op_sel_hi:[0,0,0]
	v_mfma_scale_f32_16x16x128_f8f6f4 v[34:37], v[26:33], v[226:233], v[34:37], v188, v188 op_sel_hi:[0,0,0]
	s_add_i32 s0, 0, 0x18000
	v_add_u32_e32 v14, s0, v197
	s_barrier
	ds_read_b128 v[2:5], v14
	ds_read_b128 v[6:9], v14 offset:1024
	ds_read_b128 v[10:13], v14 offset:2048
	ds_read_b128 v[14:17], v14 offset:3072
	s_mov_b32 m0, s47
	ds_read_b128 v[18:21], v169 offset:32768
	ds_read_b128 v[22:25], v169 offset:33792
	ds_read_b128 v[26:29], v169 offset:34816
	ds_read_b128 v[30:33], v169 offset:35840
	ds_read_b128 v[202:205], v169 offset:36864
	ds_read_b128 v[206:209], v169 offset:37888
	ds_read_b128 v[210:213], v169 offset:38912
	ds_read_b128 v[214:217], v169 offset:39936
	global_load_lds_dwordx4 v175, s[38:39] nt
	s_mov_b32 m0, s48
	s_nop 0
	global_load_lds_dwordx4 v173, s[38:39] nt
	s_waitcnt lgkmcnt(8)
	s_waitcnt vmcnt(10)
	s_barrier
	s_waitcnt lgkmcnt(0)
	s_waitcnt lgkmcnt(0)
	v_mfma_scale_f32_16x16x128_f8f6f4 v[158:161], v[2:9], v[18:25], v[158:161], v188, v188 op_sel_hi:[0,0,0]
	v_mfma_scale_f32_16x16x128_f8f6f4 v[150:153], v[10:17], v[18:25], v[150:153], v188, v188 op_sel_hi:[0,0,0]
	v_mfma_scale_f32_16x16x128_f8f6f4 v[142:145], v[2:9], v[26:33], v[142:145], v188, v188 op_sel_hi:[0,0,0]
	v_mfma_scale_f32_16x16x128_f8f6f4 v[134:137], v[10:17], v[26:33], v[134:137], v188, v188 op_sel_hi:[0,0,0]
	v_mfma_scale_f32_16x16x128_f8f6f4 v[126:129], v[2:9], v[202:209], v[126:129], v188, v188 op_sel_hi:[0,0,0]
	v_mfma_scale_f32_16x16x128_f8f6f4 v[118:121], v[10:17], v[202:209], v[118:121], v188, v188 op_sel_hi:[0,0,0]
	v_mfma_scale_f32_16x16x128_f8f6f4 v[110:113], v[2:9], v[210:217], v[110:113], v188, v188 op_sel_hi:[0,0,0]
	v_mfma_scale_f32_16x16x128_f8f6f4 v[102:105], v[10:17], v[210:217], v[102:105], v188, v188 op_sel_hi:[0,0,0]
	s_barrier
	s_add_i32 s36, 0, 0x1c000
	s_add_i32 s0, s0, s43
	v_add_u32_e32 v162, s36, v197
	v_lshl_add_u64 v[180:181], v[180:181], 0, s[22:23]
	s_mov_b32 m0, s0
	ds_read_b128 v[218:221], v162
	ds_read_b128 v[222:225], v162 offset:1024
	ds_read_b128 v[226:229], v162 offset:2048
	ds_read_b128 v[230:233], v162 offset:3072
	global_load_lds_dwordx4 v[180:181], off
	v_lshl_add_u64 v[180:181], v[182:183], 0, s[22:23]
	s_add_i32 m0, s0, 0x2000
	s_nop 0
	global_load_lds_dwordx4 v[180:181], off
	s_waitcnt vmcnt(10)
	s_barrier
	s_waitcnt lgkmcnt(0)
	s_waitcnt lgkmcnt(0)
	v_mfma_scale_f32_16x16x128_f8f6f4 v[154:157], v[218:225], v[18:25], v[154:157], v188, v188 op_sel_hi:[0,0,0]
	v_mfma_scale_f32_16x16x128_f8f6f4 v[146:149], v[226:233], v[18:25], v[146:149], v188, v188 op_sel_hi:[0,0,0]
	v_mfma_scale_f32_16x16x128_f8f6f4 v[138:141], v[218:225], v[26:33], v[138:141], v188, v188 op_sel_hi:[0,0,0]
	v_mfma_scale_f32_16x16x128_f8f6f4 v[130:133], v[226:233], v[26:33], v[130:133], v188, v188 op_sel_hi:[0,0,0]
	v_mfma_scale_f32_16x16x128_f8f6f4 v[122:125], v[218:225], v[202:209], v[122:125], v188, v188 op_sel_hi:[0,0,0]
	v_mfma_scale_f32_16x16x128_f8f6f4 v[114:117], v[226:233], v[202:209], v[114:117], v188, v188 op_sel_hi:[0,0,0]
	v_mfma_scale_f32_16x16x128_f8f6f4 v[106:109], v[218:225], v[210:217], v[106:109], v188, v188 op_sel_hi:[0,0,0]
	v_mfma_scale_f32_16x16x128_f8f6f4 v[98:101], v[226:233], v[210:217], v[98:101], v188, v188 op_sel_hi:[0,0,0]
	s_mov_b32 m0, s51
	v_lshl_add_u64 v[180:181], v[186:187], 0, s[22:23]
	s_barrier
	ds_read_b128 v[18:21], v169 offset:49152
	ds_read_b128 v[22:25], v169 offset:50176
	ds_read_b128 v[26:29], v169 offset:51200
	ds_read_b128 v[30:33], v169 offset:52224
	ds_read_b128 v[202:205], v169 offset:53248
	ds_read_b128 v[206:209], v169 offset:54272
	ds_read_b128 v[210:213], v169 offset:55296
	ds_read_b128 v[214:217], v169 offset:56320
	global_load_lds_dwordx4 v[180:181], off nt
	v_lshl_add_u64 v[180:181], v[184:185], 0, s[22:23]
	s_mov_b32 m0, s52
	s_nop 0
	global_load_lds_dwordx4 v[180:181], off nt
	s_waitcnt vmcnt(10)
	s_barrier
	s_waitcnt lgkmcnt(0)
	s_waitcnt lgkmcnt(0)
	v_mfma_scale_f32_16x16x128_f8f6f4 v[94:97], v[2:9], v[18:25], v[94:97], v188, v188 op_sel_hi:[0,0,0]
	v_mfma_scale_f32_16x16x128_f8f6f4 v[86:89], v[10:17], v[18:25], v[86:89], v188, v188 op_sel_hi:[0,0,0]
	v_mfma_scale_f32_16x16x128_f8f6f4 v[78:81], v[2:9], v[26:33], v[78:81], v188, v188 op_sel_hi:[0,0,0]
	v_mfma_scale_f32_16x16x128_f8f6f4 v[70:73], v[10:17], v[26:33], v[70:73], v188, v188 op_sel_hi:[0,0,0]
	v_mfma_scale_f32_16x16x128_f8f6f4 v[62:65], v[2:9], v[202:209], v[62:65], v188, v188 op_sel_hi:[0,0,0]
	v_mfma_scale_f32_16x16x128_f8f6f4 v[54:57], v[10:17], v[202:209], v[54:57], v188, v188 op_sel_hi:[0,0,0]
	v_mfma_scale_f32_16x16x128_f8f6f4 v[46:49], v[2:9], v[210:217], v[46:49], v188, v188 op_sel_hi:[0,0,0]
	v_mfma_scale_f32_16x16x128_f8f6f4 v[38:41], v[10:17], v[210:217], v[38:41], v188, v188 op_sel_hi:[0,0,0]
	s_barrier
	s_add_u32 s0, s34, 0x20080
	s_addc_u32 s1, s35, 0
	s_add_i32 s34, s36, s43
	v_lshl_add_u64 v[2:3], s[0:1], 0, v[164:165]
	s_mov_b32 m0, s34
	s_nop 0
	global_load_lds_dwordx4 v[2:3], off
	v_lshl_add_u64 v[2:3], s[0:1], 0, v[166:167]
	s_add_i32 m0, s34, 0x2000
	s_nop 0
	global_load_lds_dwordx4 v[2:3], off
	s_waitcnt vmcnt(10)
	s_barrier
	v_mfma_scale_f32_16x16x128_f8f6f4 v[90:93], v[218:225], v[18:25], v[90:93], v188, v188 op_sel_hi:[0,0,0]
	v_mfma_scale_f32_16x16x128_f8f6f4 v[82:85], v[226:233], v[18:25], v[82:85], v188, v188 op_sel_hi:[0,0,0]
	v_mfma_scale_f32_16x16x128_f8f6f4 v[74:77], v[218:225], v[26:33], v[74:77], v188, v188 op_sel_hi:[0,0,0]
	v_mfma_scale_f32_16x16x128_f8f6f4 v[66:69], v[226:233], v[26:33], v[66:69], v188, v188 op_sel_hi:[0,0,0]
	v_mfma_scale_f32_16x16x128_f8f6f4 v[58:61], v[218:225], v[202:209], v[58:61], v188, v188 op_sel_hi:[0,0,0]
	v_mfma_scale_f32_16x16x128_f8f6f4 v[50:53], v[226:233], v[202:209], v[50:53], v188, v188 op_sel_hi:[0,0,0]
	v_mfma_scale_f32_16x16x128_f8f6f4 v[42:45], v[218:225], v[210:217], v[42:45], v188, v188 op_sel_hi:[0,0,0]
	v_mfma_scale_f32_16x16x128_f8f6f4 v[34:37], v[226:233], v[210:217], v[34:37], v188, v188 op_sel_hi:[0,0,0]
	s_add_i32 s56, s56, 2
	s_cmp_gt_u32 s56, 5
	s_mov_b64 s[36:37], s[12:13]
	s_barrier
	s_cbranch_scc0 .LBB0_1302
	v_mul_f32_e32 v5, 0x3c800000, v158
	v_mul_f32_e32 v6, 0xbfb8aa3b, v5
	v_exp_f32_e32 v6, v6
	s_ashr_i32 s31, s30, 31
	s_ashr_i32 s29, s28, 31
	s_lshl_b64 s[12:13], s[30:31], 18
	v_add_f32_e32 v6, 1.0, v6
	v_rcp_f32_e32 v6, v6
	s_lshl_b64 s[28:29], s[28:29], 15
	v_mov_b32_e32 v3, v195
	s_add_u32 s0, s6, s12
	v_mul_f32_e32 v5, v5, v6
	v_mul_f32_e32 v6, 0x3c800000, v159
	v_mul_f32_e32 v7, 0xbfb8aa3b, v6
	v_exp_f32_e32 v7, v7
	v_mul_f32_e32 v5, v5, v154
	v_mul_f32_e32 v5, 0x3e000000, v5
	v_med3_f32 v5, v5, s40, v190
	v_add_f32_e32 v7, 1.0, v7
	v_rcp_f32_e32 v7, v7
	s_nop 15
	s_nop 15
	v_mov_b32_e32 v2, v196
	v_mul_f32_e32 v6, v6, v7
	v_mul_f32_e32 v7, 0x3c800000, v160
	v_mul_f32_e32 v8, 0xbfb8aa3b, v7
	v_exp_f32_e32 v8, v8
	v_mul_f32_e32 v6, v6, v155
	v_mul_f32_e32 v6, 0x3e000000, v6
	v_add_u32_e32 v4, s49, v3
	v_add_f32_e32 v8, 1.0, v8
	v_rcp_f32_e32 v8, v8
	s_addc_u32 s1, s7, s13
	s_add_u32 s12, s0, s28
	v_mul_f32_e32 v7, v7, v8
	v_mul_f32_e32 v8, 0x3c800000, v161
	v_mul_f32_e32 v9, 0xbfb8aa3b, v8
	v_exp_f32_e32 v9, v9
	v_mul_f32_e32 v7, v7, v156
	v_mul_f32_e32 v7, 0x3e000000, v7
	v_lshl_add_u32 v2, v2, 3, s50
	v_add_f32_e32 v9, 1.0, v9
	v_rcp_f32_e32 v9, v9
	s_addc_u32 s13, s1, s29
	v_ashrrev_i32_e32 v3, 31, v2
	s_and_b64 vcc, exec, s[8:9]
	v_mul_f32_e32 v8, v8, v9
	v_mul_f32_e32 v9, 0x3c800000, v150
	v_mul_f32_e32 v10, 0xbfb8aa3b, v9
	v_exp_f32_e32 v10, v10
	v_mul_f32_e32 v8, v8, v157
	v_mul_f32_e32 v8, 0x3e000000, v8
	v_mov_b32_e32 v174, v200
	v_add_f32_e32 v10, 1.0, v10
	v_rcp_f32_e32 v10, v10
	v_mov_b32_e32 v172, v199
	v_mov_b32_e32 v170, v198
	v_mov_b32_e32 v168, v171
	v_mul_f32_e32 v9, v9, v10
	v_mul_f32_e32 v10, 0x3c800000, v151
	v_mul_f32_e32 v11, 0xbfb8aa3b, v10
	v_exp_f32_e32 v11, v11
	v_mul_f32_e32 v9, v9, v146
	v_mul_f32_e32 v9, 0x3e000000, v9
	s_mov_b32 s28, s26
	v_add_f32_e32 v11, 1.0, v11
	v_rcp_f32_e32 v11, v11
	s_mov_b32 s30, s54
	s_mov_b64 s[34:35], s[14:15]
	v_mul_f32_e32 v10, v10, v11
	v_mul_f32_e32 v11, 0x3c800000, v152
	v_mul_f32_e32 v12, 0xbfb8aa3b, v11
	v_exp_f32_e32 v12, v12
	v_mul_f32_e32 v10, v10, v147
	v_mul_f32_e32 v10, 0x3e000000, v10
	v_add_f32_e32 v12, 1.0, v12
	v_rcp_f32_e32 v12, v12
	s_nop 0
	v_mul_f32_e32 v11, v11, v12
	v_mul_f32_e32 v12, 0x3c800000, v153
	v_mul_f32_e32 v13, 0xbfb8aa3b, v12
	v_exp_f32_e32 v13, v13
	v_mul_f32_e32 v11, v11, v148
	v_mul_f32_e32 v11, 0x3e000000, v11
	v_add_f32_e32 v13, 1.0, v13
	v_rcp_f32_e32 v13, v13
	s_nop 0
	v_mul_f32_e32 v12, v12, v13
	v_med3_f32 v13, v6, s40, v190
	v_mov_b32_e32 v6, v163
	v_cvt_pk_fp8_f32 v6, v5, v13
	v_med3_f32 v5, v7, s40, v190
	v_med3_f32 v7, v8, s40, v190
	v_med3_f32 v8, v10, s40, v190
	v_cvt_pk_fp8_f32 v6, v5, v7 op_sel:[0,0,1]
	v_med3_f32 v5, v9, s40, v190
	v_mov_b32_e32 v7, v163
	v_cvt_pk_fp8_f32 v7, v5, v8
	v_mul_f32_e32 v12, v12, v149
	v_mul_f32_e32 v12, 0x3e000000, v12
	v_med3_f32 v5, v11, s40, v190
	v_med3_f32 v8, v12, s40, v190
	v_cvt_pk_fp8_f32 v7, v5, v8 op_sel:[0,0,1]
	v_ashrrev_i32_e32 v5, 31, v4
	v_lshlrev_b64 v[8:9], 7, v[4:5]
	v_lshl_add_u64 v[8:9], s[12:13], 0, v[8:9]
	v_lshl_add_u64 v[8:9], v[8:9], 0, v[2:3]
	v_mul_f32_e32 v5, 0x3c800000, v142
	global_store_dwordx2 v[8:9], v[6:7], off
	v_mul_f32_e32 v6, 0xbfb8aa3b, v5
	v_exp_f32_e32 v6, v6
	s_nop 0
	v_add_f32_e32 v6, 1.0, v6
	v_rcp_f32_e32 v6, v6
	s_nop 0
	v_mul_f32_e32 v5, v5, v6
	v_mul_f32_e32 v6, 0x3c800000, v143
	v_mul_f32_e32 v7, 0xbfb8aa3b, v6
	v_exp_f32_e32 v7, v7
	v_mul_f32_e32 v5, v5, v138
	v_mul_f32_e32 v5, 0x3e000000, v5
	v_med3_f32 v5, v5, s40, v190
	v_add_f32_e32 v7, 1.0, v7
	v_rcp_f32_e32 v7, v7
	s_nop 0
	v_mul_f32_e32 v6, v6, v7
	v_mul_f32_e32 v6, v6, v139
	v_mul_f32_e32 v7, 0x3e000000, v6
	v_mul_f32_e32 v6, 0x3c800000, v144
	v_mul_f32_e32 v8, 0xbfb8aa3b, v6
	v_exp_f32_e32 v8, v8
	v_med3_f32 v7, v7, s40, v190
	v_add_f32_e32 v8, 1.0, v8
	v_rcp_f32_e32 v8, v8
	s_nop 0
	v_mul_f32_e32 v6, v6, v8
	v_mul_f32_e32 v6, v6, v140
	v_mul_f32_e32 v9, 0x3e000000, v6
	v_mul_f32_e32 v6, 0x3c800000, v145
	v_mul_f32_e32 v8, 0xbfb8aa3b, v6
	v_exp_f32_e32 v8, v8
	s_nop 0
	v_add_f32_e32 v8, 1.0, v8
	v_rcp_f32_e32 v8, v8
	s_nop 0
	v_mul_f32_e32 v6, v6, v8
	v_mul_f32_e32 v6, v6, v141
	v_mul_f32_e32 v10, 0x3e000000, v6
	v_mul_f32_e32 v6, 0x3c800000, v134
	v_mul_f32_e32 v8, 0xbfb8aa3b, v6
	v_exp_f32_e32 v8, v8
	s_nop 0
	v_add_f32_e32 v8, 1.0, v8
	v_rcp_f32_e32 v8, v8
	s_nop 0
	v_mul_f32_e32 v6, v6, v8
	v_mul_f32_e32 v6, v6, v130
	v_mul_f32_e32 v11, 0x3e000000, v6
	v_mul_f32_e32 v6, 0x3c800000, v135
	v_mul_f32_e32 v8, 0xbfb8aa3b, v6
	v_exp_f32_e32 v8, v8
	s_nop 0
	v_add_f32_e32 v8, 1.0, v8
	v_rcp_f32_e32 v8, v8
	s_nop 0
	v_mul_f32_e32 v6, v6, v8
	v_mul_f32_e32 v6, v6, v131
	v_mul_f32_e32 v12, 0x3e000000, v6
	v_mul_f32_e32 v6, 0x3c800000, v136
	v_mul_f32_e32 v8, 0xbfb8aa3b, v6
	v_exp_f32_e32 v8, v8
	s_nop 0
	v_add_f32_e32 v8, 1.0, v8
	v_rcp_f32_e32 v8, v8
	s_nop 0
	v_mul_f32_e32 v6, v6, v8
	v_mul_f32_e32 v6, v6, v132
	v_mul_f32_e32 v13, 0x3e000000, v6
	v_mul_f32_e32 v6, 0x3c800000, v137
	v_mul_f32_e32 v8, 0xbfb8aa3b, v6
	v_exp_f32_e32 v8, v8
	s_nop 0
	v_add_f32_e32 v8, 1.0, v8
	v_rcp_f32_e32 v8, v8
	s_nop 0
	v_mul_f32_e32 v6, v6, v8
	v_mov_b32_e32 v8, v163
	v_cvt_pk_fp8_f32 v8, v5, v7
	v_med3_f32 v5, v9, s40, v190
	v_med3_f32 v7, v10, s40, v190
	v_mov_b32_e32 v9, v163
	v_cvt_pk_fp8_f32 v8, v5, v7 op_sel:[0,0,1]
	v_med3_f32 v5, v11, s40, v190
	v_med3_f32 v7, v12, s40, v190
	v_cvt_pk_fp8_f32 v9, v5, v7
	v_mul_f32_e32 v6, v6, v133
	v_mul_f32_e32 v14, 0x3e000000, v6
	v_add_u32_e32 v6, 16, v4
	v_med3_f32 v5, v13, s40, v190
	v_med3_f32 v7, v14, s40, v190
	v_cvt_pk_fp8_f32 v9, v5, v7 op_sel:[0,0,1]
	v_ashrrev_i32_e32 v7, 31, v6
	v_lshlrev_b64 v[6:7], 7, v[6:7]
	v_lshl_add_u64 v[6:7], s[12:13], 0, v[6:7]
	v_lshl_add_u64 v[6:7], v[6:7], 0, v[2:3]
	v_mul_f32_e32 v5, 0x3c800000, v126
	global_store_dwordx2 v[6:7], v[8:9], off
	v_mul_f32_e32 v6, 0xbfb8aa3b, v5
	v_exp_f32_e32 v6, v6
	s_nop 0
	v_add_f32_e32 v6, 1.0, v6
	v_rcp_f32_e32 v6, v6
	s_nop 0
	v_mul_f32_e32 v5, v5, v6
	v_mul_f32_e32 v6, 0x3c800000, v127
	v_mul_f32_e32 v7, 0xbfb8aa3b, v6
	v_exp_f32_e32 v7, v7
	v_mul_f32_e32 v5, v5, v122
	v_mul_f32_e32 v5, 0x3e000000, v5
	v_med3_f32 v5, v5, s40, v190
	v_add_f32_e32 v7, 1.0, v7
	v_rcp_f32_e32 v7, v7
	s_nop 0
	v_mul_f32_e32 v6, v6, v7
	v_mul_f32_e32 v6, v6, v123
	v_mul_f32_e32 v7, 0x3e000000, v6
	v_mul_f32_e32 v6, 0x3c800000, v128
	v_mul_f32_e32 v8, 0xbfb8aa3b, v6
	v_exp_f32_e32 v8, v8
	v_med3_f32 v7, v7, s40, v190
	v_add_f32_e32 v8, 1.0, v8
	v_rcp_f32_e32 v8, v8
	s_nop 0
	v_mul_f32_e32 v6, v6, v8
	v_mul_f32_e32 v6, v6, v124
	v_mul_f32_e32 v9, 0x3e000000, v6
	v_mul_f32_e32 v6, 0x3c800000, v129
	v_mul_f32_e32 v8, 0xbfb8aa3b, v6
	v_exp_f32_e32 v8, v8
	s_nop 0
	v_add_f32_e32 v8, 1.0, v8
	v_rcp_f32_e32 v8, v8
	s_nop 0
	v_mul_f32_e32 v6, v6, v8
	v_mul_f32_e32 v6, v6, v125
	v_mul_f32_e32 v10, 0x3e000000, v6
	v_mul_f32_e32 v6, 0x3c800000, v118
	v_mul_f32_e32 v8, 0xbfb8aa3b, v6
	v_exp_f32_e32 v8, v8
	s_nop 0
	v_add_f32_e32 v8, 1.0, v8
	v_rcp_f32_e32 v8, v8
	s_nop 0
	v_mul_f32_e32 v6, v6, v8
	v_mul_f32_e32 v6, v6, v114
	v_mul_f32_e32 v11, 0x3e000000, v6
	v_mul_f32_e32 v6, 0x3c800000, v119
	v_mul_f32_e32 v8, 0xbfb8aa3b, v6
	v_exp_f32_e32 v8, v8
	s_nop 0
	v_add_f32_e32 v8, 1.0, v8
	v_rcp_f32_e32 v8, v8
	s_nop 0
	v_mul_f32_e32 v6, v6, v8
	v_mul_f32_e32 v6, v6, v115
	v_mul_f32_e32 v12, 0x3e000000, v6
	v_mul_f32_e32 v6, 0x3c800000, v120
	v_mul_f32_e32 v8, 0xbfb8aa3b, v6
	v_exp_f32_e32 v8, v8
	s_nop 0
	v_add_f32_e32 v8, 1.0, v8
	v_rcp_f32_e32 v8, v8
	s_nop 0
	v_mul_f32_e32 v6, v6, v8
	v_mul_f32_e32 v6, v6, v116
	v_mul_f32_e32 v13, 0x3e000000, v6
	v_mul_f32_e32 v6, 0x3c800000, v121
	v_mul_f32_e32 v8, 0xbfb8aa3b, v6
	v_exp_f32_e32 v8, v8
	s_nop 0
	v_add_f32_e32 v8, 1.0, v8
	v_rcp_f32_e32 v8, v8
	s_nop 0
	v_mul_f32_e32 v6, v6, v8
	v_mov_b32_e32 v8, v163
	v_cvt_pk_fp8_f32 v8, v5, v7
	v_med3_f32 v5, v9, s40, v190
	v_med3_f32 v7, v10, s40, v190
	v_mov_b32_e32 v9, v163
	v_cvt_pk_fp8_f32 v8, v5, v7 op_sel:[0,0,1]
	v_med3_f32 v5, v11, s40, v190
	v_med3_f32 v7, v12, s40, v190
	v_cvt_pk_fp8_f32 v9, v5, v7
	v_mul_f32_e32 v6, v6, v117
	v_mul_f32_e32 v14, 0x3e000000, v6
	v_add_u32_e32 v6, 32, v4
	v_med3_f32 v5, v13, s40, v190
	v_med3_f32 v7, v14, s40, v190
	v_cvt_pk_fp8_f32 v9, v5, v7 op_sel:[0,0,1]
	v_ashrrev_i32_e32 v7, 31, v6
	v_lshlrev_b64 v[6:7], 7, v[6:7]
	v_lshl_add_u64 v[6:7], s[12:13], 0, v[6:7]
	v_lshl_add_u64 v[6:7], v[6:7], 0, v[2:3]
	v_mul_f32_e32 v5, 0x3c800000, v110
	global_store_dwordx2 v[6:7], v[8:9], off
	v_mul_f32_e32 v6, 0xbfb8aa3b, v5
	v_exp_f32_e32 v6, v6
	s_nop 0
	v_add_f32_e32 v6, 1.0, v6
	v_rcp_f32_e32 v6, v6
	s_nop 0
	v_mul_f32_e32 v5, v5, v6
	v_mul_f32_e32 v6, 0x3c800000, v111
	v_mul_f32_e32 v7, 0xbfb8aa3b, v6
	v_exp_f32_e32 v7, v7
	v_mul_f32_e32 v5, v5, v106
	v_mul_f32_e32 v5, 0x3e000000, v5
	v_med3_f32 v5, v5, s40, v190
	v_add_f32_e32 v7, 1.0, v7
	v_rcp_f32_e32 v7, v7
	s_nop 0
	v_mul_f32_e32 v6, v6, v7
	v_mul_f32_e32 v6, v6, v107
	v_mul_f32_e32 v7, 0x3e000000, v6
	v_mul_f32_e32 v6, 0x3c800000, v112
	v_mul_f32_e32 v8, 0xbfb8aa3b, v6
	v_exp_f32_e32 v8, v8
	v_med3_f32 v7, v7, s40, v190
	v_add_f32_e32 v8, 1.0, v8
	v_rcp_f32_e32 v8, v8
	s_nop 0
	v_mul_f32_e32 v6, v6, v8
	v_mul_f32_e32 v6, v6, v108
	v_mul_f32_e32 v9, 0x3e000000, v6
	v_mul_f32_e32 v6, 0x3c800000, v113
	v_mul_f32_e32 v8, 0xbfb8aa3b, v6
	v_exp_f32_e32 v8, v8
	s_nop 0
	v_add_f32_e32 v8, 1.0, v8
	v_rcp_f32_e32 v8, v8
	s_nop 0
	v_mul_f32_e32 v6, v6, v8
	v_mul_f32_e32 v6, v6, v109
	v_mul_f32_e32 v10, 0x3e000000, v6
	v_mul_f32_e32 v6, 0x3c800000, v102
	v_mul_f32_e32 v8, 0xbfb8aa3b, v6
	v_exp_f32_e32 v8, v8
	s_nop 0
	v_add_f32_e32 v8, 1.0, v8
	v_rcp_f32_e32 v8, v8
	s_nop 0
	v_mul_f32_e32 v6, v6, v8
	v_mul_f32_e32 v6, v6, v98
	v_mul_f32_e32 v11, 0x3e000000, v6
	v_mul_f32_e32 v6, 0x3c800000, v103
	v_mul_f32_e32 v8, 0xbfb8aa3b, v6
	v_exp_f32_e32 v8, v8
	s_nop 0
	v_add_f32_e32 v8, 1.0, v8
	v_rcp_f32_e32 v8, v8
	s_nop 0
	v_mul_f32_e32 v6, v6, v8
	v_mul_f32_e32 v6, v6, v99
	v_mul_f32_e32 v12, 0x3e000000, v6
	v_mul_f32_e32 v6, 0x3c800000, v104
	v_mul_f32_e32 v8, 0xbfb8aa3b, v6
	v_exp_f32_e32 v8, v8
	s_nop 0
	v_add_f32_e32 v8, 1.0, v8
	v_rcp_f32_e32 v8, v8
	s_nop 0
	v_mul_f32_e32 v6, v6, v8
	v_mul_f32_e32 v6, v6, v100
	v_mul_f32_e32 v13, 0x3e000000, v6
	v_mul_f32_e32 v6, 0x3c800000, v105
	v_mul_f32_e32 v8, 0xbfb8aa3b, v6
	v_exp_f32_e32 v8, v8
	s_nop 0
	v_add_f32_e32 v8, 1.0, v8
	v_rcp_f32_e32 v8, v8
	s_nop 0
	v_mul_f32_e32 v6, v6, v8
	v_mov_b32_e32 v8, v163
	v_cvt_pk_fp8_f32 v8, v5, v7
	v_med3_f32 v5, v9, s40, v190
	v_med3_f32 v7, v10, s40, v190
	v_mov_b32_e32 v9, v163
	v_cvt_pk_fp8_f32 v8, v5, v7 op_sel:[0,0,1]
	v_med3_f32 v5, v11, s40, v190
	v_med3_f32 v7, v12, s40, v190
	v_cvt_pk_fp8_f32 v9, v5, v7
	v_mul_f32_e32 v6, v6, v101
	v_mul_f32_e32 v14, 0x3e000000, v6
	v_add_u32_e32 v6, 48, v4
	v_med3_f32 v5, v13, s40, v190
	v_med3_f32 v7, v14, s40, v190
	v_cvt_pk_fp8_f32 v9, v5, v7 op_sel:[0,0,1]
	v_ashrrev_i32_e32 v7, 31, v6
	v_lshlrev_b64 v[6:7], 7, v[6:7]
	v_lshl_add_u64 v[6:7], s[12:13], 0, v[6:7]
	v_lshl_add_u64 v[6:7], v[6:7], 0, v[2:3]
	v_mul_f32_e32 v5, 0x3c800000, v94
	global_store_dwordx2 v[6:7], v[8:9], off
	v_mul_f32_e32 v7, 0xbfb8aa3b, v5
	v_exp_f32_e32 v7, v7
	v_add_u32_e32 v6, 0x80, v4
	v_add_f32_e32 v7, 1.0, v7
	v_rcp_f32_e32 v7, v7
	s_nop 0
	v_mul_f32_e32 v5, v5, v7
	v_mul_f32_e32 v7, 0x3c800000, v95
	v_mul_f32_e32 v8, 0xbfb8aa3b, v7
	v_exp_f32_e32 v8, v8
	v_mul_f32_e32 v5, v5, v90
	v_mul_f32_e32 v5, 0x3e000000, v5
	v_med3_f32 v5, v5, s40, v190
	v_add_f32_e32 v8, 1.0, v8
	v_rcp_f32_e32 v8, v8
	s_nop 0
	v_mul_f32_e32 v7, v7, v8
	v_mul_f32_e32 v8, 0x3c800000, v96
	v_mul_f32_e32 v9, 0xbfb8aa3b, v8
	v_exp_f32_e32 v9, v9
	v_mul_f32_e32 v7, v7, v91
	v_mul_f32_e32 v7, 0x3e000000, v7
	v_med3_f32 v7, v7, s40, v190
	v_add_f32_e32 v9, 1.0, v9
	v_rcp_f32_e32 v9, v9
	s_nop 0
	v_mul_f32_e32 v8, v8, v9
	v_mul_f32_e32 v8, v8, v92
	v_mul_f32_e32 v9, 0x3e000000, v8
	v_mul_f32_e32 v8, 0x3c800000, v97
	v_mul_f32_e32 v10, 0xbfb8aa3b, v8
	v_exp_f32_e32 v10, v10
	s_nop 0
	v_add_f32_e32 v10, 1.0, v10
	v_rcp_f32_e32 v10, v10
	s_nop 0
	v_mul_f32_e32 v8, v8, v10
	v_mul_f32_e32 v8, v8, v93
	v_mul_f32_e32 v10, 0x3e000000, v8
	v_mul_f32_e32 v8, 0x3c800000, v86
	v_mul_f32_e32 v11, 0xbfb8aa3b, v8
	v_exp_f32_e32 v11, v11
	s_nop 0
	v_add_f32_e32 v11, 1.0, v11
	v_rcp_f32_e32 v11, v11
	s_nop 0
	v_mul_f32_e32 v8, v8, v11
	v_mul_f32_e32 v8, v8, v82
	v_mul_f32_e32 v11, 0x3e000000, v8
	v_mul_f32_e32 v8, 0x3c800000, v87
	v_mul_f32_e32 v12, 0xbfb8aa3b, v8
	v_exp_f32_e32 v12, v12
	s_nop 0
	v_add_f32_e32 v12, 1.0, v12
	v_rcp_f32_e32 v12, v12
	s_nop 0
	v_mul_f32_e32 v8, v8, v12
	v_mul_f32_e32 v8, v8, v83
	v_mul_f32_e32 v12, 0x3e000000, v8
	v_mul_f32_e32 v8, 0x3c800000, v88
	v_mul_f32_e32 v13, 0xbfb8aa3b, v8
	v_exp_f32_e32 v13, v13
	s_nop 0
	v_add_f32_e32 v13, 1.0, v13
	v_rcp_f32_e32 v13, v13
	s_nop 0
	v_mul_f32_e32 v8, v8, v13
	v_mul_f32_e32 v8, v8, v84
	v_mul_f32_e32 v13, 0x3e000000, v8
	v_mul_f32_e32 v8, 0x3c800000, v89
	v_mul_f32_e32 v14, 0xbfb8aa3b, v8
	v_exp_f32_e32 v14, v14
	s_nop 0
	v_add_f32_e32 v14, 1.0, v14
	v_rcp_f32_e32 v14, v14
	s_nop 0
	v_mul_f32_e32 v8, v8, v14
	v_mul_f32_e32 v8, v8, v85
	v_mul_f32_e32 v14, 0x3e000000, v8
	v_mov_b32_e32 v8, v163
	v_cvt_pk_fp8_f32 v8, v5, v7
	v_med3_f32 v5, v9, s40, v190
	v_med3_f32 v7, v10, s40, v190
	v_mov_b32_e32 v9, v163
	v_cvt_pk_fp8_f32 v8, v5, v7 op_sel:[0,0,1]
	v_med3_f32 v5, v11, s40, v190
	v_med3_f32 v7, v12, s40, v190
	v_cvt_pk_fp8_f32 v9, v5, v7
	v_med3_f32 v5, v13, s40, v190
	v_med3_f32 v7, v14, s40, v190
	v_cvt_pk_fp8_f32 v9, v5, v7 op_sel:[0,0,1]
	v_ashrrev_i32_e32 v7, 31, v6
	v_lshlrev_b64 v[6:7], 7, v[6:7]
	v_lshl_add_u64 v[6:7], s[12:13], 0, v[6:7]
	v_lshl_add_u64 v[6:7], v[6:7], 0, v[2:3]
	v_mul_f32_e32 v5, 0x3c800000, v78
	global_store_dwordx2 v[6:7], v[8:9], off
	v_mul_f32_e32 v6, 0xbfb8aa3b, v5
	v_exp_f32_e32 v6, v6
	s_nop 0
	v_add_f32_e32 v6, 1.0, v6
	v_rcp_f32_e32 v6, v6
	s_nop 0
	v_mul_f32_e32 v5, v5, v6
	v_mul_f32_e32 v6, 0x3c800000, v79
	v_mul_f32_e32 v7, 0xbfb8aa3b, v6
	v_exp_f32_e32 v7, v7
	v_mul_f32_e32 v5, v5, v74
	v_mul_f32_e32 v5, 0x3e000000, v5
	v_med3_f32 v5, v5, s40, v190
	v_add_f32_e32 v7, 1.0, v7
	v_rcp_f32_e32 v7, v7
	s_nop 0
	v_mul_f32_e32 v6, v6, v7
	v_mul_f32_e32 v6, v6, v75
	v_mul_f32_e32 v7, 0x3e000000, v6
	v_mul_f32_e32 v6, 0x3c800000, v80
	v_mul_f32_e32 v8, 0xbfb8aa3b, v6
	v_exp_f32_e32 v8, v8
	v_med3_f32 v7, v7, s40, v190
	v_add_f32_e32 v8, 1.0, v8
	v_rcp_f32_e32 v8, v8
	s_nop 0
	v_mul_f32_e32 v6, v6, v8
	v_mul_f32_e32 v6, v6, v76
	v_mul_f32_e32 v9, 0x3e000000, v6
	v_mul_f32_e32 v6, 0x3c800000, v81
	v_mul_f32_e32 v8, 0xbfb8aa3b, v6
	v_exp_f32_e32 v8, v8
	s_nop 0
	v_add_f32_e32 v8, 1.0, v8
	v_rcp_f32_e32 v8, v8
	s_nop 0
	v_mul_f32_e32 v6, v6, v8
	v_mul_f32_e32 v6, v6, v77
	v_mul_f32_e32 v10, 0x3e000000, v6
	v_mul_f32_e32 v6, 0x3c800000, v70
	v_mul_f32_e32 v8, 0xbfb8aa3b, v6
	v_exp_f32_e32 v8, v8
	s_nop 0
	v_add_f32_e32 v8, 1.0, v8
	v_rcp_f32_e32 v8, v8
	s_nop 0
	v_mul_f32_e32 v6, v6, v8
	v_mul_f32_e32 v6, v6, v66
	v_mul_f32_e32 v11, 0x3e000000, v6
	v_mul_f32_e32 v6, 0x3c800000, v71
	v_mul_f32_e32 v8, 0xbfb8aa3b, v6
	v_exp_f32_e32 v8, v8
	s_nop 0
	v_add_f32_e32 v8, 1.0, v8
	v_rcp_f32_e32 v8, v8
	s_nop 0
	v_mul_f32_e32 v6, v6, v8
	v_mul_f32_e32 v6, v6, v67
	v_mul_f32_e32 v12, 0x3e000000, v6
	v_mul_f32_e32 v6, 0x3c800000, v72
	v_mul_f32_e32 v8, 0xbfb8aa3b, v6
	v_exp_f32_e32 v8, v8
	s_nop 0
	v_add_f32_e32 v8, 1.0, v8
	v_rcp_f32_e32 v8, v8
	s_nop 0
	v_mul_f32_e32 v6, v6, v8
	v_mul_f32_e32 v6, v6, v68
	v_mul_f32_e32 v13, 0x3e000000, v6
	v_mul_f32_e32 v6, 0x3c800000, v73
	v_mul_f32_e32 v8, 0xbfb8aa3b, v6
	v_exp_f32_e32 v8, v8
	s_nop 0
	v_add_f32_e32 v8, 1.0, v8
	v_rcp_f32_e32 v8, v8
	s_nop 0
	v_mul_f32_e32 v6, v6, v8
	v_mov_b32_e32 v8, v163
	v_cvt_pk_fp8_f32 v8, v5, v7
	v_med3_f32 v5, v9, s40, v190
	v_med3_f32 v7, v10, s40, v190
	v_mov_b32_e32 v9, v163
	v_cvt_pk_fp8_f32 v8, v5, v7 op_sel:[0,0,1]
	v_med3_f32 v5, v11, s40, v190
	v_med3_f32 v7, v12, s40, v190
	v_cvt_pk_fp8_f32 v9, v5, v7
	v_mul_f32_e32 v6, v6, v69
	v_mul_f32_e32 v14, 0x3e000000, v6
	v_add_u32_e32 v6, 0x90, v4
	v_med3_f32 v5, v13, s40, v190
	v_med3_f32 v7, v14, s40, v190
	v_cvt_pk_fp8_f32 v9, v5, v7 op_sel:[0,0,1]
	v_ashrrev_i32_e32 v7, 31, v6
	v_lshlrev_b64 v[6:7], 7, v[6:7]
	v_lshl_add_u64 v[6:7], s[12:13], 0, v[6:7]
	v_lshl_add_u64 v[6:7], v[6:7], 0, v[2:3]
	v_mul_f32_e32 v5, 0x3c800000, v62
	global_store_dwordx2 v[6:7], v[8:9], off
	v_mul_f32_e32 v6, 0xbfb8aa3b, v5
	v_exp_f32_e32 v6, v6
	s_nop 0
	v_add_f32_e32 v6, 1.0, v6
	v_rcp_f32_e32 v6, v6
	s_nop 0
	v_mul_f32_e32 v5, v5, v6
	v_mul_f32_e32 v6, 0x3c800000, v63
	v_mul_f32_e32 v7, 0xbfb8aa3b, v6
	v_exp_f32_e32 v7, v7
	v_mul_f32_e32 v5, v5, v58
	v_mul_f32_e32 v5, 0x3e000000, v5
	v_med3_f32 v5, v5, s40, v190
	v_add_f32_e32 v7, 1.0, v7
	v_rcp_f32_e32 v7, v7
	s_nop 0
	v_mul_f32_e32 v6, v6, v7
	v_mul_f32_e32 v6, v6, v59
	v_mul_f32_e32 v7, 0x3e000000, v6
	v_mul_f32_e32 v6, 0x3c800000, v64
	v_mul_f32_e32 v8, 0xbfb8aa3b, v6
	v_exp_f32_e32 v8, v8
	v_med3_f32 v7, v7, s40, v190
	v_add_f32_e32 v8, 1.0, v8
	v_rcp_f32_e32 v8, v8
	s_nop 0
	v_mul_f32_e32 v6, v6, v8
	v_mul_f32_e32 v6, v6, v60
	v_mul_f32_e32 v9, 0x3e000000, v6
	v_mul_f32_e32 v6, 0x3c800000, v65
	v_mul_f32_e32 v8, 0xbfb8aa3b, v6
	v_exp_f32_e32 v8, v8
	s_nop 0
	v_add_f32_e32 v8, 1.0, v8
	v_rcp_f32_e32 v8, v8
	s_nop 0
	v_mul_f32_e32 v6, v6, v8
	v_mul_f32_e32 v6, v6, v61
	v_mul_f32_e32 v10, 0x3e000000, v6
	v_mul_f32_e32 v6, 0x3c800000, v54
	v_mul_f32_e32 v8, 0xbfb8aa3b, v6
	v_exp_f32_e32 v8, v8
	s_nop 0
	v_add_f32_e32 v8, 1.0, v8
	v_rcp_f32_e32 v8, v8
	s_nop 0
	v_mul_f32_e32 v6, v6, v8
	v_mul_f32_e32 v6, v6, v50
	v_mul_f32_e32 v11, 0x3e000000, v6
	v_mul_f32_e32 v6, 0x3c800000, v55
	v_mul_f32_e32 v8, 0xbfb8aa3b, v6
	v_exp_f32_e32 v8, v8
	s_nop 0
	v_add_f32_e32 v8, 1.0, v8
	v_rcp_f32_e32 v8, v8
	s_nop 0
	v_mul_f32_e32 v6, v6, v8
	v_mul_f32_e32 v6, v6, v51
	v_mul_f32_e32 v12, 0x3e000000, v6
	v_mul_f32_e32 v6, 0x3c800000, v56
	v_mul_f32_e32 v8, 0xbfb8aa3b, v6
	v_exp_f32_e32 v8, v8
	s_nop 0
	v_add_f32_e32 v8, 1.0, v8
	v_rcp_f32_e32 v8, v8
	s_nop 0
	v_mul_f32_e32 v6, v6, v8
	v_mul_f32_e32 v6, v6, v52
	v_mul_f32_e32 v13, 0x3e000000, v6
	v_mul_f32_e32 v6, 0x3c800000, v57
	v_mul_f32_e32 v8, 0xbfb8aa3b, v6
	v_exp_f32_e32 v8, v8
	s_nop 0
	v_add_f32_e32 v8, 1.0, v8
	v_rcp_f32_e32 v8, v8
	s_nop 0
	v_mul_f32_e32 v6, v6, v8
	v_mov_b32_e32 v8, v163
	v_cvt_pk_fp8_f32 v8, v5, v7
	v_med3_f32 v5, v9, s40, v190
	v_med3_f32 v7, v10, s40, v190
	v_mov_b32_e32 v9, v163
	v_cvt_pk_fp8_f32 v8, v5, v7 op_sel:[0,0,1]
	v_med3_f32 v5, v11, s40, v190
	v_med3_f32 v7, v12, s40, v190
	v_cvt_pk_fp8_f32 v9, v5, v7
	v_mul_f32_e32 v6, v6, v53
	v_mul_f32_e32 v14, 0x3e000000, v6
	v_add_u32_e32 v6, 0xa0, v4
	v_med3_f32 v5, v13, s40, v190
	v_med3_f32 v7, v14, s40, v190
	v_cvt_pk_fp8_f32 v9, v5, v7 op_sel:[0,0,1]
	v_ashrrev_i32_e32 v7, 31, v6
	v_lshlrev_b64 v[6:7], 7, v[6:7]
	v_lshl_add_u64 v[6:7], s[12:13], 0, v[6:7]
	v_lshl_add_u64 v[6:7], v[6:7], 0, v[2:3]
	v_mul_f32_e32 v5, 0x3c800000, v46
	global_store_dwordx2 v[6:7], v[8:9], off
	v_mul_f32_e32 v6, 0xbfb8aa3b, v5
	v_exp_f32_e32 v6, v6
	v_add_u32_e32 v4, 0xb0, v4
	v_add_f32_e32 v6, 1.0, v6
	v_rcp_f32_e32 v6, v6
	s_nop 0
	v_mul_f32_e32 v5, v5, v6
	v_mul_f32_e32 v6, 0x3c800000, v47
	v_mul_f32_e32 v7, 0xbfb8aa3b, v6
	v_exp_f32_e32 v7, v7
	v_mul_f32_e32 v5, v5, v42
	v_mul_f32_e32 v5, 0x3e000000, v5
	v_med3_f32 v5, v5, s40, v190
	v_add_f32_e32 v7, 1.0, v7
	v_rcp_f32_e32 v7, v7
	s_nop 0
	v_mul_f32_e32 v6, v6, v7
	v_mul_f32_e32 v7, 0x3c800000, v48
	v_mul_f32_e32 v8, 0xbfb8aa3b, v7
	v_exp_f32_e32 v8, v8
	v_mul_f32_e32 v6, v6, v43
	v_mul_f32_e32 v6, 0x3e000000, v6
	v_add_f32_e32 v8, 1.0, v8
	v_rcp_f32_e32 v8, v8
	s_nop 0
	v_mul_f32_e32 v7, v7, v8
	v_mul_f32_e32 v8, 0x3c800000, v49
	v_mul_f32_e32 v9, 0xbfb8aa3b, v8
	v_exp_f32_e32 v9, v9
	v_mul_f32_e32 v7, v7, v44
	v_mul_f32_e32 v7, 0x3e000000, v7
	v_add_f32_e32 v9, 1.0, v9
	v_rcp_f32_e32 v9, v9
	s_nop 0
	v_mul_f32_e32 v8, v8, v9
	v_mul_f32_e32 v9, 0x3c800000, v38
	v_mul_f32_e32 v10, 0xbfb8aa3b, v9
	v_exp_f32_e32 v10, v10
	v_mul_f32_e32 v8, v8, v45
	v_mul_f32_e32 v8, 0x3e000000, v8
	v_add_f32_e32 v10, 1.0, v10
	v_rcp_f32_e32 v10, v10
	s_nop 0
	v_mul_f32_e32 v9, v9, v10
	v_mul_f32_e32 v10, 0x3c800000, v39
	v_mul_f32_e32 v11, 0xbfb8aa3b, v10
	v_exp_f32_e32 v11, v11
	v_mul_f32_e32 v9, v9, v34
	v_mul_f32_e32 v9, 0x3e000000, v9
	v_add_f32_e32 v11, 1.0, v11
	v_rcp_f32_e32 v11, v11
	s_nop 0
	v_mul_f32_e32 v10, v10, v11
	v_mul_f32_e32 v11, 0x3c800000, v40
	v_mul_f32_e32 v12, 0xbfb8aa3b, v11
	v_exp_f32_e32 v12, v12
	v_mul_f32_e32 v10, v10, v35
	v_mul_f32_e32 v10, 0x3e000000, v10
	v_add_f32_e32 v12, 1.0, v12
	v_rcp_f32_e32 v12, v12
	s_nop 0
	v_mul_f32_e32 v11, v11, v12
	v_mul_f32_e32 v12, 0x3c800000, v41
	v_mul_f32_e32 v13, 0xbfb8aa3b, v12
	v_exp_f32_e32 v13, v13
	v_mul_f32_e32 v11, v11, v36
	v_mul_f32_e32 v11, 0x3e000000, v11
	v_add_f32_e32 v13, 1.0, v13
	v_rcp_f32_e32 v13, v13
	s_nop 0
	v_mul_f32_e32 v12, v12, v13
	v_med3_f32 v13, v6, s40, v190
	v_mov_b32_e32 v6, v163
	v_cvt_pk_fp8_f32 v6, v5, v13
	v_med3_f32 v5, v7, s40, v190
	v_med3_f32 v7, v8, s40, v190
	v_med3_f32 v8, v10, s40, v190
	v_cvt_pk_fp8_f32 v6, v5, v7 op_sel:[0,0,1]
	v_med3_f32 v5, v9, s40, v190
	v_mov_b32_e32 v7, v163
	v_cvt_pk_fp8_f32 v7, v5, v8
	v_mul_f32_e32 v12, v12, v37
	v_mul_f32_e32 v12, 0x3e000000, v12
	v_med3_f32 v5, v11, s40, v190
	v_med3_f32 v8, v12, s40, v190
	v_cvt_pk_fp8_f32 v7, v5, v8 op_sel:[0,0,1]
	v_ashrrev_i32_e32 v5, 31, v4
	v_lshlrev_b64 v[4:5], 7, v[4:5]
	v_lshl_add_u64 v[4:5], s[12:13], 0, v[4:5]
	v_lshl_add_u64 v[2:3], v[4:5], 0, v[2:3]
	global_store_dwordx2 v[2:3], v[6:7], off
	s_cbranch_vccz .LBB0_1291
	s_waitcnt vmcnt(0)
	s_cmpk_gt_u32 s42, 0xff
	s_cbranch_scc1 .LBB0_1237
	s_barrier
	s_branch .LBB0_1237

.LBB0_1369:
	ds_read_b128 v[2:5], v169
	ds_read_b128 v[6:9], v169 offset:1024
	ds_read_b128 v[10:13], v169 offset:2048
	ds_read_b128 v[14:17], v169 offset:3072
	s_add_u32 s0, s28, 0x4000
	s_addc_u32 s1, s29, 0
	s_cmp_eq_u32 s53, 4
	s_cselect_b32 s36, s49, s0
	s_cselect_b32 s37, s21, s1
	s_cselect_b32 s30, s50, s51
	s_cselect_b32 s31, s19, s52
	s_add_u32 s34, s36, 0x8000
	s_addc_u32 s35, s37, 0
	v_lshl_add_u64 v[162:163], s[28:29], 0, v[156:157]
	s_add_i32 m0, s17, 0xc000
	ds_read_b128 v[174:177], v170
	ds_read_b128 v[178:181], v170 offset:1024
	ds_read_b128 v[182:185], v170 offset:2048
	ds_read_b128 v[186:189], v170 offset:3072
	ds_read_b128 v[190:193], v170 offset:4096
	ds_read_b128 v[194:197], v170 offset:5120
	ds_read_b128 v[198:201], v170 offset:6144
	ds_read_b128 v[202:205], v170 offset:7168
	global_load_lds_dwordx4 v[162:163], off nt
	v_lshl_add_u64 v[162:163], s[28:29], 0, v[154:155]
	s_add_i32 m0, s17, 0xe000
	s_nop 0
	global_load_lds_dwordx4 v[162:163], off nt
	s_waitcnt lgkmcnt(8)
	s_waitcnt vmcnt(10)
	s_barrier
	s_waitcnt lgkmcnt(0)
	s_waitcnt lgkmcnt(0)
	v_mfma_scale_f32_16x16x128_f8f6f4 v[142:145], v[2:9], v[174:181], v[142:145], v171, v171 op_sel_hi:[0,0,0]
	v_mfma_scale_f32_16x16x128_f8f6f4 v[138:141], v[10:17], v[174:181], v[138:141], v171, v171 op_sel_hi:[0,0,0]
	v_mfma_scale_f32_16x16x128_f8f6f4 v[126:129], v[2:9], v[182:189], v[126:129], v171, v171 op_sel_hi:[0,0,0]
	v_mfma_scale_f32_16x16x128_f8f6f4 v[122:125], v[10:17], v[182:189], v[122:125], v171, v171 op_sel_hi:[0,0,0]
	v_mfma_scale_f32_16x16x128_f8f6f4 v[110:113], v[2:9], v[190:197], v[110:113], v171, v171 op_sel_hi:[0,0,0]
	v_mfma_scale_f32_16x16x128_f8f6f4 v[106:109], v[10:17], v[190:197], v[106:109], v171, v171 op_sel_hi:[0,0,0]
	v_mfma_scale_f32_16x16x128_f8f6f4 v[94:97], v[2:9], v[198:205], v[94:97], v171, v171 op_sel_hi:[0,0,0]
	v_mfma_scale_f32_16x16x128_f8f6f4 v[90:93], v[10:17], v[198:205], v[90:93], v171, v171 op_sel_hi:[0,0,0]
	s_barrier
	s_add_i32 s0, s45, s11
	v_lshl_add_u64 v[162:163], s[30:31], 0, v[150:151]
	s_mov_b32 m0, s0
	ds_read_b128 v[206:209], v172
	ds_read_b128 v[210:213], v172 offset:1024
	ds_read_b128 v[214:217], v172 offset:2048
	ds_read_b128 v[218:221], v172 offset:3072
	global_load_lds_dwordx4 v[162:163], off
	v_lshl_add_u64 v[164:165], s[30:31], 0, v[146:147]
	s_add_i32 m0, s0, 0x2000
	s_nop 0
	global_load_lds_dwordx4 v[164:165], off
	s_waitcnt vmcnt(10)
	s_barrier
	s_waitcnt lgkmcnt(0)
	s_waitcnt lgkmcnt(0)
	v_mfma_scale_f32_16x16x128_f8f6f4 v[134:137], v[206:213], v[174:181], v[134:137], v171, v171 op_sel_hi:[0,0,0]
	v_mfma_scale_f32_16x16x128_f8f6f4 v[130:133], v[214:221], v[174:181], v[130:133], v171, v171 op_sel_hi:[0,0,0]
	v_mfma_scale_f32_16x16x128_f8f6f4 v[118:121], v[206:213], v[182:189], v[118:121], v171, v171 op_sel_hi:[0,0,0]
	v_mfma_scale_f32_16x16x128_f8f6f4 v[114:117], v[214:221], v[182:189], v[114:117], v171, v171 op_sel_hi:[0,0,0]
	v_mfma_scale_f32_16x16x128_f8f6f4 v[102:105], v[206:213], v[190:197], v[102:105], v171, v171 op_sel_hi:[0,0,0]
	v_mfma_scale_f32_16x16x128_f8f6f4 v[98:101], v[214:221], v[190:197], v[98:101], v171, v171 op_sel_hi:[0,0,0]
	v_mfma_scale_f32_16x16x128_f8f6f4 v[86:89], v[206:213], v[198:205], v[86:89], v171, v171 op_sel_hi:[0,0,0]
	v_mfma_scale_f32_16x16x128_f8f6f4 v[82:85], v[214:221], v[198:205], v[82:85], v171, v171 op_sel_hi:[0,0,0]
	s_mov_b32 m0, s17
	v_lshl_add_u64 v[222:223], s[36:37], 0, v[152:153]
	s_barrier
	ds_read_b128 v[174:177], v170 offset:16384
	ds_read_b128 v[178:181], v170 offset:17408
	ds_read_b128 v[182:185], v170 offset:18432
	ds_read_b128 v[186:189], v170 offset:19456
	ds_read_b128 v[190:193], v170 offset:20480
	ds_read_b128 v[194:197], v170 offset:21504
	ds_read_b128 v[198:201], v170 offset:22528
	ds_read_b128 v[202:205], v170 offset:23552
	global_load_lds_dwordx4 v[222:223], off nt
	v_lshl_add_u64 v[222:223], s[36:37], 0, v[148:149]
	s_mov_b32 m0, s27
	s_nop 0
	global_load_lds_dwordx4 v[222:223], off nt
	s_waitcnt vmcnt(10)
	s_barrier
	s_waitcnt lgkmcnt(0)
	s_waitcnt lgkmcnt(0)
	v_mfma_scale_f32_16x16x128_f8f6f4 v[78:81], v[2:9], v[174:181], v[78:81], v171, v171 op_sel_hi:[0,0,0]
	v_mfma_scale_f32_16x16x128_f8f6f4 v[74:77], v[10:17], v[174:181], v[74:77], v171, v171 op_sel_hi:[0,0,0]
	v_mfma_scale_f32_16x16x128_f8f6f4 v[62:65], v[2:9], v[182:189], v[62:65], v171, v171 op_sel_hi:[0,0,0]
	v_mfma_scale_f32_16x16x128_f8f6f4 v[58:61], v[10:17], v[182:189], v[58:61], v171, v171 op_sel_hi:[0,0,0]
	v_mfma_scale_f32_16x16x128_f8f6f4 v[46:49], v[2:9], v[190:197], v[46:49], v171, v171 op_sel_hi:[0,0,0]
	v_mfma_scale_f32_16x16x128_f8f6f4 v[42:45], v[10:17], v[190:197], v[42:45], v171, v171 op_sel_hi:[0,0,0]
	v_mfma_scale_f32_16x16x128_f8f6f4 v[30:33], v[2:9], v[198:205], v[30:33], v171, v171 op_sel_hi:[0,0,0]
	v_mfma_scale_f32_16x16x128_f8f6f4 v[26:29], v[10:17], v[198:205], v[26:29], v171, v171 op_sel_hi:[0,0,0]
	s_barrier
	s_add_u32 s0, s30, 0x20000
	s_addc_u32 s1, s31, 0
	s_add_i32 s54, s46, s11
	v_lshl_add_u64 v[2:3], s[0:1], 0, v[150:151]
	s_mov_b32 m0, s54
	s_nop 0
	global_load_lds_dwordx4 v[2:3], off
	v_lshl_add_u64 v[2:3], s[0:1], 0, v[146:147]
	s_add_i32 m0, s54, 0x2000
	s_nop 0
	global_load_lds_dwordx4 v[2:3], off
	s_waitcnt vmcnt(10)
	s_barrier
	v_mfma_scale_f32_16x16x128_f8f6f4 v[70:73], v[206:213], v[174:181], v[70:73], v171, v171 op_sel_hi:[0,0,0]
	v_mfma_scale_f32_16x16x128_f8f6f4 v[66:69], v[214:221], v[174:181], v[66:69], v171, v171 op_sel_hi:[0,0,0]
	v_mfma_scale_f32_16x16x128_f8f6f4 v[54:57], v[206:213], v[182:189], v[54:57], v171, v171 op_sel_hi:[0,0,0]
	v_mfma_scale_f32_16x16x128_f8f6f4 v[50:53], v[214:221], v[182:189], v[50:53], v171, v171 op_sel_hi:[0,0,0]
	v_mfma_scale_f32_16x16x128_f8f6f4 v[38:41], v[206:213], v[190:197], v[38:41], v171, v171 op_sel_hi:[0,0,0]
	v_mfma_scale_f32_16x16x128_f8f6f4 v[34:37], v[214:221], v[190:197], v[34:37], v171, v171 op_sel_hi:[0,0,0]
	v_mfma_scale_f32_16x16x128_f8f6f4 v[22:25], v[206:213], v[198:205], v[22:25], v171, v171 op_sel_hi:[0,0,0]
	v_mfma_scale_f32_16x16x128_f8f6f4 v[18:21], v[214:221], v[198:205], v[18:21], v171, v171 op_sel_hi:[0,0,0]
	s_add_i32 s54, 0, 0x18000
	v_add_u32_e32 v14, s54, v168
	s_barrier
	ds_read_b128 v[2:5], v14
	ds_read_b128 v[6:9], v14 offset:1024
	ds_read_b128 v[10:13], v14 offset:2048
	ds_read_b128 v[14:17], v14 offset:3072
	s_add_u32 s0, s36, 0x4000
	s_addc_u32 s1, s37, 0
	s_mov_b32 m0, s38
	v_lshl_add_u64 v[206:207], s[0:1], 0, v[152:153]
	ds_read_b128 v[174:177], v170 offset:32768
	ds_read_b128 v[178:181], v170 offset:33792
	ds_read_b128 v[182:185], v170 offset:34816
	ds_read_b128 v[186:189], v170 offset:35840
	ds_read_b128 v[190:193], v170 offset:36864
	ds_read_b128 v[194:197], v170 offset:37888
	ds_read_b128 v[198:201], v170 offset:38912
	ds_read_b128 v[202:205], v170 offset:39936
	global_load_lds_dwordx4 v[206:207], off nt
	v_lshl_add_u64 v[206:207], s[0:1], 0, v[148:149]
	s_mov_b32 m0, s39
	s_nop 0
	global_load_lds_dwordx4 v[206:207], off nt
	s_waitcnt lgkmcnt(8)
	s_waitcnt vmcnt(10)
	s_barrier
	s_waitcnt lgkmcnt(0)
	s_waitcnt lgkmcnt(0)
	v_mfma_scale_f32_16x16x128_f8f6f4 v[142:145], v[2:9], v[174:181], v[142:145], v171, v171 op_sel_hi:[0,0,0]
	v_mfma_scale_f32_16x16x128_f8f6f4 v[138:141], v[10:17], v[174:181], v[138:141], v171, v171 op_sel_hi:[0,0,0]
	v_mfma_scale_f32_16x16x128_f8f6f4 v[126:129], v[2:9], v[182:189], v[126:129], v171, v171 op_sel_hi:[0,0,0]
	v_mfma_scale_f32_16x16x128_f8f6f4 v[122:125], v[10:17], v[182:189], v[122:125], v171, v171 op_sel_hi:[0,0,0]
	v_mfma_scale_f32_16x16x128_f8f6f4 v[110:113], v[2:9], v[190:197], v[110:113], v171, v171 op_sel_hi:[0,0,0]
	v_mfma_scale_f32_16x16x128_f8f6f4 v[106:109], v[10:17], v[190:197], v[106:109], v171, v171 op_sel_hi:[0,0,0]
	v_mfma_scale_f32_16x16x128_f8f6f4 v[94:97], v[2:9], v[198:205], v[94:97], v171, v171 op_sel_hi:[0,0,0]
	v_mfma_scale_f32_16x16x128_f8f6f4 v[90:93], v[10:17], v[198:205], v[90:93], v171, v171 op_sel_hi:[0,0,0]
	s_barrier
	s_add_i32 s36, 0, 0x1c000
	s_add_i32 s0, s54, s11
	v_add_u32_e32 v218, s36, v168
	v_lshl_add_u64 v[162:163], v[162:163], 0, s[14:15]
	s_mov_b32 m0, s0
	ds_read_b128 v[206:209], v218
	ds_read_b128 v[210:213], v218 offset:1024
	ds_read_b128 v[214:217], v218 offset:2048
	ds_read_b128 v[218:221], v218 offset:3072
	global_load_lds_dwordx4 v[162:163], off
	v_lshl_add_u64 v[162:163], v[164:165], 0, s[14:15]
	s_add_i32 m0, s0, 0x2000
	s_nop 0
	global_load_lds_dwordx4 v[162:163], off
	s_waitcnt vmcnt(10)
	s_barrier
	s_waitcnt lgkmcnt(0)
	s_waitcnt lgkmcnt(0)
	v_mfma_scale_f32_16x16x128_f8f6f4 v[134:137], v[206:213], v[174:181], v[134:137], v171, v171 op_sel_hi:[0,0,0]
	v_mfma_scale_f32_16x16x128_f8f6f4 v[130:133], v[214:221], v[174:181], v[130:133], v171, v171 op_sel_hi:[0,0,0]
	v_mfma_scale_f32_16x16x128_f8f6f4 v[118:121], v[206:213], v[182:189], v[118:121], v171, v171 op_sel_hi:[0,0,0]
	v_mfma_scale_f32_16x16x128_f8f6f4 v[114:117], v[214:221], v[182:189], v[114:117], v171, v171 op_sel_hi:[0,0,0]
	v_mfma_scale_f32_16x16x128_f8f6f4 v[102:105], v[206:213], v[190:197], v[102:105], v171, v171 op_sel_hi:[0,0,0]
	v_mfma_scale_f32_16x16x128_f8f6f4 v[98:101], v[214:221], v[190:197], v[98:101], v171, v171 op_sel_hi:[0,0,0]
	v_mfma_scale_f32_16x16x128_f8f6f4 v[86:89], v[206:213], v[198:205], v[86:89], v171, v171 op_sel_hi:[0,0,0]
	v_mfma_scale_f32_16x16x128_f8f6f4 v[82:85], v[214:221], v[198:205], v[82:85], v171, v171 op_sel_hi:[0,0,0]
	s_mov_b32 m0, s43
	v_lshl_add_u64 v[162:163], s[34:35], 0, v[152:153]
	s_barrier
	ds_read_b128 v[174:177], v170 offset:49152
	ds_read_b128 v[178:181], v170 offset:50176
	ds_read_b128 v[182:185], v170 offset:51200
	ds_read_b128 v[186:189], v170 offset:52224
	ds_read_b128 v[190:193], v170 offset:53248
	ds_read_b128 v[194:197], v170 offset:54272
	ds_read_b128 v[198:201], v170 offset:55296
	ds_read_b128 v[202:205], v170 offset:56320
	global_load_lds_dwordx4 v[162:163], off nt
	v_lshl_add_u64 v[162:163], s[34:35], 0, v[148:149]
	s_mov_b32 m0, s44
	s_nop 0
	global_load_lds_dwordx4 v[162:163], off nt
	s_waitcnt vmcnt(10)
	s_barrier
	s_waitcnt lgkmcnt(0)
	s_waitcnt lgkmcnt(0)
	v_mfma_scale_f32_16x16x128_f8f6f4 v[78:81], v[2:9], v[174:181], v[78:81], v171, v171 op_sel_hi:[0,0,0]
	v_mfma_scale_f32_16x16x128_f8f6f4 v[74:77], v[10:17], v[174:181], v[74:77], v171, v171 op_sel_hi:[0,0,0]
	v_mfma_scale_f32_16x16x128_f8f6f4 v[62:65], v[2:9], v[182:189], v[62:65], v171, v171 op_sel_hi:[0,0,0]
	v_mfma_scale_f32_16x16x128_f8f6f4 v[58:61], v[10:17], v[182:189], v[58:61], v171, v171 op_sel_hi:[0,0,0]
	v_mfma_scale_f32_16x16x128_f8f6f4 v[46:49], v[2:9], v[190:197], v[46:49], v171, v171 op_sel_hi:[0,0,0]
	v_mfma_scale_f32_16x16x128_f8f6f4 v[42:45], v[10:17], v[190:197], v[42:45], v171, v171 op_sel_hi:[0,0,0]
	v_mfma_scale_f32_16x16x128_f8f6f4 v[30:33], v[2:9], v[198:205], v[30:33], v171, v171 op_sel_hi:[0,0,0]
	v_mfma_scale_f32_16x16x128_f8f6f4 v[26:29], v[10:17], v[198:205], v[26:29], v171, v171 op_sel_hi:[0,0,0]
	s_barrier
	s_add_u32 s0, s30, 0x20080
	s_addc_u32 s1, s31, 0
	s_add_i32 s30, s36, s11
	v_lshl_add_u64 v[2:3], s[0:1], 0, v[150:151]
	s_mov_b32 m0, s30
	s_nop 0
	global_load_lds_dwordx4 v[2:3], off
	v_lshl_add_u64 v[2:3], s[0:1], 0, v[146:147]
	s_add_i32 m0, s30, 0x2000
	s_nop 0
	global_load_lds_dwordx4 v[2:3], off
	s_waitcnt vmcnt(10)
	s_barrier
	v_mfma_scale_f32_16x16x128_f8f6f4 v[70:73], v[206:213], v[174:181], v[70:73], v171, v171 op_sel_hi:[0,0,0]
	v_mfma_scale_f32_16x16x128_f8f6f4 v[66:69], v[214:221], v[174:181], v[66:69], v171, v171 op_sel_hi:[0,0,0]
	v_mfma_scale_f32_16x16x128_f8f6f4 v[54:57], v[206:213], v[182:189], v[54:57], v171, v171 op_sel_hi:[0,0,0]
	v_mfma_scale_f32_16x16x128_f8f6f4 v[50:53], v[214:221], v[182:189], v[50:53], v171, v171 op_sel_hi:[0,0,0]
	v_mfma_scale_f32_16x16x128_f8f6f4 v[38:41], v[206:213], v[190:197], v[38:41], v171, v171 op_sel_hi:[0,0,0]
	v_mfma_scale_f32_16x16x128_f8f6f4 v[34:37], v[214:221], v[190:197], v[34:37], v171, v171 op_sel_hi:[0,0,0]
	v_mfma_scale_f32_16x16x128_f8f6f4 v[22:25], v[206:213], v[198:205], v[22:25], v171, v171 op_sel_hi:[0,0,0]
	v_mfma_scale_f32_16x16x128_f8f6f4 v[18:21], v[214:221], v[198:205], v[18:21], v171, v171 op_sel_hi:[0,0,0]
	s_add_i32 s53, s53, 2
	s_add_u32 s51, s51, 0x100
	s_addc_u32 s52, s52, 0
	s_add_u32 s28, s28, 0x10000
	s_addc_u32 s29, s29, 0
	s_cmp_gt_u32 s53, 5
	s_barrier
	s_cbranch_scc0 .LBB0_1369
	v_pk_mul_f32 v[10:11], v[142:143], s[16:17] op_sel_hi:[1,0]
	v_pk_mul_f32 v[8:9], v[144:145], s[16:17] op_sel_hi:[1,0]
	v_med3_f32 v5, v10, s47, v173
	v_med3_f32 v11, v11, s47, v173
	v_mov_b32_e32 v10, 0
	v_cvt_pk_fp8_f32 v10, v5, v11
	v_mov_b32_e32 v3, v166
	v_mov_b32_e32 v2, v167
	s_lshl_b32 s0, s48, 8
	v_pk_mul_f32 v[14:15], v[138:139], s[16:17] op_sel_hi:[1,0]
	v_med3_f32 v5, v8, s47, v173
	v_med3_f32 v8, v9, s47, v173
	s_nop 15
	s_nop 15
	s_or_b32 s0, s0, s42
	v_cvt_pk_fp8_f32 v10, v5, v8 op_sel:[0,0,1]
	v_med3_f32 v5, v14, s47, v173
	v_med3_f32 v8, v15, s47, v173
	v_mov_b32_e32 v11, 0
	v_lshl_add_u32 v2, v2, 3, s0
	s_lshl_b32 s0, s26, 8
	v_cvt_pk_fp8_f32 v11, v5, v8
	s_add_i32 s0, s0, s41
	v_add_u32_e32 v4, s0, v3
	v_pk_mul_f32 v[12:13], v[140:141], s[16:17] op_sel_hi:[1,0]
	v_mov_b32_e32 v6, v4
	v_med3_f32 v5, v12, s47, v173
	v_med3_f32 v8, v13, s47, v173
	v_cvt_pk_fp8_f32 v11, v5, v8 op_sel:[0,0,1]
	v_ashrrev_i32_e32 v7, 31, v6
	v_lshlrev_b64 v[6:7], 10, v[6:7]
	v_ashrrev_i32_e32 v3, 31, v2
	v_lshl_add_u64 v[6:7], s[12:13], 0, v[6:7]
	v_lshl_add_u64 v[6:7], v[6:7], 0, v[2:3]
	global_store_dwordx2 v[6:7], v[10:11], off
	v_pk_mul_f32 v[10:11], v[134:135], s[16:17] op_sel_hi:[1,0]
	v_pk_mul_f32 v[8:9], v[136:137], s[16:17] op_sel_hi:[1,0]
	v_med3_f32 v5, v10, s47, v173
	v_med3_f32 v11, v11, s47, v173
	v_mov_b32_e32 v10, 0
	v_cvt_pk_fp8_f32 v10, v5, v11
	v_pk_mul_f32 v[14:15], v[130:131], s[16:17] op_sel_hi:[1,0]
	v_med3_f32 v5, v8, s47, v173
	v_med3_f32 v8, v9, s47, v173
	v_cvt_pk_fp8_f32 v10, v5, v8 op_sel:[0,0,1]
	v_med3_f32 v5, v14, s47, v173
	v_med3_f32 v8, v15, s47, v173
	v_mov_b32_e32 v11, 0
	v_cvt_pk_fp8_f32 v11, v5, v8
	v_pk_mul_f32 v[12:13], v[132:133], s[16:17] op_sel_hi:[1,0]
	v_pk_mul_f32 v[14:15], v[122:123], s[16:17] op_sel_hi:[1,0]
	v_med3_f32 v5, v12, s47, v173
	v_med3_f32 v8, v13, s47, v173
	v_cvt_pk_fp8_f32 v11, v5, v8 op_sel:[0,0,1]
	v_pk_mul_f32 v[8:9], v[128:129], s[16:17] op_sel_hi:[1,0]
	v_pk_mul_f32 v[12:13], v[124:125], s[16:17] op_sel_hi:[1,0]
	s_and_b64 vcc, exec, s[8:9]
	global_store_dwordx2 v[6:7], v[10:11], off offset:128
	v_pk_mul_f32 v[10:11], v[126:127], s[16:17] op_sel_hi:[1,0]
	v_add_u32_e32 v6, 16, v4
	v_med3_f32 v5, v10, s47, v173
	v_med3_f32 v11, v11, s47, v173
	v_mov_b32_e32 v10, 0
	v_cvt_pk_fp8_f32 v10, v5, v11
	v_med3_f32 v5, v8, s47, v173
	v_med3_f32 v8, v9, s47, v173
	v_mov_b32_e32 v11, 0
	v_cvt_pk_fp8_f32 v10, v5, v8 op_sel:[0,0,1]
	v_med3_f32 v5, v14, s47, v173
	v_med3_f32 v8, v15, s47, v173
	v_cvt_pk_fp8_f32 v11, v5, v8
	v_med3_f32 v5, v12, s47, v173
	v_med3_f32 v8, v13, s47, v173
	v_cvt_pk_fp8_f32 v11, v5, v8 op_sel:[0,0,1]
	v_ashrrev_i32_e32 v7, 31, v6
	v_lshlrev_b64 v[6:7], 10, v[6:7]
	v_lshl_add_u64 v[6:7], s[12:13], 0, v[6:7]
	v_lshl_add_u64 v[6:7], v[6:7], 0, v[2:3]
	global_store_dwordx2 v[6:7], v[10:11], off
	v_pk_mul_f32 v[10:11], v[118:119], s[16:17] op_sel_hi:[1,0]
	v_pk_mul_f32 v[8:9], v[120:121], s[16:17] op_sel_hi:[1,0]
	v_med3_f32 v5, v10, s47, v173
	v_med3_f32 v11, v11, s47, v173
	v_mov_b32_e32 v10, 0
	v_cvt_pk_fp8_f32 v10, v5, v11
	v_pk_mul_f32 v[14:15], v[114:115], s[16:17] op_sel_hi:[1,0]
	v_med3_f32 v5, v8, s47, v173
	v_med3_f32 v8, v9, s47, v173
	v_cvt_pk_fp8_f32 v10, v5, v8 op_sel:[0,0,1]
	v_med3_f32 v5, v14, s47, v173
	v_med3_f32 v8, v15, s47, v173
	v_mov_b32_e32 v11, 0
	v_cvt_pk_fp8_f32 v11, v5, v8
	v_pk_mul_f32 v[12:13], v[116:117], s[16:17] op_sel_hi:[1,0]
	v_pk_mul_f32 v[14:15], v[106:107], s[16:17] op_sel_hi:[1,0]
	v_med3_f32 v5, v12, s47, v173
	v_med3_f32 v8, v13, s47, v173
	v_cvt_pk_fp8_f32 v11, v5, v8 op_sel:[0,0,1]
	v_pk_mul_f32 v[8:9], v[112:113], s[16:17] op_sel_hi:[1,0]
	v_pk_mul_f32 v[12:13], v[108:109], s[16:17] op_sel_hi:[1,0]
	s_mov_b32 s48, s18
	global_store_dwordx2 v[6:7], v[10:11], off offset:128
	v_pk_mul_f32 v[10:11], v[110:111], s[16:17] op_sel_hi:[1,0]
	v_add_u32_e32 v6, 32, v4
	v_med3_f32 v5, v10, s47, v173
	v_med3_f32 v11, v11, s47, v173
	v_mov_b32_e32 v10, 0
	v_cvt_pk_fp8_f32 v10, v5, v11
	v_med3_f32 v5, v8, s47, v173
	v_med3_f32 v8, v9, s47, v173
	v_mov_b32_e32 v11, 0
	v_cvt_pk_fp8_f32 v10, v5, v8 op_sel:[0,0,1]
	v_med3_f32 v5, v14, s47, v173
	v_med3_f32 v8, v15, s47, v173
	v_cvt_pk_fp8_f32 v11, v5, v8
	v_med3_f32 v5, v12, s47, v173
	v_med3_f32 v8, v13, s47, v173
	v_cvt_pk_fp8_f32 v11, v5, v8 op_sel:[0,0,1]
	v_ashrrev_i32_e32 v7, 31, v6
	v_lshlrev_b64 v[6:7], 10, v[6:7]
	v_lshl_add_u64 v[6:7], s[12:13], 0, v[6:7]
	v_lshl_add_u64 v[6:7], v[6:7], 0, v[2:3]
	global_store_dwordx2 v[6:7], v[10:11], off
	v_pk_mul_f32 v[10:11], v[102:103], s[16:17] op_sel_hi:[1,0]
	v_pk_mul_f32 v[8:9], v[104:105], s[16:17] op_sel_hi:[1,0]
	v_med3_f32 v5, v10, s47, v173
	v_med3_f32 v11, v11, s47, v173
	v_mov_b32_e32 v10, 0
	v_cvt_pk_fp8_f32 v10, v5, v11
	v_pk_mul_f32 v[14:15], v[98:99], s[16:17] op_sel_hi:[1,0]
	v_med3_f32 v5, v8, s47, v173
	v_med3_f32 v8, v9, s47, v173
	v_cvt_pk_fp8_f32 v10, v5, v8 op_sel:[0,0,1]
	v_med3_f32 v5, v14, s47, v173
	v_med3_f32 v8, v15, s47, v173
	v_mov_b32_e32 v11, 0
	v_cvt_pk_fp8_f32 v11, v5, v8
	v_pk_mul_f32 v[12:13], v[100:101], s[16:17] op_sel_hi:[1,0]
	v_pk_mul_f32 v[14:15], v[90:91], s[16:17] op_sel_hi:[1,0]
	v_med3_f32 v5, v12, s47, v173
	v_med3_f32 v8, v13, s47, v173
	v_cvt_pk_fp8_f32 v11, v5, v8 op_sel:[0,0,1]
	v_pk_mul_f32 v[8:9], v[96:97], s[16:17] op_sel_hi:[1,0]
	v_pk_mul_f32 v[12:13], v[92:93], s[16:17] op_sel_hi:[1,0]
	s_mov_b32 s26, s20
	global_store_dwordx2 v[6:7], v[10:11], off offset:128
	v_pk_mul_f32 v[10:11], v[94:95], s[16:17] op_sel_hi:[1,0]
	v_add_u32_e32 v6, 48, v4
	v_med3_f32 v5, v10, s47, v173
	v_med3_f32 v11, v11, s47, v173
	v_mov_b32_e32 v10, 0
	v_cvt_pk_fp8_f32 v10, v5, v11
	v_med3_f32 v5, v8, s47, v173
	v_med3_f32 v8, v9, s47, v173
	v_mov_b32_e32 v11, 0
	v_cvt_pk_fp8_f32 v10, v5, v8 op_sel:[0,0,1]
	v_med3_f32 v5, v14, s47, v173
	v_med3_f32 v8, v15, s47, v173
	v_cvt_pk_fp8_f32 v11, v5, v8
	v_med3_f32 v5, v12, s47, v173
	v_med3_f32 v8, v13, s47, v173
	v_cvt_pk_fp8_f32 v11, v5, v8 op_sel:[0,0,1]
	v_ashrrev_i32_e32 v7, 31, v6
	v_lshlrev_b64 v[6:7], 10, v[6:7]
	v_lshl_add_u64 v[6:7], s[12:13], 0, v[6:7]
	v_lshl_add_u64 v[6:7], v[6:7], 0, v[2:3]
	global_store_dwordx2 v[6:7], v[10:11], off
	v_pk_mul_f32 v[10:11], v[86:87], s[16:17] op_sel_hi:[1,0]
	v_pk_mul_f32 v[8:9], v[88:89], s[16:17] op_sel_hi:[1,0]
	v_med3_f32 v5, v10, s47, v173
	v_med3_f32 v11, v11, s47, v173
	v_mov_b32_e32 v10, 0
	v_cvt_pk_fp8_f32 v10, v5, v11
	v_pk_mul_f32 v[14:15], v[82:83], s[16:17] op_sel_hi:[1,0]
	v_med3_f32 v5, v8, s47, v173
	v_med3_f32 v8, v9, s47, v173
	v_cvt_pk_fp8_f32 v10, v5, v8 op_sel:[0,0,1]
	v_med3_f32 v5, v14, s47, v173
	v_med3_f32 v8, v15, s47, v173
	v_mov_b32_e32 v11, 0
	v_cvt_pk_fp8_f32 v11, v5, v8
	v_pk_mul_f32 v[12:13], v[84:85], s[16:17] op_sel_hi:[1,0]
	v_pk_mul_f32 v[14:15], v[74:75], s[16:17] op_sel_hi:[1,0]
	v_med3_f32 v5, v12, s47, v173
	v_med3_f32 v8, v13, s47, v173
	v_cvt_pk_fp8_f32 v11, v5, v8 op_sel:[0,0,1]
	v_pk_mul_f32 v[8:9], v[80:81], s[16:17] op_sel_hi:[1,0]
	v_pk_mul_f32 v[12:13], v[76:77], s[16:17] op_sel_hi:[1,0]
	s_mov_b64 s[28:29], s[24:25]
	global_store_dwordx2 v[6:7], v[10:11], off offset:128
	v_pk_mul_f32 v[10:11], v[78:79], s[16:17] op_sel_hi:[1,0]
	v_add_u32_e32 v6, 0x80, v4
	v_med3_f32 v5, v10, s47, v173
	v_med3_f32 v11, v11, s47, v173
	v_mov_b32_e32 v10, 0
	v_cvt_pk_fp8_f32 v10, v5, v11
	v_med3_f32 v5, v8, s47, v173
	v_med3_f32 v8, v9, s47, v173
	v_mov_b32_e32 v11, 0
	v_cvt_pk_fp8_f32 v10, v5, v8 op_sel:[0,0,1]
	v_med3_f32 v5, v14, s47, v173
	v_med3_f32 v8, v15, s47, v173
	v_cvt_pk_fp8_f32 v11, v5, v8
	v_med3_f32 v5, v12, s47, v173
	v_med3_f32 v8, v13, s47, v173
	v_cvt_pk_fp8_f32 v11, v5, v8 op_sel:[0,0,1]
	v_ashrrev_i32_e32 v7, 31, v6
	v_lshlrev_b64 v[6:7], 10, v[6:7]
	v_lshl_add_u64 v[6:7], s[12:13], 0, v[6:7]
	v_lshl_add_u64 v[6:7], v[6:7], 0, v[2:3]
	global_store_dwordx2 v[6:7], v[10:11], off
	v_pk_mul_f32 v[10:11], v[70:71], s[16:17] op_sel_hi:[1,0]
	v_pk_mul_f32 v[8:9], v[72:73], s[16:17] op_sel_hi:[1,0]
	v_med3_f32 v5, v10, s47, v173
	v_med3_f32 v11, v11, s47, v173
	v_mov_b32_e32 v10, 0
	v_cvt_pk_fp8_f32 v10, v5, v11
	v_pk_mul_f32 v[14:15], v[66:67], s[16:17] op_sel_hi:[1,0]
	v_med3_f32 v5, v8, s47, v173
	v_med3_f32 v8, v9, s47, v173
	v_cvt_pk_fp8_f32 v10, v5, v8 op_sel:[0,0,1]
	v_med3_f32 v5, v14, s47, v173
	v_med3_f32 v8, v15, s47, v173
	v_mov_b32_e32 v11, 0
	v_cvt_pk_fp8_f32 v11, v5, v8
	v_pk_mul_f32 v[12:13], v[68:69], s[16:17] op_sel_hi:[1,0]
	v_pk_mul_f32 v[14:15], v[58:59], s[16:17] op_sel_hi:[1,0]
	v_med3_f32 v5, v12, s47, v173
	v_med3_f32 v8, v13, s47, v173
	v_cvt_pk_fp8_f32 v11, v5, v8 op_sel:[0,0,1]
	v_pk_mul_f32 v[8:9], v[64:65], s[16:17] op_sel_hi:[1,0]
	v_pk_mul_f32 v[12:13], v[60:61], s[16:17] op_sel_hi:[1,0]
	s_mov_b64 s[30:31], s[22:23]
	global_store_dwordx2 v[6:7], v[10:11], off offset:128
	v_pk_mul_f32 v[10:11], v[62:63], s[16:17] op_sel_hi:[1,0]
	v_add_u32_e32 v6, 0x90, v4
	v_med3_f32 v5, v10, s47, v173
	v_med3_f32 v11, v11, s47, v173
	v_mov_b32_e32 v10, 0
	v_cvt_pk_fp8_f32 v10, v5, v11
	v_med3_f32 v5, v8, s47, v173
	v_med3_f32 v8, v9, s47, v173
	v_mov_b32_e32 v11, 0
	v_cvt_pk_fp8_f32 v10, v5, v8 op_sel:[0,0,1]
	v_med3_f32 v5, v14, s47, v173
	v_med3_f32 v8, v15, s47, v173
	v_cvt_pk_fp8_f32 v11, v5, v8
	v_med3_f32 v5, v12, s47, v173
	v_med3_f32 v8, v13, s47, v173
	v_cvt_pk_fp8_f32 v11, v5, v8 op_sel:[0,0,1]
	v_ashrrev_i32_e32 v7, 31, v6
	v_lshlrev_b64 v[6:7], 10, v[6:7]
	v_lshl_add_u64 v[6:7], s[12:13], 0, v[6:7]
	v_lshl_add_u64 v[6:7], v[6:7], 0, v[2:3]
	global_store_dwordx2 v[6:7], v[10:11], off
	v_pk_mul_f32 v[10:11], v[54:55], s[16:17] op_sel_hi:[1,0]
	v_pk_mul_f32 v[8:9], v[56:57], s[16:17] op_sel_hi:[1,0]
	v_med3_f32 v5, v10, s47, v173
	v_med3_f32 v11, v11, s47, v173
	v_mov_b32_e32 v10, 0
	v_cvt_pk_fp8_f32 v10, v5, v11
	v_pk_mul_f32 v[14:15], v[50:51], s[16:17] op_sel_hi:[1,0]
	v_med3_f32 v5, v8, s47, v173
	v_med3_f32 v8, v9, s47, v173
	v_cvt_pk_fp8_f32 v10, v5, v8 op_sel:[0,0,1]
	v_med3_f32 v5, v14, s47, v173
	v_med3_f32 v8, v15, s47, v173
	v_mov_b32_e32 v11, 0
	v_cvt_pk_fp8_f32 v11, v5, v8
	v_pk_mul_f32 v[12:13], v[52:53], s[16:17] op_sel_hi:[1,0]
	v_pk_mul_f32 v[14:15], v[42:43], s[16:17] op_sel_hi:[1,0]
	v_med3_f32 v5, v12, s47, v173
	v_med3_f32 v8, v13, s47, v173
	v_cvt_pk_fp8_f32 v11, v5, v8 op_sel:[0,0,1]
	v_pk_mul_f32 v[8:9], v[48:49], s[16:17] op_sel_hi:[1,0]
	v_pk_mul_f32 v[12:13], v[44:45], s[16:17] op_sel_hi:[1,0]
	global_store_dwordx2 v[6:7], v[10:11], off offset:128
	v_pk_mul_f32 v[10:11], v[46:47], s[16:17] op_sel_hi:[1,0]
	v_add_u32_e32 v6, 0xa0, v4
	v_med3_f32 v5, v10, s47, v173
	v_med3_f32 v11, v11, s47, v173
	v_mov_b32_e32 v10, 0
	v_cvt_pk_fp8_f32 v10, v5, v11
	v_med3_f32 v5, v8, s47, v173
	v_med3_f32 v8, v9, s47, v173
	v_mov_b32_e32 v11, 0
	v_cvt_pk_fp8_f32 v10, v5, v8 op_sel:[0,0,1]
	v_med3_f32 v5, v14, s47, v173
	v_med3_f32 v8, v15, s47, v173
	v_cvt_pk_fp8_f32 v11, v5, v8
	v_med3_f32 v5, v12, s47, v173
	v_med3_f32 v8, v13, s47, v173
	v_cvt_pk_fp8_f32 v11, v5, v8 op_sel:[0,0,1]
	v_ashrrev_i32_e32 v7, 31, v6
	v_lshlrev_b64 v[6:7], 10, v[6:7]
	v_lshl_add_u64 v[6:7], s[12:13], 0, v[6:7]
	v_lshl_add_u64 v[6:7], v[6:7], 0, v[2:3]
	global_store_dwordx2 v[6:7], v[10:11], off
	v_pk_mul_f32 v[10:11], v[38:39], s[16:17] op_sel_hi:[1,0]
	v_pk_mul_f32 v[8:9], v[40:41], s[16:17] op_sel_hi:[1,0]
	v_med3_f32 v5, v10, s47, v173
	v_med3_f32 v11, v11, s47, v173
	v_mov_b32_e32 v10, 0
	v_cvt_pk_fp8_f32 v10, v5, v11
	v_pk_mul_f32 v[14:15], v[34:35], s[16:17] op_sel_hi:[1,0]
	v_med3_f32 v5, v8, s47, v173
	v_med3_f32 v8, v9, s47, v173
	v_cvt_pk_fp8_f32 v10, v5, v8 op_sel:[0,0,1]
	v_med3_f32 v5, v14, s47, v173
	v_med3_f32 v8, v15, s47, v173
	v_mov_b32_e32 v11, 0
	v_cvt_pk_fp8_f32 v11, v5, v8
	v_pk_mul_f32 v[12:13], v[36:37], s[16:17] op_sel_hi:[1,0]
	v_add_u32_e32 v4, 0xb0, v4
	v_med3_f32 v5, v12, s47, v173
	v_med3_f32 v8, v13, s47, v173
	v_cvt_pk_fp8_f32 v11, v5, v8 op_sel:[0,0,1]
	v_pk_mul_f32 v[8:9], v[28:29], s[16:17] op_sel_hi:[1,0]
	global_store_dwordx2 v[6:7], v[10:11], off offset:128
	v_pk_mul_f32 v[6:7], v[30:31], s[16:17] op_sel_hi:[1,0]
	v_pk_mul_f32 v[10:11], v[26:27], s[16:17] op_sel_hi:[1,0]
	v_ashrrev_i32_e32 v5, 31, v4
	v_med3_f32 v12, v6, s47, v173
	v_med3_f32 v7, v7, s47, v173
	v_mov_b32_e32 v6, 0
	v_lshlrev_b64 v[4:5], 10, v[4:5]
	v_cvt_pk_fp8_f32 v6, v12, v7
	v_lshl_add_u64 v[4:5], s[12:13], 0, v[4:5]
	v_lshl_add_u64 v[2:3], v[4:5], 0, v[2:3]
	v_pk_mul_f32 v[4:5], v[32:33], s[16:17] op_sel_hi:[1,0]
	v_mov_b32_e32 v7, 0
	v_med3_f32 v4, v4, s47, v173
	v_med3_f32 v5, v5, s47, v173
	v_cvt_pk_fp8_f32 v6, v4, v5 op_sel:[0,0,1]
	v_med3_f32 v4, v10, s47, v173
	v_med3_f32 v5, v11, s47, v173
	v_cvt_pk_fp8_f32 v7, v4, v5
	v_med3_f32 v4, v8, s47, v173
	v_med3_f32 v5, v9, s47, v173
	v_pk_mul_f32 v[10:11], v[18:19], s[16:17] op_sel_hi:[1,0]
	v_cvt_pk_fp8_f32 v7, v4, v5 op_sel:[0,0,1]
	v_pk_mul_f32 v[4:5], v[24:25], s[16:17] op_sel_hi:[1,0]
	v_pk_mul_f32 v[8:9], v[20:21], s[16:17] op_sel_hi:[1,0]
	v_med3_f32 v4, v4, s47, v173
	global_store_dwordx2 v[2:3], v[6:7], off
	v_pk_mul_f32 v[6:7], v[22:23], s[16:17] op_sel_hi:[1,0]
	v_med3_f32 v5, v5, s47, v173
	v_med3_f32 v12, v6, s47, v173
	v_med3_f32 v7, v7, s47, v173
	v_mov_b32_e32 v6, 0
	v_cvt_pk_fp8_f32 v6, v12, v7
	v_mov_b32_e32 v7, 0
	v_cvt_pk_fp8_f32 v6, v4, v5 op_sel:[0,0,1]
	v_med3_f32 v4, v10, s47, v173
	v_med3_f32 v5, v11, s47, v173
	v_cvt_pk_fp8_f32 v7, v4, v5
	v_med3_f32 v4, v8, s47, v173
	v_med3_f32 v5, v9, s47, v173
	v_cvt_pk_fp8_f32 v7, v4, v5 op_sel:[0,0,1]
	global_store_dwordx2 v[2:3], v[6:7], off offset:128
	s_cbranch_vccz .LBB0_1362
	s_waitcnt vmcnt(0)
	s_cmpk_gt_u32 s4, 0xff
	s_cbranch_scc1 .LBB0_1373
	s_barrier

.LBB0_1513:
	ds_read_b128 v[152:155], v149
	ds_read_b128 v[156:159], v149 offset:1024
	ds_read_b128 v[160:163], v149 offset:2048
	ds_read_b128 v[164:167], v149 offset:3072
	s_add_u32 s0, s26, 0xfffc0080
	s_addc_u32 s1, s27, -1
	s_cmp_eq_u32 s49, 12
	s_cselect_b32 s31, s21, s1
	s_cselect_b32 s30, s45, s0
	s_cselect_b32 s29, s19, s48
	s_cselect_b32 s28, s46, s47
	v_lshl_add_u64 v[200:201], s[26:27], 0, v[140:141]
	s_add_i32 m0, s10, 0xc000
	ds_read_b128 v[168:171], v150
	ds_read_b128 v[172:175], v150 offset:1024
	ds_read_b128 v[176:179], v150 offset:2048
	ds_read_b128 v[180:183], v150 offset:3072
	ds_read_b128 v[184:187], v150 offset:4096
	ds_read_b128 v[188:191], v150 offset:5120
	ds_read_b128 v[192:195], v150 offset:6144
	ds_read_b128 v[196:199], v150 offset:7168
	global_load_lds_dwordx4 v[200:201], off nt
	v_lshl_add_u64 v[200:201], s[26:27], 0, v[138:139]
	s_add_i32 m0, s10, 0xe000
	s_nop 0
	global_load_lds_dwordx4 v[200:201], off nt
	s_waitcnt lgkmcnt(8)
	s_waitcnt vmcnt(10)
	s_barrier
	s_waitcnt lgkmcnt(0)
	s_waitcnt lgkmcnt(0)
	v_mfma_f32_16x16x32_bf16 v[126:129], v[152:155], v[168:171], v[126:129]
	v_mfma_f32_16x16x32_bf16 v[122:125], v[160:163], v[168:171], v[122:125]
	v_mfma_f32_16x16x32_bf16 v[118:121], v[152:155], v[176:179], v[118:121]
	v_mfma_f32_16x16x32_bf16 v[110:113], v[160:163], v[176:179], v[110:113]
	v_mfma_f32_16x16x32_bf16 v[102:105], v[152:155], v[184:187], v[102:105]
	v_mfma_f32_16x16x32_bf16 v[94:97], v[160:163], v[184:187], v[94:97]
	v_mfma_f32_16x16x32_bf16 v[86:89], v[152:155], v[192:195], v[86:89]
	v_mfma_f32_16x16x32_bf16 v[78:81], v[160:163], v[192:195], v[78:81]
	v_mfma_f32_16x16x32_bf16 v[126:129], v[156:159], v[172:175], v[126:129]
	v_mfma_f32_16x16x32_bf16 v[122:125], v[164:167], v[172:175], v[122:125]
	v_mfma_f32_16x16x32_bf16 v[118:121], v[156:159], v[180:183], v[118:121]
	v_mfma_f32_16x16x32_bf16 v[110:113], v[164:167], v[180:183], v[110:113]
	v_mfma_f32_16x16x32_bf16 v[102:105], v[156:159], v[188:191], v[102:105]
	v_mfma_f32_16x16x32_bf16 v[94:97], v[164:167], v[188:191], v[94:97]
	v_mfma_f32_16x16x32_bf16 v[86:89], v[156:159], v[196:199], v[86:89]
	v_mfma_f32_16x16x32_bf16 v[78:81], v[164:167], v[196:199], v[78:81]
	s_barrier
	s_add_i32 s0, s42, s9
	v_lshl_add_u64 v[216:217], s[28:29], 0, v[134:135]
	s_mov_b32 m0, s0
	ds_read_b128 v[200:203], v151
	ds_read_b128 v[204:207], v151 offset:1024
	ds_read_b128 v[208:211], v151 offset:2048
	ds_read_b128 v[212:215], v151 offset:3072
	global_load_lds_dwordx4 v[216:217], off
	v_lshl_add_u64 v[218:219], s[28:29], 0, v[130:131]
	s_add_i32 m0, s0, 0x2000
	s_nop 0
	global_load_lds_dwordx4 v[218:219], off
	s_waitcnt vmcnt(10)
	s_barrier
	s_waitcnt lgkmcnt(0)
	s_waitcnt lgkmcnt(0)
	v_mfma_f32_16x16x32_bf16 v[114:117], v[200:203], v[168:171], v[114:117]
	v_mfma_f32_16x16x32_bf16 v[106:109], v[208:211], v[168:171], v[106:109]
	v_mfma_f32_16x16x32_bf16 v[98:101], v[200:203], v[176:179], v[98:101]
	v_mfma_f32_16x16x32_bf16 v[90:93], v[208:211], v[176:179], v[90:93]
	v_mfma_f32_16x16x32_bf16 v[82:85], v[200:203], v[184:187], v[82:85]
	v_mfma_f32_16x16x32_bf16 v[74:77], v[208:211], v[184:187], v[74:77]
	v_mfma_f32_16x16x32_bf16 v[70:73], v[200:203], v[192:195], v[70:73]
	v_mfma_f32_16x16x32_bf16 v[66:69], v[208:211], v[192:195], v[66:69]
	v_mfma_f32_16x16x32_bf16 v[114:117], v[204:207], v[172:175], v[114:117]
	v_mfma_f32_16x16x32_bf16 v[106:109], v[212:215], v[172:175], v[106:109]
	v_mfma_f32_16x16x32_bf16 v[98:101], v[204:207], v[180:183], v[98:101]
	v_mfma_f32_16x16x32_bf16 v[90:93], v[212:215], v[180:183], v[90:93]
	v_mfma_f32_16x16x32_bf16 v[82:85], v[204:207], v[188:191], v[82:85]
	v_mfma_f32_16x16x32_bf16 v[74:77], v[212:215], v[188:191], v[74:77]
	v_mfma_f32_16x16x32_bf16 v[70:73], v[204:207], v[196:199], v[70:73]
	v_mfma_f32_16x16x32_bf16 v[66:69], v[212:215], v[196:199], v[66:69]
	s_mov_b32 m0, s10
	v_lshl_add_u64 v[220:221], s[30:31], 0, v[136:137]
	s_barrier
	ds_read_b128 v[168:171], v150 offset:16384
	ds_read_b128 v[172:175], v150 offset:17408
	ds_read_b128 v[176:179], v150 offset:18432
	ds_read_b128 v[180:183], v150 offset:19456
	ds_read_b128 v[184:187], v150 offset:20480
	ds_read_b128 v[188:191], v150 offset:21504
	ds_read_b128 v[192:195], v150 offset:22528
	ds_read_b128 v[196:199], v150 offset:23552
	global_load_lds_dwordx4 v[220:221], off nt
	v_lshl_add_u64 v[222:223], s[30:31], 0, v[132:133]
	s_mov_b32 m0, s11
	s_nop 0
	global_load_lds_dwordx4 v[222:223], off nt
	s_waitcnt vmcnt(10)
	s_barrier
	s_waitcnt lgkmcnt(0)
	s_waitcnt lgkmcnt(0)
	v_mfma_f32_16x16x32_bf16 v[62:65], v[152:155], v[168:171], v[62:65]
	v_mfma_f32_16x16x32_bf16 v[58:61], v[160:163], v[168:171], v[58:61]
	v_mfma_f32_16x16x32_bf16 v[54:57], v[152:155], v[176:179], v[54:57]
	v_mfma_f32_16x16x32_bf16 v[50:53], v[160:163], v[176:179], v[50:53]
	v_mfma_f32_16x16x32_bf16 v[38:41], v[152:155], v[184:187], v[38:41]
	v_mfma_f32_16x16x32_bf16 v[34:37], v[160:163], v[184:187], v[34:37]
	v_mfma_f32_16x16x32_bf16 v[22:25], v[152:155], v[192:195], v[22:25]
	v_mfma_f32_16x16x32_bf16 v[18:21], v[160:163], v[192:195], v[18:21]
	v_mfma_f32_16x16x32_bf16 v[62:65], v[156:159], v[172:175], v[62:65]
	v_mfma_f32_16x16x32_bf16 v[58:61], v[164:167], v[172:175], v[58:61]
	v_mfma_f32_16x16x32_bf16 v[54:57], v[156:159], v[180:183], v[54:57]
	v_mfma_f32_16x16x32_bf16 v[50:53], v[164:167], v[180:183], v[50:53]
	v_mfma_f32_16x16x32_bf16 v[38:41], v[156:159], v[188:191], v[38:41]
	v_mfma_f32_16x16x32_bf16 v[34:37], v[164:167], v[188:191], v[34:37]
	v_mfma_f32_16x16x32_bf16 v[22:25], v[156:159], v[196:199], v[22:25]
	v_mfma_f32_16x16x32_bf16 v[18:21], v[164:167], v[196:199], v[18:21]
	s_barrier
	s_add_u32 s0, s28, 0x40000
	s_addc_u32 s1, s29, 0
	s_add_i32 s50, s43, s9
	v_lshl_add_u64 v[152:153], s[0:1], 0, v[134:135]
	s_mov_b32 m0, s50
	s_nop 0
	global_load_lds_dwordx4 v[152:153], off
	v_lshl_add_u64 v[152:153], s[0:1], 0, v[130:131]
	s_add_i32 m0, s50, 0x2000
	s_nop 0
	global_load_lds_dwordx4 v[152:153], off
	s_waitcnt vmcnt(10)
	s_barrier
	v_mfma_f32_16x16x32_bf16 v[46:49], v[200:203], v[168:171], v[46:49]
	v_mfma_f32_16x16x32_bf16 v[42:45], v[208:211], v[168:171], v[42:45]
	v_mfma_f32_16x16x32_bf16 v[30:33], v[200:203], v[176:179], v[30:33]
	v_mfma_f32_16x16x32_bf16 v[26:29], v[208:211], v[176:179], v[26:29]
	v_mfma_f32_16x16x32_bf16 v[14:17], v[200:203], v[184:187], v[14:17]
	v_mfma_f32_16x16x32_bf16 v[10:13], v[208:211], v[184:187], v[10:13]
	v_mfma_f32_16x16x32_bf16 v[6:9], v[200:203], v[192:195], v[6:9]
	v_mfma_f32_16x16x32_bf16 v[2:5], v[208:211], v[192:195], v[2:5]
	v_mfma_f32_16x16x32_bf16 v[46:49], v[204:207], v[172:175], v[46:49]
	v_mfma_f32_16x16x32_bf16 v[42:45], v[212:215], v[172:175], v[42:45]
	v_mfma_f32_16x16x32_bf16 v[30:33], v[204:207], v[180:183], v[30:33]
	v_mfma_f32_16x16x32_bf16 v[26:29], v[212:215], v[180:183], v[26:29]
	v_mfma_f32_16x16x32_bf16 v[14:17], v[204:207], v[188:191], v[14:17]
	v_mfma_f32_16x16x32_bf16 v[10:13], v[212:215], v[188:191], v[10:13]
	v_mfma_f32_16x16x32_bf16 v[6:9], v[204:207], v[196:199], v[6:9]
	v_mfma_f32_16x16x32_bf16 v[2:5], v[212:215], v[196:199], v[2:5]
	s_add_i32 s50, 0, 0x18000
	v_add_u32_e32 v164, s50, v148
	s_barrier
	ds_read_b128 v[152:155], v164
	ds_read_b128 v[156:159], v164 offset:1024
	ds_read_b128 v[160:163], v164 offset:2048
	ds_read_b128 v[164:167], v164 offset:3072
	s_add_u32 s0, s30, 0x40000
	s_addc_u32 s1, s31, 0
	s_mov_b32 m0, s17
	v_lshl_add_u64 v[200:201], s[0:1], 0, v[136:137]
	ds_read_b128 v[168:171], v150 offset:32768
	ds_read_b128 v[172:175], v150 offset:33792
	ds_read_b128 v[176:179], v150 offset:34816
	ds_read_b128 v[180:183], v150 offset:35840
	ds_read_b128 v[184:187], v150 offset:36864
	ds_read_b128 v[188:191], v150 offset:37888
	ds_read_b128 v[192:195], v150 offset:38912
	ds_read_b128 v[196:199], v150 offset:39936
	global_load_lds_dwordx4 v[200:201], off nt
	v_lshl_add_u64 v[200:201], s[0:1], 0, v[132:133]
	s_mov_b32 m0, s34
	s_nop 0
	global_load_lds_dwordx4 v[200:201], off nt
	s_waitcnt lgkmcnt(8)
	s_waitcnt vmcnt(10)
	s_barrier
	s_waitcnt lgkmcnt(0)
	s_waitcnt lgkmcnt(0)
	v_mfma_f32_16x16x32_bf16 v[126:129], v[152:155], v[168:171], v[126:129]
	v_mfma_f32_16x16x32_bf16 v[122:125], v[160:163], v[168:171], v[122:125]
	v_mfma_f32_16x16x32_bf16 v[118:121], v[152:155], v[176:179], v[118:121]
	v_mfma_f32_16x16x32_bf16 v[110:113], v[160:163], v[176:179], v[110:113]
	v_mfma_f32_16x16x32_bf16 v[102:105], v[152:155], v[184:187], v[102:105]
	v_mfma_f32_16x16x32_bf16 v[94:97], v[160:163], v[184:187], v[94:97]
	v_mfma_f32_16x16x32_bf16 v[86:89], v[152:155], v[192:195], v[86:89]
	v_mfma_f32_16x16x32_bf16 v[78:81], v[160:163], v[192:195], v[78:81]
	v_mfma_f32_16x16x32_bf16 v[126:129], v[156:159], v[172:175], v[126:129]
	v_mfma_f32_16x16x32_bf16 v[122:125], v[164:167], v[172:175], v[122:125]
	v_mfma_f32_16x16x32_bf16 v[118:121], v[156:159], v[180:183], v[118:121]
	v_mfma_f32_16x16x32_bf16 v[110:113], v[164:167], v[180:183], v[110:113]
	v_mfma_f32_16x16x32_bf16 v[102:105], v[156:159], v[188:191], v[102:105]
	v_mfma_f32_16x16x32_bf16 v[94:97], v[164:167], v[188:191], v[94:97]
	v_mfma_f32_16x16x32_bf16 v[86:89], v[156:159], v[196:199], v[86:89]
	v_mfma_f32_16x16x32_bf16 v[78:81], v[164:167], v[196:199], v[78:81]
	s_barrier
	s_add_i32 s30, 0, 0x1c000
	s_add_i32 s0, s50, s9
	v_add_u32_e32 v212, s30, v148
	v_lshl_add_u64 v[216:217], v[216:217], 0, s[14:15]
	s_mov_b32 m0, s0
	ds_read_b128 v[200:203], v212
	ds_read_b128 v[204:207], v212 offset:1024
	ds_read_b128 v[208:211], v212 offset:2048
	ds_read_b128 v[212:215], v212 offset:3072
	global_load_lds_dwordx4 v[216:217], off
	v_lshl_add_u64 v[216:217], v[218:219], 0, s[14:15]
	s_add_i32 m0, s0, 0x2000
	s_nop 0
	global_load_lds_dwordx4 v[216:217], off
	s_waitcnt vmcnt(10)
	s_barrier
	s_waitcnt lgkmcnt(0)
	s_waitcnt lgkmcnt(0)
	v_mfma_f32_16x16x32_bf16 v[114:117], v[200:203], v[168:171], v[114:117]
	v_mfma_f32_16x16x32_bf16 v[106:109], v[208:211], v[168:171], v[106:109]
	v_mfma_f32_16x16x32_bf16 v[98:101], v[200:203], v[176:179], v[98:101]
	v_mfma_f32_16x16x32_bf16 v[90:93], v[208:211], v[176:179], v[90:93]
	v_mfma_f32_16x16x32_bf16 v[82:85], v[200:203], v[184:187], v[82:85]
	v_mfma_f32_16x16x32_bf16 v[74:77], v[208:211], v[184:187], v[74:77]
	v_mfma_f32_16x16x32_bf16 v[70:73], v[200:203], v[192:195], v[70:73]
	v_mfma_f32_16x16x32_bf16 v[66:69], v[208:211], v[192:195], v[66:69]
	v_mfma_f32_16x16x32_bf16 v[114:117], v[204:207], v[172:175], v[114:117]
	v_mfma_f32_16x16x32_bf16 v[106:109], v[212:215], v[172:175], v[106:109]
	v_mfma_f32_16x16x32_bf16 v[98:101], v[204:207], v[180:183], v[98:101]
	v_mfma_f32_16x16x32_bf16 v[90:93], v[212:215], v[180:183], v[90:93]
	v_mfma_f32_16x16x32_bf16 v[82:85], v[204:207], v[188:191], v[82:85]
	v_mfma_f32_16x16x32_bf16 v[74:77], v[212:215], v[188:191], v[74:77]
	v_mfma_f32_16x16x32_bf16 v[70:73], v[204:207], v[196:199], v[70:73]
	v_mfma_f32_16x16x32_bf16 v[66:69], v[212:215], v[196:199], v[66:69]
	s_mov_b32 m0, s40
	v_lshl_add_u64 v[216:217], v[220:221], 0, s[14:15]
	s_barrier
	ds_read_b128 v[168:171], v150 offset:49152
	ds_read_b128 v[172:175], v150 offset:50176
	ds_read_b128 v[176:179], v150 offset:51200
	ds_read_b128 v[180:183], v150 offset:52224
	ds_read_b128 v[184:187], v150 offset:53248
	ds_read_b128 v[188:191], v150 offset:54272
	ds_read_b128 v[192:195], v150 offset:55296
	ds_read_b128 v[196:199], v150 offset:56320
	global_load_lds_dwordx4 v[216:217], off nt
	v_lshl_add_u64 v[216:217], v[222:223], 0, s[14:15]
	s_mov_b32 m0, s41
	s_nop 0
	global_load_lds_dwordx4 v[216:217], off nt
	s_waitcnt vmcnt(10)
	s_barrier
	s_waitcnt lgkmcnt(0)
	s_waitcnt lgkmcnt(0)
	v_mfma_f32_16x16x32_bf16 v[62:65], v[152:155], v[168:171], v[62:65]
	v_mfma_f32_16x16x32_bf16 v[58:61], v[160:163], v[168:171], v[58:61]
	v_mfma_f32_16x16x32_bf16 v[54:57], v[152:155], v[176:179], v[54:57]
	v_mfma_f32_16x16x32_bf16 v[50:53], v[160:163], v[176:179], v[50:53]
	v_mfma_f32_16x16x32_bf16 v[38:41], v[152:155], v[184:187], v[38:41]
	v_mfma_f32_16x16x32_bf16 v[34:37], v[160:163], v[184:187], v[34:37]
	v_mfma_f32_16x16x32_bf16 v[22:25], v[152:155], v[192:195], v[22:25]
	v_mfma_f32_16x16x32_bf16 v[18:21], v[160:163], v[192:195], v[18:21]
	v_mfma_f32_16x16x32_bf16 v[62:65], v[156:159], v[172:175], v[62:65]
	v_mfma_f32_16x16x32_bf16 v[58:61], v[164:167], v[172:175], v[58:61]
	v_mfma_f32_16x16x32_bf16 v[54:57], v[156:159], v[180:183], v[54:57]
	v_mfma_f32_16x16x32_bf16 v[50:53], v[164:167], v[180:183], v[50:53]
	v_mfma_f32_16x16x32_bf16 v[38:41], v[156:159], v[188:191], v[38:41]
	v_mfma_f32_16x16x32_bf16 v[34:37], v[164:167], v[188:191], v[34:37]
	v_mfma_f32_16x16x32_bf16 v[22:25], v[156:159], v[196:199], v[22:25]
	v_mfma_f32_16x16x32_bf16 v[18:21], v[164:167], v[196:199], v[18:21]
	s_barrier
	s_add_u32 s0, s28, 0x40080
	s_addc_u32 s1, s29, 0
	s_add_i32 s28, s30, s9
	v_lshl_add_u64 v[152:153], s[0:1], 0, v[134:135]
	s_mov_b32 m0, s28
	s_nop 0
	global_load_lds_dwordx4 v[152:153], off
	v_lshl_add_u64 v[152:153], s[0:1], 0, v[130:131]
	s_add_i32 m0, s28, 0x2000
	s_nop 0
	global_load_lds_dwordx4 v[152:153], off
	s_waitcnt vmcnt(10)
	s_barrier
	v_mfma_f32_16x16x32_bf16 v[46:49], v[200:203], v[168:171], v[46:49]
	v_mfma_f32_16x16x32_bf16 v[42:45], v[208:211], v[168:171], v[42:45]
	v_mfma_f32_16x16x32_bf16 v[30:33], v[200:203], v[176:179], v[30:33]
	v_mfma_f32_16x16x32_bf16 v[26:29], v[208:211], v[176:179], v[26:29]
	v_mfma_f32_16x16x32_bf16 v[14:17], v[200:203], v[184:187], v[14:17]
	v_mfma_f32_16x16x32_bf16 v[10:13], v[208:211], v[184:187], v[10:13]
	v_mfma_f32_16x16x32_bf16 v[6:9], v[200:203], v[192:195], v[6:9]
	v_mfma_f32_16x16x32_bf16 v[2:5], v[208:211], v[192:195], v[2:5]
	v_mfma_f32_16x16x32_bf16 v[46:49], v[204:207], v[172:175], v[46:49]
	v_mfma_f32_16x16x32_bf16 v[42:45], v[212:215], v[172:175], v[42:45]
	v_mfma_f32_16x16x32_bf16 v[30:33], v[204:207], v[180:183], v[30:33]
	v_mfma_f32_16x16x32_bf16 v[26:29], v[212:215], v[180:183], v[26:29]
	v_mfma_f32_16x16x32_bf16 v[14:17], v[204:207], v[188:191], v[14:17]
	v_mfma_f32_16x16x32_bf16 v[10:13], v[212:215], v[188:191], v[10:13]
	v_mfma_f32_16x16x32_bf16 v[6:9], v[204:207], v[196:199], v[6:9]
	v_mfma_f32_16x16x32_bf16 v[2:5], v[212:215], v[196:199], v[2:5]
	s_add_i32 s49, s49, 2
	s_add_u32 s47, s47, 0x100
	s_addc_u32 s48, s48, 0
	s_add_u32 s26, s26, 0x100
	s_addc_u32 s27, s27, 0
	s_cmp_gt_u32 s49, 13
	s_barrier
	s_cbranch_scc0 .LBB0_1513
	v_mov_b32_e32 v152, v146
	v_mov_b32_e32 v153, v147
	s_cmp_gt_i32 s44, 7
	s_cbranch_scc1 .LBB0_1505
	s_ashr_i32 s0, s44, 31
	s_lshr_b32 s0, s0, 30
	s_add_i32 s0, s44, s0
	s_ashr_i32 s0, s0, 2
	s_ashr_i32 s1, s0, 31
	s_lshl_b32 s19, s44, 8
	s_lshl_b64 s[26:27], s[0:1], 27
	s_add_u32 s26, s36, s26
	s_addc_u32 s27, s37, s27
	s_or_b32 s1, s19, s39
	s_lshl_b32 s0, s0, 10
	s_sub_i32 s0, s1, s0
	v_lshl_add_u32 v154, v153, 3, s0
	s_lshl_b32 s0, s16, 8
	s_add_i32 s0, s0, s38
	v_add_u32_e32 v156, s0, v152
	v_mov_b32_e32 v152, v156
	v_ashrrev_i32_e32 v155, 31, v154
	v_lshl_add_u64 v[154:155], v[154:155], 1, s[26:27]
	v_ashrrev_i32_e32 v153, 31, v152
	v_lshlrev_b64 v[152:153], 11, v[152:153]
	v_lshl_add_u64 v[152:153], v[154:155], 0, v[152:153]
	v_cvt_pk_bf16_f32 v126, v126, v127
	v_cvt_pk_bf16_f32 v127, v128, v129
	v_cvt_pk_bf16_f32 v128, v122, v123
	v_cvt_pk_bf16_f32 v129, v124, v125
	v_cvt_pk_bf16_f32 v114, v114, v115
	v_cvt_pk_bf16_f32 v115, v116, v117
	v_cvt_pk_bf16_f32 v116, v106, v107
	v_cvt_pk_bf16_f32 v117, v108, v109
	v_add_u32_e32 v106, 16, v156
	global_store_dwordx4 v[152:153], v[126:129], off
	global_store_dwordx4 v[152:153], v[114:117], off offset:256
	v_cvt_pk_bf16_f32 v108, v110, v111
	v_ashrrev_i32_e32 v107, 31, v106
	v_lshlrev_b64 v[106:107], 11, v[106:107]
	v_lshl_add_u64 v[114:115], v[154:155], 0, v[106:107]
	v_cvt_pk_bf16_f32 v106, v118, v119
	v_cvt_pk_bf16_f32 v107, v120, v121
	v_cvt_pk_bf16_f32 v109, v112, v113
	v_cvt_pk_bf16_f32 v98, v98, v99
	v_cvt_pk_bf16_f32 v99, v100, v101
	v_cvt_pk_bf16_f32 v100, v90, v91
	v_cvt_pk_bf16_f32 v101, v92, v93
	v_add_u32_e32 v90, 32, v156
	global_store_dwordx4 v[114:115], v[106:109], off
	global_store_dwordx4 v[114:115], v[98:101], off offset:256
	v_cvt_pk_bf16_f32 v92, v94, v95
	v_ashrrev_i32_e32 v91, 31, v90
	v_lshlrev_b64 v[90:91], 11, v[90:91]
	v_lshl_add_u64 v[98:99], v[154:155], 0, v[90:91]
	v_cvt_pk_bf16_f32 v90, v102, v103
	v_cvt_pk_bf16_f32 v91, v104, v105
	v_cvt_pk_bf16_f32 v93, v96, v97
	v_cvt_pk_bf16_f32 v82, v82, v83
	v_cvt_pk_bf16_f32 v83, v84, v85
	v_cvt_pk_bf16_f32 v84, v74, v75
	v_cvt_pk_bf16_f32 v85, v76, v77
	v_add_u32_e32 v74, 48, v156
	global_store_dwordx4 v[98:99], v[90:93], off
	global_store_dwordx4 v[98:99], v[82:85], off offset:256
	v_cvt_pk_bf16_f32 v76, v78, v79
	v_ashrrev_i32_e32 v75, 31, v74
	v_lshlrev_b64 v[74:75], 11, v[74:75]
	v_lshl_add_u64 v[82:83], v[154:155], 0, v[74:75]
	v_cvt_pk_bf16_f32 v74, v86, v87
	v_cvt_pk_bf16_f32 v75, v88, v89
	v_cvt_pk_bf16_f32 v77, v80, v81
	v_cvt_pk_bf16_f32 v70, v70, v71
	v_cvt_pk_bf16_f32 v71, v72, v73
	v_cvt_pk_bf16_f32 v72, v66, v67
	v_cvt_pk_bf16_f32 v73, v68, v69
	v_add_u32_e32 v66, 0x80, v156
	global_store_dwordx4 v[82:83], v[74:77], off
	global_store_dwordx4 v[82:83], v[70:73], off offset:256
	v_cvt_pk_bf16_f32 v62, v62, v63
	v_ashrrev_i32_e32 v67, 31, v66
	v_lshlrev_b64 v[66:67], 11, v[66:67]
	v_lshl_add_u64 v[66:67], v[154:155], 0, v[66:67]
	v_cvt_pk_bf16_f32 v63, v64, v65
	v_cvt_pk_bf16_f32 v64, v58, v59
	v_cvt_pk_bf16_f32 v65, v60, v61
	v_cvt_pk_bf16_f32 v46, v46, v47
	v_cvt_pk_bf16_f32 v47, v48, v49
	v_cvt_pk_bf16_f32 v48, v42, v43
	v_cvt_pk_bf16_f32 v49, v44, v45
	v_add_u32_e32 v42, 0x90, v156
	global_store_dwordx4 v[66:67], v[62:65], off
	global_store_dwordx4 v[66:67], v[46:49], off offset:256
	v_cvt_pk_bf16_f32 v44, v50, v51
	v_ashrrev_i32_e32 v43, 31, v42
	v_lshlrev_b64 v[42:43], 11, v[42:43]
	v_lshl_add_u64 v[46:47], v[154:155], 0, v[42:43]
	v_cvt_pk_bf16_f32 v42, v54, v55
	v_cvt_pk_bf16_f32 v43, v56, v57
	v_cvt_pk_bf16_f32 v45, v52, v53
	v_cvt_pk_bf16_f32 v30, v30, v31
	v_cvt_pk_bf16_f32 v31, v32, v33
	v_cvt_pk_bf16_f32 v32, v26, v27
	v_cvt_pk_bf16_f32 v33, v28, v29
	v_add_u32_e32 v26, 0xa0, v156
	global_store_dwordx4 v[46:47], v[42:45], off
	global_store_dwordx4 v[46:47], v[30:33], off offset:256
	v_cvt_pk_bf16_f32 v28, v34, v35
	v_ashrrev_i32_e32 v27, 31, v26
	v_lshlrev_b64 v[26:27], 11, v[26:27]
	v_lshl_add_u64 v[30:31], v[154:155], 0, v[26:27]
	v_cvt_pk_bf16_f32 v26, v38, v39
	v_cvt_pk_bf16_f32 v27, v40, v41
	v_cvt_pk_bf16_f32 v29, v36, v37
	v_cvt_pk_bf16_f32 v14, v14, v15
	v_cvt_pk_bf16_f32 v15, v16, v17
	v_cvt_pk_bf16_f32 v16, v10, v11
	v_cvt_pk_bf16_f32 v17, v12, v13
	v_add_u32_e32 v10, 0xb0, v156
	global_store_dwordx4 v[30:31], v[26:29], off
	global_store_dwordx4 v[30:31], v[14:17], off offset:256
	v_cvt_pk_bf16_f32 v12, v18, v19
	v_ashrrev_i32_e32 v11, 31, v10
	v_lshlrev_b64 v[10:11], 11, v[10:11]
	v_lshl_add_u64 v[14:15], v[154:155], 0, v[10:11]
	v_cvt_pk_bf16_f32 v10, v22, v23
	v_cvt_pk_bf16_f32 v11, v24, v25
	v_cvt_pk_bf16_f32 v13, v20, v21
	v_cvt_pk_bf16_f32 v6, v6, v7
	v_cvt_pk_bf16_f32 v7, v8, v9
	v_cvt_pk_bf16_f32 v8, v2, v3
	v_cvt_pk_bf16_f32 v9, v4, v5
	global_store_dwordx4 v[14:15], v[10:13], off
	global_store_dwordx4 v[14:15], v[6:9], off offset:256
	s_branch .LBB0_1505

.LBB0_1645:
	s_add_u32 s57, s48, s56
	s_addc_u32 s58, s49, 0
	s_add_u32 s59, s57, 0x100
	s_addc_u32 s60, s58, 0
	s_and_b64 s[0:1], s[54:55], exec
	s_cselect_b32 s61, s43, s60
	s_cselect_b32 s60, s83, s59
	s_add_u32 s0, s14, s56
	s_addc_u32 s1, s15, 0
	s_add_u32 s56, s0, 0x100
	s_addc_u32 s59, s1, 0
	s_and_b64 s[0:1], s[54:55], exec
	s_cselect_b32 s63, s41, s59
	s_cselect_b32 s62, s94, s56
	s_add_u32 s64, s57, 0x40080
	s_addc_u32 s65, s58, 0
	s_add_i32 s0, s85, s37
	s_add_i32 m0, s39, 0xc000
	s_add_i32 s71, s39, 0xe000
	s_add_i32 s70, s0, 0x2000
	s_add_u32 s58, s62, 0x10000
	s_addc_u32 s59, s63, 0
	s_add_i32 s1, s4, s37
	ds_read_b128 v[26:29], v225
	ds_read_b128 v[30:33], v225 offset:1024
	ds_read_b128 v[42:45], v225 offset:2048
	ds_read_b128 v[46:49], v225 offset:3072
	s_add_i32 s96, s1, 0x2000
	s_add_i32 s81, 0, 0x18000
	s_add_u32 s56, s60, 0x40000
	s_addc_u32 s57, s61, 0
	s_add_i32 s78, s81, s37
	s_add_i32 s79, 0, 0x1c000
	s_add_i32 s80, s78, 0x2000
	s_add_u32 s54, s62, 0x10080
	s_addc_u32 s55, s63, 0
	s_add_i32 vcc_hi, s79, s37
	s_add_i32 vcc_lo, vcc_hi, 0x2000
	v_lshl_add_u64 v[190:191], s[64:65], 0, v[160:161]
	ds_read_b128 v[146:149], v226
	ds_read_b128 v[150:153], v226 offset:1024
	ds_read_b128 v[166:169], v226 offset:2048
	ds_read_b128 v[170:173], v226 offset:3072
	ds_read_b128 v[174:177], v226 offset:4096
	ds_read_b128 v[178:181], v226 offset:5120
	ds_read_b128 v[182:185], v226 offset:6144
	ds_read_b128 v[186:189], v226 offset:7168
	global_load_lds_dwordx4 v[190:191], off nt
	v_lshl_add_u64 v[190:191], s[64:65], 0, v[156:157]
	s_mov_b32 m0, s71
	s_nop 0
	global_load_lds_dwordx4 v[190:191], off nt
	s_waitcnt lgkmcnt(8)
	s_waitcnt vmcnt(10)
	s_barrier
	s_waitcnt lgkmcnt(0)
	s_waitcnt lgkmcnt(0)
	v_mfma_f32_16x16x32_bf16 v[142:145], v[26:29], v[146:149], v[142:145]
	v_mfma_f32_16x16x32_bf16 v[134:137], v[42:45], v[146:149], v[134:137]
	v_mfma_f32_16x16x32_bf16 v[126:129], v[26:29], v[166:169], v[126:129]
	v_mfma_f32_16x16x32_bf16 v[118:121], v[42:45], v[166:169], v[118:121]
	v_mfma_f32_16x16x32_bf16 v[110:113], v[26:29], v[174:177], v[110:113]
	v_mfma_f32_16x16x32_bf16 v[102:105], v[42:45], v[174:177], v[102:105]
	v_mfma_f32_16x16x32_bf16 v[94:97], v[26:29], v[182:185], v[94:97]
	v_mfma_f32_16x16x32_bf16 v[86:89], v[42:45], v[182:185], v[86:89]
	v_mfma_f32_16x16x32_bf16 v[142:145], v[30:33], v[150:153], v[142:145]
	v_mfma_f32_16x16x32_bf16 v[134:137], v[46:49], v[150:153], v[134:137]
	v_mfma_f32_16x16x32_bf16 v[126:129], v[30:33], v[170:173], v[126:129]
	v_mfma_f32_16x16x32_bf16 v[118:121], v[46:49], v[170:173], v[118:121]
	v_mfma_f32_16x16x32_bf16 v[110:113], v[30:33], v[178:181], v[110:113]
	v_mfma_f32_16x16x32_bf16 v[102:105], v[46:49], v[178:181], v[102:105]
	v_mfma_f32_16x16x32_bf16 v[94:97], v[30:33], v[186:189], v[94:97]
	v_mfma_f32_16x16x32_bf16 v[86:89], v[46:49], v[186:189], v[86:89]
	s_barrier
	s_mov_b32 m0, s0
	v_lshl_add_u64 v[206:207], s[62:63], 0, v[158:159]
	ds_read_b128 v[190:193], v227
	ds_read_b128 v[194:197], v227 offset:1024
	ds_read_b128 v[198:201], v227 offset:2048
	ds_read_b128 v[202:205], v227 offset:3072
	global_load_lds_dwordx4 v[206:207], off
	v_lshl_add_u64 v[208:209], s[62:63], 0, v[154:155]
	s_mov_b32 m0, s70
	s_nop 0
	global_load_lds_dwordx4 v[208:209], off
	s_waitcnt vmcnt(10)
	s_barrier
	s_waitcnt lgkmcnt(0)
	s_waitcnt lgkmcnt(0)
	v_mfma_f32_16x16x32_bf16 v[138:141], v[190:193], v[146:149], v[138:141]
	v_mfma_f32_16x16x32_bf16 v[130:133], v[198:201], v[146:149], v[130:133]
	v_mfma_f32_16x16x32_bf16 v[122:125], v[190:193], v[166:169], v[122:125]
	v_mfma_f32_16x16x32_bf16 v[114:117], v[198:201], v[166:169], v[114:117]
	v_mfma_f32_16x16x32_bf16 v[106:109], v[190:193], v[174:177], v[106:109]
	v_mfma_f32_16x16x32_bf16 v[98:101], v[198:201], v[174:177], v[98:101]
	v_mfma_f32_16x16x32_bf16 v[90:93], v[190:193], v[182:185], v[90:93]
	v_mfma_f32_16x16x32_bf16 v[82:85], v[198:201], v[182:185], v[82:85]
	v_mfma_f32_16x16x32_bf16 v[138:141], v[194:197], v[150:153], v[138:141]
	v_mfma_f32_16x16x32_bf16 v[130:133], v[202:205], v[150:153], v[130:133]
	v_mfma_f32_16x16x32_bf16 v[122:125], v[194:197], v[170:173], v[122:125]
	v_mfma_f32_16x16x32_bf16 v[114:117], v[202:205], v[170:173], v[114:117]
	v_mfma_f32_16x16x32_bf16 v[106:109], v[194:197], v[178:181], v[106:109]
	v_mfma_f32_16x16x32_bf16 v[98:101], v[202:205], v[178:181], v[98:101]
	v_mfma_f32_16x16x32_bf16 v[90:93], v[194:197], v[186:189], v[90:93]
	v_mfma_f32_16x16x32_bf16 v[82:85], v[202:205], v[186:189], v[82:85]
	s_mov_b32 m0, s39
	v_lshl_add_u64 v[210:211], s[60:61], 0, v[160:161]
	s_barrier
	ds_read_b128 v[146:149], v226 offset:16384
	ds_read_b128 v[150:153], v226 offset:17408
	ds_read_b128 v[166:169], v226 offset:18432
	ds_read_b128 v[170:173], v226 offset:19456
	ds_read_b128 v[174:177], v226 offset:20480
	ds_read_b128 v[178:181], v226 offset:21504
	ds_read_b128 v[182:185], v226 offset:22528
	ds_read_b128 v[186:189], v226 offset:23552
	global_load_lds_dwordx4 v[210:211], off nt
	v_lshl_add_u64 v[212:213], s[60:61], 0, v[156:157]
	s_mov_b32 m0, s53
	s_nop 0
	global_load_lds_dwordx4 v[212:213], off nt
	s_waitcnt vmcnt(10)
	s_barrier
	s_waitcnt lgkmcnt(0)
	s_waitcnt lgkmcnt(0)
	v_mfma_f32_16x16x32_bf16 v[78:81], v[26:29], v[146:149], v[78:81]
	v_mfma_f32_16x16x32_bf16 v[70:73], v[42:45], v[146:149], v[70:73]
	v_mfma_f32_16x16x32_bf16 v[62:65], v[26:29], v[166:169], v[62:65]
	v_mfma_f32_16x16x32_bf16 v[54:57], v[42:45], v[166:169], v[54:57]
	v_mfma_f32_16x16x32_bf16 v[38:41], v[26:29], v[174:177], v[38:41]
	v_mfma_f32_16x16x32_bf16 v[22:25], v[42:45], v[174:177], v[22:25]
	v_mfma_f32_16x16x32_bf16 v[14:17], v[26:29], v[182:185], v[14:17]
	v_mfma_f32_16x16x32_bf16 v[6:9], v[42:45], v[182:185], v[6:9]
	v_mfma_f32_16x16x32_bf16 v[78:81], v[30:33], v[150:153], v[78:81]
	v_mfma_f32_16x16x32_bf16 v[70:73], v[46:49], v[150:153], v[70:73]
	v_mfma_f32_16x16x32_bf16 v[62:65], v[30:33], v[170:173], v[62:65]
	v_mfma_f32_16x16x32_bf16 v[54:57], v[46:49], v[170:173], v[54:57]
	v_mfma_f32_16x16x32_bf16 v[38:41], v[30:33], v[178:181], v[38:41]
	v_mfma_f32_16x16x32_bf16 v[22:25], v[46:49], v[178:181], v[22:25]
	v_mfma_f32_16x16x32_bf16 v[14:17], v[30:33], v[186:189], v[14:17]
	v_mfma_f32_16x16x32_bf16 v[6:9], v[46:49], v[186:189], v[6:9]
	s_barrier
	s_mov_b32 m0, s1
	v_lshl_add_u64 v[26:27], s[58:59], 0, v[158:159]
	global_load_lds_dwordx4 v[26:27], off
	v_lshl_add_u64 v[26:27], s[58:59], 0, v[154:155]
	s_mov_b32 m0, s96
	s_nop 0
	global_load_lds_dwordx4 v[26:27], off
	s_waitcnt vmcnt(10)
	s_barrier
	v_mfma_f32_16x16x32_bf16 v[34:37], v[190:193], v[174:177], v[34:37]
	v_mfma_f32_16x16x32_bf16 v[18:21], v[198:201], v[174:177], v[18:21]
	v_mfma_f32_16x16x32_bf16 v[10:13], v[190:193], v[182:185], v[10:13]
	v_mfma_f32_16x16x32_bf16 v[2:5], v[198:201], v[182:185], v[2:5]
	v_mfma_f32_16x16x32_bf16 v[26:29], v[190:193], v[146:149], v[74:77]
	v_mfma_f32_16x16x32_bf16 v[30:33], v[198:201], v[146:149], v[66:69]
	v_mfma_f32_16x16x32_bf16 v[42:45], v[190:193], v[166:169], v[58:61]
	v_mfma_f32_16x16x32_bf16 v[46:49], v[198:201], v[166:169], v[50:53]
	v_mfma_f32_16x16x32_bf16 v[34:37], v[194:197], v[178:181], v[34:37]
	v_mfma_f32_16x16x32_bf16 v[18:21], v[202:205], v[178:181], v[18:21]
	v_mfma_f32_16x16x32_bf16 v[10:13], v[194:197], v[186:189], v[10:13]
	v_mfma_f32_16x16x32_bf16 v[2:5], v[202:205], v[186:189], v[2:5]
	v_mfma_f32_16x16x32_bf16 v[26:29], v[194:197], v[150:153], v[26:29]
	v_mfma_f32_16x16x32_bf16 v[30:33], v[202:205], v[150:153], v[30:33]
	v_mfma_f32_16x16x32_bf16 v[42:45], v[194:197], v[170:173], v[42:45]
	v_mfma_f32_16x16x32_bf16 v[46:49], v[202:205], v[170:173], v[46:49]
	v_add_u32_e32 v74, s81, v224
	s_barrier
	ds_read_b128 v[50:53], v74
	ds_read_b128 v[58:61], v74 offset:1024
	ds_read_b128 v[66:69], v74 offset:2048
	ds_read_b128 v[74:77], v74 offset:3072
	s_mov_b32 m0, s66
	v_lshl_add_u64 v[190:191], s[56:57], 0, v[160:161]
	ds_read_b128 v[146:149], v226 offset:32768
	ds_read_b128 v[150:153], v226 offset:33792
	ds_read_b128 v[166:169], v226 offset:34816
	ds_read_b128 v[170:173], v226 offset:35840
	ds_read_b128 v[174:177], v226 offset:36864
	ds_read_b128 v[178:181], v226 offset:37888
	ds_read_b128 v[182:185], v226 offset:38912
	ds_read_b128 v[186:189], v226 offset:39936
	global_load_lds_dwordx4 v[190:191], off nt
	v_lshl_add_u64 v[190:191], s[56:57], 0, v[156:157]
	s_mov_b32 m0, s67
	s_nop 0
	global_load_lds_dwordx4 v[190:191], off nt
	s_waitcnt lgkmcnt(8)
	s_waitcnt vmcnt(10)
	s_barrier
	s_waitcnt lgkmcnt(0)
	s_waitcnt lgkmcnt(0)
	v_mfma_f32_16x16x32_bf16 v[142:145], v[50:53], v[146:149], v[142:145]
	v_mfma_f32_16x16x32_bf16 v[134:137], v[66:69], v[146:149], v[134:137]
	v_mfma_f32_16x16x32_bf16 v[126:129], v[50:53], v[166:169], v[126:129]
	v_mfma_f32_16x16x32_bf16 v[118:121], v[66:69], v[166:169], v[118:121]
	v_mfma_f32_16x16x32_bf16 v[110:113], v[50:53], v[174:177], v[110:113]
	v_mfma_f32_16x16x32_bf16 v[102:105], v[66:69], v[174:177], v[102:105]
	v_mfma_f32_16x16x32_bf16 v[94:97], v[50:53], v[182:185], v[94:97]
	v_mfma_f32_16x16x32_bf16 v[86:89], v[66:69], v[182:185], v[86:89]
	v_mfma_f32_16x16x32_bf16 v[142:145], v[58:61], v[150:153], v[142:145]
	v_mfma_f32_16x16x32_bf16 v[134:137], v[74:77], v[150:153], v[134:137]
	v_mfma_f32_16x16x32_bf16 v[126:129], v[58:61], v[170:173], v[126:129]
	v_mfma_f32_16x16x32_bf16 v[118:121], v[74:77], v[170:173], v[118:121]
	v_mfma_f32_16x16x32_bf16 v[110:113], v[58:61], v[178:181], v[110:113]
	v_mfma_f32_16x16x32_bf16 v[102:105], v[74:77], v[178:181], v[102:105]
	v_mfma_f32_16x16x32_bf16 v[94:97], v[58:61], v[186:189], v[94:97]
	v_mfma_f32_16x16x32_bf16 v[86:89], v[74:77], v[186:189], v[86:89]
	s_barrier
	s_mov_b32 m0, s78
	v_add_u32_e32 v202, s79, v224
	v_lshl_add_u64 v[206:207], v[206:207], 0, s[26:27]
	ds_read_b128 v[190:193], v202
	ds_read_b128 v[194:197], v202 offset:1024
	ds_read_b128 v[198:201], v202 offset:2048
	ds_read_b128 v[202:205], v202 offset:3072
	global_load_lds_dwordx4 v[206:207], off
	v_lshl_add_u64 v[206:207], v[208:209], 0, s[26:27]
	s_mov_b32 m0, s80
	s_nop 0
	global_load_lds_dwordx4 v[206:207], off
	s_waitcnt vmcnt(10)
	s_barrier
	s_waitcnt lgkmcnt(0)
	s_waitcnt lgkmcnt(0)
	v_mfma_f32_16x16x32_bf16 v[138:141], v[190:193], v[146:149], v[138:141]
	v_mfma_f32_16x16x32_bf16 v[130:133], v[198:201], v[146:149], v[130:133]
	v_mfma_f32_16x16x32_bf16 v[122:125], v[190:193], v[166:169], v[122:125]
	v_mfma_f32_16x16x32_bf16 v[114:117], v[198:201], v[166:169], v[114:117]
	v_mfma_f32_16x16x32_bf16 v[106:109], v[190:193], v[174:177], v[106:109]
	v_mfma_f32_16x16x32_bf16 v[98:101], v[198:201], v[174:177], v[98:101]
	v_mfma_f32_16x16x32_bf16 v[90:93], v[190:193], v[182:185], v[90:93]
	v_mfma_f32_16x16x32_bf16 v[82:85], v[198:201], v[182:185], v[82:85]
	v_mfma_f32_16x16x32_bf16 v[138:141], v[194:197], v[150:153], v[138:141]
	v_mfma_f32_16x16x32_bf16 v[130:133], v[202:205], v[150:153], v[130:133]
	v_mfma_f32_16x16x32_bf16 v[122:125], v[194:197], v[170:173], v[122:125]
	v_mfma_f32_16x16x32_bf16 v[114:117], v[202:205], v[170:173], v[114:117]
	v_mfma_f32_16x16x32_bf16 v[106:109], v[194:197], v[178:181], v[106:109]
	v_mfma_f32_16x16x32_bf16 v[98:101], v[202:205], v[178:181], v[98:101]
	v_mfma_f32_16x16x32_bf16 v[90:93], v[194:197], v[186:189], v[90:93]
	v_mfma_f32_16x16x32_bf16 v[82:85], v[202:205], v[186:189], v[82:85]
	s_mov_b32 m0, s6
	v_lshl_add_u64 v[206:207], v[210:211], 0, s[26:27]
	s_barrier
	ds_read_b128 v[146:149], v226 offset:49152
	ds_read_b128 v[150:153], v226 offset:50176
	ds_read_b128 v[166:169], v226 offset:51200
	ds_read_b128 v[170:173], v226 offset:52224
	ds_read_b128 v[174:177], v226 offset:53248
	ds_read_b128 v[178:181], v226 offset:54272
	ds_read_b128 v[182:185], v226 offset:55296
	ds_read_b128 v[186:189], v226 offset:56320
	global_load_lds_dwordx4 v[206:207], off nt
	v_lshl_add_u64 v[206:207], v[212:213], 0, s[26:27]
	s_mov_b32 m0, s7
	s_nop 0
	global_load_lds_dwordx4 v[206:207], off nt
	s_waitcnt vmcnt(10)
	s_barrier
	s_waitcnt lgkmcnt(0)
	s_waitcnt lgkmcnt(0)
	v_mfma_f32_16x16x32_bf16 v[78:81], v[50:53], v[146:149], v[78:81]
	v_mfma_f32_16x16x32_bf16 v[70:73], v[66:69], v[146:149], v[70:73]
	v_mfma_f32_16x16x32_bf16 v[62:65], v[50:53], v[166:169], v[62:65]
	v_mfma_f32_16x16x32_bf16 v[54:57], v[66:69], v[166:169], v[54:57]
	v_mfma_f32_16x16x32_bf16 v[38:41], v[50:53], v[174:177], v[38:41]
	v_mfma_f32_16x16x32_bf16 v[22:25], v[66:69], v[174:177], v[22:25]
	v_mfma_f32_16x16x32_bf16 v[14:17], v[50:53], v[182:185], v[14:17]
	v_mfma_f32_16x16x32_bf16 v[6:9], v[66:69], v[182:185], v[6:9]
	v_mfma_f32_16x16x32_bf16 v[78:81], v[58:61], v[150:153], v[78:81]
	v_mfma_f32_16x16x32_bf16 v[70:73], v[74:77], v[150:153], v[70:73]
	v_mfma_f32_16x16x32_bf16 v[62:65], v[58:61], v[170:173], v[62:65]
	v_mfma_f32_16x16x32_bf16 v[54:57], v[74:77], v[170:173], v[54:57]
	v_mfma_f32_16x16x32_bf16 v[38:41], v[58:61], v[178:181], v[38:41]
	v_mfma_f32_16x16x32_bf16 v[22:25], v[74:77], v[178:181], v[22:25]
	v_mfma_f32_16x16x32_bf16 v[14:17], v[58:61], v[186:189], v[14:17]
	v_mfma_f32_16x16x32_bf16 v[6:9], v[74:77], v[186:189], v[6:9]
	s_barrier
	s_mov_b32 m0, vcc_hi
	v_lshl_add_u64 v[50:51], s[54:55], 0, v[158:159]
	global_load_lds_dwordx4 v[50:51], off
	v_lshl_add_u64 v[50:51], s[54:55], 0, v[154:155]
	s_mov_b32 m0, vcc_lo
	s_nop 0
	global_load_lds_dwordx4 v[50:51], off
	s_waitcnt vmcnt(10)
	s_barrier
	v_mfma_f32_16x16x32_bf16 v[26:29], v[190:193], v[146:149], v[26:29]
	v_mfma_f32_16x16x32_bf16 v[74:77], v[194:197], v[150:153], v[26:29]
	v_mfma_f32_16x16x32_bf16 v[26:29], v[198:201], v[146:149], v[30:33]
	v_mfma_f32_16x16x32_bf16 v[66:69], v[202:205], v[150:153], v[26:29]
	v_mfma_f32_16x16x32_bf16 v[26:29], v[190:193], v[166:169], v[42:45]
	v_mfma_f32_16x16x32_bf16 v[58:61], v[194:197], v[170:173], v[26:29]
	v_mfma_f32_16x16x32_bf16 v[26:29], v[198:201], v[166:169], v[46:49]
	v_mfma_f32_16x16x32_bf16 v[50:53], v[202:205], v[170:173], v[26:29]
	v_mfma_f32_16x16x32_bf16 v[26:29], v[190:193], v[174:177], v[34:37]
	v_mfma_f32_16x16x32_bf16 v[18:21], v[198:201], v[174:177], v[18:21]
	v_mfma_f32_16x16x32_bf16 v[10:13], v[190:193], v[182:185], v[10:13]
	v_mfma_f32_16x16x32_bf16 v[2:5], v[198:201], v[182:185], v[2:5]
	v_mfma_f32_16x16x32_bf16 v[34:37], v[194:197], v[178:181], v[26:29]
	v_mfma_f32_16x16x32_bf16 v[18:21], v[202:205], v[178:181], v[18:21]
	v_mfma_f32_16x16x32_bf16 v[10:13], v[194:197], v[186:189], v[10:13]
	v_mfma_f32_16x16x32_bf16 v[2:5], v[202:205], v[186:189], v[2:5]
	s_movk_i32 s56, 0x100
	s_andn2_b64 vcc, exec, s[50:51]
	s_mov_b64 s[54:55], -1
	s_mov_b64 s[50:51], 0
	s_barrier
	s_cbranch_vccz .LBB0_1645
	s_lshl_b32 s0, s82, 7
	s_and_b32 s1, s0, 0x380
	v_mov_b32_e32 v167, v222
	v_mov_b32_e32 v26, v223
	s_or_b32 s1, s1, s11
	s_cmp_lt_u32 s82, 8
	v_lshl_add_u32 v166, v26, 3, s1
	s_mov_b32 s1, 0x32100000
	s_cselect_b32 s1, s1, 0x1a100000
	s_cselect_b32 s49, s9, s17
	s_cselect_b32 s48, s8, s16
	s_add_u32 s50, s18, s1
	s_addc_u32 s51, s19, 0
	s_and_b32 s0, s0, 0xfffffc00
	v_add_u32_e32 v26, s0, v166
	s_load_dwordx2 s[0:1], s[20:21], 0x78
	v_ashrrev_i32_e32 v27, 31, v26
	v_readlane_b32 s56, v254, 5
	v_lshlrev_b64 v[146:147], 2, v[26:27]
	v_readlane_b32 s57, v254, 6
	v_readlane_b32 s58, v254, 7
	v_readlane_b32 s59, v254, 8
	s_waitcnt lgkmcnt(0)
	v_lshl_add_u64 v[26:27], s[0:1], 0, v[146:147]
	v_lshl_add_u64 v[42:43], s[56:57], 0, v[146:147]
	v_lshl_add_u64 v[150:151], s[58:59], 0, v[146:147]
	global_load_dwordx4 v[30:33], v[26:27], off offset:16
	global_load_dwordx4 v[46:49], v[26:27], off
	s_nop 0
	global_load_dwordx4 v[26:29], v[42:43], off offset:16
	s_nop 0
	global_load_dwordx4 v[42:45], v[42:43], off
	s_nop 0
	global_load_dwordx4 v[146:149], v[150:151], off offset:16
	s_nop 0
	global_load_dwordx4 v[150:153], v[150:151], off
	s_lshl_b32 s0, s52, 8
	s_add_i32 s0, s0, s10
	s_waitcnt vmcnt(0)
	v_add_f32_e32 v134, v134, v30
	v_add_f32_e32 v142, v142, v46
	v_add_f32_e32 v138, v138, v42
	v_max_f32_e32 v168, v150, v150
	v_mul_f32_e64 v150, |v150|, s5
	v_exp_f32_e32 v232, v150
	v_mul_f32_e32 v138, 0xbfb8aa3b, v138
	v_exp_f32_e32 v138, v138
	v_mul_f32_e32 v142, 0xbfb8aa3b, v142
	v_add_f32_e32 v172, 1.0, v232
	v_add_f32_e32 v150, -1.0, v172
	v_sub_f32_e32 v169, v150, v172
	v_add_f32_e32 v169, 1.0, v169
	v_sub_f32_e32 v150, v232, v150
	v_add_f32_e32 v174, v150, v169
	v_max_f32_e32 v150, v151, v151
	v_min_f32_e32 v169, 0, v150
	v_mul_f32_e64 v150, |v151|, s5
	v_exp_f32_e32 v233, v150
	v_cvt_f64_f32_e32 v[170:171], v172
	v_frexp_exp_i32_f64_e32 v170, v[170:171]
	v_frexp_mant_f32_e32 v173, v172
	v_add_f32_e32 v171, 1.0, v233
	v_add_f32_e32 v150, -1.0, v171
	v_sub_f32_e32 v151, v150, v171
	v_add_f32_e32 v151, 1.0, v151
	v_sub_f32_e32 v150, v233, v150
	v_add_f32_e32 v175, v150, v151
	v_frexp_mant_f32_e32 v176, v171
	v_cvt_f64_f32_e32 v[150:151], v171
	v_cmp_gt_f32_e32 vcc, s72, v173
	v_frexp_exp_i32_f64_e32 v150, v[150:151]
	v_cmp_gt_f32_e64 s[14:15], s72, v176
	v_subbrev_co_u32_e32 v176, vcc, 0, v170, vcc
	s_nop 0
	v_subbrev_co_u32_e64 v173, s[14:15], 0, v150, s[14:15]
	v_sub_u32_e32 v151, 0, v176
	v_ldexp_f32 v150, v172, v151
	v_sub_u32_e32 v172, 0, v173
	v_ldexp_f32 v170, v174, v151
	v_ldexp_f32 v151, v171, v172
	v_ldexp_f32 v171, v175, v172
	v_pk_add_f32 v[174:175], v[150:151], 1.0 op_sel_hi:[1,0]
	v_pk_add_f32 v[184:185], v[150:151], -1.0 op_sel_hi:[1,0]
	v_pk_add_f32 v[178:179], v[174:175], -1.0 op_sel_hi:[1,0]
	v_pk_add_f32 v[186:187], v[184:185], 1.0 op_sel_hi:[1,0]
	v_pk_add_f32 v[178:179], v[150:151], v[178:179] neg_lo:[0,1] neg_hi:[0,1]
	v_pk_add_f32 v[150:151], v[150:151], v[186:187] neg_lo:[0,1] neg_hi:[0,1]
	v_pk_add_f32 v[178:179], v[170:171], v[178:179]
	v_pk_add_f32 v[150:151], v[170:171], v[150:151]
	v_pk_add_f32 v[180:181], v[174:175], v[178:179]
	v_pk_add_f32 v[170:171], v[184:185], v[150:151]
	v_rcp_f32_e32 v182, v180
	v_rcp_f32_e32 v183, v181
	v_pk_add_f32 v[174:175], v[180:181], v[174:175] neg_lo:[0,1] neg_hi:[0,1]
	v_pk_add_f32 v[184:185], v[170:171], v[184:185] neg_lo:[0,1] neg_hi:[0,1]
	v_pk_add_f32 v[174:175], v[178:179], v[174:175] neg_lo:[0,1] neg_hi:[0,1]
	v_pk_mul_f32 v[186:187], v[170:171], v[182:183]
	v_pk_add_f32 v[150:151], v[150:151], v[184:185] neg_lo:[0,1] neg_hi:[0,1]
	v_pk_mul_f32 v[178:179], v[180:181], v[186:187]
	s_mov_b32 s14, 0x3ecc95a3
	v_pk_fma_f32 v[184:185], v[186:187], v[180:181], v[178:179] neg_lo:[0,0,1] neg_hi:[0,0,1]
	v_cvt_f32_i32_e32 v177, v173
	v_pk_fma_f32 v[184:185], v[186:187], v[174:175], v[184:185]
	v_cvt_f32_i32_e32 v176, v176
	v_pk_add_f32 v[188:189], v[178:179], v[184:185]
	v_add_f32_e32 v138, 1.0, v138
	v_pk_add_f32 v[190:191], v[170:171], v[188:189] neg_lo:[0,1] neg_hi:[0,1]
	v_pk_add_f32 v[178:179], v[188:189], v[178:179] neg_lo:[0,1] neg_hi:[0,1]
	v_pk_add_f32 v[170:171], v[170:171], v[190:191] neg_lo:[0,1] neg_hi:[0,1]
	v_rcp_f32_e32 v249, v138
	v_pk_add_f32 v[170:171], v[170:171], v[188:189] neg_lo:[0,1] neg_hi:[0,1]
	v_add_f32_e32 v138, v143, v47
	v_pk_add_f32 v[150:151], v[150:151], v[170:171]
	v_pk_add_f32 v[170:171], v[178:179], v[184:185] neg_lo:[0,1] neg_hi:[0,1]
	v_mul_f32_e32 v138, 0xbfb8aa3b, v138
	v_pk_add_f32 v[150:151], v[170:171], v[150:151]
	v_exp_f32_e32 v138, v138
	v_pk_add_f32 v[170:171], v[190:191], v[150:151]
	v_exp_f32_e32 v142, v142
	v_pk_mul_f32 v[178:179], v[182:183], v[170:171]
	v_pk_add_f32 v[190:191], v[190:191], v[170:171] neg_lo:[0,1] neg_hi:[0,1]
	v_pk_mul_f32 v[184:185], v[180:181], v[178:179]
	v_pk_add_f32 v[150:151], v[150:151], v[190:191]
	v_pk_fma_f32 v[180:181], v[178:179], v[180:181], v[184:185] neg_lo:[0,0,1] neg_hi:[0,0,1]
	v_pk_add_f32 v[196:197], v[186:187], v[178:179]
	v_pk_fma_f32 v[174:175], v[178:179], v[174:175], v[180:181]
	v_add_f32_e32 v138, 1.0, v138
	v_pk_add_f32 v[180:181], v[184:185], v[174:175]
	v_rcp_f32_e32 v143, v138
	v_pk_add_f32 v[192:193], v[170:171], v[180:181] neg_lo:[0,1] neg_hi:[0,1]
	v_pk_add_f32 v[188:189], v[180:181], v[184:185] neg_lo:[0,1] neg_hi:[0,1]
	v_pk_add_f32 v[194:195], v[170:171], v[192:193] neg_lo:[0,1] neg_hi:[0,1]
	v_mov_b32_e32 v170, v181
	v_mov_b32_e32 v184, v185
	v_mov_b32_e32 v185, v193
	v_pk_add_f32 v[194:195], v[194:195], v[180:181] neg_lo:[0,1] neg_hi:[0,1]
	v_pk_add_f32 v[170:171], v[170:171], v[184:185] neg_lo:[0,1] neg_hi:[0,1]
	v_mov_b32_e32 v180, v175
	v_pk_add_f32 v[170:171], v[170:171], v[180:181] neg_lo:[0,1] neg_hi:[0,1]
	v_pk_add_f32 v[188:189], v[188:189], v[174:175] neg_lo:[0,1] neg_hi:[0,1]
	v_mov_b32_e32 v195, v171
	v_pk_add_f32 v[150:151], v[150:151], v[194:195]
	v_mov_b32_e32 v189, v170
	v_pk_add_f32 v[150:151], v[188:189], v[150:151]
	v_pk_add_f32 v[170:171], v[196:197], v[186:187] neg_lo:[0,1] neg_hi:[0,1]
	v_pk_add_f32 v[150:151], v[192:193], v[150:151]
	v_pk_add_f32 v[170:171], v[178:179], v[170:171] neg_lo:[0,1] neg_hi:[0,1]
	v_pk_mul_f32 v[150:151], v[182:183], v[150:151]
	v_pk_mul_f32 v[182:183], v[176:177], s[34:35] op_sel_hi:[1,0]
	v_pk_add_f32 v[150:151], v[170:171], v[150:151]
	v_pk_fma_f32 v[184:185], v[176:177], s[34:35], v[182:183] op_sel_hi:[1,0,1] neg_lo:[0,0,1] neg_hi:[0,0,1]
	v_pk_add_f32 v[174:175], v[196:197], v[150:151]
	v_pk_fma_f32 v[184:185], v[176:177], s[36:37], v[184:185] op_sel_hi:[1,0,1]
	v_pk_add_f32 v[170:171], v[174:175], v[196:197] neg_lo:[0,1] neg_hi:[0,1]
	v_pk_mul_f32 v[178:179], v[174:175], v[174:175]
	v_pk_add_f32 v[170:171], v[150:151], v[170:171] neg_lo:[0,1] neg_hi:[0,1]
	v_mov_b64_e32 v[150:151], s[14:15]
	v_pk_fma_f32 v[180:181], v[178:179], s[28:29], v[150:151] op_sel_hi:[1,0,0]
	v_ldexp_f32 v172, v174, 1
	v_pk_fma_f32 v[180:181], v[178:179], v[180:181], s[30:31] op_sel_hi:[1,1,0]
	v_ldexp_f32 v173, v175, 1
	v_pk_mul_f32 v[174:175], v[174:175], v[178:179]
	v_ldexp_f32 v170, v170, 1
	v_pk_mul_f32 v[174:175], v[174:175], v[180:181]
	v_ldexp_f32 v171, v171, 1
	v_pk_add_f32 v[178:179], v[172:173], v[174:175]
	v_pk_add_f32 v[176:177], v[182:183], v[184:185]
	v_pk_add_f32 v[172:173], v[178:179], v[172:173] neg_lo:[0,1] neg_hi:[0,1]
	v_pk_add_f32 v[182:183], v[176:177], v[182:183] neg_lo:[0,1] neg_hi:[0,1]
	v_pk_add_f32 v[172:173], v[174:175], v[172:173] neg_lo:[0,1] neg_hi:[0,1]
	v_pk_add_f32 v[182:183], v[184:185], v[182:183] neg_lo:[0,1] neg_hi:[0,1]
	v_pk_add_f32 v[170:171], v[170:171], v[172:173]
	v_add_f32_e32 v138, v139, v43
	v_pk_add_f32 v[190:191], v[178:179], v[170:171]
	v_mul_f32_e32 v138, 0xbfb8aa3b, v138
	v_pk_add_f32 v[172:173], v[190:191], v[178:179] neg_lo:[0,1] neg_hi:[0,1]
	v_exp_f32_e32 v138, v138
	v_pk_add_f32 v[170:171], v[170:171], v[172:173] neg_lo:[0,1] neg_hi:[0,1]
	v_add_f32_e32 v142, 1.0, v142
	v_pk_add_f32 v[184:185], v[182:183], v[170:171]
	v_add_f32_e32 v138, 1.0, v138
	v_pk_add_f32 v[172:173], v[184:185], v[182:183] neg_lo:[0,1] neg_hi:[0,1]
	v_rcp_f32_e32 v250, v138
	v_pk_add_f32 v[188:189], v[170:171], v[172:173] neg_lo:[0,1] neg_hi:[0,1]
	v_max_f32_e32 v170, v152, v152
	v_mul_f32_e64 v152, |v152|, s5
	v_exp_f32_e32 v236, v152
	v_pk_add_f32 v[174:175], v[184:185], v[172:173] neg_lo:[0,1] neg_hi:[0,1]
	v_min_f32_e32 v180, 0, v170
	v_pk_add_f32 v[186:187], v[182:183], v[174:175] neg_lo:[0,1] neg_hi:[0,1]
	v_add_f32_e32 v172, 1.0, v236
	v_add_f32_e32 v152, -1.0, v172
	v_sub_f32_e32 v170, v152, v172
	v_add_f32_e32 v170, 1.0, v170
	v_sub_f32_e32 v152, v236, v152
	v_add_f32_e32 v173, v152, v170
	v_max_f32_e32 v152, v153, v153
	v_min_f32_e32 v181, 0, v152
	v_mul_f32_e64 v152, |v153|, s5
	v_exp_f32_e32 v238, v152
	v_cvt_f64_f32_e32 v[170:171], v172
	v_frexp_exp_i32_f64_e32 v170, v[170:171]
	v_frexp_mant_f32_e32 v174, v172
	v_add_f32_e32 v171, 1.0, v238
	v_add_f32_e32 v152, -1.0, v171
	v_sub_f32_e32 v153, v152, v171
	v_add_f32_e32 v153, 1.0, v153
	v_sub_f32_e32 v152, v238, v152
	v_add_f32_e32 v175, v152, v153
	v_frexp_mant_f32_e32 v178, v171
	v_cvt_f64_f32_e32 v[152:153], v171
	v_cmp_gt_f32_e32 vcc, s72, v174
	v_frexp_exp_i32_f64_e32 v152, v[152:153]
	v_cmp_gt_f32_e64 s[14:15], s72, v178
	v_subbrev_co_u32_e32 v207, vcc, 0, v170, vcc
	s_nop 0
	v_subbrev_co_u32_e64 v206, s[14:15], 0, v152, s[14:15]
	v_sub_u32_e32 v153, 0, v207
	v_ldexp_f32 v152, v172, v153
	v_sub_u32_e32 v172, 0, v206
	v_ldexp_f32 v170, v173, v153
	v_ldexp_f32 v153, v171, v172
	v_ldexp_f32 v171, v175, v172
	v_pk_add_f32 v[172:173], v[152:153], 1.0 op_sel_hi:[1,0]
	v_pk_add_f32 v[192:193], v[152:153], -1.0 op_sel_hi:[1,0]
	v_pk_add_f32 v[174:175], v[172:173], -1.0 op_sel_hi:[1,0]
	v_pk_add_f32 v[194:195], v[192:193], 1.0 op_sel_hi:[1,0]
	v_pk_add_f32 v[174:175], v[152:153], v[174:175] neg_lo:[0,1] neg_hi:[0,1]
	v_pk_add_f32 v[152:153], v[152:153], v[194:195] neg_lo:[0,1] neg_hi:[0,1]
	v_pk_add_f32 v[174:175], v[170:171], v[174:175]
	v_pk_add_f32 v[152:153], v[170:171], v[152:153]
	v_pk_add_f32 v[178:179], v[172:173], v[174:175]
	v_pk_add_f32 v[170:171], v[192:193], v[152:153]
	v_rcp_f32_e32 v182, v178
	v_rcp_f32_e32 v183, v179
	v_pk_add_f32 v[172:173], v[178:179], v[172:173] neg_lo:[0,1] neg_hi:[0,1]
	v_pk_add_f32 v[192:193], v[170:171], v[192:193] neg_lo:[0,1] neg_hi:[0,1]
	v_pk_add_f32 v[172:173], v[174:175], v[172:173] neg_lo:[0,1] neg_hi:[0,1]
	v_pk_mul_f32 v[194:195], v[170:171], v[182:183]
	v_pk_add_f32 v[152:153], v[152:153], v[192:193] neg_lo:[0,1] neg_hi:[0,1]
	v_pk_mul_f32 v[174:175], v[178:179], v[194:195]
	v_add_f32_e32 v138, v144, v48
	v_pk_fma_f32 v[192:193], v[194:195], v[178:179], v[174:175] neg_lo:[0,0,1] neg_hi:[0,0,1]
	v_mul_f32_e32 v138, 0xbfb8aa3b, v138
	v_pk_fma_f32 v[192:193], v[194:195], v[172:173], v[192:193]
	v_exp_f32_e32 v138, v138
	v_pk_add_f32 v[196:197], v[174:175], v[192:193]
	v_rcp_f32_e32 v142, v142
	v_pk_add_f32 v[198:199], v[170:171], v[196:197] neg_lo:[0,1] neg_hi:[0,1]
	v_pk_add_f32 v[174:175], v[196:197], v[174:175] neg_lo:[0,1] neg_hi:[0,1]
	v_pk_add_f32 v[170:171], v[170:171], v[198:199] neg_lo:[0,1] neg_hi:[0,1]
	v_add_f32_e32 v138, 1.0, v138
	v_pk_add_f32 v[170:171], v[170:171], v[196:197] neg_lo:[0,1] neg_hi:[0,1]
	v_min_f32_e32 v168, 0, v168
	v_pk_add_f32 v[152:153], v[152:153], v[170:171]
	v_pk_add_f32 v[170:171], v[174:175], v[192:193] neg_lo:[0,1] neg_hi:[0,1]
	v_add_f32_e32 v130, v130, v26
	v_pk_add_f32 v[152:153], v[170:171], v[152:153]
	v_mul_f32_e32 v130, 0xbfb8aa3b, v130
	v_pk_add_f32 v[170:171], v[198:199], v[152:153]
	v_exp_f32_e32 v130, v130
	v_pk_mul_f32 v[174:175], v[182:183], v[170:171]
	v_pk_add_f32 v[198:199], v[198:199], v[170:171] neg_lo:[0,1] neg_hi:[0,1]
	v_pk_mul_f32 v[192:193], v[178:179], v[174:175]
	v_pk_add_f32 v[152:153], v[152:153], v[198:199]
	v_pk_fma_f32 v[178:179], v[174:175], v[178:179], v[192:193] neg_lo:[0,0,1] neg_hi:[0,0,1]
	v_pk_add_f32 v[204:205], v[194:195], v[174:175]
	v_pk_fma_f32 v[172:173], v[174:175], v[172:173], v[178:179]
	v_add_f32_e32 v130, 1.0, v130
	v_pk_add_f32 v[178:179], v[192:193], v[172:173]
	v_mul_f32_e32 v134, 0xbfb8aa3b, v134
	v_pk_add_f32 v[200:201], v[170:171], v[178:179] neg_lo:[0,1] neg_hi:[0,1]
	v_pk_add_f32 v[196:197], v[178:179], v[192:193] neg_lo:[0,1] neg_hi:[0,1]
	v_pk_add_f32 v[202:203], v[170:171], v[200:201] neg_lo:[0,1] neg_hi:[0,1]
	v_mov_b32_e32 v170, v179
	v_mov_b32_e32 v192, v193
	v_mov_b32_e32 v193, v201
	v_pk_add_f32 v[202:203], v[202:203], v[178:179] neg_lo:[0,1] neg_hi:[0,1]
	v_pk_add_f32 v[170:171], v[170:171], v[192:193] neg_lo:[0,1] neg_hi:[0,1]
	v_mov_b32_e32 v178, v173
	v_pk_add_f32 v[170:171], v[170:171], v[178:179] neg_lo:[0,1] neg_hi:[0,1]
	v_pk_add_f32 v[196:197], v[196:197], v[172:173] neg_lo:[0,1] neg_hi:[0,1]
	v_mov_b32_e32 v203, v171
	v_pk_add_f32 v[152:153], v[152:153], v[202:203]
	v_mov_b32_e32 v197, v170
	v_pk_add_f32 v[152:153], v[196:197], v[152:153]
	v_pk_add_f32 v[170:171], v[204:205], v[194:195] neg_lo:[0,1] neg_hi:[0,1]
	v_pk_add_f32 v[152:153], v[200:201], v[152:153]
	v_pk_add_f32 v[170:171], v[174:175], v[170:171] neg_lo:[0,1] neg_hi:[0,1]
	v_pk_mul_f32 v[152:153], v[182:183], v[152:153]
	v_cvt_f32_i32_e32 v183, v206
	v_pk_add_f32 v[152:153], v[170:171], v[152:153]
	v_cvt_f32_i32_e32 v182, v207
	v_pk_add_f32 v[170:171], v[204:205], v[152:153]
	v_exp_f32_e32 v134, v134
	v_pk_mul_f32 v[174:175], v[170:171], v[170:171]
	v_pk_add_f32 v[172:173], v[170:171], v[204:205] neg_lo:[0,1] neg_hi:[0,1]
	v_pk_fma_f32 v[178:179], v[174:175], s[28:29], v[150:151] op_sel_hi:[1,0,0]
	v_pk_add_f32 v[152:153], v[152:153], v[172:173] neg_lo:[0,1] neg_hi:[0,1]
	v_ldexp_f32 v172, v170, 1
	v_pk_fma_f32 v[178:179], v[174:175], v[178:179], s[30:31] op_sel_hi:[1,1,0]
	v_ldexp_f32 v173, v171, 1
	v_pk_mul_f32 v[170:171], v[170:171], v[174:175]
	v_pk_mul_f32 v[192:193], v[182:183], s[34:35] op_sel_hi:[1,0]
	v_pk_mul_f32 v[170:171], v[170:171], v[178:179]
	v_ldexp_f32 v152, v152, 1
	v_pk_add_f32 v[174:175], v[172:173], v[170:171]
	v_pk_fma_f32 v[194:195], v[182:183], s[34:35], v[192:193] op_sel_hi:[1,0,1] neg_lo:[0,0,1] neg_hi:[0,0,1]
	v_pk_add_f32 v[172:173], v[174:175], v[172:173] neg_lo:[0,1] neg_hi:[0,1]
	v_ldexp_f32 v153, v153, 1
	v_pk_add_f32 v[170:171], v[170:171], v[172:173] neg_lo:[0,1] neg_hi:[0,1]
	v_pk_fma_f32 v[182:183], v[182:183], s[36:37], v[194:195] op_sel_hi:[1,0,1]
	v_pk_add_f32 v[152:153], v[152:153], v[170:171]
	v_pk_add_f32 v[202:203], v[192:193], v[182:183]
	v_pk_add_f32 v[210:211], v[174:175], v[152:153]
	v_pk_add_f32 v[192:193], v[202:203], v[192:193] neg_lo:[0,1] neg_hi:[0,1]
	v_pk_add_f32 v[170:171], v[210:211], v[174:175] neg_lo:[0,1] neg_hi:[0,1]
	v_pk_add_f32 v[182:183], v[182:183], v[192:193] neg_lo:[0,1] neg_hi:[0,1]
	v_pk_add_f32 v[152:153], v[152:153], v[170:171] neg_lo:[0,1] neg_hi:[0,1]
	v_add_f32_e32 v134, 1.0, v134
	v_pk_add_f32 v[204:205], v[182:183], v[152:153]
	v_rcp_f32_e32 v134, v134
	v_pk_add_f32 v[170:171], v[204:205], v[182:183] neg_lo:[0,1] neg_hi:[0,1]
	v_add_f32_e32 v126, v126, v46
	v_pk_add_f32 v[208:209], v[152:153], v[170:171] neg_lo:[0,1] neg_hi:[0,1]
	v_max_f32_e32 v152, v146, v146
	v_mul_f32_e64 v146, |v146|, s5
	v_exp_f32_e32 v235, v146
	v_pk_add_f32 v[172:173], v[204:205], v[170:171] neg_lo:[0,1] neg_hi:[0,1]
	v_min_f32_e32 v178, 0, v152
	v_pk_add_f32 v[206:207], v[182:183], v[172:173] neg_lo:[0,1] neg_hi:[0,1]
	v_add_f32_e32 v170, 1.0, v235
	v_add_f32_e32 v146, -1.0, v170
	v_sub_f32_e32 v152, v146, v170
	v_add_f32_e32 v152, 1.0, v152
	v_sub_f32_e32 v146, v235, v146
	v_add_f32_e32 v171, v146, v152
	v_max_f32_e32 v146, v147, v147
	v_min_f32_e32 v179, 0, v146
	v_mul_f32_e64 v146, |v147|, s5
	v_exp_f32_e32 v237, v146
	v_cvt_f64_f32_e32 v[152:153], v170
	v_frexp_exp_i32_f64_e32 v152, v[152:153]
	v_frexp_mant_f32_e32 v172, v170
	v_add_f32_e32 v153, 1.0, v237
	v_add_f32_e32 v146, -1.0, v153
	v_sub_f32_e32 v147, v146, v153
	v_add_f32_e32 v147, 1.0, v147
	v_sub_f32_e32 v146, v237, v146
	v_add_f32_e32 v173, v146, v147
	v_frexp_mant_f32_e32 v174, v153
	v_cvt_f64_f32_e32 v[146:147], v153
	v_cmp_gt_f32_e32 vcc, s72, v172
	v_frexp_exp_i32_f64_e32 v146, v[146:147]
	v_cmp_gt_f32_e64 s[14:15], s72, v174
	v_subbrev_co_u32_e32 v217, vcc, 0, v152, vcc
	s_nop 0
	v_subbrev_co_u32_e64 v216, s[14:15], 0, v146, s[14:15]
	v_sub_u32_e32 v147, 0, v217
	v_ldexp_f32 v146, v170, v147
	v_sub_u32_e32 v170, 0, v216
	v_ldexp_f32 v152, v171, v147
	v_ldexp_f32 v147, v153, v170
	v_ldexp_f32 v153, v173, v170
	v_pk_add_f32 v[170:171], v[146:147], 1.0 op_sel_hi:[1,0]
	v_pk_add_f32 v[192:193], v[146:147], -1.0 op_sel_hi:[1,0]
	v_pk_add_f32 v[172:173], v[170:171], -1.0 op_sel_hi:[1,0]
	v_pk_add_f32 v[194:195], v[192:193], 1.0 op_sel_hi:[1,0]
	v_pk_add_f32 v[172:173], v[146:147], v[172:173] neg_lo:[0,1] neg_hi:[0,1]
	v_pk_add_f32 v[146:147], v[146:147], v[194:195] neg_lo:[0,1] neg_hi:[0,1]
	v_pk_add_f32 v[172:173], v[152:153], v[172:173]
	v_pk_add_f32 v[146:147], v[152:153], v[146:147]
	v_pk_add_f32 v[174:175], v[170:171], v[172:173]
	v_pk_add_f32 v[152:153], v[192:193], v[146:147]
	v_rcp_f32_e32 v182, v174
	v_rcp_f32_e32 v183, v175
	v_pk_add_f32 v[170:171], v[174:175], v[170:171] neg_lo:[0,1] neg_hi:[0,1]
	v_pk_add_f32 v[192:193], v[152:153], v[192:193] neg_lo:[0,1] neg_hi:[0,1]
	v_pk_add_f32 v[170:171], v[172:173], v[170:171] neg_lo:[0,1] neg_hi:[0,1]
	v_pk_mul_f32 v[194:195], v[152:153], v[182:183]
	v_pk_add_f32 v[146:147], v[146:147], v[192:193] neg_lo:[0,1] neg_hi:[0,1]
	v_pk_mul_f32 v[172:173], v[174:175], v[194:195]
	v_mul_f32_e32 v126, 0xbfb8aa3b, v126
	v_pk_fma_f32 v[192:193], v[194:195], v[174:175], v[172:173] neg_lo:[0,0,1] neg_hi:[0,0,1]
	v_exp_f32_e32 v126, v126
	v_pk_fma_f32 v[192:193], v[194:195], v[170:171], v[192:193]
	v_add_f32_e32 v122, v122, v42
	v_pk_add_f32 v[196:197], v[172:173], v[192:193]
	v_add_f32_e32 v126, 1.0, v126
	v_pk_add_f32 v[198:199], v[152:153], v[196:197] neg_lo:[0,1] neg_hi:[0,1]
	v_pk_add_f32 v[172:173], v[196:197], v[172:173] neg_lo:[0,1] neg_hi:[0,1]
	v_pk_add_f32 v[152:153], v[152:153], v[198:199] neg_lo:[0,1] neg_hi:[0,1]
	v_rcp_f32_e32 v126, v126
	v_pk_add_f32 v[152:153], v[152:153], v[196:197] neg_lo:[0,1] neg_hi:[0,1]
	v_mul_f32_e32 v122, 0xbfb8aa3b, v122
	v_pk_add_f32 v[146:147], v[146:147], v[152:153]
	v_pk_add_f32 v[152:153], v[172:173], v[192:193] neg_lo:[0,1] neg_hi:[0,1]
	v_exp_f32_e32 v122, v122
	v_pk_add_f32 v[146:147], v[152:153], v[146:147]
	v_add_f32_e32 v123, v123, v43
	v_pk_add_f32 v[152:153], v[198:199], v[146:147]
	v_add_f32_e32 v122, 1.0, v122
	v_pk_mul_f32 v[172:173], v[182:183], v[152:153]
	v_pk_add_f32 v[198:199], v[198:199], v[152:153] neg_lo:[0,1] neg_hi:[0,1]
	v_pk_mul_f32 v[192:193], v[174:175], v[172:173]
	v_pk_add_f32 v[146:147], v[146:147], v[198:199]
	v_pk_fma_f32 v[174:175], v[172:173], v[174:175], v[192:193] neg_lo:[0,0,1] neg_hi:[0,0,1]
	v_pk_add_f32 v[214:215], v[194:195], v[172:173]
	v_pk_fma_f32 v[170:171], v[172:173], v[170:171], v[174:175]
	v_rcp_f32_e32 v122, v122
	v_pk_add_f32 v[174:175], v[192:193], v[170:171]
	v_mul_f32_e32 v123, 0xbfb8aa3b, v123
	v_pk_add_f32 v[200:201], v[152:153], v[174:175] neg_lo:[0,1] neg_hi:[0,1]
	v_pk_add_f32 v[196:197], v[174:175], v[192:193] neg_lo:[0,1] neg_hi:[0,1]
	v_pk_add_f32 v[212:213], v[152:153], v[200:201] neg_lo:[0,1] neg_hi:[0,1]
	v_mov_b32_e32 v152, v175
	v_mov_b32_e32 v192, v193
	v_mov_b32_e32 v193, v201
	v_pk_add_f32 v[212:213], v[212:213], v[174:175] neg_lo:[0,1] neg_hi:[0,1]
	v_pk_add_f32 v[152:153], v[152:153], v[192:193] neg_lo:[0,1] neg_hi:[0,1]
	v_mov_b32_e32 v174, v171
	v_pk_add_f32 v[152:153], v[152:153], v[174:175] neg_lo:[0,1] neg_hi:[0,1]
	v_pk_add_f32 v[196:197], v[196:197], v[170:171] neg_lo:[0,1] neg_hi:[0,1]
	v_mov_b32_e32 v213, v153
	v_pk_add_f32 v[146:147], v[146:147], v[212:213]
	v_mov_b32_e32 v197, v152
	v_pk_add_f32 v[146:147], v[196:197], v[146:147]
	v_pk_add_f32 v[152:153], v[214:215], v[194:195] neg_lo:[0,1] neg_hi:[0,1]
	v_pk_add_f32 v[146:147], v[200:201], v[146:147]
	v_pk_add_f32 v[152:153], v[172:173], v[152:153] neg_lo:[0,1] neg_hi:[0,1]
	v_pk_mul_f32 v[146:147], v[182:183], v[146:147]
	v_cvt_f32_i32_e32 v183, v216
	v_pk_add_f32 v[146:147], v[152:153], v[146:147]
	v_cvt_f32_i32_e32 v182, v217
	v_pk_add_f32 v[152:153], v[214:215], v[146:147]
	v_exp_f32_e32 v123, v123
	v_pk_mul_f32 v[172:173], v[152:153], v[152:153]
	v_pk_add_f32 v[170:171], v[152:153], v[214:215] neg_lo:[0,1] neg_hi:[0,1]
	v_pk_fma_f32 v[174:175], v[172:173], s[28:29], v[150:151] op_sel_hi:[1,0,0]
	v_pk_add_f32 v[146:147], v[146:147], v[170:171] neg_lo:[0,1] neg_hi:[0,1]
	v_ldexp_f32 v170, v152, 1
	v_pk_fma_f32 v[174:175], v[172:173], v[174:175], s[30:31] op_sel_hi:[1,1,0]
	v_ldexp_f32 v171, v153, 1
	v_pk_mul_f32 v[152:153], v[152:153], v[172:173]
	v_pk_mul_f32 v[194:195], v[182:183], s[34:35] op_sel_hi:[1,0]
	v_pk_mul_f32 v[152:153], v[152:153], v[174:175]
	v_ldexp_f32 v146, v146, 1
	v_pk_add_f32 v[172:173], v[170:171], v[152:153]
	v_pk_fma_f32 v[192:193], v[182:183], s[34:35], v[194:195] op_sel_hi:[1,0,1] neg_lo:[0,0,1] neg_hi:[0,0,1]
	v_pk_add_f32 v[170:171], v[172:173], v[170:171] neg_lo:[0,1] neg_hi:[0,1]
	v_ldexp_f32 v147, v147, 1
	v_pk_add_f32 v[152:153], v[152:153], v[170:171] neg_lo:[0,1] neg_hi:[0,1]
	v_pk_fma_f32 v[182:183], v[182:183], s[36:37], v[192:193] op_sel_hi:[1,0,1]
	v_pk_add_f32 v[146:147], v[146:147], v[152:153]
	v_pk_add_f32 v[192:193], v[194:195], v[182:183]
	v_pk_add_f32 v[200:201], v[172:173], v[146:147]
	v_pk_add_f32 v[194:195], v[192:193], v[194:195] neg_lo:[0,1] neg_hi:[0,1]
	v_pk_add_f32 v[152:153], v[200:201], v[172:173] neg_lo:[0,1] neg_hi:[0,1]
	v_pk_add_f32 v[182:183], v[182:183], v[194:195] neg_lo:[0,1] neg_hi:[0,1]
	v_pk_add_f32 v[146:147], v[146:147], v[152:153] neg_lo:[0,1] neg_hi:[0,1]
	v_add_f32_e32 v123, 1.0, v123
	v_pk_add_f32 v[194:195], v[182:183], v[146:147]
	v_rcp_f32_e32 v123, v123
	v_pk_add_f32 v[152:153], v[194:195], v[182:183] neg_lo:[0,1] neg_hi:[0,1]
	v_add_f32_e32 v124, v124, v44
	v_pk_add_f32 v[170:171], v[194:195], v[152:153] neg_lo:[0,1] neg_hi:[0,1]
	v_pk_add_f32 v[198:199], v[146:147], v[152:153] neg_lo:[0,1] neg_hi:[0,1]
	v_max_f32_e32 v146, v148, v148
	v_pk_add_f32 v[196:197], v[182:183], v[170:171] neg_lo:[0,1] neg_hi:[0,1]
	v_min_f32_e32 v182, 0, v146
	v_mul_f32_e64 v146, |v148|, s5
	v_exp_f32_e32 v239, v146
	v_mul_f32_e32 v124, 0xbfb8aa3b, v124
	v_exp_f32_e32 v124, v124
	v_add_f32_e32 v118, v118, v30
	v_add_f32_e32 v148, 1.0, v239
	v_add_f32_e32 v146, -1.0, v148
	v_sub_f32_e32 v147, v146, v148
	v_add_f32_e32 v147, 1.0, v147
	v_sub_f32_e32 v146, v239, v146
	v_add_f32_e32 v152, v146, v147
	v_cvt_f64_f32_e32 v[146:147], v148
	v_frexp_exp_i32_f64_e32 v170, v[146:147]
	v_max_f32_e32 v146, v149, v149
	v_min_f32_e32 v183, 0, v146
	v_mul_f32_e64 v146, |v149|, s5
	v_exp_f32_e32 v240, v146
	v_frexp_mant_f32_e32 v153, v148
	v_cmp_gt_f32_e32 vcc, s72, v153
	v_add_f32_e32 v124, 1.0, v124
	v_add_f32_e32 v149, 1.0, v240
	v_add_f32_e32 v146, -1.0, v149
	v_sub_f32_e32 v147, v146, v149
	v_add_f32_e32 v147, 1.0, v147
	v_sub_f32_e32 v146, v240, v146
	v_add_f32_e32 v171, v146, v147
	v_frexp_mant_f32_e32 v172, v149
	v_cvt_f64_f32_e32 v[146:147], v149
	v_frexp_exp_i32_f64_e32 v146, v[146:147]
	v_cmp_gt_f32_e64 s[14:15], s72, v172
	v_subbrev_co_u32_e32 v241, vcc, 0, v170, vcc
	s_nop 0
	v_subbrev_co_u32_e64 v234, s[14:15], 0, v146, s[14:15]
	v_sub_u32_e32 v147, 0, v241
	v_ldexp_f32 v146, v148, v147
	v_ldexp_f32 v148, v152, v147
	v_sub_u32_e32 v152, 0, v234
	v_ldexp_f32 v147, v149, v152
	v_ldexp_f32 v149, v171, v152
	v_pk_add_f32 v[152:153], v[146:147], 1.0 op_sel_hi:[1,0]
	v_pk_add_f32 v[212:213], v[146:147], -1.0 op_sel_hi:[1,0]
	v_pk_add_f32 v[170:171], v[152:153], -1.0 op_sel_hi:[1,0]
	v_pk_add_f32 v[214:215], v[212:213], 1.0 op_sel_hi:[1,0]
	v_pk_add_f32 v[170:171], v[146:147], v[170:171] neg_lo:[0,1] neg_hi:[0,1]
	v_pk_add_f32 v[146:147], v[146:147], v[214:215] neg_lo:[0,1] neg_hi:[0,1]
	v_pk_add_f32 v[170:171], v[148:149], v[170:171]
	v_pk_add_f32 v[146:147], v[148:149], v[146:147]
	v_pk_add_f32 v[172:173], v[152:153], v[170:171]
	v_pk_add_f32 v[148:149], v[212:213], v[146:147]
	v_rcp_f32_e32 v174, v172
	v_rcp_f32_e32 v175, v173
	v_pk_add_f32 v[152:153], v[172:173], v[152:153] neg_lo:[0,1] neg_hi:[0,1]
	v_pk_add_f32 v[212:213], v[148:149], v[212:213] neg_lo:[0,1] neg_hi:[0,1]
	v_pk_add_f32 v[152:153], v[170:171], v[152:153] neg_lo:[0,1] neg_hi:[0,1]
	v_pk_mul_f32 v[214:215], v[148:149], v[174:175]
	v_pk_add_f32 v[146:147], v[146:147], v[212:213] neg_lo:[0,1] neg_hi:[0,1]
	v_pk_mul_f32 v[170:171], v[172:173], v[214:215]
	v_cmp_lt_f32_e64 s[14:15], |v233|, s77
	v_pk_fma_f32 v[212:213], v[214:215], v[172:173], v[170:171] neg_lo:[0,0,1] neg_hi:[0,0,1]
	v_rcp_f32_e32 v124, v124
	v_pk_fma_f32 v[212:213], v[214:215], v[152:153], v[212:213]
	v_add_f32_e32 v125, v125, v45
	v_pk_add_f32 v[216:217], v[170:171], v[212:213]
	v_mul_f32_e32 v118, 0xbfb8aa3b, v118
	v_pk_add_f32 v[218:219], v[148:149], v[216:217] neg_lo:[0,1] neg_hi:[0,1]
	v_pk_add_f32 v[170:171], v[216:217], v[170:171] neg_lo:[0,1] neg_hi:[0,1]
	v_pk_add_f32 v[148:149], v[148:149], v[218:219] neg_lo:[0,1] neg_hi:[0,1]
	v_mul_f32_e32 v125, 0xbfb8aa3b, v125
	v_pk_add_f32 v[148:149], v[148:149], v[216:217] neg_lo:[0,1] neg_hi:[0,1]
	v_exp_f32_e32 v118, v118
	v_pk_add_f32 v[146:147], v[146:147], v[148:149]
	v_pk_add_f32 v[148:149], v[170:171], v[212:213] neg_lo:[0,1] neg_hi:[0,1]
	v_exp_f32_e32 v125, v125
	v_pk_add_f32 v[146:147], v[148:149], v[146:147]
	v_add_f32_e32 v118, 1.0, v118
	v_pk_add_f32 v[148:149], v[218:219], v[146:147]
	v_add_f32_e32 v125, 1.0, v125
	v_pk_mul_f32 v[170:171], v[174:175], v[148:149]
	v_pk_add_f32 v[218:219], v[218:219], v[148:149] neg_lo:[0,1] neg_hi:[0,1]
	v_pk_mul_f32 v[212:213], v[172:173], v[170:171]
	v_pk_add_f32 v[146:147], v[146:147], v[218:219]
	v_pk_fma_f32 v[172:173], v[170:171], v[172:173], v[212:213] neg_lo:[0,0,1] neg_hi:[0,0,1]
	v_pk_add_f32 v[244:245], v[214:215], v[170:171]
	v_pk_fma_f32 v[152:153], v[170:171], v[152:153], v[172:173]
	v_rcp_f32_e32 v118, v118
	v_pk_add_f32 v[172:173], v[212:213], v[152:153]
	v_rcp_f32_e32 v125, v125
	v_pk_add_f32 v[220:221], v[148:149], v[172:173] neg_lo:[0,1] neg_hi:[0,1]
	v_pk_add_f32 v[216:217], v[172:173], v[212:213] neg_lo:[0,1] neg_hi:[0,1]
	v_pk_add_f32 v[242:243], v[148:149], v[220:221] neg_lo:[0,1] neg_hi:[0,1]
	v_mov_b32_e32 v148, v173
	v_mov_b32_e32 v212, v213
	v_mov_b32_e32 v213, v221
	v_pk_add_f32 v[242:243], v[242:243], v[172:173] neg_lo:[0,1] neg_hi:[0,1]
	v_pk_add_f32 v[148:149], v[148:149], v[212:213] neg_lo:[0,1] neg_hi:[0,1]
	v_mov_b32_e32 v172, v153
	v_pk_add_f32 v[148:149], v[148:149], v[172:173] neg_lo:[0,1] neg_hi:[0,1]
	v_pk_add_f32 v[216:217], v[216:217], v[152:153] neg_lo:[0,1] neg_hi:[0,1]
	v_mov_b32_e32 v243, v149
	v_pk_add_f32 v[146:147], v[146:147], v[242:243]
	v_mov_b32_e32 v217, v148
	v_pk_add_f32 v[146:147], v[216:217], v[146:147]
	v_pk_add_f32 v[148:149], v[244:245], v[214:215] neg_lo:[0,1] neg_hi:[0,1]
	v_pk_add_f32 v[146:147], v[220:221], v[146:147]
	v_pk_add_f32 v[148:149], v[170:171], v[148:149] neg_lo:[0,1] neg_hi:[0,1]
	v_pk_mul_f32 v[146:147], v[174:175], v[146:147]
	v_cvt_f32_i32_e32 v173, v234
	v_pk_add_f32 v[146:147], v[148:149], v[146:147]
	v_cvt_f32_i32_e32 v172, v241
	v_pk_add_f32 v[148:149], v[244:245], v[146:147]
	v_add_u32_e32 v234, s0, v167
	v_pk_mul_f32 v[170:171], v[148:149], v[148:149]
	v_pk_add_f32 v[152:153], v[148:149], v[244:245] neg_lo:[0,1] neg_hi:[0,1]
	v_pk_fma_f32 v[150:151], v[170:171], s[28:29], v[150:151] op_sel_hi:[1,0,0]
	v_pk_add_f32 v[146:147], v[146:147], v[152:153] neg_lo:[0,1] neg_hi:[0,1]
	v_ldexp_f32 v152, v148, 1
	v_pk_fma_f32 v[150:151], v[170:171], v[150:151], s[30:31] op_sel_hi:[1,1,0]
	v_ldexp_f32 v153, v149, 1
	v_pk_mul_f32 v[148:149], v[148:149], v[170:171]
	v_pk_mul_f32 v[174:175], v[172:173], s[34:35] op_sel_hi:[1,0]
	v_pk_mul_f32 v[148:149], v[148:149], v[150:151]
	v_ldexp_f32 v146, v146, 1
	v_pk_add_f32 v[150:151], v[152:153], v[148:149]
	v_pk_fma_f32 v[212:213], v[172:173], s[34:35], v[174:175] op_sel_hi:[1,0,1] neg_lo:[0,0,1] neg_hi:[0,0,1]
	v_pk_add_f32 v[152:153], v[150:151], v[152:153] neg_lo:[0,1] neg_hi:[0,1]
	v_ldexp_f32 v147, v147, 1
	v_pk_add_f32 v[148:149], v[148:149], v[152:153] neg_lo:[0,1] neg_hi:[0,1]
	v_pk_fma_f32 v[172:173], v[172:173], s[36:37], v[212:213] op_sel_hi:[1,0,1]
	v_pk_add_f32 v[146:147], v[146:147], v[148:149]
	v_pk_add_f32 v[212:213], v[174:175], v[172:173]
	v_pk_add_f32 v[220:221], v[150:151], v[146:147]
	v_pk_add_f32 v[174:175], v[212:213], v[174:175] neg_lo:[0,1] neg_hi:[0,1]
	v_pk_add_f32 v[148:149], v[220:221], v[150:151] neg_lo:[0,1] neg_hi:[0,1]
	v_pk_add_f32 v[172:173], v[172:173], v[174:175] neg_lo:[0,1] neg_hi:[0,1]
	v_pk_add_f32 v[146:147], v[146:147], v[148:149] neg_lo:[0,1] neg_hi:[0,1]
	v_ashrrev_i32_e32 v167, 31, v166
	v_pk_add_f32 v[214:215], v[172:173], v[146:147]
	v_mov_b32_e32 v242, v190
	v_pk_add_f32 v[148:149], v[214:215], v[172:173] neg_lo:[0,1] neg_hi:[0,1]
	v_mov_b32_e32 v243, v176
	v_pk_add_f32 v[218:219], v[146:147], v[148:149] neg_lo:[0,1] neg_hi:[0,1]
	v_mov_b32_e32 v146, v234
	v_pk_add_f32 v[150:151], v[214:215], v[148:149] neg_lo:[0,1] neg_hi:[0,1]
	v_ashrrev_i32_e32 v147, 31, v146
	v_lshlrev_b64 v[146:147], 10, v[146:147]
	v_lshl_add_u64 v[146:147], v[146:147], 0, v[166:167]
	v_lshlrev_b64 v[148:149], 1, v[146:147]
	v_lshl_add_u64 v[174:175], s[24:25], 0, v[148:149]
	v_pk_add_f32 v[216:217], v[172:173], v[150:151] neg_lo:[0,1] neg_hi:[0,1]
	global_load_dwordx4 v[150:153], v[174:175], off
	v_lshl_add_u64 v[170:171], s[50:51], 0, v[146:147]
	v_add_co_u32_e32 v146, vcc, s84, v174
	v_lshl_add_u64 v[172:173], s[48:49], 0, v[148:149]
	s_nop 0
	v_addc_co_u32_e32 v147, vcc, 0, v175, vcc
	global_load_dwordx4 v[146:149], v[146:147], off
	v_cmp_neq_f32_e32 vcc, s73, v232
	v_add_f32_e32 v114, v114, v26
	v_add_f32_e32 v119, v119, v31
	v_mul_f32_e32 v114, 0xbfb8aa3b, v114
	v_mul_f32_e32 v119, 0xbfb8aa3b, v119
	v_exp_f32_e32 v114, v114
	v_exp_f32_e32 v119, v119
	v_add_f32_e32 v120, v120, v32
	v_add_f32_e32 v115, v115, v27
	v_add_f32_e32 v114, 1.0, v114
	v_add_f32_e32 v119, 1.0, v119
	v_rcp_f32_e32 v114, v114
	v_rcp_f32_e32 v119, v119
	v_mul_f32_e32 v120, 0xbfb8aa3b, v120
	v_mul_f32_e32 v115, 0xbfb8aa3b, v115
	v_exp_f32_e32 v120, v120
	v_exp_f32_e32 v115, v115
	v_add_f32_e32 v121, v121, v33
	v_add_f32_e32 v116, v116, v28
	v_add_f32_e32 v120, 1.0, v120
	v_add_f32_e32 v115, 1.0, v115
	v_rcp_f32_e32 v120, v120
	v_rcp_f32_e32 v115, v115
	v_mul_f32_e32 v121, 0xbfb8aa3b, v121
	v_mul_f32_e32 v116, 0xbfb8aa3b, v116
	v_exp_f32_e32 v121, v121
	v_exp_f32_e32 v116, v116
	v_add_f32_e32 v117, v117, v29
	v_mul_f32_e32 v117, 0xbfb8aa3b, v117
	v_add_f32_e32 v121, 1.0, v121
	v_add_f32_e32 v116, 1.0, v116
	v_rcp_f32_e32 v121, v121
	v_rcp_f32_e32 v116, v116
	v_exp_f32_e32 v117, v117
	s_waitcnt vmcnt(0) lgkmcnt(0)
	v_lshlrev_b32_e32 v241, 16, v150
	v_and_b32_e32 v246, 0xffff0000, v150
	v_rcp_f32_e32 v150, v138
	v_add_f32_e32 v138, v140, v44
	v_mul_f32_e32 v138, 0xbfb8aa3b, v138
	v_exp_f32_e32 v138, v138
	v_lshlrev_b32_e32 v247, 16, v151
	v_and_b32_e32 v248, 0xffff0000, v151
	v_add_f32_e32 v117, 1.0, v117
	v_add_f32_e32 v138, 1.0, v138
	v_rcp_f32_e32 v251, v138
	v_add_f32_e32 v138, v145, v49
	v_mul_f32_e32 v138, 0xbfb8aa3b, v138
	v_exp_f32_e32 v138, v138
	v_rcp_f32_e32 v117, v117
	v_add_f32_e32 v138, 1.0, v138
	v_rcp_f32_e32 v151, v138
	v_add_f32_e32 v138, v141, v45
	v_mul_f32_e32 v138, 0xbfb8aa3b, v138
	v_exp_f32_e32 v138, v138
	s_nop 0
	v_add_f32_e32 v138, 1.0, v138
	v_rcp_f32_e32 v252, v138
	v_pk_add_f32 v[138:139], v[176:177], v[190:191]
	s_nop 0
	v_pk_add_f32 v[140:141], v[138:139], v[176:177] neg_lo:[0,1] neg_hi:[0,1]
	v_mov_b32_e32 v176, v191
	v_pk_add_f32 v[144:145], v[138:139], v[140:141] neg_lo:[0,1] neg_hi:[0,1]
	v_mov_b32_e32 v244, v140
	v_mov_b32_e32 v245, v144
	v_mov_b32_e32 v144, v141
	v_pk_add_f32 v[242:243], v[242:243], v[244:245] neg_lo:[0,1] neg_hi:[0,1]
	v_pk_add_f32 v[140:141], v[176:177], v[144:145] neg_lo:[0,1] neg_hi:[0,1]
	v_pk_add_f32 v[242:243], v[242:243], v[242:243] op_sel:[0,1] op_sel_hi:[1,0]
	v_pk_add_f32 v[140:141], v[140:141], v[140:141] op_sel_hi:[0,1]
	v_mov_b32_e32 v243, v185
	v_mov_b32_e32 v185, v141
	v_pk_add_f32 v[140:141], v[242:243], v[184:185]
	v_pk_add_f32 v[176:177], v[188:189], v[186:187]
	v_pk_add_f32 v[144:145], v[138:139], v[140:141]
	s_nop 0
	v_pk_add_f32 v[138:139], v[144:145], v[138:139] neg_lo:[0,1] neg_hi:[0,1]
	s_nop 0
	v_pk_add_f32 v[138:139], v[140:141], v[138:139] neg_lo:[0,1] neg_hi:[0,1]
	s_nop 0
	v_pk_add_f32 v[138:139], v[176:177], v[138:139]
	v_mov_b32_e32 v176, v210
	v_pk_add_f32 v[138:139], v[144:145], v[138:139]
	v_mov_b32_e32 v177, v202
	v_cndmask_b32_e32 v138, v228, v138, vcc
	v_cmp_neq_f32_e32 vcc, s73, v233
	s_nop 1
	v_cndmask_b32_e32 v139, v228, v139, vcc
	v_cmp_ngt_f32_e32 vcc, -1.0, v233
	s_nop 1
	v_cndmask_b32_e32 v139, v229, v139, vcc
	v_cmp_ngt_f32_e32 vcc, -1.0, v232
	s_nop 1
	v_cndmask_b32_e32 v138, v229, v138, vcc
	v_cmp_neq_f32_e32 vcc, -1.0, v232
	s_nop 1
	v_cndmask_b32_e32 v138, v230, v138, vcc
	v_cmp_neq_f32_e32 vcc, -1.0, v233
	s_nop 1
	v_cndmask_b32_e32 v139, v230, v139, vcc
	v_cmp_lt_f32_e64 vcc, |v232|, s77
	v_cndmask_b32_e64 v139, v139, v233, s[14:15]
	v_cmp_lt_f32_e64 s[14:15], |v238|, s77
	v_cndmask_b32_e32 v138, v138, v232, vcc
	v_pk_add_f32 v[138:139], v[168:169], v[138:139] neg_lo:[0,1] neg_hi:[0,1]
	v_cmp_neq_f32_e32 vcc, s73, v236
	v_pk_mul_f32 v[144:145], v[138:139], s[38:39] op_sel_hi:[1,0]
	s_nop 0
	v_pk_mul_f32 v[138:139], v[142:143], v[144:145]
	v_mul_f32_e32 v126, v126, v144
	v_add_f32_e32 v140, v138, v138
	v_mul_f32_e32 v140, 0x3fb8aa3b, v140
	v_exp_f32_e32 v140, v140
	v_cvt_pk_bf16_f32 v138, v138, v139
	v_sub_f32_e32 v140, 1.0, v140
	v_max_f32_e32 v140, 0, v140
	v_sqrt_f32_e32 v140, v140
	s_nop 0
	v_mul_f32_e32 v140, v249, v140
	v_mul_f32_e32 v186, v140, v241
	v_add_f32_e32 v140, v139, v139
	v_mul_f32_e32 v140, 0x3fb8aa3b, v140
	v_exp_f32_e32 v140, v140
	s_nop 0
	v_sub_f32_e32 v140, 1.0, v140
	v_max_f32_e32 v140, 0, v140
	v_sqrt_f32_e32 v140, v140
	s_nop 0
	v_mul_f32_e32 v140, v250, v140
	v_mul_f32_e32 v187, v140, v246
	v_pk_add_f32 v[140:141], v[202:203], v[210:211]
	s_nop 0
	v_pk_add_f32 v[142:143], v[140:141], v[202:203] neg_lo:[0,1] neg_hi:[0,1]
	v_mov_b32_e32 v202, v211
	v_pk_add_f32 v[168:169], v[140:141], v[142:143] neg_lo:[0,1] neg_hi:[0,1]
	v_mov_b32_e32 v184, v142
	v_mov_b32_e32 v185, v168
	v_mov_b32_e32 v168, v143
	v_pk_add_f32 v[176:177], v[176:177], v[184:185] neg_lo:[0,1] neg_hi:[0,1]
	v_pk_add_f32 v[142:143], v[202:203], v[168:169] neg_lo:[0,1] neg_hi:[0,1]
	v_pk_add_f32 v[176:177], v[176:177], v[176:177] op_sel:[0,1] op_sel_hi:[1,0]
	v_pk_add_f32 v[142:143], v[142:143], v[142:143] op_sel_hi:[0,1]
	v_mov_b32_e32 v177, v205
	v_mov_b32_e32 v205, v143
	v_pk_add_f32 v[142:143], v[176:177], v[204:205]
	v_pk_add_f32 v[176:177], v[208:209], v[206:207]
	v_pk_add_f32 v[168:169], v[140:141], v[142:143]
	s_nop 0
	v_pk_add_f32 v[140:141], v[168:169], v[140:141] neg_lo:[0,1] neg_hi:[0,1]
	s_nop 0
	v_pk_add_f32 v[140:141], v[142:143], v[140:141] neg_lo:[0,1] neg_hi:[0,1]
	s_nop 0
	v_pk_add_f32 v[140:141], v[176:177], v[140:141]
	v_rcp_f32_e32 v177, v130
	v_add_f32_e32 v130, v135, v31
	v_pk_add_f32 v[140:141], v[168:169], v[140:141]
	v_mul_f32_e32 v130, 0xbfb8aa3b, v130
	v_cndmask_b32_e32 v139, v228, v140, vcc
	v_cmp_neq_f32_e32 vcc, s73, v238
	v_exp_f32_e32 v130, v130
	v_and_b32_e32 v176, 0xffff0000, v152
	v_cndmask_b32_e32 v140, v228, v141, vcc
	v_cmp_ngt_f32_e32 vcc, -1.0, v238
	v_add_f32_e32 v130, 1.0, v130
	v_rcp_f32_e32 v135, v130
	v_cndmask_b32_e32 v140, v229, v140, vcc
	v_cmp_ngt_f32_e32 vcc, -1.0, v236
	v_add_f32_e32 v130, v131, v27
	v_mul_f32_e32 v130, 0xbfb8aa3b, v130
	v_cndmask_b32_e32 v139, v229, v139, vcc
	v_cmp_neq_f32_e32 vcc, -1.0, v236
	v_exp_f32_e32 v130, v130
	s_nop 0
	v_cndmask_b32_e32 v139, v230, v139, vcc
	v_cmp_neq_f32_e32 vcc, -1.0, v238
	v_add_f32_e32 v130, 1.0, v130
	v_rcp_f32_e32 v184, v130
	v_cndmask_b32_e32 v140, v230, v140, vcc
	v_cmp_lt_f32_e64 vcc, |v236|, s77
	v_cndmask_b32_e64 v141, v140, v238, s[14:15]
	v_add_f32_e32 v130, v136, v32
	v_cndmask_b32_e32 v140, v139, v236, vcc
	v_pk_add_f32 v[140:141], v[180:181], v[140:141] neg_lo:[0,1] neg_hi:[0,1]
	v_mul_f32_e32 v130, 0xbfb8aa3b, v130
	v_pk_mul_f32 v[142:143], v[140:141], s[38:39] op_sel_hi:[1,0]
	v_exp_f32_e32 v130, v130
	v_pk_mul_f32 v[140:141], v[150:151], v[142:143]
	v_lshlrev_b32_e32 v180, 16, v153
	v_add_f32_e32 v139, v140, v140
	v_mul_f32_e32 v139, 0x3fb8aa3b, v139
	v_exp_f32_e32 v139, v139
	v_add_f32_e32 v130, 1.0, v130
	v_rcp_f32_e32 v136, v130
	v_add_f32_e32 v130, v132, v28
	v_sub_f32_e32 v139, 1.0, v139
	v_max_f32_e32 v139, 0, v139
	v_sqrt_f32_e32 v139, v139
	v_mul_f32_e32 v130, 0xbfb8aa3b, v130
	v_exp_f32_e32 v130, v130
	v_and_b32_e32 v181, 0xffff0000, v153
	v_mul_f32_e32 v139, v251, v139
	v_mul_f32_e32 v150, v139, v247
	v_add_f32_e32 v139, v141, v141
	v_mul_f32_e32 v139, 0x3fb8aa3b, v139
	v_exp_f32_e32 v139, v139
	v_add_f32_e32 v130, 1.0, v130
	v_rcp_f32_e32 v185, v130
	v_add_f32_e32 v130, v137, v33
	v_mul_f32_e32 v130, 0xbfb8aa3b, v130
	v_exp_f32_e32 v130, v130
	v_sub_f32_e32 v139, 1.0, v139
	v_max_f32_e32 v139, 0, v139
	v_sqrt_f32_e32 v139, v139
	v_add_f32_e32 v130, 1.0, v130
	v_rcp_f32_e32 v137, v130
	v_add_f32_e32 v130, v133, v29
	v_mul_f32_e32 v130, 0xbfb8aa3b, v130
	v_mul_f32_e32 v139, v252, v139
	v_exp_f32_e32 v130, v130
	v_mul_f32_e32 v151, v139, v248
	v_cvt_pk_bf16_f32 v139, v140, v141
	v_mul_f32_e32 v140, 0x42000000, v186
	v_mul_f32_e32 v141, 0x42000000, v187
	v_mul_f32_e32 v168, 0x42000000, v150
	v_med3_f32 v140, v140, s29, v231
	v_med3_f32 v141, v141, s29, v231
	v_mov_b32_e32 v150, 0
	v_cvt_pk_fp8_f32 v150, v140, v141
	v_add_f32_e32 v130, 1.0, v130
	v_mul_f32_e32 v151, 0x42000000, v151
	v_rcp_f32_e32 v186, v130
	v_pk_add_f32 v[130:131], v[192:193], v[200:201]
	v_med3_f32 v140, v168, s29, v231
	v_med3_f32 v141, v151, s29, v231
	v_pk_add_f32 v[132:133], v[130:131], v[192:193] neg_lo:[0,1] neg_hi:[0,1]
	v_cvt_pk_fp8_f32 v150, v140, v141 op_sel:[0,0,1]
	v_pk_add_f32 v[140:141], v[130:131], v[132:133] neg_lo:[0,1] neg_hi:[0,1]
	v_lshlrev_b32_e32 v151, 16, v152
	v_mov_b32_e32 v152, v200
	v_mov_b32_e32 v153, v192
	v_mov_b32_e32 v168, v132
	v_mov_b32_e32 v169, v140
	v_mov_b32_e32 v192, v201
	v_mov_b32_e32 v140, v133
	v_pk_add_f32 v[152:153], v[152:153], v[168:169] neg_lo:[0,1] neg_hi:[0,1]
	v_pk_add_f32 v[132:133], v[192:193], v[140:141] neg_lo:[0,1] neg_hi:[0,1]
	v_pk_add_f32 v[152:153], v[152:153], v[152:153] op_sel:[0,1] op_sel_hi:[1,0]
	v_pk_add_f32 v[132:133], v[132:133], v[132:133] op_sel_hi:[0,1]
	v_mov_b32_e32 v153, v195
	v_mov_b32_e32 v195, v133
	v_pk_add_f32 v[132:133], v[152:153], v[194:195]
	v_pk_add_f32 v[152:153], v[198:199], v[196:197]
	v_pk_add_f32 v[140:141], v[130:131], v[132:133]
	v_cmp_neq_f32_e32 vcc, s73, v235
	v_pk_add_f32 v[130:131], v[140:141], v[130:131] neg_lo:[0,1] neg_hi:[0,1]
	v_cmp_lt_f32_e64 s[14:15], |v237|, s77
	v_pk_add_f32 v[130:131], v[132:133], v[130:131] neg_lo:[0,1] neg_hi:[0,1]
	v_mov_b32_e32 v168, v220
	v_pk_add_f32 v[130:131], v[152:153], v[130:131]
	v_mov_b32_e32 v169, v212
	v_pk_add_f32 v[130:131], v[140:141], v[130:131]
	s_nop 0
	v_cndmask_b32_e32 v130, v228, v130, vcc
	v_cmp_neq_f32_e32 vcc, s73, v237
	s_nop 1
	v_cndmask_b32_e32 v131, v228, v131, vcc
	v_cmp_ngt_f32_e32 vcc, -1.0, v237
	s_nop 1
	v_cndmask_b32_e32 v131, v229, v131, vcc
	v_cmp_ngt_f32_e32 vcc, -1.0, v235
	s_nop 1
	v_cndmask_b32_e32 v130, v229, v130, vcc
	v_cmp_neq_f32_e32 vcc, -1.0, v235
	s_nop 1
	v_cndmask_b32_e32 v130, v230, v130, vcc
	v_cmp_neq_f32_e32 vcc, -1.0, v237
	s_nop 1
	v_cndmask_b32_e32 v131, v230, v131, vcc
	v_cmp_lt_f32_e64 vcc, |v235|, s77
	v_cndmask_b32_e64 v131, v131, v237, s[14:15]
	v_cmp_lt_f32_e64 s[14:15], |v240|, s77
	v_cndmask_b32_e32 v130, v130, v235, vcc
	v_pk_add_f32 v[130:131], v[178:179], v[130:131] neg_lo:[0,1] neg_hi:[0,1]
	v_cmp_neq_f32_e32 vcc, s73, v239
	v_pk_mul_f32 v[130:131], v[130:131], s[38:39] op_sel_hi:[1,0]
	s_nop 0
	v_pk_mul_f32 v[132:133], v[134:135], v[130:131]
	v_mul_f32_e32 v118, v118, v130
	v_add_f32_e32 v134, v132, v132
	v_mul_f32_e32 v134, 0x3fb8aa3b, v134
	v_exp_f32_e32 v134, v134
	v_cvt_pk_bf16_f32 v140, v132, v133
	v_mul_f32_e32 v119, v119, v131
	v_sub_f32_e32 v134, 1.0, v134
	v_max_f32_e32 v134, 0, v134
	v_sqrt_f32_e32 v134, v134
	s_nop 0
	v_mul_f32_e32 v134, v177, v134
	v_mul_f32_e32 v151, v134, v151
	v_add_f32_e32 v134, v133, v133
	v_mul_f32_e32 v134, 0x3fb8aa3b, v134
	v_exp_f32_e32 v134, v134
	v_pk_add_f32 v[132:133], v[212:213], v[220:221]
	v_sub_f32_e32 v134, 1.0, v134
	v_max_f32_e32 v134, 0, v134
	v_sqrt_f32_e32 v134, v134
	s_nop 0
	v_mul_f32_e32 v134, v184, v134
	v_mul_f32_e32 v178, v134, v176
	v_pk_add_f32 v[134:135], v[132:133], v[212:213] neg_lo:[0,1] neg_hi:[0,1]
	v_mov_b32_e32 v212, v221
	v_pk_add_f32 v[152:153], v[132:133], v[134:135] neg_lo:[0,1] neg_hi:[0,1]
	v_mov_b32_e32 v176, v134
	v_mov_b32_e32 v177, v152
	v_mov_b32_e32 v152, v135
	v_pk_add_f32 v[168:169], v[168:169], v[176:177] neg_lo:[0,1] neg_hi:[0,1]
	v_pk_add_f32 v[134:135], v[212:213], v[152:153] neg_lo:[0,1] neg_hi:[0,1]
	v_pk_add_f32 v[168:169], v[168:169], v[168:169] op_sel:[0,1] op_sel_hi:[1,0]
	v_pk_add_f32 v[134:135], v[134:135], v[134:135] op_sel_hi:[0,1]
	v_mov_b32_e32 v169, v215
	v_mov_b32_e32 v215, v135
	v_pk_add_f32 v[134:135], v[168:169], v[214:215]
	v_pk_add_f32 v[168:169], v[218:219], v[216:217]
	v_pk_add_f32 v[152:153], v[132:133], v[134:135]
	s_nop 0
	v_pk_add_f32 v[132:133], v[152:153], v[132:133] neg_lo:[0,1] neg_hi:[0,1]
	s_nop 0
	v_pk_add_f32 v[132:133], v[134:135], v[132:133] neg_lo:[0,1] neg_hi:[0,1]
	s_nop 0
	v_pk_add_f32 v[132:133], v[168:169], v[132:133]
	s_nop 0
	v_pk_add_f32 v[132:133], v[152:153], v[132:133]
	s_nop 0
	v_cndmask_b32_e32 v132, v228, v132, vcc
	v_cmp_neq_f32_e32 vcc, s73, v240
	s_nop 1
	v_cndmask_b32_e32 v133, v228, v133, vcc
	v_cmp_ngt_f32_e32 vcc, -1.0, v240
	s_nop 1
	v_cndmask_b32_e32 v133, v229, v133, vcc
	v_cmp_ngt_f32_e32 vcc, -1.0, v239
	s_nop 1
	v_cndmask_b32_e32 v132, v229, v132, vcc
	v_cmp_neq_f32_e32 vcc, -1.0, v239
	s_nop 1
	v_cndmask_b32_e32 v132, v230, v132, vcc
	v_cmp_neq_f32_e32 vcc, -1.0, v240
	s_nop 1
	v_cndmask_b32_e32 v133, v230, v133, vcc
	v_cmp_lt_f32_e64 vcc, |v239|, s77
	v_cndmask_b32_e64 v133, v133, v240, s[14:15]
	s_nop 0
	v_cndmask_b32_e32 v132, v132, v239, vcc
	v_pk_add_f32 v[132:133], v[182:183], v[132:133] neg_lo:[0,1] neg_hi:[0,1]
	s_nop 0
	v_pk_mul_f32 v[132:133], v[132:133], s[38:39] op_sel_hi:[1,0]
	s_nop 0
	v_pk_mul_f32 v[134:135], v[136:137], v[132:133]
	v_mul_f32_e32 v120, v120, v132
	v_add_f32_e32 v136, v134, v134
	v_add_f32_e32 v137, v135, v135
	v_mul_f32_e32 v136, 0x3fb8aa3b, v136
	v_mul_f32_e32 v137, 0x3fb8aa3b, v137
	v_exp_f32_e32 v136, v136
	v_exp_f32_e32 v137, v137
	v_cvt_pk_bf16_f32 v141, v134, v135
	v_mul_f32_e32 v134, 0x42000000, v151
	v_sub_f32_e32 v136, 1.0, v136
	v_sub_f32_e32 v137, 1.0, v137
	v_max_f32_e32 v136, 0, v136
	v_max_f32_e32 v137, 0, v137
	v_sqrt_f32_e32 v136, v136
	v_sqrt_f32_e32 v137, v137
	v_mul_f32_e32 v135, 0x42000000, v178
	v_med3_f32 v134, v134, s29, v231
	v_med3_f32 v135, v135, s29, v231
	v_mov_b32_e32 v151, 0
	v_mul_f32_e32 v136, v185, v136
	v_mul_f32_e32 v137, v186, v137
	v_cvt_pk_fp8_f32 v151, v134, v135
	v_mul_f32_e32 v136, v136, v180
	v_mul_f32_e32 v137, v137, v181
	v_mul_f32_e32 v136, 0x42000000, v136
	v_mul_f32_e32 v137, 0x42000000, v137
	v_med3_f32 v134, v136, s29, v231
	v_med3_f32 v135, v137, s29, v231
	v_cvt_pk_fp8_f32 v151, v134, v135 op_sel:[0,0,1]
	global_store_dwordx4 v[172:173], v[138:141], off
	global_store_dwordx2 v[170:171], v[150:151], off
	s_nop 0
	v_add_f32_e32 v138, v126, v126
	v_mul_f32_e32 v138, 0x3fb8aa3b, v138
	v_exp_f32_e32 v138, v138
	v_lshlrev_b32_e32 v134, 16, v146
	v_and_b32_e32 v135, 0xffff0000, v146
	v_lshlrev_b32_e32 v136, 16, v147
	v_sub_f32_e32 v138, 1.0, v138
	v_max_f32_e32 v138, 0, v138
	v_sqrt_f32_e32 v138, v138
	v_and_b32_e32 v137, 0xffff0000, v147
	v_mul_f32_e32 v121, v121, v133
	v_mul_f32_e32 v122, v122, v138
	v_mul_f32_e32 v134, v122, v134
	v_add_f32_e32 v122, v127, v47
	v_mul_f32_e32 v122, 0xbfb8aa3b, v122
	v_exp_f32_e32 v122, v122
	s_nop 0
	v_add_f32_e32 v122, 1.0, v122
	v_rcp_f32_e32 v122, v122
	s_nop 0
	v_mul_f32_e32 v122, v122, v145
	v_add_f32_e32 v127, v122, v122
	v_mul_f32_e32 v127, 0x3fb8aa3b, v127
	v_exp_f32_e32 v127, v127
	v_cvt_pk_bf16_f32 v122, v126, v122
	v_mul_f32_e32 v126, 0x42000000, v134
	v_sub_f32_e32 v127, 1.0, v127
	v_max_f32_e32 v127, 0, v127
	v_sqrt_f32_e32 v127, v127
	s_nop 0
	v_mul_f32_e32 v123, v123, v127
	v_mul_f32_e32 v127, v123, v135
	v_add_f32_e32 v123, v128, v48
	v_mul_f32_e32 v123, 0xbfb8aa3b, v123
	v_exp_f32_e32 v123, v123
	v_mul_f32_e32 v127, 0x42000000, v127
	v_med3_f32 v127, v127, s29, v231
	v_add_f32_e32 v123, 1.0, v123
	v_rcp_f32_e32 v123, v123
	s_nop 0
	v_mul_f32_e32 v123, v123, v142
	v_add_f32_e32 v128, v123, v123
	v_mul_f32_e32 v128, 0x3fb8aa3b, v128
	v_exp_f32_e32 v128, v128
	s_nop 0
	v_sub_f32_e32 v128, 1.0, v128
	v_max_f32_e32 v128, 0, v128
	v_sqrt_f32_e32 v128, v128
	s_nop 0
	v_mul_f32_e32 v124, v124, v128
	v_add_f32_e32 v128, v129, v49
	v_mul_f32_e32 v128, 0xbfb8aa3b, v128
	v_exp_f32_e32 v128, v128
	v_mul_f32_e32 v124, v124, v136
	v_mul_f32_e32 v124, 0x42000000, v124
	v_med3_f32 v124, v124, s29, v231
	v_add_f32_e32 v128, 1.0, v128
	v_rcp_f32_e32 v128, v128
	s_nop 0
	v_mul_f32_e32 v128, v128, v143
	v_add_f32_e32 v129, v128, v128
	v_mul_f32_e32 v129, 0x3fb8aa3b, v129
	v_exp_f32_e32 v129, v129
	v_cvt_pk_bf16_f32 v123, v123, v128
	v_med3_f32 v128, v126, s29, v231
	v_mov_b32_e32 v126, 0
	v_sub_f32_e32 v129, 1.0, v129
	v_max_f32_e32 v129, 0, v129
	v_sqrt_f32_e32 v129, v129
	v_cvt_pk_fp8_f32 v126, v128, v127
	v_lshlrev_b32_e32 v127, 16, v149
	v_and_b32_e32 v128, 0xffff0000, v149
	v_mul_f32_e32 v125, v125, v129
	v_add_f32_e32 v129, v118, v118
	v_mul_f32_e32 v129, 0x3fb8aa3b, v129
	v_exp_f32_e32 v129, v129
	v_mul_f32_e32 v125, v125, v137
	v_mul_f32_e32 v125, 0x42000000, v125
	v_med3_f32 v125, v125, s29, v231
	v_sub_f32_e32 v129, 1.0, v129
	v_max_f32_e32 v129, 0, v129
	v_sqrt_f32_e32 v129, v129
	v_cvt_pk_fp8_f32 v126, v124, v125 op_sel:[0,0,1]
	v_lshlrev_b32_e32 v124, 16, v148
	v_and_b32_e32 v125, 0xffff0000, v148
	v_mul_f32_e32 v114, v114, v129
	v_mul_f32_e32 v114, v114, v124
	v_add_f32_e32 v124, v119, v119
	v_mul_f32_e32 v124, 0x3fb8aa3b, v124
	v_exp_f32_e32 v124, v124
	v_mul_f32_e32 v114, 0x42000000, v114
	v_med3_f32 v114, v114, s29, v231
	v_sub_f32_e32 v124, 1.0, v124
	v_max_f32_e32 v124, 0, v124
	v_sqrt_f32_e32 v124, v124
	s_nop 0
	v_mul_f32_e32 v115, v115, v124
	v_add_f32_e32 v124, v120, v120
	v_mul_f32_e32 v124, 0x3fb8aa3b, v124
	v_exp_f32_e32 v124, v124
	v_mul_f32_e32 v115, v115, v125
	v_mul_f32_e32 v115, 0x42000000, v115
	v_med3_f32 v115, v115, s29, v231
	v_sub_f32_e32 v124, 1.0, v124
	v_max_f32_e32 v124, 0, v124
	v_sqrt_f32_e32 v124, v124
	v_cvt_pk_bf16_f32 v125, v120, v121
	v_mul_f32_e32 v116, v116, v124
	v_add_f32_e32 v124, v121, v121
	v_mul_f32_e32 v124, 0x3fb8aa3b, v124
	v_exp_f32_e32 v124, v124
	v_mul_f32_e32 v116, v116, v127
	v_mov_b32_e32 v127, 0
	v_cvt_pk_fp8_f32 v127, v114, v115
	v_sub_f32_e32 v124, 1.0, v124
	v_max_f32_e32 v124, 0, v124
	v_sqrt_f32_e32 v124, v124
	v_mul_f32_e32 v116, 0x42000000, v116
	v_med3_f32 v114, v116, s29, v231
	v_mul_f32_e32 v117, v117, v124
	v_mul_f32_e32 v117, v117, v128
	v_mul_f32_e32 v117, 0x42000000, v117
	v_med3_f32 v115, v117, s29, v231
	v_cvt_pk_fp8_f32 v127, v114, v115 op_sel:[0,0,1]
	v_add_co_u32_e32 v114, vcc, s84, v172
	v_cvt_pk_bf16_f32 v124, v118, v119
	s_nop 0
	v_addc_co_u32_e32 v115, vcc, 0, v173, vcc
	global_store_dwordx4 v[114:115], v[122:125], off
	v_add_co_u32_e32 v114, vcc, s93, v170
	s_nop 1
	v_addc_co_u32_e32 v115, vcc, 0, v171, vcc
	global_store_dwordx2 v[114:115], v[126:127], off
	v_add_co_u32_e32 v114, vcc, s92, v174
	v_add_f32_e32 v110, v110, v46
	s_nop 0
	v_addc_co_u32_e32 v115, vcc, 0, v175, vcc
	global_load_dwordx4 v[114:117], v[114:115], off
	v_mul_f32_e32 v110, 0xbfb8aa3b, v110
	v_add_f32_e32 v111, v111, v47
	v_exp_f32_e32 v110, v110
	v_mul_f32_e32 v111, 0xbfb8aa3b, v111
	v_exp_f32_e32 v111, v111
	v_add_f32_e32 v112, v112, v48
	v_add_f32_e32 v113, v113, v49
	v_add_f32_e32 v110, 1.0, v110
	v_mul_f32_e32 v112, 0xbfb8aa3b, v112
	v_mul_f32_e32 v113, 0xbfb8aa3b, v113
	v_rcp_f32_e32 v110, v110
	v_exp_f32_e32 v112, v112
	v_exp_f32_e32 v113, v113
	v_add_f32_e32 v111, 1.0, v111
	v_rcp_f32_e32 v111, v111
	v_add_co_u32_e32 v118, vcc, s89, v174
	v_add_f32_e32 v120, v106, v42
	s_nop 0
	v_addc_co_u32_e32 v119, vcc, 0, v175, vcc
	v_add_f32_e32 v122, v108, v44
	v_mul_f32_e32 v110, v110, v144
	v_add_f32_e32 v121, v107, v43
	v_add_f32_e32 v123, v109, v45
	global_load_dwordx4 v[106:109], v[118:119], off
	v_mul_f32_e32 v118, 0xbfb8aa3b, v120
	v_mul_f32_e32 v120, 0xbfb8aa3b, v122
	v_add_f32_e32 v112, 1.0, v112
	v_add_f32_e32 v113, 1.0, v113
	v_add_f32_e32 v122, v110, v110
	v_rcp_f32_e32 v112, v112
	v_rcp_f32_e32 v113, v113
	v_mul_f32_e32 v111, v111, v145
	v_mul_f32_e32 v122, 0x3fb8aa3b, v122
	v_mul_f32_e32 v119, 0xbfb8aa3b, v121
	v_mul_f32_e32 v121, 0xbfb8aa3b, v123
	v_add_f32_e32 v123, v111, v111
	v_exp_f32_e32 v122, v122
	v_exp_f32_e32 v118, v118
	v_mul_f32_e32 v123, 0x3fb8aa3b, v123
	v_exp_f32_e32 v123, v123
	v_exp_f32_e32 v119, v119
	v_mul_f32_e32 v112, v112, v142
	v_mul_f32_e32 v113, v113, v143
	v_add_f32_e32 v124, v112, v112
	v_add_f32_e32 v125, v113, v113
	v_sub_f32_e32 v122, 1.0, v122
	v_add_f32_e32 v118, 1.0, v118
	v_mul_f32_e32 v124, 0x3fb8aa3b, v124
	v_mul_f32_e32 v125, 0x3fb8aa3b, v125
	v_max_f32_e32 v122, 0, v122
	v_rcp_f32_e32 v118, v118
	v_exp_f32_e32 v124, v124
	v_exp_f32_e32 v125, v125
	v_sub_f32_e32 v123, 1.0, v123
	v_sqrt_f32_e32 v122, v122
	v_exp_f32_e32 v120, v120
	v_exp_f32_e32 v121, v121
	v_add_f32_e32 v119, 1.0, v119
	v_max_f32_e32 v123, 0, v123
	v_rcp_f32_e32 v119, v119
	v_sqrt_f32_e32 v123, v123
	v_add_f32_e32 v102, v102, v30
	v_mul_f32_e32 v102, 0xbfb8aa3b, v102
	v_sub_f32_e32 v124, 1.0, v124
	v_sub_f32_e32 v125, 1.0, v125
	v_mul_f32_e32 v118, v118, v122
	v_exp_f32_e32 v102, v102
	v_add_f32_e32 v120, 1.0, v120
	v_add_f32_e32 v121, 1.0, v121
	v_max_f32_e32 v124, 0, v124
	v_rcp_f32_e32 v120, v120
	v_rcp_f32_e32 v121, v121
	v_sqrt_f32_e32 v124, v124
	v_mul_f32_e32 v119, v119, v123
	v_cvt_pk_bf16_f32 v110, v110, v111
	v_cvt_pk_bf16_f32 v111, v112, v113
	v_add_f32_e32 v102, 1.0, v102
	v_rcp_f32_e32 v102, v102
	s_waitcnt vmcnt(0) lgkmcnt(0)
	v_lshlrev_b32_e32 v122, 16, v114
	v_mul_f32_e32 v118, v118, v122
	v_max_f32_e32 v122, 0, v125
	v_and_b32_e32 v114, 0xffff0000, v114
	v_sqrt_f32_e32 v122, v122
	v_mul_f32_e32 v114, v119, v114
	v_mul_f32_e32 v112, 0x42000000, v118
	v_mul_f32_e32 v113, 0x42000000, v114
	v_med3_f32 v112, v112, s29, v231
	v_med3_f32 v113, v113, s29, v231
	v_mov_b32_e32 v114, 0
	v_lshlrev_b32_e32 v123, 16, v115
	v_and_b32_e32 v115, 0xffff0000, v115
	v_mul_f32_e32 v119, v120, v124
	v_mul_f32_e32 v120, v121, v122
	v_cvt_pk_fp8_f32 v114, v112, v113
	v_mul_f32_e32 v119, v119, v123
	v_mul_f32_e32 v115, v120, v115
	v_mul_f32_e32 v118, 0x42000000, v119
	v_mul_f32_e32 v112, 0x42000000, v115
	v_med3_f32 v113, v118, s29, v231
	v_med3_f32 v112, v112, s29, v231
	v_mul_f32_e32 v102, v102, v130
	v_cvt_pk_fp8_f32 v114, v113, v112 op_sel:[0,0,1]
	v_lshlrev_b32_e32 v112, 16, v116
	v_and_b32_e32 v113, 0xffff0000, v116
	v_add_f32_e32 v116, v102, v102
	v_add_f32_e32 v103, v103, v31
	v_add_f32_e32 v98, v98, v26
	v_mul_f32_e32 v116, 0x3fb8aa3b, v116
	v_mul_f32_e32 v103, 0xbfb8aa3b, v103
	v_mul_f32_e32 v98, 0xbfb8aa3b, v98
	v_exp_f32_e32 v116, v116
	v_exp_f32_e32 v103, v103
	v_exp_f32_e32 v98, v98
	v_add_f32_e32 v104, v104, v32
	v_sub_f32_e32 v116, 1.0, v116
	v_add_f32_e32 v103, 1.0, v103
	v_add_f32_e32 v98, 1.0, v98
	v_max_f32_e32 v116, 0, v116
	v_rcp_f32_e32 v103, v103
	v_rcp_f32_e32 v98, v98
	v_sqrt_f32_e32 v116, v116
	v_add_f32_e32 v105, v105, v33
	v_mul_f32_e32 v103, v103, v131
	v_add_f32_e32 v99, v99, v27
	v_mul_f32_e32 v98, v98, v116
	v_add_f32_e32 v116, v103, v103
	v_mul_f32_e32 v116, 0x3fb8aa3b, v116
	v_mul_f32_e32 v104, 0xbfb8aa3b, v104
	v_mul_f32_e32 v105, 0xbfb8aa3b, v105
	v_mul_f32_e32 v99, 0xbfb8aa3b, v99
	v_exp_f32_e32 v116, v116
	v_exp_f32_e32 v104, v104
	v_exp_f32_e32 v105, v105
	v_exp_f32_e32 v99, v99
	v_sub_f32_e32 v116, 1.0, v116
	v_add_f32_e32 v104, 1.0, v104
	v_add_f32_e32 v105, 1.0, v105
	v_add_f32_e32 v99, 1.0, v99
	v_max_f32_e32 v116, 0, v116
	v_rcp_f32_e32 v104, v104
	v_rcp_f32_e32 v105, v105
	v_rcp_f32_e32 v99, v99
	v_sqrt_f32_e32 v116, v116
	v_mul_f32_e32 v104, v104, v132
	v_mul_f32_e32 v105, v105, v133
	v_mul_f32_e32 v98, v98, v112
	v_mul_f32_e32 v99, v99, v116
	v_add_f32_e32 v112, v104, v104
	v_add_f32_e32 v116, v105, v105
	v_add_f32_e32 v100, v100, v28
	v_mul_f32_e32 v112, 0x3fb8aa3b, v112
	v_add_f32_e32 v101, v101, v29
	v_mul_f32_e32 v116, 0x3fb8aa3b, v116
	v_mul_f32_e32 v100, 0xbfb8aa3b, v100
	v_exp_f32_e32 v112, v112
	v_mul_f32_e32 v101, 0xbfb8aa3b, v101
	v_exp_f32_e32 v116, v116
	v_add_f32_e32 v94, v94, v46
	v_exp_f32_e32 v100, v100
	v_exp_f32_e32 v101, v101
	v_mul_f32_e32 v94, 0xbfb8aa3b, v94
	v_exp_f32_e32 v94, v94
	v_sub_f32_e32 v112, 1.0, v112
	v_sub_f32_e32 v116, 1.0, v116
	v_add_f32_e32 v100, 1.0, v100
	v_max_f32_e32 v112, 0, v112
	v_add_f32_e32 v101, 1.0, v101
	v_max_f32_e32 v116, 0, v116
	v_rcp_f32_e32 v100, v100
	v_sqrt_f32_e32 v112, v112
	v_rcp_f32_e32 v101, v101
	v_sqrt_f32_e32 v116, v116
	v_add_f32_e32 v94, 1.0, v94
	v_rcp_f32_e32 v94, v94
	v_mul_f32_e32 v99, v99, v113
	v_lshlrev_b32_e32 v115, 16, v117
	v_and_b32_e32 v117, 0xffff0000, v117
	v_mul_f32_e32 v100, v100, v112
	v_mul_f32_e32 v101, v101, v116
	v_mul_f32_e32 v98, 0x42000000, v98
	v_mul_f32_e32 v99, 0x42000000, v99
	v_mul_f32_e32 v100, v100, v115
	v_mul_f32_e32 v101, v101, v117
	v_med3_f32 v98, v98, s29, v231
	v_med3_f32 v99, v99, s29, v231
	v_mov_b32_e32 v115, 0
	v_mul_f32_e32 v94, v94, v144
	v_cvt_pk_fp8_f32 v115, v98, v99
	v_mul_f32_e32 v98, 0x42000000, v101
	v_add_f32_e32 v101, v94, v94
	v_add_f32_e32 v95, v95, v47
	v_add_f32_e32 v90, v90, v42
	v_mul_f32_e32 v101, 0x3fb8aa3b, v101
	v_mul_f32_e32 v95, 0xbfb8aa3b, v95
	v_mul_f32_e32 v90, 0xbfb8aa3b, v90
	v_exp_f32_e32 v101, v101
	v_exp_f32_e32 v95, v95
	v_exp_f32_e32 v90, v90
	v_add_f32_e32 v91, v91, v43
	v_sub_f32_e32 v101, 1.0, v101
	v_add_f32_e32 v95, 1.0, v95
	v_add_f32_e32 v90, 1.0, v90
	v_max_f32_e32 v101, 0, v101
	v_rcp_f32_e32 v95, v95
	v_rcp_f32_e32 v90, v90
	v_sqrt_f32_e32 v101, v101
	v_add_f32_e32 v96, v96, v48
	v_mul_f32_e32 v95, v95, v145
	v_mul_f32_e32 v91, 0xbfb8aa3b, v91
	v_mul_f32_e32 v90, v90, v101
	v_add_f32_e32 v101, v95, v95
	v_mul_f32_e32 v101, 0x3fb8aa3b, v101
	v_exp_f32_e32 v101, v101
	v_mul_f32_e32 v96, 0xbfb8aa3b, v96
	v_add_f32_e32 v97, v97, v49
	v_exp_f32_e32 v91, v91
	v_exp_f32_e32 v96, v96
	v_mul_f32_e32 v97, 0xbfb8aa3b, v97
	v_exp_f32_e32 v97, v97
	v_mul_f32_e32 v100, 0x42000000, v100
	v_med3_f32 v99, v100, s29, v231
	v_med3_f32 v98, v98, s29, v231
	v_sub_f32_e32 v101, 1.0, v101
	v_add_f32_e32 v92, v92, v44
	v_cvt_pk_fp8_f32 v115, v99, v98 op_sel:[0,0,1]
	v_add_co_u32_e32 v98, vcc, s92, v172
	v_add_f32_e32 v91, 1.0, v91
	v_max_f32_e32 v101, 0, v101
	v_add_f32_e32 v96, 1.0, v96
	v_mul_f32_e32 v92, 0xbfb8aa3b, v92
	v_cvt_pk_bf16_f32 v112, v102, v103
	v_cvt_pk_bf16_f32 v113, v104, v105
	v_addc_co_u32_e32 v99, vcc, 0, v173, vcc
	v_rcp_f32_e32 v91, v91
	v_sqrt_f32_e32 v101, v101
	v_exp_f32_e32 v92, v92
	v_rcp_f32_e32 v96, v96
	v_add_f32_e32 v97, 1.0, v97
	global_store_dwordx4 v[98:99], v[110:113], off
	v_add_co_u32_e32 v98, vcc, s84, v170
	v_rcp_f32_e32 v97, v97
	s_nop 0
	v_addc_co_u32_e32 v99, vcc, 0, v171, vcc
	global_store_dwordx2 v[98:99], v[114:115], off
	v_lshlrev_b32_e32 v98, 16, v106
	v_mul_f32_e32 v98, v90, v98
	v_mul_f32_e32 v90, v91, v101
	v_add_f32_e32 v91, 1.0, v92
	v_mul_f32_e32 v92, v96, v142
	v_add_f32_e32 v96, v92, v92
	v_mul_f32_e32 v97, v97, v143
	v_mul_f32_e32 v96, 0x3fb8aa3b, v96
	v_add_f32_e32 v101, v97, v97
	v_exp_f32_e32 v96, v96
	v_add_f32_e32 v93, v93, v45
	v_mul_f32_e32 v101, 0x3fb8aa3b, v101
	v_mul_f32_e32 v93, 0xbfb8aa3b, v93
	v_exp_f32_e32 v101, v101
	v_exp_f32_e32 v93, v93
	v_add_f32_e32 v86, v86, v30
	v_mul_f32_e32 v86, 0xbfb8aa3b, v86
	v_sub_f32_e32 v96, 1.0, v96
	v_exp_f32_e32 v86, v86
	v_max_f32_e32 v96, 0, v96
	v_sub_f32_e32 v101, 1.0, v101
	v_rcp_f32_e32 v91, v91
	v_sqrt_f32_e32 v96, v96
	v_add_f32_e32 v93, 1.0, v93
	v_max_f32_e32 v101, 0, v101
	v_rcp_f32_e32 v93, v93
	v_sqrt_f32_e32 v101, v101
	v_add_f32_e32 v86, 1.0, v86
	v_and_b32_e32 v99, 0xffff0000, v106
	v_rcp_f32_e32 v86, v86
	v_lshlrev_b32_e32 v100, 16, v107
	v_mul_f32_e32 v99, v90, v99
	v_mul_f32_e32 v90, v91, v96
	v_and_b32_e32 v102, 0xffff0000, v107
	v_mul_f32_e32 v96, v90, v100
	v_mul_f32_e32 v90, v93, v101
	v_mul_f32_e32 v93, v90, v102
	v_cvt_pk_bf16_f32 v90, v94, v95
	v_cvt_pk_bf16_f32 v91, v92, v97
	v_mul_f32_e32 v92, 0x42000000, v98
	v_mul_f32_e32 v94, 0x42000000, v99
	v_mul_f32_e32 v95, 0x42000000, v96
	v_med3_f32 v92, v92, s29, v231
	v_med3_f32 v96, v94, s29, v231
	v_mov_b32_e32 v94, 0
	v_mul_f32_e32 v86, v86, v130
	v_cvt_pk_fp8_f32 v94, v92, v96
	v_add_f32_e32 v96, v86, v86
	v_add_f32_e32 v87, v87, v31
	v_add_f32_e32 v82, v82, v26
	v_mul_f32_e32 v96, 0x3fb8aa3b, v96
	v_mul_f32_e32 v87, 0xbfb8aa3b, v87
	v_mul_f32_e32 v82, 0xbfb8aa3b, v82
	v_exp_f32_e32 v96, v96
	v_exp_f32_e32 v87, v87
	v_exp_f32_e32 v82, v82
	v_add_f32_e32 v88, v88, v32
	v_sub_f32_e32 v96, 1.0, v96
	v_add_f32_e32 v87, 1.0, v87
	v_add_f32_e32 v82, 1.0, v82
	v_max_f32_e32 v96, 0, v96
	v_rcp_f32_e32 v87, v87
	v_rcp_f32_e32 v82, v82
	v_sqrt_f32_e32 v96, v96
	v_mul_f32_e32 v88, 0xbfb8aa3b, v88
	v_mul_f32_e32 v87, v87, v131
	v_exp_f32_e32 v88, v88
	v_mul_f32_e32 v82, v82, v96
	v_add_f32_e32 v96, v87, v87
	v_add_f32_e32 v89, v89, v33
	v_add_f32_e32 v83, v83, v27
	v_mul_f32_e32 v96, 0x3fb8aa3b, v96
	v_mul_f32_e32 v89, 0xbfb8aa3b, v89
	v_mul_f32_e32 v83, 0xbfb8aa3b, v83
	v_exp_f32_e32 v96, v96
	v_exp_f32_e32 v89, v89
	v_exp_f32_e32 v83, v83
	v_add_f32_e32 v88, 1.0, v88
	v_rcp_f32_e32 v88, v88
	v_sub_f32_e32 v96, 1.0, v96
	v_add_f32_e32 v89, 1.0, v89
	v_mul_f32_e32 v92, 0x42000000, v93
	v_add_f32_e32 v83, 1.0, v83
	v_max_f32_e32 v96, 0, v96
	v_rcp_f32_e32 v89, v89
	v_med3_f32 v93, v95, s29, v231
	v_med3_f32 v92, v92, s29, v231
	v_rcp_f32_e32 v83, v83
	v_sqrt_f32_e32 v96, v96
	v_cvt_pk_fp8_f32 v94, v93, v92 op_sel:[0,0,1]
	v_lshlrev_b32_e32 v92, 16, v108
	v_mul_f32_e32 v88, v88, v132
	v_mul_f32_e32 v82, v82, v92
	v_add_f32_e32 v92, v88, v88
	v_add_f32_e32 v84, v84, v28
	v_mul_f32_e32 v92, 0x3fb8aa3b, v92
	v_mul_f32_e32 v89, v89, v133
	v_mul_f32_e32 v84, 0xbfb8aa3b, v84
	v_mul_f32_e32 v83, v83, v96
	v_exp_f32_e32 v92, v92
	v_add_f32_e32 v96, v89, v89
	v_exp_f32_e32 v84, v84
	v_add_f32_e32 v85, v85, v29
	v_mul_f32_e32 v96, 0x3fb8aa3b, v96
	v_mul_f32_e32 v85, 0xbfb8aa3b, v85
	v_exp_f32_e32 v96, v96
	v_exp_f32_e32 v85, v85
	v_sub_f32_e32 v92, 1.0, v92
	v_add_f32_e32 v84, 1.0, v84
	v_max_f32_e32 v92, 0, v92
	v_rcp_f32_e32 v84, v84
	v_sqrt_f32_e32 v92, v92
	v_sub_f32_e32 v96, 1.0, v96
	v_add_f32_e32 v85, 1.0, v85
	v_max_f32_e32 v96, 0, v96
	v_and_b32_e32 v93, 0xffff0000, v108
	v_rcp_f32_e32 v85, v85
	v_sqrt_f32_e32 v96, v96
	v_mul_f32_e32 v83, v83, v93
	v_lshlrev_b32_e32 v95, 16, v109
	v_mul_f32_e32 v84, v84, v92
	v_mul_f32_e32 v82, 0x42000000, v82
	v_mul_f32_e32 v83, 0x42000000, v83
	v_mul_f32_e32 v84, v84, v95
	v_med3_f32 v82, v82, s29, v231
	v_med3_f32 v83, v83, s29, v231
	v_mov_b32_e32 v95, 0
	v_and_b32_e32 v97, 0xffff0000, v109
	v_mul_f32_e32 v85, v85, v96
	v_cvt_pk_fp8_f32 v95, v82, v83
	v_mul_f32_e32 v85, v85, v97
	v_mul_f32_e32 v84, 0x42000000, v84
	v_mul_f32_e32 v82, 0x42000000, v85
	v_med3_f32 v83, v84, s29, v231
	v_med3_f32 v82, v82, s29, v231
	v_cvt_pk_fp8_f32 v95, v83, v82 op_sel:[0,0,1]
	v_add_co_u32_e32 v82, vcc, s89, v172
	v_cvt_pk_bf16_f32 v92, v86, v87
	v_cvt_pk_bf16_f32 v93, v88, v89
	v_addc_co_u32_e32 v83, vcc, 0, v173, vcc
	s_mov_b32 s0, 0xc000
	global_store_dwordx4 v[82:83], v[90:93], off
	v_add_co_u32_e32 v82, vcc, s0, v170
	s_nop 1
	v_addc_co_u32_e32 v83, vcc, 0, v171, vcc
	global_store_dwordx2 v[82:83], v[94:95], off
	v_add_u32_e32 v82, 0x80, v234
	v_add_f32_e32 v78, v78, v46
	v_ashrrev_i32_e32 v83, 31, v82
	v_lshlrev_b64 v[82:83], 10, v[82:83]
	v_lshl_add_u64 v[88:89], v[82:83], 0, v[166:167]
	v_lshlrev_b64 v[90:91], 1, v[88:89]
	v_lshl_add_u64 v[82:83], s[24:25], 0, v[90:91]
	global_load_dwordx4 v[84:87], v[82:83], off
	v_mul_f32_e32 v78, 0xbfb8aa3b, v78
	v_exp_f32_e32 v92, v78
	v_add_f32_e32 v79, v79, v47
	v_add_f32_e32 v80, v80, v48
	v_mul_f32_e32 v79, 0xbfb8aa3b, v79
	v_add_f32_e32 v74, v74, v42
	v_add_f32_e32 v81, v81, v49
	v_mul_f32_e32 v80, 0xbfb8aa3b, v80
	v_exp_f32_e32 v93, v79
	v_add_f32_e32 v75, v75, v43
	v_add_f32_e32 v76, v76, v44
	v_add_f32_e32 v77, v77, v45
	v_mul_f32_e32 v74, 0xbfb8aa3b, v74
	v_mul_f32_e32 v81, 0xbfb8aa3b, v81
	v_exp_f32_e32 v94, v80
	v_lshl_add_u64 v[78:79], s[50:51], 0, v[88:89]
	v_add_f32_e32 v88, 1.0, v92
	v_mul_f32_e32 v75, 0xbfb8aa3b, v75
	v_mul_f32_e32 v76, 0xbfb8aa3b, v76
	v_mul_f32_e32 v77, 0xbfb8aa3b, v77
	v_exp_f32_e32 v74, v74
	v_exp_f32_e32 v95, v81
	v_rcp_f32_e32 v88, v88
	v_exp_f32_e32 v75, v75
	v_exp_f32_e32 v76, v76
	v_exp_f32_e32 v77, v77
	v_lshl_add_u64 v[80:81], s[48:49], 0, v[90:91]
	v_add_f32_e32 v90, 1.0, v93
	v_add_f32_e32 v92, 1.0, v94
	v_rcp_f32_e32 v90, v90
	v_add_f32_e32 v89, 1.0, v74
	v_add_f32_e32 v93, 1.0, v95
	v_add_co_u32_e32 v74, vcc, s84, v82
	v_rcp_f32_e32 v92, v92
	v_mul_f32_e32 v88, v88, v144
	v_add_f32_e32 v91, 1.0, v75
	v_add_f32_e32 v76, 1.0, v76
	v_add_f32_e32 v77, 1.0, v77
	v_addc_co_u32_e32 v75, vcc, 0, v83, vcc
	v_rcp_f32_e32 v93, v93
	v_add_f32_e32 v96, v88, v88
	v_rcp_f32_e32 v94, v76
	v_rcp_f32_e32 v95, v77
	global_load_dwordx4 v[74:77], v[74:75], off
	v_mul_f32_e32 v96, 0x3fb8aa3b, v96
	v_mul_f32_e32 v90, v90, v145
	v_exp_f32_e32 v96, v96
	v_mul_f32_e32 v92, v92, v142
	v_add_f32_e32 v97, v90, v90
	v_mul_f32_e32 v93, v93, v143
	v_add_f32_e32 v98, v92, v92
	v_mul_f32_e32 v97, 0x3fb8aa3b, v97
	v_add_f32_e32 v99, v93, v93
	v_mul_f32_e32 v98, 0x3fb8aa3b, v98
	v_exp_f32_e32 v97, v97
	v_mul_f32_e32 v99, 0x3fb8aa3b, v99
	v_exp_f32_e32 v98, v98
	v_sub_f32_e32 v96, 1.0, v96
	v_exp_f32_e32 v99, v99
	v_max_f32_e32 v96, 0, v96
	v_rcp_f32_e32 v89, v89
	v_sqrt_f32_e32 v96, v96
	v_add_f32_e32 v70, v70, v30
	v_sub_f32_e32 v97, 1.0, v97
	v_mul_f32_e32 v70, 0xbfb8aa3b, v70
	v_sub_f32_e32 v98, 1.0, v98
	v_max_f32_e32 v97, 0, v97
	v_exp_f32_e32 v70, v70
	v_rcp_f32_e32 v91, v91
	v_sub_f32_e32 v99, 1.0, v99
	v_max_f32_e32 v98, 0, v98
	v_sqrt_f32_e32 v97, v97
	v_max_f32_e32 v99, 0, v99
	v_sqrt_f32_e32 v98, v98
	v_mul_f32_e32 v89, v89, v96
	v_add_f32_e32 v70, 1.0, v70
	v_mul_f32_e32 v91, v91, v97
	s_waitcnt vmcnt(0) lgkmcnt(0)
	v_lshlrev_b32_e32 v96, 16, v84
	v_mul_f32_e32 v89, v89, v96
	v_sqrt_f32_e32 v96, v99
	v_and_b32_e32 v84, 0xffff0000, v84
	v_rcp_f32_e32 v70, v70
	v_lshlrev_b32_e32 v97, 16, v85
	v_mul_f32_e32 v91, v91, v84
	v_mul_f32_e32 v84, v94, v98
	v_and_b32_e32 v85, 0xffff0000, v85
	v_mul_f32_e32 v94, v84, v97
	v_mul_f32_e32 v84, v95, v96
	v_mul_f32_e32 v95, v84, v85
	v_cvt_pk_bf16_f32 v84, v88, v90
	v_mul_f32_e32 v88, 0x42000000, v89
	v_mul_f32_e32 v89, 0x42000000, v91
	v_med3_f32 v91, v88, s29, v231
	v_med3_f32 v89, v89, s29, v231
	v_mov_b32_e32 v88, 0
	v_mul_f32_e32 v70, v70, v130
	v_cvt_pk_fp8_f32 v88, v91, v89
	v_add_f32_e32 v91, v70, v70
	v_add_f32_e32 v71, v71, v31
	v_add_f32_e32 v66, v66, v26
	v_mul_f32_e32 v91, 0x3fb8aa3b, v91
	v_mul_f32_e32 v71, 0xbfb8aa3b, v71
	v_mul_f32_e32 v66, 0xbfb8aa3b, v66
	v_exp_f32_e32 v91, v91
	v_exp_f32_e32 v71, v71
	v_exp_f32_e32 v66, v66
	v_add_f32_e32 v73, v73, v33
	v_sub_f32_e32 v91, 1.0, v91
	v_add_f32_e32 v71, 1.0, v71
	v_add_f32_e32 v66, 1.0, v66
	v_max_f32_e32 v91, 0, v91
	v_rcp_f32_e32 v71, v71
	v_rcp_f32_e32 v66, v66
	v_sqrt_f32_e32 v91, v91
	v_add_f32_e32 v67, v67, v27
	v_mul_f32_e32 v71, v71, v131
	v_add_f32_e32 v72, v72, v32
	v_mul_f32_e32 v66, v66, v91
	v_add_f32_e32 v91, v71, v71
	v_mul_f32_e32 v91, 0x3fb8aa3b, v91
	v_mul_f32_e32 v73, 0xbfb8aa3b, v73
	v_mul_f32_e32 v67, 0xbfb8aa3b, v67
	v_exp_f32_e32 v91, v91
	v_mul_f32_e32 v72, 0xbfb8aa3b, v72
	v_exp_f32_e32 v73, v73
	v_exp_f32_e32 v67, v67
	v_exp_f32_e32 v72, v72
	v_sub_f32_e32 v91, 1.0, v91
	v_add_f32_e32 v73, 1.0, v73
	v_add_f32_e32 v67, 1.0, v67
	v_max_f32_e32 v91, 0, v91
	v_add_f32_e32 v72, 1.0, v72
	v_rcp_f32_e32 v73, v73
	v_rcp_f32_e32 v67, v67
	v_sqrt_f32_e32 v91, v91
	v_rcp_f32_e32 v72, v72
	v_mul_f32_e32 v90, 0x42000000, v94
	v_mul_f32_e32 v89, 0x42000000, v95
	v_med3_f32 v90, v90, s29, v231
	v_med3_f32 v89, v89, s29, v231
	v_mul_f32_e32 v73, v73, v133
	v_cvt_pk_fp8_f32 v88, v90, v89 op_sel:[0,0,1]
	v_lshlrev_b32_e32 v89, 16, v86
	v_mul_f32_e32 v67, v67, v91
	v_mul_f32_e32 v72, v72, v132
	v_add_f32_e32 v91, v73, v73
	v_mul_f32_e32 v66, v66, v89
	v_add_f32_e32 v89, v72, v72
	v_add_f32_e32 v69, v69, v29
	v_mul_f32_e32 v91, 0x3fb8aa3b, v91
	v_add_f32_e32 v68, v68, v28
	v_mul_f32_e32 v89, 0x3fb8aa3b, v89
	v_mul_f32_e32 v69, 0xbfb8aa3b, v69
	v_exp_f32_e32 v91, v91
	v_add_f32_e32 v62, v62, v46
	v_mul_f32_e32 v68, 0xbfb8aa3b, v68
	v_exp_f32_e32 v89, v89
	v_exp_f32_e32 v69, v69
	v_mul_f32_e32 v62, 0xbfb8aa3b, v62
	v_exp_f32_e32 v68, v68
	v_exp_f32_e32 v62, v62
	v_sub_f32_e32 v91, 1.0, v91
	v_sub_f32_e32 v89, 1.0, v89
	v_add_f32_e32 v69, 1.0, v69
	v_max_f32_e32 v91, 0, v91
	v_add_f32_e32 v68, 1.0, v68
	v_max_f32_e32 v89, 0, v89
	v_rcp_f32_e32 v69, v69
	v_sqrt_f32_e32 v91, v91
	v_add_f32_e32 v62, 1.0, v62
	v_rcp_f32_e32 v68, v68
	v_sqrt_f32_e32 v89, v89
	v_rcp_f32_e32 v62, v62
	v_and_b32_e32 v86, 0xffff0000, v86
	v_mul_f32_e32 v67, v67, v86
	v_lshlrev_b32_e32 v90, 16, v87
	v_and_b32_e32 v87, 0xffff0000, v87
	v_mul_f32_e32 v69, v69, v91
	v_mul_f32_e32 v66, 0x42000000, v66
	v_mul_f32_e32 v67, 0x42000000, v67
	v_mul_f32_e32 v68, v68, v89
	v_mul_f32_e32 v69, v69, v87
	v_med3_f32 v66, v66, s29, v231
	v_med3_f32 v67, v67, s29, v231
	v_mov_b32_e32 v89, 0
	v_mul_f32_e32 v62, v62, v144
	v_cvt_pk_fp8_f32 v89, v66, v67
	v_mul_f32_e32 v66, 0x42000000, v69
	v_add_f32_e32 v69, v62, v62
	v_add_f32_e32 v63, v63, v47
	v_add_f32_e32 v58, v58, v42
	v_mul_f32_e32 v69, 0x3fb8aa3b, v69
	v_mul_f32_e32 v63, 0xbfb8aa3b, v63
	v_mul_f32_e32 v58, 0xbfb8aa3b, v58
	v_exp_f32_e32 v69, v69
	v_exp_f32_e32 v63, v63
	v_exp_f32_e32 v58, v58
	v_add_f32_e32 v59, v59, v43
	v_sub_f32_e32 v69, 1.0, v69
	v_add_f32_e32 v63, 1.0, v63
	v_add_f32_e32 v58, 1.0, v58
	v_max_f32_e32 v69, 0, v69
	v_rcp_f32_e32 v63, v63
	v_rcp_f32_e32 v58, v58
	v_sqrt_f32_e32 v69, v69
	v_add_f32_e32 v64, v64, v48
	v_mul_f32_e32 v63, v63, v145
	v_mul_f32_e32 v59, 0xbfb8aa3b, v59
	v_mul_f32_e32 v58, v58, v69
	v_add_f32_e32 v69, v63, v63
	v_mul_f32_e32 v69, 0x3fb8aa3b, v69
	v_exp_f32_e32 v69, v69
	v_mul_f32_e32 v64, 0xbfb8aa3b, v64
	v_add_f32_e32 v65, v65, v49
	v_exp_f32_e32 v59, v59
	v_exp_f32_e32 v64, v64
	v_mul_f32_e32 v65, 0xbfb8aa3b, v65
	v_exp_f32_e32 v65, v65
	v_sub_f32_e32 v69, 1.0, v69
	v_add_f32_e32 v60, v60, v44
	v_add_f32_e32 v59, 1.0, v59
	v_max_f32_e32 v69, 0, v69
	v_add_f32_e32 v64, 1.0, v64
	v_mul_f32_e32 v60, 0xbfb8aa3b, v60
	v_mul_f32_e32 v68, v68, v90
	v_rcp_f32_e32 v59, v59
	v_sqrt_f32_e32 v69, v69
	v_exp_f32_e32 v60, v60
	v_rcp_f32_e32 v64, v64
	v_add_f32_e32 v65, 1.0, v65
	v_mul_f32_e32 v68, 0x42000000, v68
	v_rcp_f32_e32 v65, v65
	v_med3_f32 v67, v68, s29, v231
	v_med3_f32 v66, v66, s29, v231
	v_cvt_pk_fp8_f32 v89, v67, v66 op_sel:[0,0,1]
	v_lshlrev_b32_e32 v66, 16, v74
	v_mul_f32_e32 v66, v58, v66
	v_mul_f32_e32 v58, v59, v69
	v_add_f32_e32 v59, 1.0, v60
	v_mul_f32_e32 v60, v64, v142
	v_add_f32_e32 v64, v60, v60
	v_mul_f32_e32 v65, v65, v143
	v_mul_f32_e32 v64, 0x3fb8aa3b, v64
	v_add_f32_e32 v69, v65, v65
	v_exp_f32_e32 v64, v64
	v_add_f32_e32 v61, v61, v45
	v_mul_f32_e32 v69, 0x3fb8aa3b, v69
	v_mul_f32_e32 v61, 0xbfb8aa3b, v61
	v_exp_f32_e32 v69, v69
	v_exp_f32_e32 v61, v61
	v_add_f32_e32 v54, v54, v30
	v_mul_f32_e32 v54, 0xbfb8aa3b, v54
	v_sub_f32_e32 v64, 1.0, v64
	v_exp_f32_e32 v54, v54
	v_max_f32_e32 v64, 0, v64
	v_sub_f32_e32 v69, 1.0, v69
	v_rcp_f32_e32 v59, v59
	v_sqrt_f32_e32 v64, v64
	v_add_f32_e32 v61, 1.0, v61
	v_max_f32_e32 v69, 0, v69
	v_rcp_f32_e32 v61, v61
	v_sqrt_f32_e32 v69, v69
	v_add_f32_e32 v54, 1.0, v54
	v_and_b32_e32 v67, 0xffff0000, v74
	v_rcp_f32_e32 v54, v54
	v_lshlrev_b32_e32 v68, 16, v75
	v_mul_f32_e32 v67, v58, v67
	v_mul_f32_e32 v58, v59, v64
	v_cvt_pk_bf16_f32 v86, v70, v71
	v_and_b32_e32 v70, 0xffff0000, v75
	v_mul_f32_e32 v64, v58, v68
	v_mul_f32_e32 v58, v61, v69
	v_mul_f32_e32 v61, v58, v70
	v_cvt_pk_bf16_f32 v58, v62, v63
	v_cvt_pk_bf16_f32 v59, v60, v65
	v_mul_f32_e32 v60, 0x42000000, v66
	v_mul_f32_e32 v62, 0x42000000, v67
	v_mul_f32_e32 v63, 0x42000000, v64
	v_med3_f32 v60, v60, s29, v231
	v_med3_f32 v64, v62, s29, v231
	v_mov_b32_e32 v62, 0
	v_mul_f32_e32 v54, v54, v130
	v_cvt_pk_fp8_f32 v62, v60, v64
	v_add_f32_e32 v64, v54, v54
	v_add_f32_e32 v55, v55, v31
	v_add_f32_e32 v50, v50, v26
	v_mul_f32_e32 v64, 0x3fb8aa3b, v64
	v_mul_f32_e32 v55, 0xbfb8aa3b, v55
	v_mul_f32_e32 v50, 0xbfb8aa3b, v50
	v_exp_f32_e32 v64, v64
	v_exp_f32_e32 v55, v55
	v_exp_f32_e32 v50, v50
	v_add_f32_e32 v56, v56, v32
	v_sub_f32_e32 v64, 1.0, v64
	v_add_f32_e32 v55, 1.0, v55
	v_add_f32_e32 v50, 1.0, v50
	v_max_f32_e32 v64, 0, v64
	v_rcp_f32_e32 v55, v55
	v_rcp_f32_e32 v50, v50
	v_sqrt_f32_e32 v64, v64
	v_mul_f32_e32 v56, 0xbfb8aa3b, v56
	v_mul_f32_e32 v55, v55, v131
	v_exp_f32_e32 v56, v56
	v_mul_f32_e32 v50, v50, v64
	v_add_f32_e32 v64, v55, v55
	v_add_f32_e32 v57, v57, v33
	v_add_f32_e32 v51, v51, v27
	v_mul_f32_e32 v64, 0x3fb8aa3b, v64
	v_mul_f32_e32 v57, 0xbfb8aa3b, v57
	v_mul_f32_e32 v51, 0xbfb8aa3b, v51
	v_exp_f32_e32 v64, v64
	v_exp_f32_e32 v57, v57
	v_exp_f32_e32 v51, v51
	v_add_f32_e32 v56, 1.0, v56
	v_rcp_f32_e32 v56, v56
	v_sub_f32_e32 v64, 1.0, v64
	v_add_f32_e32 v57, 1.0, v57
	v_mul_f32_e32 v60, 0x42000000, v61
	v_add_f32_e32 v51, 1.0, v51
	v_max_f32_e32 v64, 0, v64
	v_rcp_f32_e32 v57, v57
	v_med3_f32 v61, v63, s29, v231
	v_med3_f32 v60, v60, s29, v231
	v_rcp_f32_e32 v51, v51
	v_sqrt_f32_e32 v64, v64
	v_cvt_pk_fp8_f32 v62, v61, v60 op_sel:[0,0,1]
	v_lshlrev_b32_e32 v60, 16, v76
	v_mul_f32_e32 v56, v56, v132
	v_mul_f32_e32 v50, v50, v60
	v_add_f32_e32 v60, v56, v56
	v_add_f32_e32 v52, v52, v28
	v_mul_f32_e32 v60, 0x3fb8aa3b, v60
	v_mul_f32_e32 v57, v57, v133
	v_mul_f32_e32 v52, 0xbfb8aa3b, v52
	v_mul_f32_e32 v51, v51, v64
	v_exp_f32_e32 v60, v60
	v_add_f32_e32 v64, v57, v57
	v_exp_f32_e32 v52, v52
	v_add_f32_e32 v53, v53, v29
	v_mul_f32_e32 v64, 0x3fb8aa3b, v64
	v_mul_f32_e32 v53, 0xbfb8aa3b, v53
	v_exp_f32_e32 v64, v64
	v_exp_f32_e32 v53, v53
	v_sub_f32_e32 v60, 1.0, v60
	v_add_f32_e32 v52, 1.0, v52
	v_max_f32_e32 v60, 0, v60
	v_rcp_f32_e32 v52, v52
	v_sqrt_f32_e32 v60, v60
	v_sub_f32_e32 v64, 1.0, v64
	v_add_f32_e32 v53, 1.0, v53
	v_max_f32_e32 v64, 0, v64
	v_and_b32_e32 v61, 0xffff0000, v76
	v_rcp_f32_e32 v53, v53
	v_sqrt_f32_e32 v64, v64
	v_mul_f32_e32 v51, v51, v61
	v_lshlrev_b32_e32 v63, 16, v77
	v_mul_f32_e32 v52, v52, v60
	v_mul_f32_e32 v50, 0x42000000, v50
	v_mul_f32_e32 v51, 0x42000000, v51
	v_mul_f32_e32 v52, v52, v63
	v_med3_f32 v50, v50, s29, v231
	v_med3_f32 v51, v51, s29, v231
	v_mov_b32_e32 v63, 0
	v_and_b32_e32 v65, 0xffff0000, v77
	v_mul_f32_e32 v53, v53, v64
	v_cvt_pk_fp8_f32 v63, v50, v51
	v_mul_f32_e32 v53, v53, v65
	v_mul_f32_e32 v52, 0x42000000, v52
	v_mul_f32_e32 v50, 0x42000000, v53
	v_med3_f32 v51, v52, s29, v231
	v_med3_f32 v50, v50, s29, v231
	v_cvt_pk_fp8_f32 v63, v51, v50 op_sel:[0,0,1]
	v_add_co_u32_e32 v50, vcc, s84, v80
	v_cvt_pk_bf16_f32 v85, v92, v93
	v_cvt_pk_bf16_f32 v87, v72, v73
	v_cvt_pk_bf16_f32 v60, v54, v55
	v_cvt_pk_bf16_f32 v61, v56, v57
	v_addc_co_u32_e32 v51, vcc, 0, v81, vcc
	global_store_dwordx4 v[80:81], v[84:87], off
	global_store_dwordx2 v[78:79], v[88:89], off
	global_store_dwordx4 v[50:51], v[58:61], off
	v_add_co_u32_e32 v50, vcc, s93, v78
	s_nop 1
	v_addc_co_u32_e32 v51, vcc, 0, v79, vcc
	global_store_dwordx2 v[50:51], v[62:63], off
	v_add_co_u32_e32 v50, vcc, s92, v82
	v_add_f32_e32 v38, v38, v46
	s_nop 0
	v_addc_co_u32_e32 v51, vcc, 0, v83, vcc
	global_load_dwordx4 v[54:57], v[50:51], off
	v_mul_f32_e32 v38, 0xbfb8aa3b, v38
	v_exp_f32_e32 v38, v38
	v_add_f32_e32 v34, v34, v42
	v_mul_f32_e32 v34, 0xbfb8aa3b, v34
	v_exp_f32_e32 v34, v34
	v_add_f32_e32 v38, 1.0, v38
	v_rcp_f32_e32 v38, v38
	v_add_f32_e32 v39, v39, v47
	v_add_f32_e32 v34, 1.0, v34
	v_mul_f32_e32 v39, 0xbfb8aa3b, v39
	v_exp_f32_e32 v39, v39
	v_add_f32_e32 v35, v35, v43
	v_mul_f32_e32 v35, 0xbfb8aa3b, v35
	v_exp_f32_e32 v35, v35
	v_add_f32_e32 v39, 1.0, v39
	v_rcp_f32_e32 v39, v39
	v_add_f32_e32 v36, v36, v44
	v_add_f32_e32 v35, 1.0, v35
	v_rcp_f32_e32 v35, v35
	v_mul_f32_e32 v39, v39, v145
	v_mul_f32_e32 v36, 0xbfb8aa3b, v36
	v_exp_f32_e32 v36, v36
	v_add_co_u32_e32 v50, vcc, s89, v82
	v_add_f32_e32 v22, v22, v30
	v_add_f32_e32 v36, 1.0, v36
	v_rcp_f32_e32 v36, v36
	v_addc_co_u32_e32 v51, vcc, 0, v83, vcc
	global_load_dwordx4 v[50:53], v[50:51], off
	v_add_f32_e32 v37, v37, v45
	v_mul_f32_e32 v22, 0xbfb8aa3b, v22
	v_mul_f32_e32 v37, 0xbfb8aa3b, v37
	v_exp_f32_e32 v22, v22
	v_exp_f32_e32 v37, v37
	v_add_f32_e32 v18, v18, v26
	v_add_f32_e32 v23, v23, v31
	v_add_f32_e32 v22, 1.0, v22
	v_add_f32_e32 v37, 1.0, v37
	v_rcp_f32_e32 v22, v22
	v_rcp_f32_e32 v37, v37
	v_mul_f32_e32 v18, 0xbfb8aa3b, v18
	v_mul_f32_e32 v23, 0xbfb8aa3b, v23
	v_mul_f32_e32 v22, v22, v130
	v_exp_f32_e32 v18, v18
	v_exp_f32_e32 v23, v23
	v_add_f32_e32 v24, v24, v32
	v_add_f32_e32 v19, v19, v27
	v_add_f32_e32 v18, 1.0, v18
	v_add_f32_e32 v23, 1.0, v23
	v_rcp_f32_e32 v18, v18
	v_rcp_f32_e32 v23, v23
	v_mul_f32_e32 v24, 0xbfb8aa3b, v24
	v_mul_f32_e32 v19, 0xbfb8aa3b, v19
	v_exp_f32_e32 v24, v24
	v_mul_f32_e32 v23, v23, v131
	v_exp_f32_e32 v19, v19
	v_add_f32_e32 v25, v25, v33
	v_add_f32_e32 v24, 1.0, v24
	v_rcp_f32_e32 v24, v24
	v_add_f32_e32 v19, 1.0, v19
	v_rcp_f32_e32 v19, v19
	v_add_f32_e32 v20, v20, v28
	v_mul_f32_e32 v24, v24, v132
	v_mul_f32_e32 v25, 0xbfb8aa3b, v25
	v_mul_f32_e32 v20, 0xbfb8aa3b, v20
	v_exp_f32_e32 v25, v25
	v_exp_f32_e32 v20, v20
	v_add_f32_e32 v14, v14, v46
	v_add_f32_e32 v21, v21, v29
	v_add_f32_e32 v25, 1.0, v25
	v_add_f32_e32 v20, 1.0, v20
	v_rcp_f32_e32 v25, v25
	v_rcp_f32_e32 v20, v20
	v_mul_f32_e32 v14, 0xbfb8aa3b, v14
	v_mul_f32_e32 v21, 0xbfb8aa3b, v21
	v_mul_f32_e32 v25, v25, v133
	v_exp_f32_e32 v14, v14
	v_exp_f32_e32 v21, v21
	s_waitcnt vmcnt(0) lgkmcnt(0)
	v_lshlrev_b32_e32 v58, 16, v54
	v_and_b32_e32 v59, 0xffff0000, v54
	v_lshlrev_b32_e32 v60, 16, v55
	v_and_b32_e32 v54, 0xffff0000, v55
	v_rcp_f32_e32 v55, v34
	v_mul_f32_e32 v34, v38, v144
	v_add_f32_e32 v38, v34, v34
	v_mul_f32_e32 v38, 0x3fb8aa3b, v38
	v_exp_f32_e32 v38, v38
	v_cvt_pk_bf16_f32 v34, v34, v39
	v_add_f32_e32 v14, 1.0, v14
	v_add_f32_e32 v21, 1.0, v21
	v_sub_f32_e32 v38, 1.0, v38
	v_max_f32_e32 v38, 0, v38
	v_sqrt_f32_e32 v38, v38
	v_rcp_f32_e32 v14, v14
	v_rcp_f32_e32 v21, v21
	v_add_f32_e32 v10, v10, v42
	v_mul_f32_e32 v38, v55, v38
	v_add_f32_e32 v55, v39, v39
	v_mul_f32_e32 v55, 0x3fb8aa3b, v55
	v_exp_f32_e32 v55, v55
	v_mul_f32_e32 v38, v38, v58
	v_mul_f32_e32 v38, 0x42000000, v38
	v_mul_f32_e32 v14, v14, v144
	v_sub_f32_e32 v55, 1.0, v55
	v_max_f32_e32 v55, 0, v55
	v_sqrt_f32_e32 v55, v55
	v_mul_f32_e32 v10, 0xbfb8aa3b, v10
	v_exp_f32_e32 v10, v10
	v_add_f32_e32 v11, v11, v43
	v_mul_f32_e32 v35, v35, v55
	v_mul_f32_e32 v55, v35, v59
	v_add_f32_e32 v35, v40, v48
	v_mul_f32_e32 v35, 0xbfb8aa3b, v35
	v_exp_f32_e32 v35, v35
	v_mul_f32_e32 v39, 0x42000000, v55
	v_med3_f32 v39, v39, s29, v231
	v_add_f32_e32 v10, 1.0, v10
	v_add_f32_e32 v35, 1.0, v35
	v_rcp_f32_e32 v35, v35
	v_rcp_f32_e32 v10, v10
	v_mul_f32_e32 v11, 0xbfb8aa3b, v11
	v_exp_f32_e32 v11, v11
	v_mul_f32_e32 v35, v35, v142
	v_add_f32_e32 v40, v35, v35
	v_mul_f32_e32 v40, 0x3fb8aa3b, v40
	v_exp_f32_e32 v40, v40
	v_add_f32_e32 v11, 1.0, v11
	v_rcp_f32_e32 v11, v11
	v_add_f32_e32 v12, v12, v44
	v_sub_f32_e32 v40, 1.0, v40
	v_max_f32_e32 v40, 0, v40
	v_sqrt_f32_e32 v40, v40
	v_mul_f32_e32 v12, 0xbfb8aa3b, v12
	v_exp_f32_e32 v12, v12
	v_add_f32_e32 v6, v6, v30
	v_mul_f32_e32 v36, v36, v40
	v_add_f32_e32 v40, v41, v49
	v_mul_f32_e32 v40, 0xbfb8aa3b, v40
	v_exp_f32_e32 v40, v40
	v_mul_f32_e32 v36, v36, v60
	v_mul_f32_e32 v36, 0x42000000, v36
	v_med3_f32 v36, v36, s29, v231
	v_add_f32_e32 v40, 1.0, v40
	v_rcp_f32_e32 v40, v40
	v_add_f32_e32 v12, 1.0, v12
	v_rcp_f32_e32 v12, v12
	v_add_f32_e32 v13, v13, v45
	v_mul_f32_e32 v40, v40, v143
	v_add_f32_e32 v41, v40, v40
	v_mul_f32_e32 v41, 0x3fb8aa3b, v41
	v_exp_f32_e32 v41, v41
	v_cvt_pk_bf16_f32 v35, v35, v40
	v_med3_f32 v40, v38, s29, v231
	v_mov_b32_e32 v38, 0
	v_sub_f32_e32 v41, 1.0, v41
	v_max_f32_e32 v41, 0, v41
	v_sqrt_f32_e32 v41, v41
	v_cvt_pk_fp8_f32 v38, v40, v39
	v_lshlrev_b32_e32 v39, 16, v57
	v_and_b32_e32 v40, 0xffff0000, v57
	v_mul_f32_e32 v37, v37, v41
	v_add_f32_e32 v41, v22, v22
	v_mul_f32_e32 v41, 0x3fb8aa3b, v41
	v_exp_f32_e32 v41, v41
	v_mul_f32_e32 v37, v37, v54
	v_mul_f32_e32 v37, 0x42000000, v37
	v_med3_f32 v37, v37, s29, v231
	v_sub_f32_e32 v41, 1.0, v41
	v_max_f32_e32 v41, 0, v41
	v_sqrt_f32_e32 v41, v41
	v_cvt_pk_fp8_f32 v38, v36, v37 op_sel:[0,0,1]
	v_lshlrev_b32_e32 v36, 16, v56
	v_and_b32_e32 v37, 0xffff0000, v56
	v_mul_f32_e32 v18, v18, v41
	v_mul_f32_e32 v18, v18, v36
	v_add_f32_e32 v36, v23, v23
	v_mul_f32_e32 v36, 0x3fb8aa3b, v36
	v_exp_f32_e32 v36, v36
	v_mul_f32_e32 v18, 0x42000000, v18
	v_med3_f32 v18, v18, s29, v231
	v_mul_f32_e32 v6, 0xbfb8aa3b, v6
	v_sub_f32_e32 v36, 1.0, v36
	v_max_f32_e32 v36, 0, v36
	v_sqrt_f32_e32 v36, v36
	v_mul_f32_e32 v13, 0xbfb8aa3b, v13
	v_exp_f32_e32 v6, v6
	v_exp_f32_e32 v13, v13
	v_mul_f32_e32 v19, v19, v36
	v_add_f32_e32 v36, v24, v24
	v_mul_f32_e32 v36, 0x3fb8aa3b, v36
	v_exp_f32_e32 v36, v36
	v_mul_f32_e32 v19, v19, v37
	v_mul_f32_e32 v19, 0x42000000, v19
	v_med3_f32 v19, v19, s29, v231
	v_sub_f32_e32 v36, 1.0, v36
	v_max_f32_e32 v36, 0, v36
	v_sqrt_f32_e32 v36, v36
	v_cvt_pk_bf16_f32 v37, v24, v25
	v_add_f32_e32 v6, 1.0, v6
	v_add_f32_e32 v13, 1.0, v13
	v_mul_f32_e32 v20, v20, v36
	v_add_f32_e32 v36, v25, v25
	v_mul_f32_e32 v36, 0x3fb8aa3b, v36
	v_exp_f32_e32 v36, v36
	v_mul_f32_e32 v20, v20, v39
	v_mov_b32_e32 v39, 0
	v_cvt_pk_fp8_f32 v39, v18, v19
	v_sub_f32_e32 v36, 1.0, v36
	v_max_f32_e32 v36, 0, v36
	v_sqrt_f32_e32 v36, v36
	v_mul_f32_e32 v20, 0x42000000, v20
	v_med3_f32 v18, v20, s29, v231
	v_rcp_f32_e32 v6, v6
	v_mul_f32_e32 v21, v21, v36
	v_cvt_pk_bf16_f32 v36, v22, v23
	v_add_f32_e32 v22, v14, v14
	v_mul_f32_e32 v22, 0x3fb8aa3b, v22
	v_exp_f32_e32 v22, v22
	v_mul_f32_e32 v21, v21, v40
	v_mul_f32_e32 v21, 0x42000000, v21
	v_med3_f32 v19, v21, s29, v231
	v_sub_f32_e32 v22, 1.0, v22
	v_max_f32_e32 v22, 0, v22
	v_cvt_pk_fp8_f32 v39, v18, v19 op_sel:[0,0,1]
	v_add_co_u32_e32 v18, vcc, s92, v80
	v_sqrt_f32_e32 v22, v22
	s_nop 0
	v_addc_co_u32_e32 v19, vcc, 0, v81, vcc
	global_store_dwordx4 v[18:19], v[34:37], off
	v_add_co_u32_e32 v18, vcc, s84, v78
	v_mul_f32_e32 v10, v10, v22
	s_nop 0
	v_addc_co_u32_e32 v19, vcc, 0, v79, vcc
	global_store_dwordx2 v[18:19], v[38:39], off
	v_lshlrev_b32_e32 v18, 16, v50
	v_mul_f32_e32 v18, v10, v18
	v_add_f32_e32 v10, v15, v47
	v_mul_f32_e32 v10, 0xbfb8aa3b, v10
	v_exp_f32_e32 v10, v10
	v_and_b32_e32 v19, 0xffff0000, v50
	v_rcp_f32_e32 v13, v13
	v_mul_f32_e32 v6, v6, v130
	v_add_f32_e32 v10, 1.0, v10
	v_rcp_f32_e32 v10, v10
	v_add_f32_e32 v2, v2, v26
	v_add_f32_e32 v7, v7, v31
	v_mul_f32_e32 v2, 0xbfb8aa3b, v2
	v_mul_f32_e32 v10, v10, v145
	v_add_f32_e32 v15, v10, v10
	v_mul_f32_e32 v15, 0x3fb8aa3b, v15
	v_exp_f32_e32 v15, v15
	v_mul_f32_e32 v7, 0xbfb8aa3b, v7
	v_exp_f32_e32 v2, v2
	v_exp_f32_e32 v7, v7
	v_sub_f32_e32 v15, 1.0, v15
	v_max_f32_e32 v15, 0, v15
	v_sqrt_f32_e32 v15, v15
	v_cvt_pk_bf16_f32 v10, v14, v10
	v_mul_f32_e32 v14, 0x42000000, v18
	v_add_f32_e32 v2, 1.0, v2
	v_mul_f32_e32 v11, v11, v15
	v_mul_f32_e32 v15, v11, v19
	v_add_f32_e32 v11, v16, v48
	v_mul_f32_e32 v11, 0xbfb8aa3b, v11
	v_exp_f32_e32 v11, v11
	v_mul_f32_e32 v15, 0x42000000, v15
	v_med3_f32 v15, v15, s29, v231
	v_add_f32_e32 v7, 1.0, v7
	v_add_f32_e32 v11, 1.0, v11
	v_rcp_f32_e32 v11, v11
	v_lshlrev_b32_e32 v20, 16, v51
	v_and_b32_e32 v21, 0xffff0000, v51
	v_rcp_f32_e32 v2, v2
	v_mul_f32_e32 v11, v11, v142
	v_add_f32_e32 v16, v11, v11
	v_mul_f32_e32 v16, 0x3fb8aa3b, v16
	v_exp_f32_e32 v16, v16
	v_rcp_f32_e32 v7, v7
	v_add_f32_e32 v8, v8, v32
	v_add_f32_e32 v3, v3, v27
	v_sub_f32_e32 v16, 1.0, v16
	v_max_f32_e32 v16, 0, v16
	v_sqrt_f32_e32 v16, v16
	v_mul_f32_e32 v7, v7, v131
	v_mul_f32_e32 v8, 0xbfb8aa3b, v8
	v_mul_f32_e32 v3, 0xbfb8aa3b, v3
	v_mul_f32_e32 v12, v12, v16
	v_add_f32_e32 v16, v17, v49
	v_mul_f32_e32 v16, 0xbfb8aa3b, v16
	v_exp_f32_e32 v16, v16
	v_mul_f32_e32 v12, v12, v20
	v_mul_f32_e32 v12, 0x42000000, v12
	v_med3_f32 v12, v12, s29, v231
	v_add_f32_e32 v16, 1.0, v16
	v_rcp_f32_e32 v16, v16
	v_exp_f32_e32 v8, v8
	v_exp_f32_e32 v3, v3
	v_add_f32_e32 v9, v9, v33
	v_mul_f32_e32 v16, v16, v143
	v_add_f32_e32 v17, v16, v16
	v_mul_f32_e32 v17, 0x3fb8aa3b, v17
	v_exp_f32_e32 v17, v17
	v_cvt_pk_bf16_f32 v11, v11, v16
	v_med3_f32 v16, v14, s29, v231
	v_mov_b32_e32 v14, 0
	v_sub_f32_e32 v17, 1.0, v17
	v_max_f32_e32 v17, 0, v17
	v_sqrt_f32_e32 v17, v17
	v_cvt_pk_fp8_f32 v14, v16, v15
	v_add_f32_e32 v8, 1.0, v8
	v_add_f32_e32 v3, 1.0, v3
	v_mul_f32_e32 v13, v13, v17
	v_add_f32_e32 v17, v6, v6
	v_mul_f32_e32 v17, 0x3fb8aa3b, v17
	v_exp_f32_e32 v17, v17
	v_mul_f32_e32 v13, v13, v21
	v_mul_f32_e32 v13, 0x42000000, v13
	v_med3_f32 v13, v13, s29, v231
	v_sub_f32_e32 v17, 1.0, v17
	v_max_f32_e32 v17, 0, v17
	v_sqrt_f32_e32 v17, v17
	v_cvt_pk_fp8_f32 v14, v12, v13 op_sel:[0,0,1]
	v_lshlrev_b32_e32 v12, 16, v52
	v_rcp_f32_e32 v8, v8
	v_mul_f32_e32 v2, v2, v17
	v_mul_f32_e32 v2, v2, v12
	v_add_f32_e32 v12, v7, v7
	v_mul_f32_e32 v12, 0x3fb8aa3b, v12
	v_exp_f32_e32 v12, v12
	v_rcp_f32_e32 v3, v3
	v_mul_f32_e32 v8, v8, v132
	v_add_f32_e32 v4, v4, v28
	v_sub_f32_e32 v12, 1.0, v12
	v_max_f32_e32 v12, 0, v12
	v_sqrt_f32_e32 v12, v12
	v_mul_f32_e32 v9, 0xbfb8aa3b, v9
	v_mul_f32_e32 v4, 0xbfb8aa3b, v4
	v_exp_f32_e32 v9, v9
	v_mul_f32_e32 v3, v3, v12
	v_add_f32_e32 v12, v8, v8
	v_mul_f32_e32 v12, 0x3fb8aa3b, v12
	v_exp_f32_e32 v12, v12
	v_exp_f32_e32 v4, v4
	v_add_f32_e32 v9, 1.0, v9
	v_rcp_f32_e32 v9, v9
	v_sub_f32_e32 v12, 1.0, v12
	v_add_f32_e32 v4, 1.0, v4
	v_max_f32_e32 v12, 0, v12
	v_rcp_f32_e32 v4, v4
	v_sqrt_f32_e32 v12, v12
	v_mul_f32_e32 v9, v9, v133
	v_add_f32_e32 v5, v5, v29
	v_mul_f32_e32 v5, 0xbfb8aa3b, v5
	v_mul_f32_e32 v4, v4, v12
	v_add_f32_e32 v12, v9, v9
	v_mul_f32_e32 v12, 0x3fb8aa3b, v12
	v_exp_f32_e32 v12, v12
	v_exp_f32_e32 v5, v5
	v_and_b32_e32 v13, 0xffff0000, v52
	v_mul_f32_e32 v3, v3, v13
	v_sub_f32_e32 v12, 1.0, v12
	v_add_f32_e32 v5, 1.0, v5
	v_max_f32_e32 v12, 0, v12
	v_rcp_f32_e32 v5, v5
	v_sqrt_f32_e32 v12, v12
	v_lshlrev_b32_e32 v15, 16, v53
	v_mul_f32_e32 v2, 0x42000000, v2
	v_mul_f32_e32 v3, 0x42000000, v3
	v_mul_f32_e32 v4, v4, v15
	v_med3_f32 v2, v2, s29, v231
	v_med3_f32 v3, v3, s29, v231
	v_mov_b32_e32 v15, 0
	v_and_b32_e32 v16, 0xffff0000, v53
	v_mul_f32_e32 v5, v5, v12
	v_cvt_pk_fp8_f32 v15, v2, v3
	v_mul_f32_e32 v5, v5, v16
	v_mul_f32_e32 v4, 0x42000000, v4
	v_mul_f32_e32 v5, 0x42000000, v5
	v_med3_f32 v2, v4, s29, v231
	v_med3_f32 v3, v5, s29, v231
	v_cvt_pk_fp8_f32 v15, v2, v3 op_sel:[0,0,1]
	v_add_co_u32_e32 v2, vcc, 0x18000, v80
	v_cvt_pk_bf16_f32 v12, v6, v7
	v_cvt_pk_bf16_f32 v13, v8, v9
	v_addc_co_u32_e32 v3, vcc, 0, v81, vcc
	global_store_dwordx4 v[2:3], v[10:13], off
	v_add_co_u32_e32 v2, vcc, 0xc000, v78
	s_nop 1
	v_addc_co_u32_e32 v3, vcc, 0, v79, vcc
	global_store_dwordx2 v[2:3], v[14:15], off
	s_and_b64 vcc, exec, s[12:13]
	s_mov_b32 s82, s40
	s_mov_b32 s52, s42
	s_mov_b64 s[14:15], s[46:47]
	s_mov_b64 s[48:49], s[44:45]
	s_mov_b32 s94, s23
	s_cbranch_vccz .LBB0_1638
	s_waitcnt vmcnt(0)
	s_cmpk_gt_u32 s22, 0xff
	v_readlane_b32 s81, v253, 46
	v_readlane_b32 s80, v253, 45
	v_readlane_b32 s89, v253, 44
	s_cbranch_scc1 .LBB0_1649
	s_barrier

.LBB0_2041:
	s_add_u32 s14, s38, 0x100
	s_addc_u32 s15, s39, 0
	s_add_u32 s36, s35, s38
	s_addc_u32 s37, s55, s39
	s_cmpk_eq_i32 s38, 0x300
	s_cselect_b64 vcc, -1, 0
	s_and_b64 s[0:1], vcc, exec
	s_cselect_b32 s1, 0, s14
	s_cselect_b32 s0, 0, s15
	s_cselect_b32 s36, s31, s36
	s_cselect_b32 s37, s29, s37
	s_add_u32 s40, s18, s1
	s_addc_u32 s41, s19, s0
	s_add_i32 s1, 0, 0x10000
	v_add_u32_e32 v14, s1, v197
	ds_read_b128 v[2:5], v14
	ds_read_b128 v[6:9], v14 offset:1024
	ds_read_b128 v[10:13], v14 offset:2048
	ds_read_b128 v[14:17], v14 offset:3072
	v_cndmask_b32_e32 v162, v168, v171, vcc
	v_cndmask_b32_e32 v184, v170, v198, vcc
	v_cndmask_b32_e32 v175, v172, v199, vcc
	v_cndmask_b32_e32 v173, v174, v200, vcc
	v_lshl_add_u64 v[18:19], v[178:179], 0, s[38:39]
	s_add_i32 m0, s45, 0xc000
	ds_read_b128 v[202:205], v169
	ds_read_b128 v[206:209], v169 offset:1024
	ds_read_b128 v[210:213], v169 offset:2048
	ds_read_b128 v[214:217], v169 offset:3072
	ds_read_b128 v[218:221], v169 offset:4096
	ds_read_b128 v[222:225], v169 offset:5120
	ds_read_b128 v[226:229], v169 offset:6144
	ds_read_b128 v[230:233], v169 offset:7168
	global_load_lds_dwordx4 v[18:19], off nt
	v_lshl_add_u64 v[18:19], v[176:177], 0, s[38:39]
	s_add_i32 m0, s45, 0xe000
	s_nop 0
	global_load_lds_dwordx4 v[18:19], off nt
	s_waitcnt lgkmcnt(8)
	s_waitcnt vmcnt(10)
	s_barrier
	s_waitcnt lgkmcnt(0)
	s_waitcnt lgkmcnt(0)
	v_mfma_scale_f32_16x16x128_f8f6f4 v[158:161], v[2:9], v[202:209], v[158:161], v188, v188 op_sel_hi:[0,0,0]
	v_mfma_scale_f32_16x16x128_f8f6f4 v[150:153], v[10:17], v[202:209], v[150:153], v188, v188 op_sel_hi:[0,0,0]
	v_mfma_scale_f32_16x16x128_f8f6f4 v[142:145], v[2:9], v[210:217], v[142:145], v188, v188 op_sel_hi:[0,0,0]
	v_mfma_scale_f32_16x16x128_f8f6f4 v[134:137], v[10:17], v[210:217], v[134:137], v188, v188 op_sel_hi:[0,0,0]
	v_mfma_scale_f32_16x16x128_f8f6f4 v[126:129], v[2:9], v[218:225], v[126:129], v188, v188 op_sel_hi:[0,0,0]
	v_mfma_scale_f32_16x16x128_f8f6f4 v[118:121], v[10:17], v[218:225], v[118:121], v188, v188 op_sel_hi:[0,0,0]
	v_mfma_scale_f32_16x16x128_f8f6f4 v[110:113], v[2:9], v[226:233], v[110:113], v188, v188 op_sel_hi:[0,0,0]
	v_mfma_scale_f32_16x16x128_f8f6f4 v[102:105], v[10:17], v[226:233], v[102:105], v188, v188 op_sel_hi:[0,0,0]
	s_barrier
	s_add_i32 s0, 0, 0x14000
	s_add_i32 s1, s1, s43
	v_add_u32_e32 v30, s0, v197
	v_lshl_add_u64 v[180:181], s[36:37], 0, v[164:165]
	s_mov_b32 m0, s1
	ds_read_b128 v[18:21], v30
	ds_read_b128 v[22:25], v30 offset:1024
	ds_read_b128 v[26:29], v30 offset:2048
	ds_read_b128 v[30:33], v30 offset:3072
	global_load_lds_dwordx4 v[180:181], off
	v_lshl_add_u64 v[182:183], s[36:37], 0, v[166:167]
	s_add_i32 m0, s1, 0x2000
	s_nop 0
	global_load_lds_dwordx4 v[182:183], off
	s_waitcnt vmcnt(10)
	s_barrier
	s_waitcnt lgkmcnt(0)
	s_waitcnt lgkmcnt(0)
	v_mfma_scale_f32_16x16x128_f8f6f4 v[154:157], v[18:25], v[202:209], v[154:157], v188, v188 op_sel_hi:[0,0,0]
	v_mfma_scale_f32_16x16x128_f8f6f4 v[146:149], v[26:33], v[202:209], v[146:149], v188, v188 op_sel_hi:[0,0,0]
	v_mfma_scale_f32_16x16x128_f8f6f4 v[138:141], v[18:25], v[210:217], v[138:141], v188, v188 op_sel_hi:[0,0,0]
	v_mfma_scale_f32_16x16x128_f8f6f4 v[130:133], v[26:33], v[210:217], v[130:133], v188, v188 op_sel_hi:[0,0,0]
	v_mfma_scale_f32_16x16x128_f8f6f4 v[122:125], v[18:25], v[218:225], v[122:125], v188, v188 op_sel_hi:[0,0,0]
	v_mfma_scale_f32_16x16x128_f8f6f4 v[114:117], v[26:33], v[218:225], v[114:117], v188, v188 op_sel_hi:[0,0,0]
	v_mfma_scale_f32_16x16x128_f8f6f4 v[106:109], v[18:25], v[226:233], v[106:109], v188, v188 op_sel_hi:[0,0,0]
	v_mfma_scale_f32_16x16x128_f8f6f4 v[98:101], v[26:33], v[226:233], v[98:101], v188, v188 op_sel_hi:[0,0,0]
	s_mov_b32 m0, s45
	s_barrier
	ds_read_b128 v[202:205], v169 offset:16384
	ds_read_b128 v[206:209], v169 offset:17408
	ds_read_b128 v[210:213], v169 offset:18432
	ds_read_b128 v[214:217], v169 offset:19456
	ds_read_b128 v[218:221], v169 offset:20480
	ds_read_b128 v[222:225], v169 offset:21504
	ds_read_b128 v[226:229], v169 offset:22528
	ds_read_b128 v[230:233], v169 offset:23552
	global_load_lds_dwordx4 v162, s[40:41] nt
	s_mov_b32 m0, s46
	v_mov_b32_e32 v185, v163
	global_load_lds_dwordx4 v184, s[40:41] nt
	s_waitcnt vmcnt(10)
	s_barrier
	s_waitcnt lgkmcnt(0)
	v_lshl_add_u64 v[186:187], s[40:41], 0, v[162:163]
	v_lshl_add_u64 v[184:185], s[40:41], 0, v[184:185]
	s_waitcnt lgkmcnt(0)
	v_mfma_scale_f32_16x16x128_f8f6f4 v[94:97], v[2:9], v[202:209], v[94:97], v188, v188 op_sel_hi:[0,0,0]
	v_mfma_scale_f32_16x16x128_f8f6f4 v[86:89], v[10:17], v[202:209], v[86:89], v188, v188 op_sel_hi:[0,0,0]
	v_mfma_scale_f32_16x16x128_f8f6f4 v[78:81], v[2:9], v[210:217], v[78:81], v188, v188 op_sel_hi:[0,0,0]
	v_mfma_scale_f32_16x16x128_f8f6f4 v[70:73], v[10:17], v[210:217], v[70:73], v188, v188 op_sel_hi:[0,0,0]
	v_mfma_scale_f32_16x16x128_f8f6f4 v[62:65], v[2:9], v[218:225], v[62:65], v188, v188 op_sel_hi:[0,0,0]
	v_mfma_scale_f32_16x16x128_f8f6f4 v[54:57], v[10:17], v[218:225], v[54:57], v188, v188 op_sel_hi:[0,0,0]
	v_mfma_scale_f32_16x16x128_f8f6f4 v[46:49], v[2:9], v[226:233], v[46:49], v188, v188 op_sel_hi:[0,0,0]
	v_mfma_scale_f32_16x16x128_f8f6f4 v[38:41], v[10:17], v[226:233], v[38:41], v188, v188 op_sel_hi:[0,0,0]
	s_barrier
	s_add_u32 s38, s36, 0x20000
	s_addc_u32 s39, s37, 0
	s_add_i32 s0, s0, s43
	v_lshl_add_u64 v[2:3], s[38:39], 0, v[164:165]
	s_mov_b32 m0, s0
	s_nop 0
	global_load_lds_dwordx4 v[2:3], off
	v_lshl_add_u64 v[2:3], s[38:39], 0, v[166:167]
	s_add_i32 m0, s0, 0x2000
	s_nop 0
	global_load_lds_dwordx4 v[2:3], off
	s_waitcnt vmcnt(10)
	s_barrier
	v_mfma_scale_f32_16x16x128_f8f6f4 v[90:93], v[18:25], v[202:209], v[90:93], v188, v188 op_sel_hi:[0,0,0]
	v_mfma_scale_f32_16x16x128_f8f6f4 v[82:85], v[26:33], v[202:209], v[82:85], v188, v188 op_sel_hi:[0,0,0]
	v_mfma_scale_f32_16x16x128_f8f6f4 v[74:77], v[18:25], v[210:217], v[74:77], v188, v188 op_sel_hi:[0,0,0]
	v_mfma_scale_f32_16x16x128_f8f6f4 v[66:69], v[26:33], v[210:217], v[66:69], v188, v188 op_sel_hi:[0,0,0]
	v_mfma_scale_f32_16x16x128_f8f6f4 v[58:61], v[18:25], v[218:225], v[58:61], v188, v188 op_sel_hi:[0,0,0]
	v_mfma_scale_f32_16x16x128_f8f6f4 v[50:53], v[26:33], v[218:225], v[50:53], v188, v188 op_sel_hi:[0,0,0]
	v_mfma_scale_f32_16x16x128_f8f6f4 v[42:45], v[18:25], v[226:233], v[42:45], v188, v188 op_sel_hi:[0,0,0]
	v_mfma_scale_f32_16x16x128_f8f6f4 v[34:37], v[26:33], v[226:233], v[34:37], v188, v188 op_sel_hi:[0,0,0]
	s_add_i32 s0, 0, 0x18000
	v_add_u32_e32 v14, s0, v197
	s_barrier
	ds_read_b128 v[2:5], v14
	ds_read_b128 v[6:9], v14 offset:1024
	ds_read_b128 v[10:13], v14 offset:2048
	ds_read_b128 v[14:17], v14 offset:3072
	s_mov_b32 m0, s47
	ds_read_b128 v[18:21], v169 offset:32768
	ds_read_b128 v[22:25], v169 offset:33792
	ds_read_b128 v[26:29], v169 offset:34816
	ds_read_b128 v[30:33], v169 offset:35840
	ds_read_b128 v[202:205], v169 offset:36864
	ds_read_b128 v[206:209], v169 offset:37888
	ds_read_b128 v[210:213], v169 offset:38912
	ds_read_b128 v[214:217], v169 offset:39936
	global_load_lds_dwordx4 v175, s[40:41] nt
	s_mov_b32 m0, s48
	s_nop 0
	global_load_lds_dwordx4 v173, s[40:41] nt
	s_waitcnt lgkmcnt(8)
	s_waitcnt vmcnt(10)
	s_barrier
	s_waitcnt lgkmcnt(0)
	s_waitcnt lgkmcnt(0)
	v_mfma_scale_f32_16x16x128_f8f6f4 v[158:161], v[2:9], v[18:25], v[158:161], v188, v188 op_sel_hi:[0,0,0]
	v_mfma_scale_f32_16x16x128_f8f6f4 v[150:153], v[10:17], v[18:25], v[150:153], v188, v188 op_sel_hi:[0,0,0]
	v_mfma_scale_f32_16x16x128_f8f6f4 v[142:145], v[2:9], v[26:33], v[142:145], v188, v188 op_sel_hi:[0,0,0]
	v_mfma_scale_f32_16x16x128_f8f6f4 v[134:137], v[10:17], v[26:33], v[134:137], v188, v188 op_sel_hi:[0,0,0]
	v_mfma_scale_f32_16x16x128_f8f6f4 v[126:129], v[2:9], v[202:209], v[126:129], v188, v188 op_sel_hi:[0,0,0]
	v_mfma_scale_f32_16x16x128_f8f6f4 v[118:121], v[10:17], v[202:209], v[118:121], v188, v188 op_sel_hi:[0,0,0]
	v_mfma_scale_f32_16x16x128_f8f6f4 v[110:113], v[2:9], v[210:217], v[110:113], v188, v188 op_sel_hi:[0,0,0]
	v_mfma_scale_f32_16x16x128_f8f6f4 v[102:105], v[10:17], v[210:217], v[102:105], v188, v188 op_sel_hi:[0,0,0]
	s_barrier
	s_add_i32 s38, 0, 0x1c000
	s_add_i32 s0, s0, s43
	v_add_u32_e32 v162, s38, v197
	v_lshl_add_u64 v[180:181], v[180:181], 0, s[24:25]
	s_mov_b32 m0, s0
	ds_read_b128 v[218:221], v162
	ds_read_b128 v[222:225], v162 offset:1024
	ds_read_b128 v[226:229], v162 offset:2048
	ds_read_b128 v[230:233], v162 offset:3072
	global_load_lds_dwordx4 v[180:181], off
	v_lshl_add_u64 v[180:181], v[182:183], 0, s[24:25]
	s_add_i32 m0, s0, 0x2000
	s_nop 0
	global_load_lds_dwordx4 v[180:181], off
	s_waitcnt vmcnt(10)
	s_barrier
	s_waitcnt lgkmcnt(0)
	s_waitcnt lgkmcnt(0)
	v_mfma_scale_f32_16x16x128_f8f6f4 v[154:157], v[218:225], v[18:25], v[154:157], v188, v188 op_sel_hi:[0,0,0]
	v_mfma_scale_f32_16x16x128_f8f6f4 v[146:149], v[226:233], v[18:25], v[146:149], v188, v188 op_sel_hi:[0,0,0]
	v_mfma_scale_f32_16x16x128_f8f6f4 v[138:141], v[218:225], v[26:33], v[138:141], v188, v188 op_sel_hi:[0,0,0]
	v_mfma_scale_f32_16x16x128_f8f6f4 v[130:133], v[226:233], v[26:33], v[130:133], v188, v188 op_sel_hi:[0,0,0]
	v_mfma_scale_f32_16x16x128_f8f6f4 v[122:125], v[218:225], v[202:209], v[122:125], v188, v188 op_sel_hi:[0,0,0]
	v_mfma_scale_f32_16x16x128_f8f6f4 v[114:117], v[226:233], v[202:209], v[114:117], v188, v188 op_sel_hi:[0,0,0]
	v_mfma_scale_f32_16x16x128_f8f6f4 v[106:109], v[218:225], v[210:217], v[106:109], v188, v188 op_sel_hi:[0,0,0]
	v_mfma_scale_f32_16x16x128_f8f6f4 v[98:101], v[226:233], v[210:217], v[98:101], v188, v188 op_sel_hi:[0,0,0]
	s_mov_b32 m0, s51
	v_lshl_add_u64 v[180:181], v[186:187], 0, s[24:25]
	s_barrier
	ds_read_b128 v[18:21], v169 offset:49152
	ds_read_b128 v[22:25], v169 offset:50176
	ds_read_b128 v[26:29], v169 offset:51200
	ds_read_b128 v[30:33], v169 offset:52224
	ds_read_b128 v[202:205], v169 offset:53248
	ds_read_b128 v[206:209], v169 offset:54272
	ds_read_b128 v[210:213], v169 offset:55296
	ds_read_b128 v[214:217], v169 offset:56320
	global_load_lds_dwordx4 v[180:181], off nt
	v_lshl_add_u64 v[180:181], v[184:185], 0, s[24:25]
	s_mov_b32 m0, s52
	s_nop 0
	global_load_lds_dwordx4 v[180:181], off nt
	s_waitcnt vmcnt(10)
	s_barrier
	s_waitcnt lgkmcnt(0)
	s_waitcnt lgkmcnt(0)
	v_mfma_scale_f32_16x16x128_f8f6f4 v[94:97], v[2:9], v[18:25], v[94:97], v188, v188 op_sel_hi:[0,0,0]
	v_mfma_scale_f32_16x16x128_f8f6f4 v[86:89], v[10:17], v[18:25], v[86:89], v188, v188 op_sel_hi:[0,0,0]
	v_mfma_scale_f32_16x16x128_f8f6f4 v[78:81], v[2:9], v[26:33], v[78:81], v188, v188 op_sel_hi:[0,0,0]
	v_mfma_scale_f32_16x16x128_f8f6f4 v[70:73], v[10:17], v[26:33], v[70:73], v188, v188 op_sel_hi:[0,0,0]
	v_mfma_scale_f32_16x16x128_f8f6f4 v[62:65], v[2:9], v[202:209], v[62:65], v188, v188 op_sel_hi:[0,0,0]
	v_mfma_scale_f32_16x16x128_f8f6f4 v[54:57], v[10:17], v[202:209], v[54:57], v188, v188 op_sel_hi:[0,0,0]
	v_mfma_scale_f32_16x16x128_f8f6f4 v[46:49], v[2:9], v[210:217], v[46:49], v188, v188 op_sel_hi:[0,0,0]
	v_mfma_scale_f32_16x16x128_f8f6f4 v[38:41], v[10:17], v[210:217], v[38:41], v188, v188 op_sel_hi:[0,0,0]
	s_barrier
	s_add_u32 s0, s36, 0x20080
	s_addc_u32 s1, s37, 0
	s_add_i32 s36, s38, s43
	v_lshl_add_u64 v[2:3], s[0:1], 0, v[164:165]
	s_mov_b32 m0, s36
	s_nop 0
	global_load_lds_dwordx4 v[2:3], off
	v_lshl_add_u64 v[2:3], s[0:1], 0, v[166:167]
	s_add_i32 m0, s36, 0x2000
	s_nop 0
	global_load_lds_dwordx4 v[2:3], off
	s_waitcnt vmcnt(10)
	s_barrier
	v_mfma_scale_f32_16x16x128_f8f6f4 v[90:93], v[218:225], v[18:25], v[90:93], v188, v188 op_sel_hi:[0,0,0]
	v_mfma_scale_f32_16x16x128_f8f6f4 v[82:85], v[226:233], v[18:25], v[82:85], v188, v188 op_sel_hi:[0,0,0]
	v_mfma_scale_f32_16x16x128_f8f6f4 v[74:77], v[218:225], v[26:33], v[74:77], v188, v188 op_sel_hi:[0,0,0]
	v_mfma_scale_f32_16x16x128_f8f6f4 v[66:69], v[226:233], v[26:33], v[66:69], v188, v188 op_sel_hi:[0,0,0]
	v_mfma_scale_f32_16x16x128_f8f6f4 v[58:61], v[218:225], v[202:209], v[58:61], v188, v188 op_sel_hi:[0,0,0]
	v_mfma_scale_f32_16x16x128_f8f6f4 v[50:53], v[226:233], v[202:209], v[50:53], v188, v188 op_sel_hi:[0,0,0]
	v_mfma_scale_f32_16x16x128_f8f6f4 v[42:45], v[218:225], v[210:217], v[42:45], v188, v188 op_sel_hi:[0,0,0]
	v_mfma_scale_f32_16x16x128_f8f6f4 v[34:37], v[226:233], v[210:217], v[34:37], v188, v188 op_sel_hi:[0,0,0]
	s_add_i32 s56, s56, 2
	s_cmp_gt_u32 s56, 5
	s_mov_b64 s[38:39], s[14:15]
	s_barrier
	s_cbranch_scc0 .LBB0_2041
	v_mul_f32_e32 v5, 0x3c800000, v158
	v_mul_f32_e32 v6, 0xbfb8aa3b, v5
	v_exp_f32_e32 v6, v6
	s_ashr_i32 s35, s34, 31
	s_ashr_i32 s31, s30, 31
	s_lshl_b64 s[14:15], s[34:35], 18
	v_add_f32_e32 v6, 1.0, v6
	v_rcp_f32_e32 v6, v6
	s_lshl_b64 s[30:31], s[30:31], 15
	v_mov_b32_e32 v3, v195
	s_add_u32 s0, s6, s14
	v_mul_f32_e32 v5, v5, v6
	v_mul_f32_e32 v6, 0x3c800000, v159
	v_mul_f32_e32 v7, 0xbfb8aa3b, v6
	v_exp_f32_e32 v7, v7
	v_mul_f32_e32 v5, v5, v154
	v_mul_f32_e32 v5, 0x3e000000, v5
	v_med3_f32 v5, v5, s10, v190
	v_add_f32_e32 v7, 1.0, v7
	v_rcp_f32_e32 v7, v7
	s_nop 15
	s_nop 15
	v_mov_b32_e32 v2, v196
	v_mul_f32_e32 v6, v6, v7
	v_mul_f32_e32 v7, 0x3c800000, v160
	v_mul_f32_e32 v8, 0xbfb8aa3b, v7
	v_exp_f32_e32 v8, v8
	v_mul_f32_e32 v6, v6, v155
	v_mul_f32_e32 v6, 0x3e000000, v6
	v_add_u32_e32 v4, s49, v3
	v_add_f32_e32 v8, 1.0, v8
	v_rcp_f32_e32 v8, v8
	s_addc_u32 s1, s7, s15
	s_add_u32 s14, s0, s30
	v_mul_f32_e32 v7, v7, v8
	v_mul_f32_e32 v8, 0x3c800000, v161
	v_mul_f32_e32 v9, 0xbfb8aa3b, v8
	v_exp_f32_e32 v9, v9
	v_mul_f32_e32 v7, v7, v156
	v_mul_f32_e32 v7, 0x3e000000, v7
	v_lshl_add_u32 v2, v2, 3, s50
	v_add_f32_e32 v9, 1.0, v9
	v_rcp_f32_e32 v9, v9
	s_addc_u32 s15, s1, s31
	v_ashrrev_i32_e32 v3, 31, v2
	s_and_b64 vcc, exec, s[12:13]
	v_mul_f32_e32 v8, v8, v9
	v_mul_f32_e32 v9, 0x3c800000, v150
	v_mul_f32_e32 v10, 0xbfb8aa3b, v9
	v_exp_f32_e32 v10, v10
	v_mul_f32_e32 v8, v8, v157
	v_mul_f32_e32 v8, 0x3e000000, v8
	v_mov_b32_e32 v174, v200
	v_add_f32_e32 v10, 1.0, v10
	v_rcp_f32_e32 v10, v10
	v_mov_b32_e32 v172, v199
	v_mov_b32_e32 v170, v198
	v_mov_b32_e32 v168, v171
	v_mul_f32_e32 v9, v9, v10
	v_mul_f32_e32 v10, 0x3c800000, v151
	v_mul_f32_e32 v11, 0xbfb8aa3b, v10
	v_exp_f32_e32 v11, v11
	v_mul_f32_e32 v9, v9, v146
	v_mul_f32_e32 v9, 0x3e000000, v9
	s_mov_b32 s30, s28
	v_add_f32_e32 v11, 1.0, v11
	v_rcp_f32_e32 v11, v11
	s_mov_b32 s34, s54
	s_mov_b64 s[36:37], s[16:17]
	v_mul_f32_e32 v10, v10, v11
	v_mul_f32_e32 v11, 0x3c800000, v152
	v_mul_f32_e32 v12, 0xbfb8aa3b, v11
	v_exp_f32_e32 v12, v12
	v_mul_f32_e32 v10, v10, v147
	v_mul_f32_e32 v10, 0x3e000000, v10
	v_add_f32_e32 v12, 1.0, v12
	v_rcp_f32_e32 v12, v12
	s_nop 0
	v_mul_f32_e32 v11, v11, v12
	v_mul_f32_e32 v12, 0x3c800000, v153
	v_mul_f32_e32 v13, 0xbfb8aa3b, v12
	v_exp_f32_e32 v13, v13
	v_mul_f32_e32 v11, v11, v148
	v_mul_f32_e32 v11, 0x3e000000, v11
	v_add_f32_e32 v13, 1.0, v13
	v_rcp_f32_e32 v13, v13
	s_nop 0
	v_mul_f32_e32 v12, v12, v13
	v_med3_f32 v13, v6, s10, v190
	v_mov_b32_e32 v6, v163
	v_cvt_pk_fp8_f32 v6, v5, v13
	v_med3_f32 v5, v7, s10, v190
	v_med3_f32 v7, v8, s10, v190
	v_med3_f32 v8, v10, s10, v190
	v_cvt_pk_fp8_f32 v6, v5, v7 op_sel:[0,0,1]
	v_med3_f32 v5, v9, s10, v190
	v_mov_b32_e32 v7, v163
	v_cvt_pk_fp8_f32 v7, v5, v8
	v_mul_f32_e32 v12, v12, v149
	v_mul_f32_e32 v12, 0x3e000000, v12
	v_med3_f32 v5, v11, s10, v190
	v_med3_f32 v8, v12, s10, v190
	v_cvt_pk_fp8_f32 v7, v5, v8 op_sel:[0,0,1]
	v_ashrrev_i32_e32 v5, 31, v4
	v_lshlrev_b64 v[8:9], 7, v[4:5]
	v_lshl_add_u64 v[8:9], s[14:15], 0, v[8:9]
	v_lshl_add_u64 v[8:9], v[8:9], 0, v[2:3]
	v_mul_f32_e32 v5, 0x3c800000, v142
	global_store_dwordx2 v[8:9], v[6:7], off
	v_mul_f32_e32 v6, 0xbfb8aa3b, v5
	v_exp_f32_e32 v6, v6
	s_nop 0
	v_add_f32_e32 v6, 1.0, v6
	v_rcp_f32_e32 v6, v6
	s_nop 0
	v_mul_f32_e32 v5, v5, v6
	v_mul_f32_e32 v6, 0x3c800000, v143
	v_mul_f32_e32 v7, 0xbfb8aa3b, v6
	v_exp_f32_e32 v7, v7
	v_mul_f32_e32 v5, v5, v138
	v_mul_f32_e32 v5, 0x3e000000, v5
	v_med3_f32 v5, v5, s10, v190
	v_add_f32_e32 v7, 1.0, v7
	v_rcp_f32_e32 v7, v7
	s_nop 0
	v_mul_f32_e32 v6, v6, v7
	v_mul_f32_e32 v6, v6, v139
	v_mul_f32_e32 v7, 0x3e000000, v6
	v_mul_f32_e32 v6, 0x3c800000, v144
	v_mul_f32_e32 v8, 0xbfb8aa3b, v6
	v_exp_f32_e32 v8, v8
	v_med3_f32 v7, v7, s10, v190
	v_add_f32_e32 v8, 1.0, v8
	v_rcp_f32_e32 v8, v8
	s_nop 0
	v_mul_f32_e32 v6, v6, v8
	v_mul_f32_e32 v6, v6, v140
	v_mul_f32_e32 v9, 0x3e000000, v6
	v_mul_f32_e32 v6, 0x3c800000, v145
	v_mul_f32_e32 v8, 0xbfb8aa3b, v6
	v_exp_f32_e32 v8, v8
	s_nop 0
	v_add_f32_e32 v8, 1.0, v8
	v_rcp_f32_e32 v8, v8
	s_nop 0
	v_mul_f32_e32 v6, v6, v8
	v_mul_f32_e32 v6, v6, v141
	v_mul_f32_e32 v10, 0x3e000000, v6
	v_mul_f32_e32 v6, 0x3c800000, v134
	v_mul_f32_e32 v8, 0xbfb8aa3b, v6
	v_exp_f32_e32 v8, v8
	s_nop 0
	v_add_f32_e32 v8, 1.0, v8
	v_rcp_f32_e32 v8, v8
	s_nop 0
	v_mul_f32_e32 v6, v6, v8
	v_mul_f32_e32 v6, v6, v130
	v_mul_f32_e32 v11, 0x3e000000, v6
	v_mul_f32_e32 v6, 0x3c800000, v135
	v_mul_f32_e32 v8, 0xbfb8aa3b, v6
	v_exp_f32_e32 v8, v8
	s_nop 0
	v_add_f32_e32 v8, 1.0, v8
	v_rcp_f32_e32 v8, v8
	s_nop 0
	v_mul_f32_e32 v6, v6, v8
	v_mul_f32_e32 v6, v6, v131
	v_mul_f32_e32 v12, 0x3e000000, v6
	v_mul_f32_e32 v6, 0x3c800000, v136
	v_mul_f32_e32 v8, 0xbfb8aa3b, v6
	v_exp_f32_e32 v8, v8
	s_nop 0
	v_add_f32_e32 v8, 1.0, v8
	v_rcp_f32_e32 v8, v8
	s_nop 0
	v_mul_f32_e32 v6, v6, v8
	v_mul_f32_e32 v6, v6, v132
	v_mul_f32_e32 v13, 0x3e000000, v6
	v_mul_f32_e32 v6, 0x3c800000, v137
	v_mul_f32_e32 v8, 0xbfb8aa3b, v6
	v_exp_f32_e32 v8, v8
	s_nop 0
	v_add_f32_e32 v8, 1.0, v8
	v_rcp_f32_e32 v8, v8
	s_nop 0
	v_mul_f32_e32 v6, v6, v8
	v_mov_b32_e32 v8, v163
	v_cvt_pk_fp8_f32 v8, v5, v7
	v_med3_f32 v5, v9, s10, v190
	v_med3_f32 v7, v10, s10, v190
	v_mov_b32_e32 v9, v163
	v_cvt_pk_fp8_f32 v8, v5, v7 op_sel:[0,0,1]
	v_med3_f32 v5, v11, s10, v190
	v_med3_f32 v7, v12, s10, v190
	v_cvt_pk_fp8_f32 v9, v5, v7
	v_mul_f32_e32 v6, v6, v133
	v_mul_f32_e32 v14, 0x3e000000, v6
	v_add_u32_e32 v6, 16, v4
	v_med3_f32 v5, v13, s10, v190
	v_med3_f32 v7, v14, s10, v190
	v_cvt_pk_fp8_f32 v9, v5, v7 op_sel:[0,0,1]
	v_ashrrev_i32_e32 v7, 31, v6
	v_lshlrev_b64 v[6:7], 7, v[6:7]
	v_lshl_add_u64 v[6:7], s[14:15], 0, v[6:7]
	v_lshl_add_u64 v[6:7], v[6:7], 0, v[2:3]
	v_mul_f32_e32 v5, 0x3c800000, v126
	global_store_dwordx2 v[6:7], v[8:9], off
	v_mul_f32_e32 v6, 0xbfb8aa3b, v5
	v_exp_f32_e32 v6, v6
	s_nop 0
	v_add_f32_e32 v6, 1.0, v6
	v_rcp_f32_e32 v6, v6
	s_nop 0
	v_mul_f32_e32 v5, v5, v6
	v_mul_f32_e32 v6, 0x3c800000, v127
	v_mul_f32_e32 v7, 0xbfb8aa3b, v6
	v_exp_f32_e32 v7, v7
	v_mul_f32_e32 v5, v5, v122
	v_mul_f32_e32 v5, 0x3e000000, v5
	v_med3_f32 v5, v5, s10, v190
	v_add_f32_e32 v7, 1.0, v7
	v_rcp_f32_e32 v7, v7
	s_nop 0
	v_mul_f32_e32 v6, v6, v7
	v_mul_f32_e32 v6, v6, v123
	v_mul_f32_e32 v7, 0x3e000000, v6
	v_mul_f32_e32 v6, 0x3c800000, v128
	v_mul_f32_e32 v8, 0xbfb8aa3b, v6
	v_exp_f32_e32 v8, v8
	v_med3_f32 v7, v7, s10, v190
	v_add_f32_e32 v8, 1.0, v8
	v_rcp_f32_e32 v8, v8
	s_nop 0
	v_mul_f32_e32 v6, v6, v8
	v_mul_f32_e32 v6, v6, v124
	v_mul_f32_e32 v9, 0x3e000000, v6
	v_mul_f32_e32 v6, 0x3c800000, v129
	v_mul_f32_e32 v8, 0xbfb8aa3b, v6
	v_exp_f32_e32 v8, v8
	s_nop 0
	v_add_f32_e32 v8, 1.0, v8
	v_rcp_f32_e32 v8, v8
	s_nop 0
	v_mul_f32_e32 v6, v6, v8
	v_mul_f32_e32 v6, v6, v125
	v_mul_f32_e32 v10, 0x3e000000, v6
	v_mul_f32_e32 v6, 0x3c800000, v118
	v_mul_f32_e32 v8, 0xbfb8aa3b, v6
	v_exp_f32_e32 v8, v8
	s_nop 0
	v_add_f32_e32 v8, 1.0, v8
	v_rcp_f32_e32 v8, v8
	s_nop 0
	v_mul_f32_e32 v6, v6, v8
	v_mul_f32_e32 v6, v6, v114
	v_mul_f32_e32 v11, 0x3e000000, v6
	v_mul_f32_e32 v6, 0x3c800000, v119
	v_mul_f32_e32 v8, 0xbfb8aa3b, v6
	v_exp_f32_e32 v8, v8
	s_nop 0
	v_add_f32_e32 v8, 1.0, v8
	v_rcp_f32_e32 v8, v8
	s_nop 0
	v_mul_f32_e32 v6, v6, v8
	v_mul_f32_e32 v6, v6, v115
	v_mul_f32_e32 v12, 0x3e000000, v6
	v_mul_f32_e32 v6, 0x3c800000, v120
	v_mul_f32_e32 v8, 0xbfb8aa3b, v6
	v_exp_f32_e32 v8, v8
	s_nop 0
	v_add_f32_e32 v8, 1.0, v8
	v_rcp_f32_e32 v8, v8
	s_nop 0
	v_mul_f32_e32 v6, v6, v8
	v_mul_f32_e32 v6, v6, v116
	v_mul_f32_e32 v13, 0x3e000000, v6
	v_mul_f32_e32 v6, 0x3c800000, v121
	v_mul_f32_e32 v8, 0xbfb8aa3b, v6
	v_exp_f32_e32 v8, v8
	s_nop 0
	v_add_f32_e32 v8, 1.0, v8
	v_rcp_f32_e32 v8, v8
	s_nop 0
	v_mul_f32_e32 v6, v6, v8
	v_mov_b32_e32 v8, v163
	v_cvt_pk_fp8_f32 v8, v5, v7
	v_med3_f32 v5, v9, s10, v190
	v_med3_f32 v7, v10, s10, v190
	v_mov_b32_e32 v9, v163
	v_cvt_pk_fp8_f32 v8, v5, v7 op_sel:[0,0,1]
	v_med3_f32 v5, v11, s10, v190
	v_med3_f32 v7, v12, s10, v190
	v_cvt_pk_fp8_f32 v9, v5, v7
	v_mul_f32_e32 v6, v6, v117
	v_mul_f32_e32 v14, 0x3e000000, v6
	v_add_u32_e32 v6, 32, v4
	v_med3_f32 v5, v13, s10, v190
	v_med3_f32 v7, v14, s10, v190
	v_cvt_pk_fp8_f32 v9, v5, v7 op_sel:[0,0,1]
	v_ashrrev_i32_e32 v7, 31, v6
	v_lshlrev_b64 v[6:7], 7, v[6:7]
	v_lshl_add_u64 v[6:7], s[14:15], 0, v[6:7]
	v_lshl_add_u64 v[6:7], v[6:7], 0, v[2:3]
	v_mul_f32_e32 v5, 0x3c800000, v110
	global_store_dwordx2 v[6:7], v[8:9], off
	v_mul_f32_e32 v6, 0xbfb8aa3b, v5
	v_exp_f32_e32 v6, v6
	s_nop 0
	v_add_f32_e32 v6, 1.0, v6
	v_rcp_f32_e32 v6, v6
	s_nop 0
	v_mul_f32_e32 v5, v5, v6
	v_mul_f32_e32 v6, 0x3c800000, v111
	v_mul_f32_e32 v7, 0xbfb8aa3b, v6
	v_exp_f32_e32 v7, v7
	v_mul_f32_e32 v5, v5, v106
	v_mul_f32_e32 v5, 0x3e000000, v5
	v_med3_f32 v5, v5, s10, v190
	v_add_f32_e32 v7, 1.0, v7
	v_rcp_f32_e32 v7, v7
	s_nop 0
	v_mul_f32_e32 v6, v6, v7
	v_mul_f32_e32 v6, v6, v107
	v_mul_f32_e32 v7, 0x3e000000, v6
	v_mul_f32_e32 v6, 0x3c800000, v112
	v_mul_f32_e32 v8, 0xbfb8aa3b, v6
	v_exp_f32_e32 v8, v8
	v_med3_f32 v7, v7, s10, v190
	v_add_f32_e32 v8, 1.0, v8
	v_rcp_f32_e32 v8, v8
	s_nop 0
	v_mul_f32_e32 v6, v6, v8
	v_mul_f32_e32 v6, v6, v108
	v_mul_f32_e32 v9, 0x3e000000, v6
	v_mul_f32_e32 v6, 0x3c800000, v113
	v_mul_f32_e32 v8, 0xbfb8aa3b, v6
	v_exp_f32_e32 v8, v8
	s_nop 0
	v_add_f32_e32 v8, 1.0, v8
	v_rcp_f32_e32 v8, v8
	s_nop 0
	v_mul_f32_e32 v6, v6, v8
	v_mul_f32_e32 v6, v6, v109
	v_mul_f32_e32 v10, 0x3e000000, v6
	v_mul_f32_e32 v6, 0x3c800000, v102
	v_mul_f32_e32 v8, 0xbfb8aa3b, v6
	v_exp_f32_e32 v8, v8
	s_nop 0
	v_add_f32_e32 v8, 1.0, v8
	v_rcp_f32_e32 v8, v8
	s_nop 0
	v_mul_f32_e32 v6, v6, v8
	v_mul_f32_e32 v6, v6, v98
	v_mul_f32_e32 v11, 0x3e000000, v6
	v_mul_f32_e32 v6, 0x3c800000, v103
	v_mul_f32_e32 v8, 0xbfb8aa3b, v6
	v_exp_f32_e32 v8, v8
	s_nop 0
	v_add_f32_e32 v8, 1.0, v8
	v_rcp_f32_e32 v8, v8
	s_nop 0
	v_mul_f32_e32 v6, v6, v8
	v_mul_f32_e32 v6, v6, v99
	v_mul_f32_e32 v12, 0x3e000000, v6
	v_mul_f32_e32 v6, 0x3c800000, v104
	v_mul_f32_e32 v8, 0xbfb8aa3b, v6
	v_exp_f32_e32 v8, v8
	s_nop 0
	v_add_f32_e32 v8, 1.0, v8
	v_rcp_f32_e32 v8, v8
	s_nop 0
	v_mul_f32_e32 v6, v6, v8
	v_mul_f32_e32 v6, v6, v100
	v_mul_f32_e32 v13, 0x3e000000, v6
	v_mul_f32_e32 v6, 0x3c800000, v105
	v_mul_f32_e32 v8, 0xbfb8aa3b, v6
	v_exp_f32_e32 v8, v8
	s_nop 0
	v_add_f32_e32 v8, 1.0, v8
	v_rcp_f32_e32 v8, v8
	s_nop 0
	v_mul_f32_e32 v6, v6, v8
	v_mov_b32_e32 v8, v163
	v_cvt_pk_fp8_f32 v8, v5, v7
	v_med3_f32 v5, v9, s10, v190
	v_med3_f32 v7, v10, s10, v190
	v_mov_b32_e32 v9, v163
	v_cvt_pk_fp8_f32 v8, v5, v7 op_sel:[0,0,1]
	v_med3_f32 v5, v11, s10, v190
	v_med3_f32 v7, v12, s10, v190
	v_cvt_pk_fp8_f32 v9, v5, v7
	v_mul_f32_e32 v6, v6, v101
	v_mul_f32_e32 v14, 0x3e000000, v6
	v_add_u32_e32 v6, 48, v4
	v_med3_f32 v5, v13, s10, v190
	v_med3_f32 v7, v14, s10, v190
	v_cvt_pk_fp8_f32 v9, v5, v7 op_sel:[0,0,1]
	v_ashrrev_i32_e32 v7, 31, v6
	v_lshlrev_b64 v[6:7], 7, v[6:7]
	v_lshl_add_u64 v[6:7], s[14:15], 0, v[6:7]
	v_lshl_add_u64 v[6:7], v[6:7], 0, v[2:3]
	v_mul_f32_e32 v5, 0x3c800000, v94
	global_store_dwordx2 v[6:7], v[8:9], off
	v_mul_f32_e32 v7, 0xbfb8aa3b, v5
	v_exp_f32_e32 v7, v7
	v_add_u32_e32 v6, 0x80, v4
	v_add_f32_e32 v7, 1.0, v7
	v_rcp_f32_e32 v7, v7
	s_nop 0
	v_mul_f32_e32 v5, v5, v7
	v_mul_f32_e32 v7, 0x3c800000, v95
	v_mul_f32_e32 v8, 0xbfb8aa3b, v7
	v_exp_f32_e32 v8, v8
	v_mul_f32_e32 v5, v5, v90
	v_mul_f32_e32 v5, 0x3e000000, v5
	v_med3_f32 v5, v5, s10, v190
	v_add_f32_e32 v8, 1.0, v8
	v_rcp_f32_e32 v8, v8
	s_nop 0
	v_mul_f32_e32 v7, v7, v8
	v_mul_f32_e32 v8, 0x3c800000, v96
	v_mul_f32_e32 v9, 0xbfb8aa3b, v8
	v_exp_f32_e32 v9, v9
	v_mul_f32_e32 v7, v7, v91
	v_mul_f32_e32 v7, 0x3e000000, v7
	v_med3_f32 v7, v7, s10, v190
	v_add_f32_e32 v9, 1.0, v9
	v_rcp_f32_e32 v9, v9
	s_nop 0
	v_mul_f32_e32 v8, v8, v9
	v_mul_f32_e32 v8, v8, v92
	v_mul_f32_e32 v9, 0x3e000000, v8
	v_mul_f32_e32 v8, 0x3c800000, v97
	v_mul_f32_e32 v10, 0xbfb8aa3b, v8
	v_exp_f32_e32 v10, v10
	s_nop 0
	v_add_f32_e32 v10, 1.0, v10
	v_rcp_f32_e32 v10, v10
	s_nop 0
	v_mul_f32_e32 v8, v8, v10
	v_mul_f32_e32 v8, v8, v93
	v_mul_f32_e32 v10, 0x3e000000, v8
	v_mul_f32_e32 v8, 0x3c800000, v86
	v_mul_f32_e32 v11, 0xbfb8aa3b, v8
	v_exp_f32_e32 v11, v11
	s_nop 0
	v_add_f32_e32 v11, 1.0, v11
	v_rcp_f32_e32 v11, v11
	s_nop 0
	v_mul_f32_e32 v8, v8, v11
	v_mul_f32_e32 v8, v8, v82
	v_mul_f32_e32 v11, 0x3e000000, v8
	v_mul_f32_e32 v8, 0x3c800000, v87
	v_mul_f32_e32 v12, 0xbfb8aa3b, v8
	v_exp_f32_e32 v12, v12
	s_nop 0
	v_add_f32_e32 v12, 1.0, v12
	v_rcp_f32_e32 v12, v12
	s_nop 0
	v_mul_f32_e32 v8, v8, v12
	v_mul_f32_e32 v8, v8, v83
	v_mul_f32_e32 v12, 0x3e000000, v8
	v_mul_f32_e32 v8, 0x3c800000, v88
	v_mul_f32_e32 v13, 0xbfb8aa3b, v8
	v_exp_f32_e32 v13, v13
	s_nop 0
	v_add_f32_e32 v13, 1.0, v13
	v_rcp_f32_e32 v13, v13
	s_nop 0
	v_mul_f32_e32 v8, v8, v13
	v_mul_f32_e32 v8, v8, v84
	v_mul_f32_e32 v13, 0x3e000000, v8
	v_mul_f32_e32 v8, 0x3c800000, v89
	v_mul_f32_e32 v14, 0xbfb8aa3b, v8
	v_exp_f32_e32 v14, v14
	s_nop 0
	v_add_f32_e32 v14, 1.0, v14
	v_rcp_f32_e32 v14, v14
	s_nop 0
	v_mul_f32_e32 v8, v8, v14
	v_mul_f32_e32 v8, v8, v85
	v_mul_f32_e32 v14, 0x3e000000, v8
	v_mov_b32_e32 v8, v163
	v_cvt_pk_fp8_f32 v8, v5, v7
	v_med3_f32 v5, v9, s10, v190
	v_med3_f32 v7, v10, s10, v190
	v_mov_b32_e32 v9, v163
	v_cvt_pk_fp8_f32 v8, v5, v7 op_sel:[0,0,1]
	v_med3_f32 v5, v11, s10, v190
	v_med3_f32 v7, v12, s10, v190
	v_cvt_pk_fp8_f32 v9, v5, v7
	v_med3_f32 v5, v13, s10, v190
	v_med3_f32 v7, v14, s10, v190
	v_cvt_pk_fp8_f32 v9, v5, v7 op_sel:[0,0,1]
	v_ashrrev_i32_e32 v7, 31, v6
	v_lshlrev_b64 v[6:7], 7, v[6:7]
	v_lshl_add_u64 v[6:7], s[14:15], 0, v[6:7]
	v_lshl_add_u64 v[6:7], v[6:7], 0, v[2:3]
	v_mul_f32_e32 v5, 0x3c800000, v78
	global_store_dwordx2 v[6:7], v[8:9], off
	v_mul_f32_e32 v6, 0xbfb8aa3b, v5
	v_exp_f32_e32 v6, v6
	s_nop 0
	v_add_f32_e32 v6, 1.0, v6
	v_rcp_f32_e32 v6, v6
	s_nop 0
	v_mul_f32_e32 v5, v5, v6
	v_mul_f32_e32 v6, 0x3c800000, v79
	v_mul_f32_e32 v7, 0xbfb8aa3b, v6
	v_exp_f32_e32 v7, v7
	v_mul_f32_e32 v5, v5, v74
	v_mul_f32_e32 v5, 0x3e000000, v5
	v_med3_f32 v5, v5, s10, v190
	v_add_f32_e32 v7, 1.0, v7
	v_rcp_f32_e32 v7, v7
	s_nop 0
	v_mul_f32_e32 v6, v6, v7
	v_mul_f32_e32 v6, v6, v75
	v_mul_f32_e32 v7, 0x3e000000, v6
	v_mul_f32_e32 v6, 0x3c800000, v80
	v_mul_f32_e32 v8, 0xbfb8aa3b, v6
	v_exp_f32_e32 v8, v8
	v_med3_f32 v7, v7, s10, v190
	v_add_f32_e32 v8, 1.0, v8
	v_rcp_f32_e32 v8, v8
	s_nop 0
	v_mul_f32_e32 v6, v6, v8
	v_mul_f32_e32 v6, v6, v76
	v_mul_f32_e32 v9, 0x3e000000, v6
	v_mul_f32_e32 v6, 0x3c800000, v81
	v_mul_f32_e32 v8, 0xbfb8aa3b, v6
	v_exp_f32_e32 v8, v8
	s_nop 0
	v_add_f32_e32 v8, 1.0, v8
	v_rcp_f32_e32 v8, v8
	s_nop 0
	v_mul_f32_e32 v6, v6, v8
	v_mul_f32_e32 v6, v6, v77
	v_mul_f32_e32 v10, 0x3e000000, v6
	v_mul_f32_e32 v6, 0x3c800000, v70
	v_mul_f32_e32 v8, 0xbfb8aa3b, v6
	v_exp_f32_e32 v8, v8
	s_nop 0
	v_add_f32_e32 v8, 1.0, v8
	v_rcp_f32_e32 v8, v8
	s_nop 0
	v_mul_f32_e32 v6, v6, v8
	v_mul_f32_e32 v6, v6, v66
	v_mul_f32_e32 v11, 0x3e000000, v6
	v_mul_f32_e32 v6, 0x3c800000, v71
	v_mul_f32_e32 v8, 0xbfb8aa3b, v6
	v_exp_f32_e32 v8, v8
	s_nop 0
	v_add_f32_e32 v8, 1.0, v8
	v_rcp_f32_e32 v8, v8
	s_nop 0
	v_mul_f32_e32 v6, v6, v8
	v_mul_f32_e32 v6, v6, v67
	v_mul_f32_e32 v12, 0x3e000000, v6
	v_mul_f32_e32 v6, 0x3c800000, v72
	v_mul_f32_e32 v8, 0xbfb8aa3b, v6
	v_exp_f32_e32 v8, v8
	s_nop 0
	v_add_f32_e32 v8, 1.0, v8
	v_rcp_f32_e32 v8, v8
	s_nop 0
	v_mul_f32_e32 v6, v6, v8
	v_mul_f32_e32 v6, v6, v68
	v_mul_f32_e32 v13, 0x3e000000, v6
	v_mul_f32_e32 v6, 0x3c800000, v73
	v_mul_f32_e32 v8, 0xbfb8aa3b, v6
	v_exp_f32_e32 v8, v8
	s_nop 0
	v_add_f32_e32 v8, 1.0, v8
	v_rcp_f32_e32 v8, v8
	s_nop 0
	v_mul_f32_e32 v6, v6, v8
	v_mov_b32_e32 v8, v163
	v_cvt_pk_fp8_f32 v8, v5, v7
	v_med3_f32 v5, v9, s10, v190
	v_med3_f32 v7, v10, s10, v190
	v_mov_b32_e32 v9, v163
	v_cvt_pk_fp8_f32 v8, v5, v7 op_sel:[0,0,1]
	v_med3_f32 v5, v11, s10, v190
	v_med3_f32 v7, v12, s10, v190
	v_cvt_pk_fp8_f32 v9, v5, v7
	v_mul_f32_e32 v6, v6, v69
	v_mul_f32_e32 v14, 0x3e000000, v6
	v_add_u32_e32 v6, 0x90, v4
	v_med3_f32 v5, v13, s10, v190
	v_med3_f32 v7, v14, s10, v190
	v_cvt_pk_fp8_f32 v9, v5, v7 op_sel:[0,0,1]
	v_ashrrev_i32_e32 v7, 31, v6
	v_lshlrev_b64 v[6:7], 7, v[6:7]
	v_lshl_add_u64 v[6:7], s[14:15], 0, v[6:7]
	v_lshl_add_u64 v[6:7], v[6:7], 0, v[2:3]
	v_mul_f32_e32 v5, 0x3c800000, v62
	global_store_dwordx2 v[6:7], v[8:9], off
	v_mul_f32_e32 v6, 0xbfb8aa3b, v5
	v_exp_f32_e32 v6, v6
	s_nop 0
	v_add_f32_e32 v6, 1.0, v6
	v_rcp_f32_e32 v6, v6
	s_nop 0
	v_mul_f32_e32 v5, v5, v6
	v_mul_f32_e32 v6, 0x3c800000, v63
	v_mul_f32_e32 v7, 0xbfb8aa3b, v6
	v_exp_f32_e32 v7, v7
	v_mul_f32_e32 v5, v5, v58
	v_mul_f32_e32 v5, 0x3e000000, v5
	v_med3_f32 v5, v5, s10, v190
	v_add_f32_e32 v7, 1.0, v7
	v_rcp_f32_e32 v7, v7
	s_nop 0
	v_mul_f32_e32 v6, v6, v7
	v_mul_f32_e32 v6, v6, v59
	v_mul_f32_e32 v7, 0x3e000000, v6
	v_mul_f32_e32 v6, 0x3c800000, v64
	v_mul_f32_e32 v8, 0xbfb8aa3b, v6
	v_exp_f32_e32 v8, v8
	v_med3_f32 v7, v7, s10, v190
	v_add_f32_e32 v8, 1.0, v8
	v_rcp_f32_e32 v8, v8
	s_nop 0
	v_mul_f32_e32 v6, v6, v8
	v_mul_f32_e32 v6, v6, v60
	v_mul_f32_e32 v9, 0x3e000000, v6
	v_mul_f32_e32 v6, 0x3c800000, v65
	v_mul_f32_e32 v8, 0xbfb8aa3b, v6
	v_exp_f32_e32 v8, v8
	s_nop 0
	v_add_f32_e32 v8, 1.0, v8
	v_rcp_f32_e32 v8, v8
	s_nop 0
	v_mul_f32_e32 v6, v6, v8
	v_mul_f32_e32 v6, v6, v61
	v_mul_f32_e32 v10, 0x3e000000, v6
	v_mul_f32_e32 v6, 0x3c800000, v54
	v_mul_f32_e32 v8, 0xbfb8aa3b, v6
	v_exp_f32_e32 v8, v8
	s_nop 0
	v_add_f32_e32 v8, 1.0, v8
	v_rcp_f32_e32 v8, v8
	s_nop 0
	v_mul_f32_e32 v6, v6, v8
	v_mul_f32_e32 v6, v6, v50
	v_mul_f32_e32 v11, 0x3e000000, v6
	v_mul_f32_e32 v6, 0x3c800000, v55
	v_mul_f32_e32 v8, 0xbfb8aa3b, v6
	v_exp_f32_e32 v8, v8
	s_nop 0
	v_add_f32_e32 v8, 1.0, v8
	v_rcp_f32_e32 v8, v8
	s_nop 0
	v_mul_f32_e32 v6, v6, v8
	v_mul_f32_e32 v6, v6, v51
	v_mul_f32_e32 v12, 0x3e000000, v6
	v_mul_f32_e32 v6, 0x3c800000, v56
	v_mul_f32_e32 v8, 0xbfb8aa3b, v6
	v_exp_f32_e32 v8, v8
	s_nop 0
	v_add_f32_e32 v8, 1.0, v8
	v_rcp_f32_e32 v8, v8
	s_nop 0
	v_mul_f32_e32 v6, v6, v8
	v_mul_f32_e32 v6, v6, v52
	v_mul_f32_e32 v13, 0x3e000000, v6
	v_mul_f32_e32 v6, 0x3c800000, v57
	v_mul_f32_e32 v8, 0xbfb8aa3b, v6
	v_exp_f32_e32 v8, v8
	s_nop 0
	v_add_f32_e32 v8, 1.0, v8
	v_rcp_f32_e32 v8, v8
	s_nop 0
	v_mul_f32_e32 v6, v6, v8
	v_mov_b32_e32 v8, v163
	v_cvt_pk_fp8_f32 v8, v5, v7
	v_med3_f32 v5, v9, s10, v190
	v_med3_f32 v7, v10, s10, v190
	v_mov_b32_e32 v9, v163
	v_cvt_pk_fp8_f32 v8, v5, v7 op_sel:[0,0,1]
	v_med3_f32 v5, v11, s10, v190
	v_med3_f32 v7, v12, s10, v190
	v_cvt_pk_fp8_f32 v9, v5, v7
	v_mul_f32_e32 v6, v6, v53
	v_mul_f32_e32 v14, 0x3e000000, v6
	v_add_u32_e32 v6, 0xa0, v4
	v_med3_f32 v5, v13, s10, v190
	v_med3_f32 v7, v14, s10, v190
	v_cvt_pk_fp8_f32 v9, v5, v7 op_sel:[0,0,1]
	v_ashrrev_i32_e32 v7, 31, v6
	v_lshlrev_b64 v[6:7], 7, v[6:7]
	v_lshl_add_u64 v[6:7], s[14:15], 0, v[6:7]
	v_lshl_add_u64 v[6:7], v[6:7], 0, v[2:3]
	v_mul_f32_e32 v5, 0x3c800000, v46
	global_store_dwordx2 v[6:7], v[8:9], off
	v_mul_f32_e32 v6, 0xbfb8aa3b, v5
	v_exp_f32_e32 v6, v6
	v_add_u32_e32 v4, 0xb0, v4
	v_add_f32_e32 v6, 1.0, v6
	v_rcp_f32_e32 v6, v6
	s_nop 0
	v_mul_f32_e32 v5, v5, v6
	v_mul_f32_e32 v6, 0x3c800000, v47
	v_mul_f32_e32 v7, 0xbfb8aa3b, v6
	v_exp_f32_e32 v7, v7
	v_mul_f32_e32 v5, v5, v42
	v_mul_f32_e32 v5, 0x3e000000, v5
	v_med3_f32 v5, v5, s10, v190
	v_add_f32_e32 v7, 1.0, v7
	v_rcp_f32_e32 v7, v7
	s_nop 0
	v_mul_f32_e32 v6, v6, v7
	v_mul_f32_e32 v7, 0x3c800000, v48
	v_mul_f32_e32 v8, 0xbfb8aa3b, v7
	v_exp_f32_e32 v8, v8
	v_mul_f32_e32 v6, v6, v43
	v_mul_f32_e32 v6, 0x3e000000, v6
	v_add_f32_e32 v8, 1.0, v8
	v_rcp_f32_e32 v8, v8
	s_nop 0
	v_mul_f32_e32 v7, v7, v8
	v_mul_f32_e32 v8, 0x3c800000, v49
	v_mul_f32_e32 v9, 0xbfb8aa3b, v8
	v_exp_f32_e32 v9, v9
	v_mul_f32_e32 v7, v7, v44
	v_mul_f32_e32 v7, 0x3e000000, v7
	v_add_f32_e32 v9, 1.0, v9
	v_rcp_f32_e32 v9, v9
	s_nop 0
	v_mul_f32_e32 v8, v8, v9
	v_mul_f32_e32 v9, 0x3c800000, v38
	v_mul_f32_e32 v10, 0xbfb8aa3b, v9
	v_exp_f32_e32 v10, v10
	v_mul_f32_e32 v8, v8, v45
	v_mul_f32_e32 v8, 0x3e000000, v8
	v_add_f32_e32 v10, 1.0, v10
	v_rcp_f32_e32 v10, v10
	s_nop 0
	v_mul_f32_e32 v9, v9, v10
	v_mul_f32_e32 v10, 0x3c800000, v39
	v_mul_f32_e32 v11, 0xbfb8aa3b, v10
	v_exp_f32_e32 v11, v11
	v_mul_f32_e32 v9, v9, v34
	v_mul_f32_e32 v9, 0x3e000000, v9
	v_add_f32_e32 v11, 1.0, v11
	v_rcp_f32_e32 v11, v11
	s_nop 0
	v_mul_f32_e32 v10, v10, v11
	v_mul_f32_e32 v11, 0x3c800000, v40
	v_mul_f32_e32 v12, 0xbfb8aa3b, v11
	v_exp_f32_e32 v12, v12
	v_mul_f32_e32 v10, v10, v35
	v_mul_f32_e32 v10, 0x3e000000, v10
	v_add_f32_e32 v12, 1.0, v12
	v_rcp_f32_e32 v12, v12
	s_nop 0
	v_mul_f32_e32 v11, v11, v12
	v_mul_f32_e32 v12, 0x3c800000, v41
	v_mul_f32_e32 v13, 0xbfb8aa3b, v12
	v_exp_f32_e32 v13, v13
	v_mul_f32_e32 v11, v11, v36
	v_mul_f32_e32 v11, 0x3e000000, v11
	v_add_f32_e32 v13, 1.0, v13
	v_rcp_f32_e32 v13, v13
	s_nop 0
	v_mul_f32_e32 v12, v12, v13
	v_med3_f32 v13, v6, s10, v190
	v_mov_b32_e32 v6, v163
	v_cvt_pk_fp8_f32 v6, v5, v13
	v_med3_f32 v5, v7, s10, v190
	v_med3_f32 v7, v8, s10, v190
	v_med3_f32 v8, v10, s10, v190
	v_cvt_pk_fp8_f32 v6, v5, v7 op_sel:[0,0,1]
	v_med3_f32 v5, v9, s10, v190
	v_mov_b32_e32 v7, v163
	v_cvt_pk_fp8_f32 v7, v5, v8
	v_mul_f32_e32 v12, v12, v37
	v_mul_f32_e32 v12, 0x3e000000, v12
	v_med3_f32 v5, v11, s10, v190
	v_med3_f32 v8, v12, s10, v190
	v_cvt_pk_fp8_f32 v7, v5, v8 op_sel:[0,0,1]
	v_ashrrev_i32_e32 v5, 31, v4
	v_lshlrev_b64 v[4:5], 7, v[4:5]
	v_lshl_add_u64 v[4:5], s[14:15], 0, v[4:5]
	v_lshl_add_u64 v[2:3], v[4:5], 0, v[2:3]
	global_store_dwordx2 v[2:3], v[6:7], off
	s_cbranch_vccz .LBB0_2030
	s_waitcnt vmcnt(0)
	s_cmpk_gt_u32 s42, 0xff
	s_cbranch_scc1 .LBB0_1976
	s_barrier
	s_branch .LBB0_1976

.LBB0_2108:
	ds_read_b128 v[2:5], v169
	ds_read_b128 v[6:9], v169 offset:1024
	ds_read_b128 v[10:13], v169 offset:2048
	ds_read_b128 v[14:17], v169 offset:3072
	s_add_u32 s0, s30, 0x4000
	s_addc_u32 s1, s31, 0
	s_cmp_eq_u32 s53, 4
	s_cselect_b32 s38, s49, s0
	s_cselect_b32 s39, s23, s1
	s_cselect_b32 s34, s50, s51
	s_cselect_b32 s35, s21, s52
	s_add_u32 s36, s38, 0x8000
	s_addc_u32 s37, s39, 0
	v_lshl_add_u64 v[162:163], s[30:31], 0, v[156:157]
	s_add_i32 m0, s10, 0xc000
	ds_read_b128 v[174:177], v170
	ds_read_b128 v[178:181], v170 offset:1024
	ds_read_b128 v[182:185], v170 offset:2048
	ds_read_b128 v[186:189], v170 offset:3072
	ds_read_b128 v[190:193], v170 offset:4096
	ds_read_b128 v[194:197], v170 offset:5120
	ds_read_b128 v[198:201], v170 offset:6144
	ds_read_b128 v[202:205], v170 offset:7168
	global_load_lds_dwordx4 v[162:163], off nt
	v_lshl_add_u64 v[162:163], s[30:31], 0, v[154:155]
	s_add_i32 m0, s10, 0xe000
	s_nop 0
	global_load_lds_dwordx4 v[162:163], off nt
	s_waitcnt lgkmcnt(8)
	s_waitcnt vmcnt(10)
	s_barrier
	s_waitcnt lgkmcnt(0)
	s_waitcnt lgkmcnt(0)
	v_mfma_scale_f32_16x16x128_f8f6f4 v[142:145], v[2:9], v[174:181], v[142:145], v171, v171 op_sel_hi:[0,0,0]
	v_mfma_scale_f32_16x16x128_f8f6f4 v[138:141], v[10:17], v[174:181], v[138:141], v171, v171 op_sel_hi:[0,0,0]
	v_mfma_scale_f32_16x16x128_f8f6f4 v[126:129], v[2:9], v[182:189], v[126:129], v171, v171 op_sel_hi:[0,0,0]
	v_mfma_scale_f32_16x16x128_f8f6f4 v[122:125], v[10:17], v[182:189], v[122:125], v171, v171 op_sel_hi:[0,0,0]
	v_mfma_scale_f32_16x16x128_f8f6f4 v[110:113], v[2:9], v[190:197], v[110:113], v171, v171 op_sel_hi:[0,0,0]
	v_mfma_scale_f32_16x16x128_f8f6f4 v[106:109], v[10:17], v[190:197], v[106:109], v171, v171 op_sel_hi:[0,0,0]
	v_mfma_scale_f32_16x16x128_f8f6f4 v[94:97], v[2:9], v[198:205], v[94:97], v171, v171 op_sel_hi:[0,0,0]
	v_mfma_scale_f32_16x16x128_f8f6f4 v[90:93], v[10:17], v[198:205], v[90:93], v171, v171 op_sel_hi:[0,0,0]
	s_barrier
	s_add_i32 s0, s45, s9
	v_lshl_add_u64 v[162:163], s[34:35], 0, v[150:151]
	s_mov_b32 m0, s0
	ds_read_b128 v[206:209], v172
	ds_read_b128 v[210:213], v172 offset:1024
	ds_read_b128 v[214:217], v172 offset:2048
	ds_read_b128 v[218:221], v172 offset:3072
	global_load_lds_dwordx4 v[162:163], off
	v_lshl_add_u64 v[164:165], s[34:35], 0, v[146:147]
	s_add_i32 m0, s0, 0x2000
	s_nop 0
	global_load_lds_dwordx4 v[164:165], off
	s_waitcnt vmcnt(10)
	s_barrier
	s_waitcnt lgkmcnt(0)
	s_waitcnt lgkmcnt(0)
	v_mfma_scale_f32_16x16x128_f8f6f4 v[134:137], v[206:213], v[174:181], v[134:137], v171, v171 op_sel_hi:[0,0,0]
	v_mfma_scale_f32_16x16x128_f8f6f4 v[130:133], v[214:221], v[174:181], v[130:133], v171, v171 op_sel_hi:[0,0,0]
	v_mfma_scale_f32_16x16x128_f8f6f4 v[118:121], v[206:213], v[182:189], v[118:121], v171, v171 op_sel_hi:[0,0,0]
	v_mfma_scale_f32_16x16x128_f8f6f4 v[114:117], v[214:221], v[182:189], v[114:117], v171, v171 op_sel_hi:[0,0,0]
	v_mfma_scale_f32_16x16x128_f8f6f4 v[102:105], v[206:213], v[190:197], v[102:105], v171, v171 op_sel_hi:[0,0,0]
	v_mfma_scale_f32_16x16x128_f8f6f4 v[98:101], v[214:221], v[190:197], v[98:101], v171, v171 op_sel_hi:[0,0,0]
	v_mfma_scale_f32_16x16x128_f8f6f4 v[86:89], v[206:213], v[198:205], v[86:89], v171, v171 op_sel_hi:[0,0,0]
	v_mfma_scale_f32_16x16x128_f8f6f4 v[82:85], v[214:221], v[198:205], v[82:85], v171, v171 op_sel_hi:[0,0,0]
	s_mov_b32 m0, s10
	v_lshl_add_u64 v[222:223], s[38:39], 0, v[152:153]
	s_barrier
	ds_read_b128 v[174:177], v170 offset:16384
	ds_read_b128 v[178:181], v170 offset:17408
	ds_read_b128 v[182:185], v170 offset:18432
	ds_read_b128 v[186:189], v170 offset:19456
	ds_read_b128 v[190:193], v170 offset:20480
	ds_read_b128 v[194:197], v170 offset:21504
	ds_read_b128 v[198:201], v170 offset:22528
	ds_read_b128 v[202:205], v170 offset:23552
	global_load_lds_dwordx4 v[222:223], off nt
	v_lshl_add_u64 v[222:223], s[38:39], 0, v[148:149]
	s_mov_b32 m0, s11
	s_nop 0
	global_load_lds_dwordx4 v[222:223], off nt
	s_waitcnt vmcnt(10)
	s_barrier
	s_waitcnt lgkmcnt(0)
	s_waitcnt lgkmcnt(0)
	v_mfma_scale_f32_16x16x128_f8f6f4 v[78:81], v[2:9], v[174:181], v[78:81], v171, v171 op_sel_hi:[0,0,0]
	v_mfma_scale_f32_16x16x128_f8f6f4 v[74:77], v[10:17], v[174:181], v[74:77], v171, v171 op_sel_hi:[0,0,0]
	v_mfma_scale_f32_16x16x128_f8f6f4 v[62:65], v[2:9], v[182:189], v[62:65], v171, v171 op_sel_hi:[0,0,0]
	v_mfma_scale_f32_16x16x128_f8f6f4 v[58:61], v[10:17], v[182:189], v[58:61], v171, v171 op_sel_hi:[0,0,0]
	v_mfma_scale_f32_16x16x128_f8f6f4 v[46:49], v[2:9], v[190:197], v[46:49], v171, v171 op_sel_hi:[0,0,0]
	v_mfma_scale_f32_16x16x128_f8f6f4 v[42:45], v[10:17], v[190:197], v[42:45], v171, v171 op_sel_hi:[0,0,0]
	v_mfma_scale_f32_16x16x128_f8f6f4 v[30:33], v[2:9], v[198:205], v[30:33], v171, v171 op_sel_hi:[0,0,0]
	v_mfma_scale_f32_16x16x128_f8f6f4 v[26:29], v[10:17], v[198:205], v[26:29], v171, v171 op_sel_hi:[0,0,0]
	s_barrier
	s_add_u32 s0, s34, 0x20000
	s_addc_u32 s1, s35, 0
	s_add_i32 s54, s46, s9
	v_lshl_add_u64 v[2:3], s[0:1], 0, v[150:151]
	s_mov_b32 m0, s54
	s_nop 0
	global_load_lds_dwordx4 v[2:3], off
	v_lshl_add_u64 v[2:3], s[0:1], 0, v[146:147]
	s_add_i32 m0, s54, 0x2000
	s_nop 0
	global_load_lds_dwordx4 v[2:3], off
	s_waitcnt vmcnt(10)
	s_barrier
	v_mfma_scale_f32_16x16x128_f8f6f4 v[70:73], v[206:213], v[174:181], v[70:73], v171, v171 op_sel_hi:[0,0,0]
	v_mfma_scale_f32_16x16x128_f8f6f4 v[66:69], v[214:221], v[174:181], v[66:69], v171, v171 op_sel_hi:[0,0,0]
	v_mfma_scale_f32_16x16x128_f8f6f4 v[54:57], v[206:213], v[182:189], v[54:57], v171, v171 op_sel_hi:[0,0,0]
	v_mfma_scale_f32_16x16x128_f8f6f4 v[50:53], v[214:221], v[182:189], v[50:53], v171, v171 op_sel_hi:[0,0,0]
	v_mfma_scale_f32_16x16x128_f8f6f4 v[38:41], v[206:213], v[190:197], v[38:41], v171, v171 op_sel_hi:[0,0,0]
	v_mfma_scale_f32_16x16x128_f8f6f4 v[34:37], v[214:221], v[190:197], v[34:37], v171, v171 op_sel_hi:[0,0,0]
	v_mfma_scale_f32_16x16x128_f8f6f4 v[22:25], v[206:213], v[198:205], v[22:25], v171, v171 op_sel_hi:[0,0,0]
	v_mfma_scale_f32_16x16x128_f8f6f4 v[18:21], v[214:221], v[198:205], v[18:21], v171, v171 op_sel_hi:[0,0,0]
	s_add_i32 s54, 0, 0x18000
	v_add_u32_e32 v14, s54, v168
	s_barrier
	ds_read_b128 v[2:5], v14
	ds_read_b128 v[6:9], v14 offset:1024
	ds_read_b128 v[10:13], v14 offset:2048
	ds_read_b128 v[14:17], v14 offset:3072
	s_add_u32 s0, s38, 0x4000
	s_addc_u32 s1, s39, 0
	s_mov_b32 m0, s19
	v_lshl_add_u64 v[206:207], s[0:1], 0, v[152:153]
	ds_read_b128 v[174:177], v170 offset:32768
	ds_read_b128 v[178:181], v170 offset:33792
	ds_read_b128 v[182:185], v170 offset:34816
	ds_read_b128 v[186:189], v170 offset:35840
	ds_read_b128 v[190:193], v170 offset:36864
	ds_read_b128 v[194:197], v170 offset:37888
	ds_read_b128 v[198:201], v170 offset:38912
	ds_read_b128 v[202:205], v170 offset:39936
	global_load_lds_dwordx4 v[206:207], off nt
	v_lshl_add_u64 v[206:207], s[0:1], 0, v[148:149]
	s_mov_b32 m0, s29
	s_nop 0
	global_load_lds_dwordx4 v[206:207], off nt
	s_waitcnt lgkmcnt(8)
	s_waitcnt vmcnt(10)
	s_barrier
	s_waitcnt lgkmcnt(0)
	s_waitcnt lgkmcnt(0)
	v_mfma_scale_f32_16x16x128_f8f6f4 v[142:145], v[2:9], v[174:181], v[142:145], v171, v171 op_sel_hi:[0,0,0]
	v_mfma_scale_f32_16x16x128_f8f6f4 v[138:141], v[10:17], v[174:181], v[138:141], v171, v171 op_sel_hi:[0,0,0]
	v_mfma_scale_f32_16x16x128_f8f6f4 v[126:129], v[2:9], v[182:189], v[126:129], v171, v171 op_sel_hi:[0,0,0]
	v_mfma_scale_f32_16x16x128_f8f6f4 v[122:125], v[10:17], v[182:189], v[122:125], v171, v171 op_sel_hi:[0,0,0]
	v_mfma_scale_f32_16x16x128_f8f6f4 v[110:113], v[2:9], v[190:197], v[110:113], v171, v171 op_sel_hi:[0,0,0]
	v_mfma_scale_f32_16x16x128_f8f6f4 v[106:109], v[10:17], v[190:197], v[106:109], v171, v171 op_sel_hi:[0,0,0]
	v_mfma_scale_f32_16x16x128_f8f6f4 v[94:97], v[2:9], v[198:205], v[94:97], v171, v171 op_sel_hi:[0,0,0]
	v_mfma_scale_f32_16x16x128_f8f6f4 v[90:93], v[10:17], v[198:205], v[90:93], v171, v171 op_sel_hi:[0,0,0]
	s_barrier
	s_add_i32 s38, 0, 0x1c000
	s_add_i32 s0, s54, s9
	v_add_u32_e32 v218, s38, v168
	v_lshl_add_u64 v[162:163], v[162:163], 0, s[16:17]
	s_mov_b32 m0, s0
	ds_read_b128 v[206:209], v218
	ds_read_b128 v[210:213], v218 offset:1024
	ds_read_b128 v[214:217], v218 offset:2048
	ds_read_b128 v[218:221], v218 offset:3072
	global_load_lds_dwordx4 v[162:163], off
	v_lshl_add_u64 v[162:163], v[164:165], 0, s[16:17]
	s_add_i32 m0, s0, 0x2000
	s_nop 0
	global_load_lds_dwordx4 v[162:163], off
	s_waitcnt vmcnt(10)
	s_barrier
	s_waitcnt lgkmcnt(0)
	s_waitcnt lgkmcnt(0)
	v_mfma_scale_f32_16x16x128_f8f6f4 v[134:137], v[206:213], v[174:181], v[134:137], v171, v171 op_sel_hi:[0,0,0]
	v_mfma_scale_f32_16x16x128_f8f6f4 v[130:133], v[214:221], v[174:181], v[130:133], v171, v171 op_sel_hi:[0,0,0]
	v_mfma_scale_f32_16x16x128_f8f6f4 v[118:121], v[206:213], v[182:189], v[118:121], v171, v171 op_sel_hi:[0,0,0]
	v_mfma_scale_f32_16x16x128_f8f6f4 v[114:117], v[214:221], v[182:189], v[114:117], v171, v171 op_sel_hi:[0,0,0]
	v_mfma_scale_f32_16x16x128_f8f6f4 v[102:105], v[206:213], v[190:197], v[102:105], v171, v171 op_sel_hi:[0,0,0]
	v_mfma_scale_f32_16x16x128_f8f6f4 v[98:101], v[214:221], v[190:197], v[98:101], v171, v171 op_sel_hi:[0,0,0]
	v_mfma_scale_f32_16x16x128_f8f6f4 v[86:89], v[206:213], v[198:205], v[86:89], v171, v171 op_sel_hi:[0,0,0]
	v_mfma_scale_f32_16x16x128_f8f6f4 v[82:85], v[214:221], v[198:205], v[82:85], v171, v171 op_sel_hi:[0,0,0]
	s_mov_b32 m0, s43
	v_lshl_add_u64 v[162:163], s[36:37], 0, v[152:153]
	s_barrier
	ds_read_b128 v[174:177], v170 offset:49152
	ds_read_b128 v[178:181], v170 offset:50176
	ds_read_b128 v[182:185], v170 offset:51200
	ds_read_b128 v[186:189], v170 offset:52224
	ds_read_b128 v[190:193], v170 offset:53248
	ds_read_b128 v[194:197], v170 offset:54272
	ds_read_b128 v[198:201], v170 offset:55296
	ds_read_b128 v[202:205], v170 offset:56320
	global_load_lds_dwordx4 v[162:163], off nt
	v_lshl_add_u64 v[162:163], s[36:37], 0, v[148:149]
	s_mov_b32 m0, s44
	s_nop 0
	global_load_lds_dwordx4 v[162:163], off nt
	s_waitcnt vmcnt(10)
	s_barrier
	s_waitcnt lgkmcnt(0)
	s_waitcnt lgkmcnt(0)
	v_mfma_scale_f32_16x16x128_f8f6f4 v[78:81], v[2:9], v[174:181], v[78:81], v171, v171 op_sel_hi:[0,0,0]
	v_mfma_scale_f32_16x16x128_f8f6f4 v[74:77], v[10:17], v[174:181], v[74:77], v171, v171 op_sel_hi:[0,0,0]
	v_mfma_scale_f32_16x16x128_f8f6f4 v[62:65], v[2:9], v[182:189], v[62:65], v171, v171 op_sel_hi:[0,0,0]
	v_mfma_scale_f32_16x16x128_f8f6f4 v[58:61], v[10:17], v[182:189], v[58:61], v171, v171 op_sel_hi:[0,0,0]
	v_mfma_scale_f32_16x16x128_f8f6f4 v[46:49], v[2:9], v[190:197], v[46:49], v171, v171 op_sel_hi:[0,0,0]
	v_mfma_scale_f32_16x16x128_f8f6f4 v[42:45], v[10:17], v[190:197], v[42:45], v171, v171 op_sel_hi:[0,0,0]
	v_mfma_scale_f32_16x16x128_f8f6f4 v[30:33], v[2:9], v[198:205], v[30:33], v171, v171 op_sel_hi:[0,0,0]
	v_mfma_scale_f32_16x16x128_f8f6f4 v[26:29], v[10:17], v[198:205], v[26:29], v171, v171 op_sel_hi:[0,0,0]
	s_barrier
	s_add_u32 s0, s34, 0x20080
	s_addc_u32 s1, s35, 0
	s_add_i32 s34, s38, s9
	v_lshl_add_u64 v[2:3], s[0:1], 0, v[150:151]
	s_mov_b32 m0, s34
	s_nop 0
	global_load_lds_dwordx4 v[2:3], off
	v_lshl_add_u64 v[2:3], s[0:1], 0, v[146:147]
	s_add_i32 m0, s34, 0x2000
	s_nop 0
	global_load_lds_dwordx4 v[2:3], off
	s_waitcnt vmcnt(10)
	s_barrier
	v_mfma_scale_f32_16x16x128_f8f6f4 v[70:73], v[206:213], v[174:181], v[70:73], v171, v171 op_sel_hi:[0,0,0]
	v_mfma_scale_f32_16x16x128_f8f6f4 v[66:69], v[214:221], v[174:181], v[66:69], v171, v171 op_sel_hi:[0,0,0]
	v_mfma_scale_f32_16x16x128_f8f6f4 v[54:57], v[206:213], v[182:189], v[54:57], v171, v171 op_sel_hi:[0,0,0]
	v_mfma_scale_f32_16x16x128_f8f6f4 v[50:53], v[214:221], v[182:189], v[50:53], v171, v171 op_sel_hi:[0,0,0]
	v_mfma_scale_f32_16x16x128_f8f6f4 v[38:41], v[206:213], v[190:197], v[38:41], v171, v171 op_sel_hi:[0,0,0]
	v_mfma_scale_f32_16x16x128_f8f6f4 v[34:37], v[214:221], v[190:197], v[34:37], v171, v171 op_sel_hi:[0,0,0]
	v_mfma_scale_f32_16x16x128_f8f6f4 v[22:25], v[206:213], v[198:205], v[22:25], v171, v171 op_sel_hi:[0,0,0]
	v_mfma_scale_f32_16x16x128_f8f6f4 v[18:21], v[214:221], v[198:205], v[18:21], v171, v171 op_sel_hi:[0,0,0]
	s_add_i32 s53, s53, 2
	s_add_u32 s51, s51, 0x100
	s_addc_u32 s52, s52, 0
	s_add_u32 s30, s30, 0x10000
	s_addc_u32 s31, s31, 0
	s_cmp_gt_u32 s53, 5
	s_barrier
	s_cbranch_scc0 .LBB0_2108
	v_pk_mul_f32 v[10:11], v[142:143], s[18:19] op_sel_hi:[1,0]
	v_pk_mul_f32 v[8:9], v[144:145], s[18:19] op_sel_hi:[1,0]
	v_med3_f32 v5, v10, s47, v173
	v_med3_f32 v11, v11, s47, v173
	v_mov_b32_e32 v10, 0
	v_cvt_pk_fp8_f32 v10, v5, v11
	v_mov_b32_e32 v3, v166
	v_mov_b32_e32 v2, v167
	s_lshl_b32 s0, s48, 8
	v_pk_mul_f32 v[14:15], v[138:139], s[18:19] op_sel_hi:[1,0]
	v_med3_f32 v5, v8, s47, v173
	v_med3_f32 v8, v9, s47, v173
	s_nop 15
	s_nop 15
	s_or_b32 s0, s0, s42
	v_cvt_pk_fp8_f32 v10, v5, v8 op_sel:[0,0,1]
	v_med3_f32 v5, v14, s47, v173
	v_med3_f32 v8, v15, s47, v173
	v_mov_b32_e32 v11, 0
	v_lshl_add_u32 v2, v2, 3, s0
	s_lshl_b32 s0, s28, 8
	v_cvt_pk_fp8_f32 v11, v5, v8
	s_add_i32 s0, s0, s41
	v_add_u32_e32 v4, s0, v3
	v_pk_mul_f32 v[12:13], v[140:141], s[18:19] op_sel_hi:[1,0]
	v_mov_b32_e32 v6, v4
	v_med3_f32 v5, v12, s47, v173
	v_med3_f32 v8, v13, s47, v173
	v_cvt_pk_fp8_f32 v11, v5, v8 op_sel:[0,0,1]
	v_ashrrev_i32_e32 v7, 31, v6
	v_lshlrev_b64 v[6:7], 10, v[6:7]
	v_ashrrev_i32_e32 v3, 31, v2
	v_lshl_add_u64 v[6:7], s[14:15], 0, v[6:7]
	v_lshl_add_u64 v[6:7], v[6:7], 0, v[2:3]
	global_store_dwordx2 v[6:7], v[10:11], off
	v_pk_mul_f32 v[10:11], v[134:135], s[18:19] op_sel_hi:[1,0]
	v_pk_mul_f32 v[8:9], v[136:137], s[18:19] op_sel_hi:[1,0]
	v_med3_f32 v5, v10, s47, v173
	v_med3_f32 v11, v11, s47, v173
	v_mov_b32_e32 v10, 0
	v_cvt_pk_fp8_f32 v10, v5, v11
	v_pk_mul_f32 v[14:15], v[130:131], s[18:19] op_sel_hi:[1,0]
	v_med3_f32 v5, v8, s47, v173
	v_med3_f32 v8, v9, s47, v173
	v_cvt_pk_fp8_f32 v10, v5, v8 op_sel:[0,0,1]
	v_med3_f32 v5, v14, s47, v173
	v_med3_f32 v8, v15, s47, v173
	v_mov_b32_e32 v11, 0
	v_cvt_pk_fp8_f32 v11, v5, v8
	v_pk_mul_f32 v[12:13], v[132:133], s[18:19] op_sel_hi:[1,0]
	v_pk_mul_f32 v[14:15], v[122:123], s[18:19] op_sel_hi:[1,0]
	v_med3_f32 v5, v12, s47, v173
	v_med3_f32 v8, v13, s47, v173
	v_cvt_pk_fp8_f32 v11, v5, v8 op_sel:[0,0,1]
	v_pk_mul_f32 v[8:9], v[128:129], s[18:19] op_sel_hi:[1,0]
	v_pk_mul_f32 v[12:13], v[124:125], s[18:19] op_sel_hi:[1,0]
	s_and_b64 vcc, exec, s[12:13]
	global_store_dwordx2 v[6:7], v[10:11], off offset:128
	v_pk_mul_f32 v[10:11], v[126:127], s[18:19] op_sel_hi:[1,0]
	v_add_u32_e32 v6, 16, v4
	v_med3_f32 v5, v10, s47, v173
	v_med3_f32 v11, v11, s47, v173
	v_mov_b32_e32 v10, 0
	v_cvt_pk_fp8_f32 v10, v5, v11
	v_med3_f32 v5, v8, s47, v173
	v_med3_f32 v8, v9, s47, v173
	v_mov_b32_e32 v11, 0
	v_cvt_pk_fp8_f32 v10, v5, v8 op_sel:[0,0,1]
	v_med3_f32 v5, v14, s47, v173
	v_med3_f32 v8, v15, s47, v173
	v_cvt_pk_fp8_f32 v11, v5, v8
	v_med3_f32 v5, v12, s47, v173
	v_med3_f32 v8, v13, s47, v173
	v_cvt_pk_fp8_f32 v11, v5, v8 op_sel:[0,0,1]
	v_ashrrev_i32_e32 v7, 31, v6
	v_lshlrev_b64 v[6:7], 10, v[6:7]
	v_lshl_add_u64 v[6:7], s[14:15], 0, v[6:7]
	v_lshl_add_u64 v[6:7], v[6:7], 0, v[2:3]
	global_store_dwordx2 v[6:7], v[10:11], off
	v_pk_mul_f32 v[10:11], v[118:119], s[18:19] op_sel_hi:[1,0]
	v_pk_mul_f32 v[8:9], v[120:121], s[18:19] op_sel_hi:[1,0]
	v_med3_f32 v5, v10, s47, v173
	v_med3_f32 v11, v11, s47, v173
	v_mov_b32_e32 v10, 0
	v_cvt_pk_fp8_f32 v10, v5, v11
	v_pk_mul_f32 v[14:15], v[114:115], s[18:19] op_sel_hi:[1,0]
	v_med3_f32 v5, v8, s47, v173
	v_med3_f32 v8, v9, s47, v173
	v_cvt_pk_fp8_f32 v10, v5, v8 op_sel:[0,0,1]
	v_med3_f32 v5, v14, s47, v173
	v_med3_f32 v8, v15, s47, v173
	v_mov_b32_e32 v11, 0
	v_cvt_pk_fp8_f32 v11, v5, v8
	v_pk_mul_f32 v[12:13], v[116:117], s[18:19] op_sel_hi:[1,0]
	v_pk_mul_f32 v[14:15], v[106:107], s[18:19] op_sel_hi:[1,0]
	v_med3_f32 v5, v12, s47, v173
	v_med3_f32 v8, v13, s47, v173
	v_cvt_pk_fp8_f32 v11, v5, v8 op_sel:[0,0,1]
	v_pk_mul_f32 v[8:9], v[112:113], s[18:19] op_sel_hi:[1,0]
	v_pk_mul_f32 v[12:13], v[108:109], s[18:19] op_sel_hi:[1,0]
	s_mov_b32 s48, s20
	global_store_dwordx2 v[6:7], v[10:11], off offset:128
	v_pk_mul_f32 v[10:11], v[110:111], s[18:19] op_sel_hi:[1,0]
	v_add_u32_e32 v6, 32, v4
	v_med3_f32 v5, v10, s47, v173
	v_med3_f32 v11, v11, s47, v173
	v_mov_b32_e32 v10, 0
	v_cvt_pk_fp8_f32 v10, v5, v11
	v_med3_f32 v5, v8, s47, v173
	v_med3_f32 v8, v9, s47, v173
	v_mov_b32_e32 v11, 0
	v_cvt_pk_fp8_f32 v10, v5, v8 op_sel:[0,0,1]
	v_med3_f32 v5, v14, s47, v173
	v_med3_f32 v8, v15, s47, v173
	v_cvt_pk_fp8_f32 v11, v5, v8
	v_med3_f32 v5, v12, s47, v173
	v_med3_f32 v8, v13, s47, v173
	v_cvt_pk_fp8_f32 v11, v5, v8 op_sel:[0,0,1]
	v_ashrrev_i32_e32 v7, 31, v6
	v_lshlrev_b64 v[6:7], 10, v[6:7]
	v_lshl_add_u64 v[6:7], s[14:15], 0, v[6:7]
	v_lshl_add_u64 v[6:7], v[6:7], 0, v[2:3]
	global_store_dwordx2 v[6:7], v[10:11], off
	v_pk_mul_f32 v[10:11], v[102:103], s[18:19] op_sel_hi:[1,0]
	v_pk_mul_f32 v[8:9], v[104:105], s[18:19] op_sel_hi:[1,0]
	v_med3_f32 v5, v10, s47, v173
	v_med3_f32 v11, v11, s47, v173
	v_mov_b32_e32 v10, 0
	v_cvt_pk_fp8_f32 v10, v5, v11
	v_pk_mul_f32 v[14:15], v[98:99], s[18:19] op_sel_hi:[1,0]
	v_med3_f32 v5, v8, s47, v173
	v_med3_f32 v8, v9, s47, v173
	v_cvt_pk_fp8_f32 v10, v5, v8 op_sel:[0,0,1]
	v_med3_f32 v5, v14, s47, v173
	v_med3_f32 v8, v15, s47, v173
	v_mov_b32_e32 v11, 0
	v_cvt_pk_fp8_f32 v11, v5, v8
	v_pk_mul_f32 v[12:13], v[100:101], s[18:19] op_sel_hi:[1,0]
	v_pk_mul_f32 v[14:15], v[90:91], s[18:19] op_sel_hi:[1,0]
	v_med3_f32 v5, v12, s47, v173
	v_med3_f32 v8, v13, s47, v173
	v_cvt_pk_fp8_f32 v11, v5, v8 op_sel:[0,0,1]
	v_pk_mul_f32 v[8:9], v[96:97], s[18:19] op_sel_hi:[1,0]
	v_pk_mul_f32 v[12:13], v[92:93], s[18:19] op_sel_hi:[1,0]
	s_mov_b32 s28, s22
	global_store_dwordx2 v[6:7], v[10:11], off offset:128
	v_pk_mul_f32 v[10:11], v[94:95], s[18:19] op_sel_hi:[1,0]
	v_add_u32_e32 v6, 48, v4
	v_med3_f32 v5, v10, s47, v173
	v_med3_f32 v11, v11, s47, v173
	v_mov_b32_e32 v10, 0
	v_cvt_pk_fp8_f32 v10, v5, v11
	v_med3_f32 v5, v8, s47, v173
	v_med3_f32 v8, v9, s47, v173
	v_mov_b32_e32 v11, 0
	v_cvt_pk_fp8_f32 v10, v5, v8 op_sel:[0,0,1]
	v_med3_f32 v5, v14, s47, v173
	v_med3_f32 v8, v15, s47, v173
	v_cvt_pk_fp8_f32 v11, v5, v8
	v_med3_f32 v5, v12, s47, v173
	v_med3_f32 v8, v13, s47, v173
	v_cvt_pk_fp8_f32 v11, v5, v8 op_sel:[0,0,1]
	v_ashrrev_i32_e32 v7, 31, v6
	v_lshlrev_b64 v[6:7], 10, v[6:7]
	v_lshl_add_u64 v[6:7], s[14:15], 0, v[6:7]
	v_lshl_add_u64 v[6:7], v[6:7], 0, v[2:3]
	global_store_dwordx2 v[6:7], v[10:11], off
	v_pk_mul_f32 v[10:11], v[86:87], s[18:19] op_sel_hi:[1,0]
	v_pk_mul_f32 v[8:9], v[88:89], s[18:19] op_sel_hi:[1,0]
	v_med3_f32 v5, v10, s47, v173
	v_med3_f32 v11, v11, s47, v173
	v_mov_b32_e32 v10, 0
	v_cvt_pk_fp8_f32 v10, v5, v11
	v_pk_mul_f32 v[14:15], v[82:83], s[18:19] op_sel_hi:[1,0]
	v_med3_f32 v5, v8, s47, v173
	v_med3_f32 v8, v9, s47, v173
	v_cvt_pk_fp8_f32 v10, v5, v8 op_sel:[0,0,1]
	v_med3_f32 v5, v14, s47, v173
	v_med3_f32 v8, v15, s47, v173
	v_mov_b32_e32 v11, 0
	v_cvt_pk_fp8_f32 v11, v5, v8
	v_pk_mul_f32 v[12:13], v[84:85], s[18:19] op_sel_hi:[1,0]
	v_pk_mul_f32 v[14:15], v[74:75], s[18:19] op_sel_hi:[1,0]
	v_med3_f32 v5, v12, s47, v173
	v_med3_f32 v8, v13, s47, v173
	v_cvt_pk_fp8_f32 v11, v5, v8 op_sel:[0,0,1]
	v_pk_mul_f32 v[8:9], v[80:81], s[18:19] op_sel_hi:[1,0]
	v_pk_mul_f32 v[12:13], v[76:77], s[18:19] op_sel_hi:[1,0]
	s_mov_b64 s[30:31], s[26:27]
	global_store_dwordx2 v[6:7], v[10:11], off offset:128
	v_pk_mul_f32 v[10:11], v[78:79], s[18:19] op_sel_hi:[1,0]
	v_add_u32_e32 v6, 0x80, v4
	v_med3_f32 v5, v10, s47, v173
	v_med3_f32 v11, v11, s47, v173
	v_mov_b32_e32 v10, 0
	v_cvt_pk_fp8_f32 v10, v5, v11
	v_med3_f32 v5, v8, s47, v173
	v_med3_f32 v8, v9, s47, v173
	v_mov_b32_e32 v11, 0
	v_cvt_pk_fp8_f32 v10, v5, v8 op_sel:[0,0,1]
	v_med3_f32 v5, v14, s47, v173
	v_med3_f32 v8, v15, s47, v173
	v_cvt_pk_fp8_f32 v11, v5, v8
	v_med3_f32 v5, v12, s47, v173
	v_med3_f32 v8, v13, s47, v173
	v_cvt_pk_fp8_f32 v11, v5, v8 op_sel:[0,0,1]
	v_ashrrev_i32_e32 v7, 31, v6
	v_lshlrev_b64 v[6:7], 10, v[6:7]
	v_lshl_add_u64 v[6:7], s[14:15], 0, v[6:7]
	v_lshl_add_u64 v[6:7], v[6:7], 0, v[2:3]
	global_store_dwordx2 v[6:7], v[10:11], off
	v_pk_mul_f32 v[10:11], v[70:71], s[18:19] op_sel_hi:[1,0]
	v_pk_mul_f32 v[8:9], v[72:73], s[18:19] op_sel_hi:[1,0]
	v_med3_f32 v5, v10, s47, v173
	v_med3_f32 v11, v11, s47, v173
	v_mov_b32_e32 v10, 0
	v_cvt_pk_fp8_f32 v10, v5, v11
	v_pk_mul_f32 v[14:15], v[66:67], s[18:19] op_sel_hi:[1,0]
	v_med3_f32 v5, v8, s47, v173
	v_med3_f32 v8, v9, s47, v173
	v_cvt_pk_fp8_f32 v10, v5, v8 op_sel:[0,0,1]
	v_med3_f32 v5, v14, s47, v173
	v_med3_f32 v8, v15, s47, v173
	v_mov_b32_e32 v11, 0
	v_cvt_pk_fp8_f32 v11, v5, v8
	v_pk_mul_f32 v[12:13], v[68:69], s[18:19] op_sel_hi:[1,0]
	v_pk_mul_f32 v[14:15], v[58:59], s[18:19] op_sel_hi:[1,0]
	v_med3_f32 v5, v12, s47, v173
	v_med3_f32 v8, v13, s47, v173
	v_cvt_pk_fp8_f32 v11, v5, v8 op_sel:[0,0,1]
	v_pk_mul_f32 v[8:9], v[64:65], s[18:19] op_sel_hi:[1,0]
	v_pk_mul_f32 v[12:13], v[60:61], s[18:19] op_sel_hi:[1,0]
	s_mov_b64 s[34:35], s[24:25]
	global_store_dwordx2 v[6:7], v[10:11], off offset:128
	v_pk_mul_f32 v[10:11], v[62:63], s[18:19] op_sel_hi:[1,0]
	v_add_u32_e32 v6, 0x90, v4
	v_med3_f32 v5, v10, s47, v173
	v_med3_f32 v11, v11, s47, v173
	v_mov_b32_e32 v10, 0
	v_cvt_pk_fp8_f32 v10, v5, v11
	v_med3_f32 v5, v8, s47, v173
	v_med3_f32 v8, v9, s47, v173
	v_mov_b32_e32 v11, 0
	v_cvt_pk_fp8_f32 v10, v5, v8 op_sel:[0,0,1]
	v_med3_f32 v5, v14, s47, v173
	v_med3_f32 v8, v15, s47, v173
	v_cvt_pk_fp8_f32 v11, v5, v8
	v_med3_f32 v5, v12, s47, v173
	v_med3_f32 v8, v13, s47, v173
	v_cvt_pk_fp8_f32 v11, v5, v8 op_sel:[0,0,1]
	v_ashrrev_i32_e32 v7, 31, v6
	v_lshlrev_b64 v[6:7], 10, v[6:7]
	v_lshl_add_u64 v[6:7], s[14:15], 0, v[6:7]
	v_lshl_add_u64 v[6:7], v[6:7], 0, v[2:3]
	global_store_dwordx2 v[6:7], v[10:11], off
	v_pk_mul_f32 v[10:11], v[54:55], s[18:19] op_sel_hi:[1,0]
	v_pk_mul_f32 v[8:9], v[56:57], s[18:19] op_sel_hi:[1,0]
	v_med3_f32 v5, v10, s47, v173
	v_med3_f32 v11, v11, s47, v173
	v_mov_b32_e32 v10, 0
	v_cvt_pk_fp8_f32 v10, v5, v11
	v_pk_mul_f32 v[14:15], v[50:51], s[18:19] op_sel_hi:[1,0]
	v_med3_f32 v5, v8, s47, v173
	v_med3_f32 v8, v9, s47, v173
	v_cvt_pk_fp8_f32 v10, v5, v8 op_sel:[0,0,1]
	v_med3_f32 v5, v14, s47, v173
	v_med3_f32 v8, v15, s47, v173
	v_mov_b32_e32 v11, 0
	v_cvt_pk_fp8_f32 v11, v5, v8
	v_pk_mul_f32 v[12:13], v[52:53], s[18:19] op_sel_hi:[1,0]
	v_pk_mul_f32 v[14:15], v[42:43], s[18:19] op_sel_hi:[1,0]
	v_med3_f32 v5, v12, s47, v173
	v_med3_f32 v8, v13, s47, v173
	v_cvt_pk_fp8_f32 v11, v5, v8 op_sel:[0,0,1]
	v_pk_mul_f32 v[8:9], v[48:49], s[18:19] op_sel_hi:[1,0]
	v_pk_mul_f32 v[12:13], v[44:45], s[18:19] op_sel_hi:[1,0]
	global_store_dwordx2 v[6:7], v[10:11], off offset:128
	v_pk_mul_f32 v[10:11], v[46:47], s[18:19] op_sel_hi:[1,0]
	v_add_u32_e32 v6, 0xa0, v4
	v_med3_f32 v5, v10, s47, v173
	v_med3_f32 v11, v11, s47, v173
	v_mov_b32_e32 v10, 0
	v_cvt_pk_fp8_f32 v10, v5, v11
	v_med3_f32 v5, v8, s47, v173
	v_med3_f32 v8, v9, s47, v173
	v_mov_b32_e32 v11, 0
	v_cvt_pk_fp8_f32 v10, v5, v8 op_sel:[0,0,1]
	v_med3_f32 v5, v14, s47, v173
	v_med3_f32 v8, v15, s47, v173
	v_cvt_pk_fp8_f32 v11, v5, v8
	v_med3_f32 v5, v12, s47, v173
	v_med3_f32 v8, v13, s47, v173
	v_cvt_pk_fp8_f32 v11, v5, v8 op_sel:[0,0,1]
	v_ashrrev_i32_e32 v7, 31, v6
	v_lshlrev_b64 v[6:7], 10, v[6:7]
	v_lshl_add_u64 v[6:7], s[14:15], 0, v[6:7]
	v_lshl_add_u64 v[6:7], v[6:7], 0, v[2:3]
	global_store_dwordx2 v[6:7], v[10:11], off
	v_pk_mul_f32 v[10:11], v[38:39], s[18:19] op_sel_hi:[1,0]
	v_pk_mul_f32 v[8:9], v[40:41], s[18:19] op_sel_hi:[1,0]
	v_med3_f32 v5, v10, s47, v173
	v_med3_f32 v11, v11, s47, v173
	v_mov_b32_e32 v10, 0
	v_cvt_pk_fp8_f32 v10, v5, v11
	v_pk_mul_f32 v[14:15], v[34:35], s[18:19] op_sel_hi:[1,0]
	v_med3_f32 v5, v8, s47, v173
	v_med3_f32 v8, v9, s47, v173
	v_cvt_pk_fp8_f32 v10, v5, v8 op_sel:[0,0,1]
	v_med3_f32 v5, v14, s47, v173
	v_med3_f32 v8, v15, s47, v173
	v_mov_b32_e32 v11, 0
	v_cvt_pk_fp8_f32 v11, v5, v8
	v_pk_mul_f32 v[12:13], v[36:37], s[18:19] op_sel_hi:[1,0]
	v_add_u32_e32 v4, 0xb0, v4
	v_med3_f32 v5, v12, s47, v173
	v_med3_f32 v8, v13, s47, v173
	v_cvt_pk_fp8_f32 v11, v5, v8 op_sel:[0,0,1]
	v_pk_mul_f32 v[8:9], v[28:29], s[18:19] op_sel_hi:[1,0]
	global_store_dwordx2 v[6:7], v[10:11], off offset:128
	v_pk_mul_f32 v[6:7], v[30:31], s[18:19] op_sel_hi:[1,0]
	v_pk_mul_f32 v[10:11], v[26:27], s[18:19] op_sel_hi:[1,0]
	v_ashrrev_i32_e32 v5, 31, v4
	v_med3_f32 v12, v6, s47, v173
	v_med3_f32 v7, v7, s47, v173
	v_mov_b32_e32 v6, 0
	v_lshlrev_b64 v[4:5], 10, v[4:5]
	v_cvt_pk_fp8_f32 v6, v12, v7
	v_lshl_add_u64 v[4:5], s[14:15], 0, v[4:5]
	v_lshl_add_u64 v[2:3], v[4:5], 0, v[2:3]
	v_pk_mul_f32 v[4:5], v[32:33], s[18:19] op_sel_hi:[1,0]
	v_mov_b32_e32 v7, 0
	v_med3_f32 v4, v4, s47, v173
	v_med3_f32 v5, v5, s47, v173
	v_cvt_pk_fp8_f32 v6, v4, v5 op_sel:[0,0,1]
	v_med3_f32 v4, v10, s47, v173
	v_med3_f32 v5, v11, s47, v173
	v_cvt_pk_fp8_f32 v7, v4, v5
	v_med3_f32 v4, v8, s47, v173
	v_med3_f32 v5, v9, s47, v173
	v_pk_mul_f32 v[10:11], v[18:19], s[18:19] op_sel_hi:[1,0]
	v_cvt_pk_fp8_f32 v7, v4, v5 op_sel:[0,0,1]
	v_pk_mul_f32 v[4:5], v[24:25], s[18:19] op_sel_hi:[1,0]
	v_pk_mul_f32 v[8:9], v[20:21], s[18:19] op_sel_hi:[1,0]
	v_med3_f32 v4, v4, s47, v173
	global_store_dwordx2 v[2:3], v[6:7], off
	v_pk_mul_f32 v[6:7], v[22:23], s[18:19] op_sel_hi:[1,0]
	v_med3_f32 v5, v5, s47, v173
	v_med3_f32 v12, v6, s47, v173
	v_med3_f32 v7, v7, s47, v173
	v_mov_b32_e32 v6, 0
	v_cvt_pk_fp8_f32 v6, v12, v7
	v_mov_b32_e32 v7, 0
	v_cvt_pk_fp8_f32 v6, v4, v5 op_sel:[0,0,1]
	v_med3_f32 v4, v10, s47, v173
	v_med3_f32 v5, v11, s47, v173
	v_cvt_pk_fp8_f32 v7, v4, v5
	v_med3_f32 v4, v8, s47, v173
	v_med3_f32 v5, v9, s47, v173
	v_cvt_pk_fp8_f32 v7, v4, v5 op_sel:[0,0,1]
	global_store_dwordx2 v[2:3], v[6:7], off offset:128
	s_cbranch_vccz .LBB0_2101
	s_waitcnt vmcnt(0)
	s_cmpk_gt_u32 s4, 0xff
	s_cbranch_scc1 .LBB0_2112
	s_barrier

.LBB0_2325:
	ds_read_b128 v[130:133], v165
	ds_read_b128 v[134:137], v165 offset:1024
	ds_read_b128 v[154:157], v165 offset:2048
	ds_read_b128 v[158:161], v165 offset:3072
	s_add_u32 s36, s34, 0x100
	s_addc_u32 s37, s35, 0
	s_cmp_eq_u32 s59, 2
	s_cselect_b32 s41, s13, s37
	s_cselect_b32 s40, s12, s36
	s_cselect_b32 s39, s15, s58
	s_cselect_b32 s38, s14, s20
	v_lshl_add_u64 v[202:203], s[34:35], 0, v[148:149]
	s_add_i32 m0, s17, 0xc000
	ds_read_b128 v[170:173], v166
	ds_read_b128 v[174:177], v166 offset:1024
	ds_read_b128 v[178:181], v166 offset:2048
	ds_read_b128 v[182:185], v166 offset:3072
	ds_read_b128 v[186:189], v166 offset:4096
	ds_read_b128 v[190:193], v166 offset:5120
	ds_read_b128 v[194:197], v166 offset:6144
	ds_read_b128 v[198:201], v166 offset:7168
	global_load_lds_dwordx4 v[202:203], off nt
	v_lshl_add_u64 v[202:203], s[34:35], 0, v[146:147]
	s_add_i32 m0, s17, 0xe000
	s_nop 0
	global_load_lds_dwordx4 v[202:203], off nt
	s_waitcnt lgkmcnt(8)
	s_waitcnt vmcnt(10)
	s_barrier
	s_waitcnt lgkmcnt(0)
	s_waitcnt lgkmcnt(0)
	v_mfma_f32_16x16x32_bf16 v[126:129], v[130:133], v[170:173], v[126:129]
	v_mfma_f32_16x16x32_bf16 v[122:125], v[154:157], v[170:173], v[122:125]
	v_mfma_f32_16x16x32_bf16 v[114:117], v[130:133], v[178:181], v[114:117]
	v_mfma_f32_16x16x32_bf16 v[106:109], v[154:157], v[178:181], v[106:109]
	v_mfma_f32_16x16x32_bf16 v[98:101], v[130:133], v[186:189], v[98:101]
	v_mfma_f32_16x16x32_bf16 v[90:93], v[154:157], v[186:189], v[90:93]
	v_mfma_f32_16x16x32_bf16 v[82:85], v[130:133], v[194:197], v[82:85]
	v_mfma_f32_16x16x32_bf16 v[74:77], v[154:157], v[194:197], v[74:77]
	v_mfma_f32_16x16x32_bf16 v[126:129], v[134:137], v[174:177], v[126:129]
	v_mfma_f32_16x16x32_bf16 v[122:125], v[158:161], v[174:177], v[122:125]
	v_mfma_f32_16x16x32_bf16 v[114:117], v[134:137], v[182:185], v[114:117]
	v_mfma_f32_16x16x32_bf16 v[106:109], v[158:161], v[182:185], v[106:109]
	v_mfma_f32_16x16x32_bf16 v[98:101], v[134:137], v[190:193], v[98:101]
	v_mfma_f32_16x16x32_bf16 v[90:93], v[158:161], v[190:193], v[90:93]
	v_mfma_f32_16x16x32_bf16 v[82:85], v[134:137], v[198:201], v[82:85]
	v_mfma_f32_16x16x32_bf16 v[74:77], v[158:161], v[198:201], v[74:77]
	s_barrier
	s_add_i32 s0, s49, s8
	v_lshl_add_u64 v[218:219], s[38:39], 0, v[142:143]
	s_mov_b32 m0, s0
	ds_read_b128 v[202:205], v167
	ds_read_b128 v[206:209], v167 offset:1024
	ds_read_b128 v[210:213], v167 offset:2048
	ds_read_b128 v[214:217], v167 offset:3072
	global_load_lds_dwordx4 v[218:219], off
	v_lshl_add_u64 v[220:221], s[38:39], 0, v[138:139]
	s_add_i32 m0, s0, 0x2000
	s_nop 0
	global_load_lds_dwordx4 v[220:221], off
	s_waitcnt vmcnt(10)
	s_barrier
	s_waitcnt lgkmcnt(0)
	s_waitcnt lgkmcnt(0)
	v_mfma_f32_16x16x32_bf16 v[118:121], v[202:205], v[170:173], v[118:121]
	v_mfma_f32_16x16x32_bf16 v[110:113], v[210:213], v[170:173], v[110:113]
	v_mfma_f32_16x16x32_bf16 v[102:105], v[202:205], v[178:181], v[102:105]
	v_mfma_f32_16x16x32_bf16 v[94:97], v[210:213], v[178:181], v[94:97]
	v_mfma_f32_16x16x32_bf16 v[86:89], v[202:205], v[186:189], v[86:89]
	v_mfma_f32_16x16x32_bf16 v[78:81], v[210:213], v[186:189], v[78:81]
	v_mfma_f32_16x16x32_bf16 v[70:73], v[202:205], v[194:197], v[70:73]
	v_mfma_f32_16x16x32_bf16 v[66:69], v[210:213], v[194:197], v[66:69]
	v_mfma_f32_16x16x32_bf16 v[118:121], v[206:209], v[174:177], v[118:121]
	v_mfma_f32_16x16x32_bf16 v[110:113], v[214:217], v[174:177], v[110:113]
	v_mfma_f32_16x16x32_bf16 v[102:105], v[206:209], v[182:185], v[102:105]
	v_mfma_f32_16x16x32_bf16 v[94:97], v[214:217], v[182:185], v[94:97]
	v_mfma_f32_16x16x32_bf16 v[86:89], v[206:209], v[190:193], v[86:89]
	v_mfma_f32_16x16x32_bf16 v[78:81], v[214:217], v[190:193], v[78:81]
	v_mfma_f32_16x16x32_bf16 v[70:73], v[206:209], v[198:201], v[70:73]
	v_mfma_f32_16x16x32_bf16 v[66:69], v[214:217], v[198:201], v[66:69]
	s_mov_b32 m0, s17
	v_lshl_add_u64 v[222:223], s[40:41], 0, v[144:145]
	s_barrier
	ds_read_b128 v[170:173], v166 offset:16384
	ds_read_b128 v[174:177], v166 offset:17408
	ds_read_b128 v[178:181], v166 offset:18432
	ds_read_b128 v[182:185], v166 offset:19456
	ds_read_b128 v[186:189], v166 offset:20480
	ds_read_b128 v[190:193], v166 offset:21504
	ds_read_b128 v[194:197], v166 offset:22528
	ds_read_b128 v[198:201], v166 offset:23552
	global_load_lds_dwordx4 v[222:223], off nt
	v_lshl_add_u64 v[224:225], s[40:41], 0, v[140:141]
	s_mov_b32 m0, s42
	s_nop 0
	global_load_lds_dwordx4 v[224:225], off nt
	s_waitcnt vmcnt(10)
	s_barrier
	s_waitcnt lgkmcnt(0)
	s_waitcnt lgkmcnt(0)
	v_mfma_f32_16x16x32_bf16 v[62:65], v[130:133], v[170:173], v[62:65]
	v_mfma_f32_16x16x32_bf16 v[58:61], v[154:157], v[170:173], v[58:61]
	v_mfma_f32_16x16x32_bf16 v[50:53], v[130:133], v[178:181], v[50:53]
	v_mfma_f32_16x16x32_bf16 v[42:45], v[154:157], v[178:181], v[42:45]
	v_mfma_f32_16x16x32_bf16 v[34:37], v[130:133], v[186:189], v[34:37]
	v_mfma_f32_16x16x32_bf16 v[26:29], v[154:157], v[186:189], v[26:29]
	v_mfma_f32_16x16x32_bf16 v[18:21], v[130:133], v[194:197], v[18:21]
	v_mfma_f32_16x16x32_bf16 v[10:13], v[154:157], v[194:197], v[10:13]
	v_mfma_f32_16x16x32_bf16 v[62:65], v[134:137], v[174:177], v[62:65]
	v_mfma_f32_16x16x32_bf16 v[58:61], v[158:161], v[174:177], v[58:61]
	v_mfma_f32_16x16x32_bf16 v[50:53], v[134:137], v[182:185], v[50:53]
	v_mfma_f32_16x16x32_bf16 v[42:45], v[158:161], v[182:185], v[42:45]
	v_mfma_f32_16x16x32_bf16 v[34:37], v[134:137], v[190:193], v[34:37]
	v_mfma_f32_16x16x32_bf16 v[26:29], v[158:161], v[190:193], v[26:29]
	v_mfma_f32_16x16x32_bf16 v[18:21], v[134:137], v[198:201], v[18:21]
	v_mfma_f32_16x16x32_bf16 v[10:13], v[158:161], v[198:201], v[10:13]
	s_barrier
	s_add_u32 s0, s38, 0x18000
	s_addc_u32 s1, s39, 0
	s_add_i32 s34, s50, s8
	v_lshl_add_u64 v[130:131], s[0:1], 0, v[142:143]
	s_mov_b32 m0, s34
	s_nop 0
	global_load_lds_dwordx4 v[130:131], off
	v_lshl_add_u64 v[130:131], s[0:1], 0, v[138:139]
	s_add_i32 m0, s34, 0x2000
	s_nop 0
	global_load_lds_dwordx4 v[130:131], off
	s_waitcnt vmcnt(10)
	s_barrier
	v_mfma_f32_16x16x32_bf16 v[54:57], v[202:205], v[170:173], v[54:57]
	v_mfma_f32_16x16x32_bf16 v[46:49], v[210:213], v[170:173], v[46:49]
	v_mfma_f32_16x16x32_bf16 v[38:41], v[202:205], v[178:181], v[38:41]
	v_mfma_f32_16x16x32_bf16 v[30:33], v[210:213], v[178:181], v[30:33]
	v_mfma_f32_16x16x32_bf16 v[22:25], v[202:205], v[186:189], v[22:25]
	v_mfma_f32_16x16x32_bf16 v[14:17], v[210:213], v[186:189], v[14:17]
	v_mfma_f32_16x16x32_bf16 v[6:9], v[202:205], v[194:197], v[6:9]
	v_mfma_f32_16x16x32_bf16 v[2:5], v[210:213], v[194:197], v[2:5]
	v_mfma_f32_16x16x32_bf16 v[54:57], v[206:209], v[174:177], v[54:57]
	v_mfma_f32_16x16x32_bf16 v[46:49], v[214:217], v[174:177], v[46:49]
	v_mfma_f32_16x16x32_bf16 v[38:41], v[206:209], v[182:185], v[38:41]
	v_mfma_f32_16x16x32_bf16 v[30:33], v[214:217], v[182:185], v[30:33]
	v_mfma_f32_16x16x32_bf16 v[22:25], v[206:209], v[190:193], v[22:25]
	v_mfma_f32_16x16x32_bf16 v[14:17], v[214:217], v[190:193], v[14:17]
	v_mfma_f32_16x16x32_bf16 v[6:9], v[206:209], v[198:201], v[6:9]
	v_mfma_f32_16x16x32_bf16 v[2:5], v[214:217], v[198:201], v[2:5]
	s_add_i32 s34, 0, 0x18000
	v_add_u32_e32 v158, s34, v164
	s_barrier
	ds_read_b128 v[130:133], v158
	ds_read_b128 v[134:137], v158 offset:1024
	ds_read_b128 v[154:157], v158 offset:2048
	ds_read_b128 v[158:161], v158 offset:3072
	s_add_u32 s0, s40, 0x18000
	s_addc_u32 s1, s41, 0
	s_mov_b32 m0, s43
	v_lshl_add_u64 v[202:203], s[0:1], 0, v[144:145]
	ds_read_b128 v[170:173], v166 offset:32768
	ds_read_b128 v[174:177], v166 offset:33792
	ds_read_b128 v[178:181], v166 offset:34816
	ds_read_b128 v[182:185], v166 offset:35840
	ds_read_b128 v[186:189], v166 offset:36864
	ds_read_b128 v[190:193], v166 offset:37888
	ds_read_b128 v[194:197], v166 offset:38912
	ds_read_b128 v[198:201], v166 offset:39936
	global_load_lds_dwordx4 v[202:203], off nt
	v_lshl_add_u64 v[202:203], s[0:1], 0, v[140:141]
	s_mov_b32 m0, s44
	s_nop 0
	global_load_lds_dwordx4 v[202:203], off nt
	s_waitcnt lgkmcnt(8)
	s_waitcnt vmcnt(10)
	s_barrier
	s_waitcnt lgkmcnt(0)
	s_waitcnt lgkmcnt(0)
	v_mfma_f32_16x16x32_bf16 v[126:129], v[130:133], v[170:173], v[126:129]
	v_mfma_f32_16x16x32_bf16 v[122:125], v[154:157], v[170:173], v[122:125]
	v_mfma_f32_16x16x32_bf16 v[114:117], v[130:133], v[178:181], v[114:117]
	v_mfma_f32_16x16x32_bf16 v[106:109], v[154:157], v[178:181], v[106:109]
	v_mfma_f32_16x16x32_bf16 v[98:101], v[130:133], v[186:189], v[98:101]
	v_mfma_f32_16x16x32_bf16 v[90:93], v[154:157], v[186:189], v[90:93]
	v_mfma_f32_16x16x32_bf16 v[82:85], v[130:133], v[194:197], v[82:85]
	v_mfma_f32_16x16x32_bf16 v[74:77], v[154:157], v[194:197], v[74:77]
	v_mfma_f32_16x16x32_bf16 v[126:129], v[134:137], v[174:177], v[126:129]
	v_mfma_f32_16x16x32_bf16 v[122:125], v[158:161], v[174:177], v[122:125]
	v_mfma_f32_16x16x32_bf16 v[114:117], v[134:137], v[182:185], v[114:117]
	v_mfma_f32_16x16x32_bf16 v[106:109], v[158:161], v[182:185], v[106:109]
	v_mfma_f32_16x16x32_bf16 v[98:101], v[134:137], v[190:193], v[98:101]
	v_mfma_f32_16x16x32_bf16 v[90:93], v[158:161], v[190:193], v[90:93]
	v_mfma_f32_16x16x32_bf16 v[82:85], v[134:137], v[198:201], v[82:85]
	v_mfma_f32_16x16x32_bf16 v[74:77], v[158:161], v[198:201], v[74:77]
	s_barrier
	s_add_i32 s35, 0, 0x1c000
	s_add_i32 s0, s34, s8
	v_add_u32_e32 v169, s35, v164
	v_lshl_add_u64 v[218:219], v[218:219], 0, s[30:31]
	s_mov_b32 m0, s0
	ds_read_b128 v[202:205], v169
	ds_read_b128 v[206:209], v169 offset:1024
	ds_read_b128 v[210:213], v169 offset:2048
	ds_read_b128 v[214:217], v169 offset:3072
	global_load_lds_dwordx4 v[218:219], off
	v_lshl_add_u64 v[218:219], v[220:221], 0, s[30:31]
	s_add_i32 m0, s0, 0x2000
	s_nop 0
	global_load_lds_dwordx4 v[218:219], off
	s_waitcnt vmcnt(10)
	s_barrier
	s_waitcnt lgkmcnt(0)
	s_waitcnt lgkmcnt(0)
	v_mfma_f32_16x16x32_bf16 v[118:121], v[202:205], v[170:173], v[118:121]
	v_mfma_f32_16x16x32_bf16 v[110:113], v[210:213], v[170:173], v[110:113]
	v_mfma_f32_16x16x32_bf16 v[102:105], v[202:205], v[178:181], v[102:105]
	v_mfma_f32_16x16x32_bf16 v[94:97], v[210:213], v[178:181], v[94:97]
	v_mfma_f32_16x16x32_bf16 v[86:89], v[202:205], v[186:189], v[86:89]
	v_mfma_f32_16x16x32_bf16 v[78:81], v[210:213], v[186:189], v[78:81]
	v_mfma_f32_16x16x32_bf16 v[70:73], v[202:205], v[194:197], v[70:73]
	v_mfma_f32_16x16x32_bf16 v[66:69], v[210:213], v[194:197], v[66:69]
	v_mfma_f32_16x16x32_bf16 v[118:121], v[206:209], v[174:177], v[118:121]
	v_mfma_f32_16x16x32_bf16 v[110:113], v[214:217], v[174:177], v[110:113]
	v_mfma_f32_16x16x32_bf16 v[102:105], v[206:209], v[182:185], v[102:105]
	v_mfma_f32_16x16x32_bf16 v[94:97], v[214:217], v[182:185], v[94:97]
	v_mfma_f32_16x16x32_bf16 v[86:89], v[206:209], v[190:193], v[86:89]
	v_mfma_f32_16x16x32_bf16 v[78:81], v[214:217], v[190:193], v[78:81]
	v_mfma_f32_16x16x32_bf16 v[70:73], v[206:209], v[198:201], v[70:73]
	v_mfma_f32_16x16x32_bf16 v[66:69], v[214:217], v[198:201], v[66:69]
	s_mov_b32 m0, s46
	v_lshl_add_u64 v[218:219], v[222:223], 0, s[30:31]
	s_barrier
	ds_read_b128 v[170:173], v166 offset:49152
	ds_read_b128 v[174:177], v166 offset:50176
	ds_read_b128 v[178:181], v166 offset:51200
	ds_read_b128 v[182:185], v166 offset:52224
	ds_read_b128 v[186:189], v166 offset:53248
	ds_read_b128 v[190:193], v166 offset:54272
	ds_read_b128 v[194:197], v166 offset:55296
	ds_read_b128 v[198:201], v166 offset:56320
	global_load_lds_dwordx4 v[218:219], off nt
	v_lshl_add_u64 v[218:219], v[224:225], 0, s[30:31]
	s_mov_b32 m0, s47
	s_nop 0
	global_load_lds_dwordx4 v[218:219], off nt
	s_waitcnt vmcnt(10)
	s_barrier
	s_waitcnt lgkmcnt(0)
	s_waitcnt lgkmcnt(0)
	v_mfma_f32_16x16x32_bf16 v[62:65], v[130:133], v[170:173], v[62:65]
	v_mfma_f32_16x16x32_bf16 v[58:61], v[154:157], v[170:173], v[58:61]
	v_mfma_f32_16x16x32_bf16 v[50:53], v[130:133], v[178:181], v[50:53]
	v_mfma_f32_16x16x32_bf16 v[42:45], v[154:157], v[178:181], v[42:45]
	v_mfma_f32_16x16x32_bf16 v[34:37], v[130:133], v[186:189], v[34:37]
	v_mfma_f32_16x16x32_bf16 v[26:29], v[154:157], v[186:189], v[26:29]
	v_mfma_f32_16x16x32_bf16 v[18:21], v[130:133], v[194:197], v[18:21]
	v_mfma_f32_16x16x32_bf16 v[10:13], v[154:157], v[194:197], v[10:13]
	v_mfma_f32_16x16x32_bf16 v[62:65], v[134:137], v[174:177], v[62:65]
	v_mfma_f32_16x16x32_bf16 v[58:61], v[158:161], v[174:177], v[58:61]
	v_mfma_f32_16x16x32_bf16 v[50:53], v[134:137], v[182:185], v[50:53]
	v_mfma_f32_16x16x32_bf16 v[42:45], v[158:161], v[182:185], v[42:45]
	v_mfma_f32_16x16x32_bf16 v[34:37], v[134:137], v[190:193], v[34:37]
	v_mfma_f32_16x16x32_bf16 v[26:29], v[158:161], v[190:193], v[26:29]
	v_mfma_f32_16x16x32_bf16 v[18:21], v[134:137], v[198:201], v[18:21]
	v_mfma_f32_16x16x32_bf16 v[10:13], v[158:161], v[198:201], v[10:13]
	s_barrier
	s_add_u32 s0, s38, 0x18080
	s_addc_u32 s1, s39, 0
	s_add_i32 s34, s35, s8
	v_lshl_add_u64 v[130:131], s[0:1], 0, v[142:143]
	s_mov_b32 m0, s34
	s_nop 0
	global_load_lds_dwordx4 v[130:131], off
	v_lshl_add_u64 v[130:131], s[0:1], 0, v[138:139]
	s_add_i32 m0, s34, 0x2000
	s_nop 0
	global_load_lds_dwordx4 v[130:131], off
	s_waitcnt vmcnt(10)
	s_barrier
	v_mfma_f32_16x16x32_bf16 v[54:57], v[202:205], v[170:173], v[54:57]
	v_mfma_f32_16x16x32_bf16 v[46:49], v[210:213], v[170:173], v[46:49]
	v_mfma_f32_16x16x32_bf16 v[38:41], v[202:205], v[178:181], v[38:41]
	v_mfma_f32_16x16x32_bf16 v[30:33], v[210:213], v[178:181], v[30:33]
	v_mfma_f32_16x16x32_bf16 v[22:25], v[202:205], v[186:189], v[22:25]
	v_mfma_f32_16x16x32_bf16 v[14:17], v[210:213], v[186:189], v[14:17]
	v_mfma_f32_16x16x32_bf16 v[6:9], v[202:205], v[194:197], v[6:9]
	v_mfma_f32_16x16x32_bf16 v[2:5], v[210:213], v[194:197], v[2:5]
	v_mfma_f32_16x16x32_bf16 v[54:57], v[206:209], v[174:177], v[54:57]
	v_mfma_f32_16x16x32_bf16 v[46:49], v[214:217], v[174:177], v[46:49]
	v_mfma_f32_16x16x32_bf16 v[38:41], v[206:209], v[182:185], v[38:41]
	v_mfma_f32_16x16x32_bf16 v[30:33], v[214:217], v[182:185], v[30:33]
	v_mfma_f32_16x16x32_bf16 v[22:25], v[206:209], v[190:193], v[22:25]
	v_mfma_f32_16x16x32_bf16 v[14:17], v[214:217], v[190:193], v[14:17]
	v_mfma_f32_16x16x32_bf16 v[6:9], v[206:209], v[198:201], v[6:9]
	v_mfma_f32_16x16x32_bf16 v[2:5], v[214:217], v[198:201], v[2:5]
	s_add_i32 s59, s59, 2
	s_add_u32 s20, s20, 0x100
	s_addc_u32 s58, s58, 0
	s_cmp_gt_u32 s59, 3
	s_mov_b64 s[34:35], s[36:37]
	s_barrier
	s_cbranch_scc0 .LBB0_2325
	v_mov_b32_e32 v169, v162
	v_mov_b32_e32 v130, v163
	s_mov_b64 s[34:35], -1
	v_lshlrev_b32_e32 v154, 3, v130
	s_cmp_gt_i32 s57, 3
	v_ashrrev_i32_e32 v155, 31, v154
	s_cbranch_scc0 .LBB0_2328
	s_lshl_b32 s0, s56, 8
	s_add_i32 s0, s0, s45
	v_add_u32_e32 v248, s0, v169
	v_mov_b32_e32 v136, v248
	v_lshlrev_b64 v[132:133], 2, v[154:155]
	v_ashrrev_i32_e32 v137, 31, v136
	v_lshl_add_u64 v[130:131], s[26:27], 0, v[132:133]
	v_lshlrev_b64 v[134:135], 7, v[136:137]
	v_lshl_add_u64 v[156:157], v[130:131], 0, v[134:135]
	v_lshl_add_u64 v[132:133], s[24:25], 0, v[132:133]
	global_load_dwordx4 v[170:173], v[156:157], off
	global_load_dwordx4 v[174:177], v[156:157], off offset:16
	v_lshl_add_u64 v[134:135], v[132:133], 0, v[134:135]
	global_load_dwordx4 v[178:181], v[134:135], off
	global_load_dwordx4 v[182:185], v[134:135], off offset:16
	v_add_u32_e32 v160, 16, v136
	v_ashrrev_i32_e32 v161, 31, v160
	v_lshlrev_b64 v[134:135], 7, v[160:161]
	v_lshl_add_u64 v[156:157], v[130:131], 0, v[134:135]
	global_load_dwordx4 v[186:189], v[156:157], off
	global_load_dwordx4 v[194:197], v[156:157], off offset:16
	v_lshl_add_u64 v[134:135], v[132:133], 0, v[134:135]
	global_load_dwordx4 v[190:193], v[134:135], off
	global_load_dwordx4 v[198:201], v[134:135], off offset:16
	v_add_u32_e32 v238, 32, v136
	v_add_u32_e32 v134, 48, v136
	v_ashrrev_i32_e32 v239, 31, v238
	v_ashrrev_i32_e32 v135, 31, v134
	v_lshlrev_b64 v[202:203], 7, v[238:239]
	v_lshlrev_b64 v[204:205], 7, v[134:135]
	v_lshl_add_u64 v[206:207], v[132:133], 0, v[202:203]
	v_lshl_add_u64 v[214:215], v[130:131], 0, v[202:203]
	v_lshl_add_u64 v[222:223], v[132:133], 0, v[204:205]
	v_lshl_add_u64 v[230:231], v[130:131], 0, v[204:205]
	global_load_dwordx4 v[202:205], v[206:207], off
	s_nop 0
	global_load_dwordx4 v[206:209], v[206:207], off offset:16
	s_nop 0
	global_load_dwordx4 v[210:213], v[214:215], off
	s_nop 0
	global_load_dwordx4 v[214:217], v[214:215], off offset:16
	s_nop 0
	global_load_dwordx4 v[218:221], v[222:223], off
	s_nop 0
	global_load_dwordx4 v[222:225], v[222:223], off offset:16
	s_nop 0
	global_load_dwordx4 v[226:229], v[230:231], off
	s_nop 0
	global_load_dwordx4 v[230:233], v[230:231], off offset:16
	v_mov_b32_e32 v234, 0
	v_mov_b32_e32 v235, 0
	v_mov_b32_e32 v236, 0
	v_mov_b32_e32 v237, 0
	s_lshl_b32 s0, s57, 2
	s_add_i32 s0, s48, s0
	v_mov_b64_e32 v[156:157], s[22:23]
	s_mul_i32 s20, s0, 0xc0
	v_lshl_add_u64 v[158:159], s[20:21], 0, v[154:155]
	v_mad_i64_i32 v[136:137], s[0:1], v136, s52, v[156:157]
	v_lshl_add_u64 v[136:137], v[136:137], 0, v[158:159]
	s_mov_b64 s[34:35], 0
	s_waitcnt vmcnt(0) lgkmcnt(0)
	v_pk_mul_f32 v[240:241], v[120:121], v[172:173]
	v_pk_mul_f32 v[242:243], v[118:119], v[170:171]
	v_pk_mul_f32 v[172:173], v[128:129], v[172:173]
	v_pk_mul_f32 v[246:247], v[110:111], v[174:175]
	v_pk_mul_f32 v[170:171], v[126:127], v[170:171]
	v_pk_mul_f32 v[174:175], v[122:123], v[174:175]
	v_pk_fma_f32 v[240:241], v[128:129], v[180:181], v[240:241] neg_lo:[0,0,1] neg_hi:[0,0,1]
	v_pk_fma_f32 v[242:243], v[126:127], v[178:179], v[242:243] neg_lo:[0,0,1] neg_hi:[0,0,1]
	v_pk_fma_f32 v[172:173], v[120:121], v[180:181], v[172:173]
	v_pk_fma_f32 v[180:181], v[122:123], v[182:183], v[246:247] neg_lo:[0,0,1] neg_hi:[0,0,1]
	v_pk_fma_f32 v[170:171], v[118:119], v[178:179], v[170:171]
	v_pk_fma_f32 v[174:175], v[110:111], v[182:183], v[174:175]
	v_med3_f32 v135, v242, s51, v168
	v_med3_f32 v161, v243, s51, v168
	v_med3_f32 v180, v180, s51, v168
	v_med3_f32 v181, v181, s51, v168
	v_med3_f32 v170, v170, s51, v168
	v_med3_f32 v171, v171, s51, v168
	v_med3_f32 v174, v174, s51, v168
	v_med3_f32 v175, v175, s51, v168
	v_cvt_pk_fp8_f32 v234, v135, v161
	v_cvt_pk_fp8_f32 v235, v180, v181
	v_pk_mul_f32 v[244:245], v[112:113], v[176:177]
	v_cvt_pk_fp8_f32 v236, v170, v171
	v_cvt_pk_fp8_f32 v237, v174, v175
	v_pk_mul_f32 v[176:177], v[124:125], v[176:177]
	v_pk_fma_f32 v[178:179], v[124:125], v[184:185], v[244:245] neg_lo:[0,0,1] neg_hi:[0,0,1]
	v_pk_fma_f32 v[176:177], v[112:113], v[184:185], v[176:177]
	v_med3_f32 v184, v240, s51, v168
	v_med3_f32 v185, v241, s51, v168
	v_med3_f32 v178, v178, s51, v168
	v_med3_f32 v179, v179, s51, v168
	v_med3_f32 v172, v172, s51, v168
	v_med3_f32 v173, v173, s51, v168
	v_med3_f32 v176, v176, s51, v168
	v_med3_f32 v177, v177, s51, v168
	v_cvt_pk_fp8_f32 v234, v184, v185 op_sel:[0,0,1]
	v_cvt_pk_fp8_f32 v235, v178, v179 op_sel:[0,0,1]
	v_cvt_pk_fp8_f32 v236, v172, v173 op_sel:[0,0,1]
	v_cvt_pk_fp8_f32 v237, v176, v177 op_sel:[0,0,1]
	v_pk_mul_f32 v[170:171], v[102:103], v[186:187]
	v_pk_mul_f32 v[182:183], v[104:105], v[188:189]
	global_store_dwordx2 v[136:137], v[234:235], off offset:128
	global_store_dwordx2 v[136:137], v[236:237], off offset:160
	v_pk_fma_f32 v[136:137], v[114:115], v[190:191], v[170:171] neg_lo:[0,0,1] neg_hi:[0,0,1]
	v_pk_mul_f32 v[178:179], v[94:95], v[194:195]
	v_pk_fma_f32 v[172:173], v[116:117], v[192:193], v[182:183] neg_lo:[0,0,1] neg_hi:[0,0,1]
	v_pk_fma_f32 v[178:179], v[106:107], v[198:199], v[178:179] neg_lo:[0,0,1] neg_hi:[0,0,1]
	v_med3_f32 v135, v136, s51, v168
	v_med3_f32 v137, v137, s51, v168
	v_mov_b32_e32 v136, 0
	v_cvt_pk_fp8_f32 v136, v135, v137
	v_med3_f32 v135, v172, s51, v168
	v_med3_f32 v161, v173, s51, v168
	v_med3_f32 v172, v178, s51, v168
	v_med3_f32 v173, v179, s51, v168
	v_mov_b32_e32 v137, 0
	v_cvt_pk_fp8_f32 v137, v172, v173
	v_pk_mul_f32 v[176:177], v[96:97], v[196:197]
	v_pk_mul_f32 v[174:175], v[114:115], v[186:187]
	v_pk_fma_f32 v[176:177], v[108:109], v[200:201], v[176:177] neg_lo:[0,0,1] neg_hi:[0,0,1]
	v_pk_mul_f32 v[170:171], v[116:117], v[188:189]
	v_pk_fma_f32 v[174:175], v[102:103], v[190:191], v[174:175]
	v_pk_mul_f32 v[182:183], v[106:107], v[194:195]
	v_cvt_pk_fp8_f32 v136, v135, v161 op_sel:[0,0,1]
	v_med3_f32 v135, v176, s51, v168
	v_med3_f32 v161, v177, s51, v168
	v_pk_fma_f32 v[170:171], v[104:105], v[192:193], v[170:171]
	v_pk_fma_f32 v[182:183], v[94:95], v[198:199], v[182:183]
	v_cvt_pk_fp8_f32 v137, v135, v161 op_sel:[0,0,1]
	v_med3_f32 v135, v174, s51, v168
	v_med3_f32 v161, v175, s51, v168
	v_mov_b32_e32 v172, 0
	v_cvt_pk_fp8_f32 v172, v135, v161
	v_med3_f32 v135, v170, s51, v168
	v_med3_f32 v161, v171, s51, v168
	v_med3_f32 v170, v182, s51, v168
	v_med3_f32 v171, v183, s51, v168
	v_mov_b32_e32 v173, 0
	v_cvt_pk_fp8_f32 v173, v170, v171
	v_pk_mul_f32 v[180:181], v[108:109], v[196:197]
	v_cvt_pk_fp8_f32 v172, v135, v161 op_sel:[0,0,1]
	v_pk_fma_f32 v[180:181], v[96:97], v[200:201], v[180:181]
	v_pk_mul_f32 v[176:177], v[78:79], v[214:215]
	v_med3_f32 v135, v180, s51, v168
	v_med3_f32 v161, v181, s51, v168
	v_cvt_pk_fp8_f32 v173, v135, v161 op_sel:[0,0,1]
	v_mad_i64_i32 v[160:161], s[0:1], v160, s52, v[156:157]
	v_lshl_add_u64 v[160:161], v[160:161], 0, v[158:159]
	global_store_dwordx2 v[160:161], v[136:137], off offset:128
	global_store_dwordx2 v[160:161], v[172:173], off offset:160
	v_pk_mul_f32 v[160:161], v[86:87], v[210:211]
	v_pk_mul_f32 v[136:137], v[88:89], v[212:213]
	v_pk_fma_f32 v[160:161], v[98:99], v[202:203], v[160:161] neg_lo:[0,0,1] neg_hi:[0,0,1]
	v_pk_fma_f32 v[136:137], v[100:101], v[204:205], v[136:137] neg_lo:[0,0,1] neg_hi:[0,0,1]
	v_pk_fma_f32 v[176:177], v[90:91], v[206:207], v[176:177] neg_lo:[0,0,1] neg_hi:[0,0,1]
	v_med3_f32 v135, v160, s51, v168
	v_med3_f32 v161, v161, s51, v168
	v_mov_b32_e32 v160, 0
	v_cvt_pk_fp8_f32 v160, v135, v161
	v_med3_f32 v135, v136, s51, v168
	v_med3_f32 v136, v137, s51, v168
	v_med3_f32 v137, v176, s51, v168
	v_med3_f32 v176, v177, s51, v168
	v_mov_b32_e32 v161, 0
	v_cvt_pk_fp8_f32 v161, v137, v176
	v_pk_mul_f32 v[174:175], v[80:81], v[216:217]
	v_pk_mul_f32 v[172:173], v[98:99], v[210:211]
	v_pk_fma_f32 v[174:175], v[92:93], v[208:209], v[174:175] neg_lo:[0,0,1] neg_hi:[0,0,1]
	v_pk_mul_f32 v[170:171], v[100:101], v[212:213]
	v_pk_fma_f32 v[172:173], v[86:87], v[202:203], v[172:173]
	v_pk_mul_f32 v[180:181], v[90:91], v[214:215]
	v_cvt_pk_fp8_f32 v160, v135, v136 op_sel:[0,0,1]
	v_med3_f32 v135, v174, s51, v168
	v_med3_f32 v136, v175, s51, v168
	v_pk_fma_f32 v[170:171], v[88:89], v[204:205], v[170:171]
	v_pk_fma_f32 v[180:181], v[78:79], v[206:207], v[180:181]
	v_cvt_pk_fp8_f32 v161, v135, v136 op_sel:[0,0,1]
	v_med3_f32 v135, v172, s51, v168
	v_med3_f32 v137, v173, s51, v168
	v_mov_b32_e32 v136, 0
	v_cvt_pk_fp8_f32 v136, v135, v137
	v_med3_f32 v135, v170, s51, v168
	v_med3_f32 v170, v171, s51, v168
	v_med3_f32 v171, v180, s51, v168
	v_med3_f32 v172, v181, s51, v168
	v_mov_b32_e32 v137, 0
	v_cvt_pk_fp8_f32 v137, v171, v172
	v_pk_mul_f32 v[178:179], v[92:93], v[216:217]
	v_cvt_pk_fp8_f32 v136, v135, v170 op_sel:[0,0,1]
	v_pk_fma_f32 v[178:179], v[80:81], v[208:209], v[178:179]
	v_pk_mul_f32 v[176:177], v[66:67], v[230:231]
	v_med3_f32 v135, v178, s51, v168
	v_med3_f32 v170, v179, s51, v168
	v_cvt_pk_fp8_f32 v137, v135, v170 op_sel:[0,0,1]
	v_mad_i64_i32 v[170:171], s[0:1], v238, s52, v[156:157]
	v_lshl_add_u64 v[170:171], v[170:171], 0, v[158:159]
	global_store_dwordx2 v[170:171], v[160:161], off offset:128
	global_store_dwordx2 v[170:171], v[136:137], off offset:160
	v_pk_mul_f32 v[160:161], v[70:71], v[226:227]
	v_pk_mul_f32 v[136:137], v[72:73], v[228:229]
	v_pk_fma_f32 v[160:161], v[82:83], v[218:219], v[160:161] neg_lo:[0,0,1] neg_hi:[0,0,1]
	v_pk_fma_f32 v[136:137], v[84:85], v[220:221], v[136:137] neg_lo:[0,0,1] neg_hi:[0,0,1]
	v_pk_fma_f32 v[176:177], v[74:75], v[222:223], v[176:177] neg_lo:[0,0,1] neg_hi:[0,0,1]
	v_med3_f32 v135, v160, s51, v168
	v_med3_f32 v161, v161, s51, v168
	v_mov_b32_e32 v160, 0
	v_cvt_pk_fp8_f32 v160, v135, v161
	v_med3_f32 v135, v136, s51, v168
	v_med3_f32 v136, v137, s51, v168
	v_med3_f32 v137, v176, s51, v168
	v_med3_f32 v176, v177, s51, v168
	v_mov_b32_e32 v161, 0
	v_cvt_pk_fp8_f32 v161, v137, v176
	v_pk_mul_f32 v[174:175], v[68:69], v[232:233]
	v_pk_mul_f32 v[172:173], v[82:83], v[226:227]
	v_pk_fma_f32 v[174:175], v[76:77], v[224:225], v[174:175] neg_lo:[0,0,1] neg_hi:[0,0,1]
	v_pk_mul_f32 v[170:171], v[84:85], v[228:229]
	v_pk_fma_f32 v[172:173], v[70:71], v[218:219], v[172:173]
	v_pk_mul_f32 v[180:181], v[74:75], v[230:231]
	v_cvt_pk_fp8_f32 v160, v135, v136 op_sel:[0,0,1]
	v_med3_f32 v135, v174, s51, v168
	v_med3_f32 v136, v175, s51, v168
	v_pk_fma_f32 v[170:171], v[72:73], v[220:221], v[170:171]
	v_pk_fma_f32 v[180:181], v[66:67], v[222:223], v[180:181]
	v_cvt_pk_fp8_f32 v161, v135, v136 op_sel:[0,0,1]
	v_med3_f32 v135, v172, s51, v168
	v_med3_f32 v137, v173, s51, v168
	v_mov_b32_e32 v136, 0
	v_cvt_pk_fp8_f32 v136, v135, v137
	v_med3_f32 v135, v170, s51, v168
	v_med3_f32 v170, v171, s51, v168
	v_med3_f32 v171, v180, s51, v168
	v_med3_f32 v172, v181, s51, v168
	v_mov_b32_e32 v137, 0
	v_cvt_pk_fp8_f32 v137, v171, v172
	v_pk_mul_f32 v[178:179], v[76:77], v[232:233]
	v_cvt_pk_fp8_f32 v136, v135, v170 op_sel:[0,0,1]
	v_pk_fma_f32 v[178:179], v[68:69], v[224:225], v[178:179]
	v_add_u32_e32 v226, 0x80, v248
	v_med3_f32 v135, v178, s51, v168
	v_med3_f32 v170, v179, s51, v168
	v_cvt_pk_fp8_f32 v137, v135, v170 op_sel:[0,0,1]
	v_mad_i64_i32 v[134:135], s[0:1], v134, s52, v[156:157]
	v_lshl_add_u64 v[134:135], v[134:135], 0, v[158:159]
	global_store_dwordx2 v[134:135], v[160:161], off offset:128
	global_store_dwordx2 v[134:135], v[136:137], off offset:160
	s_nop 0
	v_ashrrev_i32_e32 v227, 31, v226
	v_lshlrev_b64 v[134:135], 7, v[226:227]
	v_lshl_add_u64 v[136:137], v[130:131], 0, v[134:135]
	global_load_dwordx4 v[170:173], v[136:137], off
	v_lshl_add_u64 v[134:135], v[132:133], 0, v[134:135]
	global_load_dwordx4 v[174:177], v[134:135], off
	global_load_dwordx4 v[178:181], v[136:137], off offset:16
	global_load_dwordx4 v[182:185], v[134:135], off offset:16
	v_add_u32_e32 v228, 16, v226
	v_ashrrev_i32_e32 v229, 31, v228
	v_lshlrev_b64 v[134:135], 7, v[228:229]
	v_lshl_add_u64 v[136:137], v[130:131], 0, v[134:135]
	global_load_dwordx4 v[186:189], v[136:137], off
	v_lshl_add_u64 v[134:135], v[132:133], 0, v[134:135]
	global_load_dwordx4 v[190:193], v[134:135], off
	global_load_dwordx4 v[194:197], v[136:137], off offset:16
	global_load_dwordx4 v[198:201], v[134:135], off offset:16
	v_add_u32_e32 v230, 32, v226
	v_ashrrev_i32_e32 v231, 31, v230
	v_lshlrev_b64 v[134:135], 7, v[230:231]
	v_lshl_add_u64 v[136:137], v[132:133], 0, v[134:135]
	v_lshl_add_u64 v[134:135], v[130:131], 0, v[134:135]
	global_load_dwordx4 v[202:205], v[136:137], off
	global_load_dwordx4 v[206:209], v[136:137], off offset:16
	global_load_dwordx4 v[210:213], v[134:135], off
	global_load_dwordx4 v[214:217], v[134:135], off offset:16
	v_add_u32_e32 v160, 48, v226
	v_ashrrev_i32_e32 v161, 31, v160
	v_lshlrev_b64 v[134:135], 7, v[160:161]
	v_lshl_add_u64 v[132:133], v[132:133], 0, v[134:135]
	v_lshl_add_u64 v[134:135], v[130:131], 0, v[134:135]
	global_load_dwordx4 v[218:221], v[132:133], off
	s_nop 0
	global_load_dwordx4 v[130:133], v[132:133], off offset:16
	s_nop 0
	global_load_dwordx4 v[222:225], v[134:135], off
	s_nop 0
	global_load_dwordx4 v[134:137], v[134:135], off offset:16
	s_waitcnt vmcnt(0) lgkmcnt(0)
	v_pk_mul_f32 v[232:233], v[56:57], v[172:173]
	v_pk_mul_f32 v[234:235], v[54:55], v[170:171]
	v_pk_mul_f32 v[172:173], v[64:65], v[172:173]
	v_pk_fma_f32 v[232:233], v[64:65], v[176:177], v[232:233] neg_lo:[0,0,1] neg_hi:[0,0,1]
	v_pk_fma_f32 v[234:235], v[62:63], v[174:175], v[234:235] neg_lo:[0,0,1] neg_hi:[0,0,1]
	v_pk_fma_f32 v[172:173], v[56:57], v[176:177], v[172:173]
	v_pk_mul_f32 v[176:177], v[46:47], v[178:179]
	v_pk_mul_f32 v[178:179], v[58:59], v[178:179]
	v_pk_fma_f32 v[176:177], v[58:59], v[182:183], v[176:177] neg_lo:[0,0,1] neg_hi:[0,0,1]
	v_pk_fma_f32 v[178:179], v[46:47], v[182:183], v[178:179]
	v_med3_f32 v161, v234, s51, v168
	v_med3_f32 v183, v235, s51, v168
	v_mov_b32_e32 v182, 0
	v_cvt_pk_fp8_f32 v182, v161, v183
	v_med3_f32 v176, v176, s51, v168
	v_med3_f32 v177, v177, s51, v168
	v_mov_b32_e32 v183, 0
	v_pk_mul_f32 v[170:171], v[62:63], v[170:171]
	v_cvt_pk_fp8_f32 v183, v176, v177
	v_pk_fma_f32 v[170:171], v[54:55], v[174:175], v[170:171]
	v_pk_mul_f32 v[174:175], v[48:49], v[180:181]
	v_pk_mul_f32 v[180:181], v[60:61], v[180:181]
	v_pk_fma_f32 v[174:175], v[60:61], v[184:185], v[174:175] neg_lo:[0,0,1] neg_hi:[0,0,1]
	v_pk_fma_f32 v[180:181], v[48:49], v[184:185], v[180:181]
	v_med3_f32 v161, v232, s51, v168
	v_med3_f32 v184, v233, s51, v168
	v_cvt_pk_fp8_f32 v182, v161, v184 op_sel:[0,0,1]
	v_med3_f32 v161, v174, s51, v168
	v_med3_f32 v174, v175, s51, v168
	v_cvt_pk_fp8_f32 v183, v161, v174 op_sel:[0,0,1]
	v_med3_f32 v161, v170, s51, v168
	v_med3_f32 v171, v171, s51, v168
	v_mov_b32_e32 v170, 0
	v_cvt_pk_fp8_f32 v170, v161, v171
	v_med3_f32 v161, v172, s51, v168
	v_med3_f32 v172, v173, s51, v168
	v_med3_f32 v173, v178, s51, v168
	v_med3_f32 v174, v179, s51, v168
	v_mov_b32_e32 v171, 0
	v_cvt_pk_fp8_f32 v171, v173, v174
	v_cvt_pk_fp8_f32 v170, v161, v172 op_sel:[0,0,1]
	v_med3_f32 v161, v180, s51, v168
	v_med3_f32 v172, v181, s51, v168
	v_cvt_pk_fp8_f32 v171, v161, v172 op_sel:[0,0,1]
	v_mad_i64_i32 v[172:173], s[0:1], v226, s52, v[156:157]
	v_lshl_add_u64 v[172:173], v[172:173], 0, v[158:159]
	global_store_dwordx2 v[172:173], v[182:183], off offset:128
	global_store_dwordx2 v[172:173], v[170:171], off offset:160
	v_pk_mul_f32 v[172:173], v[38:39], v[186:187]
	v_pk_mul_f32 v[170:171], v[40:41], v[188:189]
	v_pk_fma_f32 v[172:173], v[50:51], v[190:191], v[172:173] neg_lo:[0,0,1] neg_hi:[0,0,1]
	v_pk_mul_f32 v[180:181], v[30:31], v[194:195]
	v_pk_fma_f32 v[170:171], v[52:53], v[192:193], v[170:171] neg_lo:[0,0,1] neg_hi:[0,0,1]
	v_pk_fma_f32 v[180:181], v[42:43], v[198:199], v[180:181] neg_lo:[0,0,1] neg_hi:[0,0,1]
	v_med3_f32 v161, v172, s51, v168
	v_med3_f32 v173, v173, s51, v168
	v_mov_b32_e32 v172, 0
	v_cvt_pk_fp8_f32 v172, v161, v173
	v_med3_f32 v161, v170, s51, v168
	v_med3_f32 v170, v171, s51, v168
	v_med3_f32 v171, v180, s51, v168
	v_med3_f32 v180, v181, s51, v168
	v_mov_b32_e32 v173, 0
	v_cvt_pk_fp8_f32 v173, v171, v180
	v_pk_mul_f32 v[178:179], v[32:33], v[196:197]
	v_pk_mul_f32 v[176:177], v[50:51], v[186:187]
	v_pk_fma_f32 v[178:179], v[44:45], v[200:201], v[178:179] neg_lo:[0,0,1] neg_hi:[0,0,1]
	v_pk_mul_f32 v[174:175], v[52:53], v[188:189]
	v_pk_fma_f32 v[176:177], v[38:39], v[190:191], v[176:177]
	v_pk_mul_f32 v[184:185], v[42:43], v[194:195]
	v_cvt_pk_fp8_f32 v172, v161, v170 op_sel:[0,0,1]
	v_med3_f32 v161, v178, s51, v168
	v_med3_f32 v170, v179, s51, v168
	v_pk_fma_f32 v[174:175], v[40:41], v[192:193], v[174:175]
	v_pk_fma_f32 v[184:185], v[30:31], v[198:199], v[184:185]
	v_cvt_pk_fp8_f32 v173, v161, v170 op_sel:[0,0,1]
	v_med3_f32 v161, v176, s51, v168
	v_med3_f32 v171, v177, s51, v168
	v_mov_b32_e32 v170, 0
	v_cvt_pk_fp8_f32 v170, v161, v171
	v_med3_f32 v161, v174, s51, v168
	v_med3_f32 v174, v175, s51, v168
	v_med3_f32 v175, v184, s51, v168
	v_med3_f32 v176, v185, s51, v168
	v_mov_b32_e32 v171, 0
	v_cvt_pk_fp8_f32 v171, v175, v176
	v_pk_mul_f32 v[182:183], v[44:45], v[196:197]
	v_cvt_pk_fp8_f32 v170, v161, v174 op_sel:[0,0,1]
	v_pk_fma_f32 v[182:183], v[32:33], v[200:201], v[182:183]
	v_pk_mul_f32 v[180:181], v[14:15], v[214:215]
	v_med3_f32 v161, v182, s51, v168
	v_med3_f32 v174, v183, s51, v168
	v_cvt_pk_fp8_f32 v171, v161, v174 op_sel:[0,0,1]
	v_mad_i64_i32 v[174:175], s[0:1], v228, s52, v[156:157]
	v_lshl_add_u64 v[174:175], v[174:175], 0, v[158:159]
	global_store_dwordx2 v[174:175], v[172:173], off offset:128
	global_store_dwordx2 v[174:175], v[170:171], off offset:160
	v_pk_mul_f32 v[172:173], v[22:23], v[210:211]
	v_pk_mul_f32 v[170:171], v[24:25], v[212:213]
	v_pk_fma_f32 v[172:173], v[34:35], v[202:203], v[172:173] neg_lo:[0,0,1] neg_hi:[0,0,1]
	v_pk_fma_f32 v[170:171], v[36:37], v[204:205], v[170:171] neg_lo:[0,0,1] neg_hi:[0,0,1]
	v_pk_fma_f32 v[180:181], v[26:27], v[206:207], v[180:181] neg_lo:[0,0,1] neg_hi:[0,0,1]
	v_med3_f32 v161, v172, s51, v168
	v_med3_f32 v173, v173, s51, v168
	v_mov_b32_e32 v172, 0
	v_cvt_pk_fp8_f32 v172, v161, v173
	v_med3_f32 v161, v170, s51, v168
	v_med3_f32 v170, v171, s51, v168
	v_med3_f32 v171, v180, s51, v168
	v_med3_f32 v180, v181, s51, v168
	v_mov_b32_e32 v173, 0
	v_cvt_pk_fp8_f32 v173, v171, v180
	v_pk_mul_f32 v[178:179], v[16:17], v[216:217]
	v_pk_mul_f32 v[176:177], v[34:35], v[210:211]
	v_pk_fma_f32 v[178:179], v[28:29], v[208:209], v[178:179] neg_lo:[0,0,1] neg_hi:[0,0,1]
	v_pk_mul_f32 v[174:175], v[36:37], v[212:213]
	v_pk_fma_f32 v[176:177], v[22:23], v[202:203], v[176:177]
	v_pk_mul_f32 v[184:185], v[26:27], v[214:215]
	v_cvt_pk_fp8_f32 v172, v161, v170 op_sel:[0,0,1]
	v_med3_f32 v161, v178, s51, v168
	v_med3_f32 v170, v179, s51, v168
	v_pk_fma_f32 v[174:175], v[24:25], v[204:205], v[174:175]
	v_pk_fma_f32 v[184:185], v[14:15], v[206:207], v[184:185]
	v_cvt_pk_fp8_f32 v173, v161, v170 op_sel:[0,0,1]
	v_med3_f32 v161, v176, s51, v168
	v_med3_f32 v171, v177, s51, v168
	v_mov_b32_e32 v170, 0
	v_cvt_pk_fp8_f32 v170, v161, v171
	v_med3_f32 v161, v174, s51, v168
	v_med3_f32 v174, v175, s51, v168
	v_med3_f32 v175, v184, s51, v168
	v_med3_f32 v176, v185, s51, v168
	v_mov_b32_e32 v171, 0
	v_cvt_pk_fp8_f32 v171, v175, v176
	v_pk_mul_f32 v[182:183], v[28:29], v[216:217]
	v_cvt_pk_fp8_f32 v170, v161, v174 op_sel:[0,0,1]
	v_pk_fma_f32 v[182:183], v[16:17], v[208:209], v[182:183]
	v_pk_mul_f32 v[178:179], v[4:5], v[136:137]
	v_med3_f32 v161, v182, s51, v168
	v_med3_f32 v174, v183, s51, v168
	v_cvt_pk_fp8_f32 v171, v161, v174 op_sel:[0,0,1]
	v_mad_i64_i32 v[174:175], s[0:1], v230, s52, v[156:157]
	v_lshl_add_u64 v[174:175], v[174:175], 0, v[158:159]
	global_store_dwordx2 v[174:175], v[172:173], off offset:128
	global_store_dwordx2 v[174:175], v[170:171], off offset:160
	v_pk_mul_f32 v[172:173], v[6:7], v[222:223]
	v_pk_mul_f32 v[170:171], v[8:9], v[224:225]
	v_pk_fma_f32 v[172:173], v[18:19], v[218:219], v[172:173] neg_lo:[0,0,1] neg_hi:[0,0,1]
	v_pk_mul_f32 v[180:181], v[2:3], v[134:135]
	v_pk_mul_f32 v[136:137], v[12:13], v[136:137]
	v_pk_mul_f32 v[134:135], v[10:11], v[134:135]
	v_pk_fma_f32 v[170:171], v[20:21], v[220:221], v[170:171] neg_lo:[0,0,1] neg_hi:[0,0,1]
	v_pk_fma_f32 v[178:179], v[12:13], v[132:133], v[178:179] neg_lo:[0,0,1] neg_hi:[0,0,1]
	v_pk_fma_f32 v[180:181], v[10:11], v[130:131], v[180:181] neg_lo:[0,0,1] neg_hi:[0,0,1]
	v_pk_fma_f32 v[132:133], v[4:5], v[132:133], v[136:137]
	v_pk_fma_f32 v[130:131], v[2:3], v[130:131], v[134:135]
	v_med3_f32 v135, v172, s51, v168
	v_med3_f32 v136, v173, s51, v168
	v_mov_b32_e32 v134, 0
	v_cvt_pk_fp8_f32 v134, v135, v136
	v_med3_f32 v136, v170, s51, v168
	v_med3_f32 v161, v180, s51, v168
	v_med3_f32 v170, v181, s51, v168
	v_mov_b32_e32 v135, 0
	v_cvt_pk_fp8_f32 v135, v161, v170
	v_pk_mul_f32 v[176:177], v[18:19], v[222:223]
	v_med3_f32 v137, v171, s51, v168
	v_pk_fma_f32 v[176:177], v[6:7], v[218:219], v[176:177]
	v_cvt_pk_fp8_f32 v134, v136, v137 op_sel:[0,0,1]
	v_med3_f32 v136, v178, s51, v168
	v_med3_f32 v137, v179, s51, v168
	v_cvt_pk_fp8_f32 v135, v136, v137 op_sel:[0,0,1]
	v_med3_f32 v137, v176, s51, v168
	v_med3_f32 v161, v177, s51, v168
	v_mov_b32_e32 v136, 0
	v_cvt_pk_fp8_f32 v136, v137, v161
	v_med3_f32 v130, v130, s51, v168
	v_med3_f32 v131, v131, s51, v168
	v_mov_b32_e32 v137, 0
	v_cvt_pk_fp8_f32 v137, v130, v131
	v_pk_mul_f32 v[174:175], v[20:21], v[224:225]
	v_med3_f32 v130, v132, s51, v168
	v_pk_fma_f32 v[174:175], v[8:9], v[220:221], v[174:175]
	v_med3_f32 v131, v133, s51, v168
	v_med3_f32 v161, v174, s51, v168
	v_med3_f32 v170, v175, s51, v168
	v_cvt_pk_fp8_f32 v136, v161, v170 op_sel:[0,0,1]
	v_cvt_pk_fp8_f32 v137, v130, v131 op_sel:[0,0,1]
	v_mad_i64_i32 v[130:131], s[0:1], v160, s52, v[156:157]
	v_lshl_add_u64 v[130:131], v[130:131], 0, v[158:159]
	global_store_dwordx2 v[130:131], v[134:135], off offset:128
	global_store_dwordx2 v[130:131], v[136:137], off offset:160

.LBB0_2344:
	s_add_u32 s39, s30, s38
	s_addc_u32 s40, s31, 0
	s_add_u32 s41, s39, 0x100
	s_addc_u32 s42, s40, 0
	s_and_b64 s[0:1], s[36:37], exec
	s_cselect_b32 s43, s21, s42
	s_cselect_b32 s42, s62, s41
	s_add_u32 s0, s28, s38
	s_addc_u32 s1, s29, 0
	s_add_u32 s38, s0, 0x100
	s_addc_u32 s41, s1, 0
	s_and_b64 s[0:1], s[36:37], exec
	s_cselect_b32 s45, s19, s41
	s_cselect_b32 s44, s63, s38
	s_add_u32 s46, s39, 0x10080
	s_addc_u32 s47, s40, 0
	s_add_i32 s70, s58, s9
	s_add_i32 m0, s27, 0xc000
	s_add_i32 s71, s27, 0xe000
	s_add_i32 s0, s70, 0x2000
	s_add_u32 s40, s44, 0x10000
	s_addc_u32 s41, s45, 0
	s_add_i32 s77, s59, s9
	ds_read_b128 v[152:155], v147
	ds_read_b128 v[156:159], v147 offset:1024
	ds_read_b128 v[160:163], v147 offset:2048
	ds_read_b128 v[164:167], v147 offset:3072
	s_add_i32 s1, s77, 0x2000
	s_add_i32 s73, 0, 0x18000
	s_add_u32 s38, s42, 0x10000
	s_addc_u32 s39, s43, 0
	s_add_i32 s72, s73, s9
	s_add_i32 s69, 0, 0x1c000
	s_add_i32 s67, s72, 0x2000
	s_add_u32 s36, s44, 0x10080
	s_addc_u32 s37, s45, 0
	s_add_i32 s65, s69, s9
	s_add_i32 s64, s65, 0x2000
	v_lshl_add_u64 v[142:143], s[46:47], 0, v[136:137]
	ds_read_b128 v[168:171], v148
	ds_read_b128 v[172:175], v148 offset:1024
	ds_read_b128 v[176:179], v148 offset:2048
	ds_read_b128 v[180:183], v148 offset:3072
	ds_read_b128 v[184:187], v148 offset:4096
	ds_read_b128 v[188:191], v148 offset:5120
	ds_read_b128 v[192:195], v148 offset:6144
	ds_read_b128 v[196:199], v148 offset:7168
	global_load_lds_dwordx4 v[142:143], off nt
	v_lshl_add_u64 v[142:143], s[46:47], 0, v[132:133]
	s_mov_b32 m0, s71
	s_nop 0
	global_load_lds_dwordx4 v[142:143], off nt
	s_waitcnt lgkmcnt(8)
	s_waitcnt vmcnt(10)
	s_barrier
	s_waitcnt lgkmcnt(0)
	s_waitcnt lgkmcnt(0)
	v_mfma_f32_16x16x32_bf16 v[126:129], v[152:155], v[168:171], v[126:129]
	v_mfma_f32_16x16x32_bf16 v[122:125], v[160:163], v[168:171], v[122:125]
	v_mfma_f32_16x16x32_bf16 v[110:113], v[152:155], v[176:179], v[110:113]
	v_mfma_f32_16x16x32_bf16 v[106:109], v[160:163], v[176:179], v[106:109]
	v_mfma_f32_16x16x32_bf16 v[94:97], v[152:155], v[184:187], v[94:97]
	v_mfma_f32_16x16x32_bf16 v[90:93], v[160:163], v[184:187], v[90:93]
	v_mfma_f32_16x16x32_bf16 v[78:81], v[152:155], v[192:195], v[78:81]
	v_mfma_f32_16x16x32_bf16 v[74:77], v[160:163], v[192:195], v[74:77]
	v_mfma_f32_16x16x32_bf16 v[126:129], v[156:159], v[172:175], v[126:129]
	v_mfma_f32_16x16x32_bf16 v[122:125], v[164:167], v[172:175], v[122:125]
	v_mfma_f32_16x16x32_bf16 v[110:113], v[156:159], v[180:183], v[110:113]
	v_mfma_f32_16x16x32_bf16 v[106:109], v[164:167], v[180:183], v[106:109]
	v_mfma_f32_16x16x32_bf16 v[94:97], v[156:159], v[188:191], v[94:97]
	v_mfma_f32_16x16x32_bf16 v[90:93], v[164:167], v[188:191], v[90:93]
	v_mfma_f32_16x16x32_bf16 v[78:81], v[156:159], v[196:199], v[78:81]
	v_mfma_f32_16x16x32_bf16 v[74:77], v[164:167], v[196:199], v[74:77]
	s_barrier
	s_mov_b32 m0, s70
	v_lshl_add_u64 v[142:143], s[44:45], 0, v[134:135]
	ds_read_b128 v[200:203], v149
	ds_read_b128 v[204:207], v149 offset:1024
	ds_read_b128 v[208:211], v149 offset:2048
	ds_read_b128 v[212:215], v149 offset:3072
	global_load_lds_dwordx4 v[142:143], off
	v_lshl_add_u64 v[216:217], s[44:45], 0, v[130:131]
	s_mov_b32 m0, s0
	s_nop 0
	global_load_lds_dwordx4 v[216:217], off
	s_waitcnt vmcnt(10)
	s_barrier
	s_waitcnt lgkmcnt(0)
	s_waitcnt lgkmcnt(0)
	v_mfma_f32_16x16x32_bf16 v[118:121], v[200:203], v[168:171], v[118:121]
	v_mfma_f32_16x16x32_bf16 v[114:117], v[208:211], v[168:171], v[114:117]
	v_mfma_f32_16x16x32_bf16 v[102:105], v[200:203], v[176:179], v[102:105]
	v_mfma_f32_16x16x32_bf16 v[98:101], v[208:211], v[176:179], v[98:101]
	v_mfma_f32_16x16x32_bf16 v[86:89], v[200:203], v[184:187], v[86:89]
	v_mfma_f32_16x16x32_bf16 v[82:85], v[208:211], v[184:187], v[82:85]
	v_mfma_f32_16x16x32_bf16 v[70:73], v[200:203], v[192:195], v[70:73]
	v_mfma_f32_16x16x32_bf16 v[66:69], v[208:211], v[192:195], v[66:69]
	v_mfma_f32_16x16x32_bf16 v[118:121], v[204:207], v[172:175], v[118:121]
	v_mfma_f32_16x16x32_bf16 v[114:117], v[212:215], v[172:175], v[114:117]
	v_mfma_f32_16x16x32_bf16 v[102:105], v[204:207], v[180:183], v[102:105]
	v_mfma_f32_16x16x32_bf16 v[98:101], v[212:215], v[180:183], v[98:101]
	v_mfma_f32_16x16x32_bf16 v[86:89], v[204:207], v[188:191], v[86:89]
	v_mfma_f32_16x16x32_bf16 v[82:85], v[212:215], v[188:191], v[82:85]
	v_mfma_f32_16x16x32_bf16 v[70:73], v[204:207], v[196:199], v[70:73]
	v_mfma_f32_16x16x32_bf16 v[66:69], v[212:215], v[196:199], v[66:69]
	s_mov_b32 m0, s27
	v_lshl_add_u64 v[218:219], s[42:43], 0, v[136:137]
	s_barrier
	ds_read_b128 v[168:171], v148 offset:16384
	ds_read_b128 v[172:175], v148 offset:17408
	ds_read_b128 v[176:179], v148 offset:18432
	ds_read_b128 v[180:183], v148 offset:19456
	ds_read_b128 v[184:187], v148 offset:20480
	ds_read_b128 v[188:191], v148 offset:21504
	ds_read_b128 v[192:195], v148 offset:22528
	ds_read_b128 v[196:199], v148 offset:23552
	global_load_lds_dwordx4 v[218:219], off nt
	v_lshl_add_u64 v[220:221], s[42:43], 0, v[132:133]
	s_mov_b32 m0, s48
	s_nop 0
	global_load_lds_dwordx4 v[220:221], off nt
	s_waitcnt vmcnt(10)
	s_barrier
	s_waitcnt lgkmcnt(0)
	s_waitcnt lgkmcnt(0)
	v_mfma_f32_16x16x32_bf16 v[62:65], v[152:155], v[168:171], v[62:65]
	v_mfma_f32_16x16x32_bf16 v[58:61], v[160:163], v[168:171], v[58:61]
	v_mfma_f32_16x16x32_bf16 v[46:49], v[152:155], v[176:179], v[46:49]
	v_mfma_f32_16x16x32_bf16 v[42:45], v[160:163], v[176:179], v[42:45]
	v_mfma_f32_16x16x32_bf16 v[30:33], v[152:155], v[184:187], v[30:33]
	v_mfma_f32_16x16x32_bf16 v[26:29], v[160:163], v[184:187], v[26:29]
	v_mfma_f32_16x16x32_bf16 v[14:17], v[152:155], v[192:195], v[14:17]
	v_mfma_f32_16x16x32_bf16 v[10:13], v[160:163], v[192:195], v[10:13]
	v_mfma_f32_16x16x32_bf16 v[62:65], v[156:159], v[172:175], v[62:65]
	v_mfma_f32_16x16x32_bf16 v[58:61], v[164:167], v[172:175], v[58:61]
	v_mfma_f32_16x16x32_bf16 v[46:49], v[156:159], v[180:183], v[46:49]
	v_mfma_f32_16x16x32_bf16 v[42:45], v[164:167], v[180:183], v[42:45]
	v_mfma_f32_16x16x32_bf16 v[30:33], v[156:159], v[188:191], v[30:33]
	v_mfma_f32_16x16x32_bf16 v[26:29], v[164:167], v[188:191], v[26:29]
	v_mfma_f32_16x16x32_bf16 v[14:17], v[156:159], v[196:199], v[14:17]
	v_mfma_f32_16x16x32_bf16 v[10:13], v[164:167], v[196:199], v[10:13]
	s_barrier
	s_mov_b32 m0, s77
	v_lshl_add_u64 v[152:153], s[40:41], 0, v[134:135]
	global_load_lds_dwordx4 v[152:153], off
	v_lshl_add_u64 v[152:153], s[40:41], 0, v[130:131]
	s_mov_b32 m0, s1
	s_nop 0
	global_load_lds_dwordx4 v[152:153], off
	s_waitcnt vmcnt(10)
	s_barrier
	v_mfma_f32_16x16x32_bf16 v[54:57], v[200:203], v[168:171], v[54:57]
	v_mfma_f32_16x16x32_bf16 v[50:53], v[208:211], v[168:171], v[50:53]
	v_mfma_f32_16x16x32_bf16 v[38:41], v[200:203], v[176:179], v[38:41]
	v_mfma_f32_16x16x32_bf16 v[34:37], v[208:211], v[176:179], v[34:37]
	v_mfma_f32_16x16x32_bf16 v[22:25], v[200:203], v[184:187], v[22:25]
	v_mfma_f32_16x16x32_bf16 v[18:21], v[208:211], v[184:187], v[18:21]
	v_mfma_f32_16x16x32_bf16 v[6:9], v[200:203], v[192:195], v[6:9]
	v_mfma_f32_16x16x32_bf16 v[2:5], v[208:211], v[192:195], v[2:5]
	v_mfma_f32_16x16x32_bf16 v[54:57], v[204:207], v[172:175], v[54:57]
	v_mfma_f32_16x16x32_bf16 v[50:53], v[212:215], v[172:175], v[50:53]
	v_mfma_f32_16x16x32_bf16 v[38:41], v[204:207], v[180:183], v[38:41]
	v_mfma_f32_16x16x32_bf16 v[34:37], v[212:215], v[180:183], v[34:37]
	v_mfma_f32_16x16x32_bf16 v[22:25], v[204:207], v[188:191], v[22:25]
	v_mfma_f32_16x16x32_bf16 v[18:21], v[212:215], v[188:191], v[18:21]
	v_mfma_f32_16x16x32_bf16 v[6:9], v[204:207], v[196:199], v[6:9]
	v_mfma_f32_16x16x32_bf16 v[2:5], v[212:215], v[196:199], v[2:5]
	v_add_u32_e32 v151, s73, v146
	s_barrier
	ds_read_b128 v[152:155], v151
	ds_read_b128 v[156:159], v151 offset:1024
	ds_read_b128 v[160:163], v151 offset:2048
	ds_read_b128 v[164:167], v151 offset:3072
	s_mov_b32 m0, s49
	v_lshl_add_u64 v[200:201], s[38:39], 0, v[136:137]
	ds_read_b128 v[168:171], v148 offset:32768
	ds_read_b128 v[172:175], v148 offset:33792
	ds_read_b128 v[176:179], v148 offset:34816
	ds_read_b128 v[180:183], v148 offset:35840
	ds_read_b128 v[184:187], v148 offset:36864
	ds_read_b128 v[188:191], v148 offset:37888
	ds_read_b128 v[192:195], v148 offset:38912
	ds_read_b128 v[196:199], v148 offset:39936
	global_load_lds_dwordx4 v[200:201], off nt
	v_lshl_add_u64 v[200:201], s[38:39], 0, v[132:133]
	s_mov_b32 m0, s50
	s_nop 0
	global_load_lds_dwordx4 v[200:201], off nt
	s_waitcnt lgkmcnt(8)
	s_waitcnt vmcnt(10)
	s_barrier
	s_waitcnt lgkmcnt(0)
	s_waitcnt lgkmcnt(0)
	v_mfma_f32_16x16x32_bf16 v[126:129], v[152:155], v[168:171], v[126:129]
	v_mfma_f32_16x16x32_bf16 v[122:125], v[160:163], v[168:171], v[122:125]
	v_mfma_f32_16x16x32_bf16 v[110:113], v[152:155], v[176:179], v[110:113]
	v_mfma_f32_16x16x32_bf16 v[106:109], v[160:163], v[176:179], v[106:109]
	v_mfma_f32_16x16x32_bf16 v[94:97], v[152:155], v[184:187], v[94:97]
	v_mfma_f32_16x16x32_bf16 v[90:93], v[160:163], v[184:187], v[90:93]
	v_mfma_f32_16x16x32_bf16 v[78:81], v[152:155], v[192:195], v[78:81]
	v_mfma_f32_16x16x32_bf16 v[74:77], v[160:163], v[192:195], v[74:77]
	v_mfma_f32_16x16x32_bf16 v[126:129], v[156:159], v[172:175], v[126:129]
	v_mfma_f32_16x16x32_bf16 v[122:125], v[164:167], v[172:175], v[122:125]
	v_mfma_f32_16x16x32_bf16 v[110:113], v[156:159], v[180:183], v[110:113]
	v_mfma_f32_16x16x32_bf16 v[106:109], v[164:167], v[180:183], v[106:109]
	v_mfma_f32_16x16x32_bf16 v[94:97], v[156:159], v[188:191], v[94:97]
	v_mfma_f32_16x16x32_bf16 v[90:93], v[164:167], v[188:191], v[90:93]
	v_mfma_f32_16x16x32_bf16 v[78:81], v[156:159], v[196:199], v[78:81]
	v_mfma_f32_16x16x32_bf16 v[74:77], v[164:167], v[196:199], v[74:77]
	s_barrier
	s_mov_b32 m0, s72
	v_add_u32_e32 v151, s69, v146
	v_lshl_add_u64 v[142:143], v[142:143], 0, s[16:17]
	ds_read_b128 v[200:203], v151
	ds_read_b128 v[204:207], v151 offset:1024
	ds_read_b128 v[208:211], v151 offset:2048
	ds_read_b128 v[212:215], v151 offset:3072
	global_load_lds_dwordx4 v[142:143], off
	v_lshl_add_u64 v[142:143], v[216:217], 0, s[16:17]
	s_mov_b32 m0, s67
	s_nop 0
	global_load_lds_dwordx4 v[142:143], off
	s_waitcnt vmcnt(10)
	s_barrier
	s_waitcnt lgkmcnt(0)
	s_waitcnt lgkmcnt(0)
	v_mfma_f32_16x16x32_bf16 v[118:121], v[200:203], v[168:171], v[118:121]
	v_mfma_f32_16x16x32_bf16 v[114:117], v[208:211], v[168:171], v[114:117]
	v_mfma_f32_16x16x32_bf16 v[102:105], v[200:203], v[176:179], v[102:105]
	v_mfma_f32_16x16x32_bf16 v[98:101], v[208:211], v[176:179], v[98:101]
	v_mfma_f32_16x16x32_bf16 v[86:89], v[200:203], v[184:187], v[86:89]
	v_mfma_f32_16x16x32_bf16 v[82:85], v[208:211], v[184:187], v[82:85]
	v_mfma_f32_16x16x32_bf16 v[70:73], v[200:203], v[192:195], v[70:73]
	v_mfma_f32_16x16x32_bf16 v[66:69], v[208:211], v[192:195], v[66:69]
	v_mfma_f32_16x16x32_bf16 v[118:121], v[204:207], v[172:175], v[118:121]
	v_mfma_f32_16x16x32_bf16 v[114:117], v[212:215], v[172:175], v[114:117]
	v_mfma_f32_16x16x32_bf16 v[102:105], v[204:207], v[180:183], v[102:105]
	v_mfma_f32_16x16x32_bf16 v[98:101], v[212:215], v[180:183], v[98:101]
	v_mfma_f32_16x16x32_bf16 v[86:89], v[204:207], v[188:191], v[86:89]
	v_mfma_f32_16x16x32_bf16 v[82:85], v[212:215], v[188:191], v[82:85]
	v_mfma_f32_16x16x32_bf16 v[70:73], v[204:207], v[196:199], v[70:73]
	v_mfma_f32_16x16x32_bf16 v[66:69], v[212:215], v[196:199], v[66:69]
	s_mov_b32 m0, s56
	v_lshl_add_u64 v[142:143], v[218:219], 0, s[16:17]
	s_barrier
	ds_read_b128 v[168:171], v148 offset:49152
	ds_read_b128 v[172:175], v148 offset:50176
	ds_read_b128 v[176:179], v148 offset:51200
	ds_read_b128 v[180:183], v148 offset:52224
	ds_read_b128 v[184:187], v148 offset:53248
	ds_read_b128 v[188:191], v148 offset:54272
	ds_read_b128 v[192:195], v148 offset:55296
	ds_read_b128 v[196:199], v148 offset:56320
	global_load_lds_dwordx4 v[142:143], off nt
	v_lshl_add_u64 v[142:143], v[220:221], 0, s[16:17]
	s_mov_b32 m0, s57
	s_nop 0
	global_load_lds_dwordx4 v[142:143], off nt
	s_waitcnt vmcnt(10)
	s_barrier
	s_waitcnt lgkmcnt(0)
	s_waitcnt lgkmcnt(0)
	v_mfma_f32_16x16x32_bf16 v[62:65], v[152:155], v[168:171], v[62:65]
	v_mfma_f32_16x16x32_bf16 v[58:61], v[160:163], v[168:171], v[58:61]
	v_mfma_f32_16x16x32_bf16 v[46:49], v[152:155], v[176:179], v[46:49]
	v_mfma_f32_16x16x32_bf16 v[42:45], v[160:163], v[176:179], v[42:45]
	v_mfma_f32_16x16x32_bf16 v[30:33], v[152:155], v[184:187], v[30:33]
	v_mfma_f32_16x16x32_bf16 v[26:29], v[160:163], v[184:187], v[26:29]
	v_mfma_f32_16x16x32_bf16 v[14:17], v[152:155], v[192:195], v[14:17]
	v_mfma_f32_16x16x32_bf16 v[10:13], v[160:163], v[192:195], v[10:13]
	v_mfma_f32_16x16x32_bf16 v[62:65], v[156:159], v[172:175], v[62:65]
	v_mfma_f32_16x16x32_bf16 v[58:61], v[164:167], v[172:175], v[58:61]
	v_mfma_f32_16x16x32_bf16 v[46:49], v[156:159], v[180:183], v[46:49]
	v_mfma_f32_16x16x32_bf16 v[42:45], v[164:167], v[180:183], v[42:45]
	v_mfma_f32_16x16x32_bf16 v[30:33], v[156:159], v[188:191], v[30:33]
	v_mfma_f32_16x16x32_bf16 v[26:29], v[164:167], v[188:191], v[26:29]
	v_mfma_f32_16x16x32_bf16 v[14:17], v[156:159], v[196:199], v[14:17]
	v_mfma_f32_16x16x32_bf16 v[10:13], v[164:167], v[196:199], v[10:13]
	s_barrier
	s_mov_b32 m0, s65
	v_lshl_add_u64 v[142:143], s[36:37], 0, v[134:135]
	global_load_lds_dwordx4 v[142:143], off
	v_lshl_add_u64 v[142:143], s[36:37], 0, v[130:131]
	s_mov_b32 m0, s64
	s_nop 0
	global_load_lds_dwordx4 v[142:143], off
	s_waitcnt vmcnt(10)
	s_barrier
	v_mfma_f32_16x16x32_bf16 v[54:57], v[200:203], v[168:171], v[54:57]
	v_mfma_f32_16x16x32_bf16 v[50:53], v[208:211], v[168:171], v[50:53]
	v_mfma_f32_16x16x32_bf16 v[38:41], v[200:203], v[176:179], v[38:41]
	v_mfma_f32_16x16x32_bf16 v[34:37], v[208:211], v[176:179], v[34:37]
	v_mfma_f32_16x16x32_bf16 v[22:25], v[200:203], v[184:187], v[22:25]
	v_mfma_f32_16x16x32_bf16 v[18:21], v[208:211], v[184:187], v[18:21]
	v_mfma_f32_16x16x32_bf16 v[6:9], v[200:203], v[192:195], v[6:9]
	v_mfma_f32_16x16x32_bf16 v[2:5], v[208:211], v[192:195], v[2:5]
	v_mfma_f32_16x16x32_bf16 v[54:57], v[204:207], v[172:175], v[54:57]
	v_mfma_f32_16x16x32_bf16 v[50:53], v[212:215], v[172:175], v[50:53]
	v_mfma_f32_16x16x32_bf16 v[38:41], v[204:207], v[180:183], v[38:41]
	v_mfma_f32_16x16x32_bf16 v[34:37], v[212:215], v[180:183], v[34:37]
	v_mfma_f32_16x16x32_bf16 v[22:25], v[204:207], v[188:191], v[22:25]
	v_mfma_f32_16x16x32_bf16 v[18:21], v[212:215], v[188:191], v[18:21]
	v_mfma_f32_16x16x32_bf16 v[6:9], v[204:207], v[196:199], v[6:9]
	v_mfma_f32_16x16x32_bf16 v[2:5], v[212:215], v[196:199], v[2:5]
	s_movk_i32 s38, 0x100
	s_andn2_b64 vcc, exec, s[34:35]
	s_mov_b64 s[36:37], -1
	s_mov_b64 s[34:35], 0
	s_barrier
	s_cbranch_vccz .LBB0_2344
	s_lshl_b32 s0, s26, 8
	v_mov_b32_e32 v143, v144
	s_add_i32 s0, s0, s53
	v_mov_b32_e32 v142, v145
	v_add_u32_e32 v151, s0, v143
	v_mov_b32_e32 v154, v151
	v_max_f32_e32 v126, v126, v126
	v_ashrrev_i32_e32 v152, 8, v154
	v_and_b32_e32 v152, -8, v152
	v_add_u32_e32 v152, s55, v152
	v_ashrrev_i32_e32 v153, 31, v152
	v_lshlrev_b64 v[152:153], 11, v[152:153]
	v_and_or_b32 v152, v154, s60, v152
	v_med3_f32 v154, v126, s61, v150
	v_max_f32_e32 v126, v127, v127
	v_med3_f32 v127, v126, s61, v150
	v_mov_b32_e32 v126, 0
	v_cvt_pk_fp8_f32 v126, v154, v127
	v_max_f32_e32 v127, v128, v128
	v_max_f32_e32 v128, v129, v129
	v_med3_f32 v127, v127, s61, v150
	v_med3_f32 v128, v128, s61, v150
	v_max_f32_e32 v122, v122, v122
	v_max_f32_e32 v123, v123, v123
	v_cvt_pk_fp8_f32 v126, v127, v128 op_sel:[0,0,1]
	v_med3_f32 v122, v122, s61, v150
	v_med3_f32 v123, v123, s61, v150
	v_mov_b32_e32 v127, 0
	v_cvt_pk_fp8_f32 v127, v122, v123
	v_max_f32_e32 v122, v124, v124
	v_max_f32_e32 v123, v125, v125
	v_med3_f32 v122, v122, s61, v150
	v_med3_f32 v123, v123, s61, v150
	v_lshl_add_u32 v142, v142, 3, s54
	v_cvt_pk_fp8_f32 v127, v122, v123 op_sel:[0,0,1]
	v_mov_b64_e32 v[122:123], s[12:13]
	v_ashrrev_i32_e32 v143, 31, v142
	v_mad_u64_u32 v[124:125], s[0:1], v152, s51, v[122:123]
	v_cvt_pk_bf16_f32 v118, v118, v119
	v_cvt_pk_bf16_f32 v119, v120, v121
	v_cvt_pk_bf16_f32 v120, v114, v115
	v_lshlrev_b64 v[114:115], 8, v[152:153]
	v_mad_i32_i24 v125, v153, s51, v125
	v_cvt_pk_bf16_f32 v121, v116, v117
	v_lshl_add_u64 v[116:117], s[14:15], 0, v[114:115]
	v_lshlrev_b64 v[114:115], 1, v[142:143]
	v_lshl_add_u64 v[124:125], v[124:125], 0, v[142:143]
	v_lshl_add_u64 v[116:117], v[116:117], 0, v[114:115]
	global_store_dwordx2 v[124:125], v[126:127], off
	global_store_dwordx4 v[116:117], v[118:121], off
	v_max_f32_e32 v110, v110, v110
	v_max_f32_e32 v106, v106, v106
	v_add_u32_e32 v118, 16, v151
	v_max_f32_e32 v107, v107, v107
	v_ashrrev_i32_e32 v116, 8, v118
	v_and_b32_e32 v116, -8, v116
	v_add_u32_e32 v116, s55, v116
	v_ashrrev_i32_e32 v117, 31, v116
	v_lshlrev_b64 v[116:117], 11, v[116:117]
	v_and_or_b32 v116, v118, s60, v116
	v_med3_f32 v118, v110, s61, v150
	v_max_f32_e32 v110, v111, v111
	v_med3_f32 v111, v110, s61, v150
	v_mov_b32_e32 v110, 0
	v_cvt_pk_fp8_f32 v110, v118, v111
	v_max_f32_e32 v111, v112, v112
	v_max_f32_e32 v112, v113, v113
	v_med3_f32 v111, v111, s61, v150
	v_med3_f32 v112, v112, s61, v150
	v_cvt_pk_fp8_f32 v110, v111, v112 op_sel:[0,0,1]
	v_med3_f32 v106, v106, s61, v150
	v_med3_f32 v107, v107, s61, v150
	v_mov_b32_e32 v111, 0
	v_cvt_pk_fp8_f32 v111, v106, v107
	v_max_f32_e32 v106, v108, v108
	v_max_f32_e32 v107, v109, v109
	v_med3_f32 v106, v106, s61, v150
	v_med3_f32 v107, v107, s61, v150
	v_cvt_pk_fp8_f32 v111, v106, v107 op_sel:[0,0,1]
	v_mad_u64_u32 v[106:107], s[0:1], v116, s51, v[122:123]
	v_cvt_pk_bf16_f32 v102, v102, v103
	v_cvt_pk_bf16_f32 v103, v104, v105
	v_cvt_pk_bf16_f32 v104, v98, v99
	v_lshlrev_b64 v[98:99], 8, v[116:117]
	v_mad_i32_i24 v107, v117, s51, v107
	v_lshl_add_u64 v[98:99], s[14:15], 0, v[98:99]
	v_lshl_add_u64 v[106:107], v[106:107], 0, v[142:143]
	v_cvt_pk_bf16_f32 v105, v100, v101
	v_lshl_add_u64 v[98:99], v[98:99], 0, v[114:115]
	v_add_u32_e32 v100, 32, v151
	global_store_dwordx2 v[106:107], v[110:111], off
	global_store_dwordx4 v[98:99], v[102:105], off
	v_max_f32_e32 v94, v94, v94
	v_ashrrev_i32_e32 v98, 8, v100
	v_and_b32_e32 v98, -8, v98
	v_add_u32_e32 v98, s55, v98
	v_ashrrev_i32_e32 v99, 31, v98
	v_lshlrev_b64 v[98:99], 11, v[98:99]
	v_and_or_b32 v98, v100, s60, v98
	v_med3_f32 v100, v94, s61, v150
	v_max_f32_e32 v94, v95, v95
	v_med3_f32 v95, v94, s61, v150
	v_mov_b32_e32 v94, 0
	v_cvt_pk_fp8_f32 v94, v100, v95
	v_max_f32_e32 v95, v96, v96
	v_max_f32_e32 v96, v97, v97
	v_med3_f32 v95, v95, s61, v150
	v_med3_f32 v96, v96, s61, v150
	v_max_f32_e32 v90, v90, v90
	v_max_f32_e32 v91, v91, v91
	v_cvt_pk_fp8_f32 v94, v95, v96 op_sel:[0,0,1]
	v_med3_f32 v90, v90, s61, v150
	v_med3_f32 v91, v91, s61, v150
	v_mov_b32_e32 v95, 0
	v_cvt_pk_fp8_f32 v95, v90, v91
	v_max_f32_e32 v90, v92, v92
	v_max_f32_e32 v91, v93, v93
	v_med3_f32 v90, v90, s61, v150
	v_med3_f32 v91, v91, s61, v150
	v_cvt_pk_fp8_f32 v95, v90, v91 op_sel:[0,0,1]
	v_mad_u64_u32 v[90:91], s[0:1], v98, s51, v[122:123]
	v_cvt_pk_bf16_f32 v86, v86, v87
	v_cvt_pk_bf16_f32 v87, v88, v89
	v_cvt_pk_bf16_f32 v88, v82, v83
	v_lshlrev_b64 v[82:83], 8, v[98:99]
	v_mad_i32_i24 v91, v99, s51, v91
	v_lshl_add_u64 v[82:83], s[14:15], 0, v[82:83]
	v_lshl_add_u64 v[90:91], v[90:91], 0, v[142:143]
	v_cvt_pk_bf16_f32 v89, v84, v85
	v_lshl_add_u64 v[82:83], v[82:83], 0, v[114:115]
	v_add_u32_e32 v84, 48, v151
	global_store_dwordx2 v[90:91], v[94:95], off
	global_store_dwordx4 v[82:83], v[86:89], off
	v_max_f32_e32 v78, v78, v78
	v_ashrrev_i32_e32 v82, 8, v84
	v_and_b32_e32 v82, -8, v82
	v_add_u32_e32 v82, s55, v82
	v_ashrrev_i32_e32 v83, 31, v82
	v_lshlrev_b64 v[82:83], 11, v[82:83]
	v_and_or_b32 v82, v84, s60, v82
	v_med3_f32 v84, v78, s61, v150
	v_max_f32_e32 v78, v79, v79
	v_med3_f32 v79, v78, s61, v150
	v_mov_b32_e32 v78, 0
	v_cvt_pk_fp8_f32 v78, v84, v79
	v_max_f32_e32 v79, v80, v80
	v_max_f32_e32 v80, v81, v81
	v_med3_f32 v79, v79, s61, v150
	v_med3_f32 v80, v80, s61, v150
	v_max_f32_e32 v74, v74, v74
	v_max_f32_e32 v75, v75, v75
	v_cvt_pk_fp8_f32 v78, v79, v80 op_sel:[0,0,1]
	v_med3_f32 v74, v74, s61, v150
	v_med3_f32 v75, v75, s61, v150
	v_mov_b32_e32 v79, 0
	v_cvt_pk_fp8_f32 v79, v74, v75
	v_max_f32_e32 v74, v76, v76
	v_max_f32_e32 v75, v77, v77
	v_med3_f32 v74, v74, s61, v150
	v_med3_f32 v75, v75, s61, v150
	v_cvt_pk_fp8_f32 v79, v74, v75 op_sel:[0,0,1]
	v_mad_u64_u32 v[74:75], s[0:1], v82, s51, v[122:123]
	v_cvt_pk_bf16_f32 v70, v70, v71
	v_cvt_pk_bf16_f32 v71, v72, v73
	v_cvt_pk_bf16_f32 v72, v66, v67
	v_lshlrev_b64 v[66:67], 8, v[82:83]
	v_mad_i32_i24 v75, v83, s51, v75
	v_lshl_add_u64 v[66:67], s[14:15], 0, v[66:67]
	v_lshl_add_u64 v[74:75], v[74:75], 0, v[142:143]
	v_cvt_pk_bf16_f32 v73, v68, v69
	v_lshl_add_u64 v[66:67], v[66:67], 0, v[114:115]
	v_add_u32_e32 v68, 0x80, v151
	global_store_dwordx2 v[74:75], v[78:79], off
	global_store_dwordx4 v[66:67], v[70:73], off
	v_max_f32_e32 v62, v62, v62
	v_ashrrev_i32_e32 v66, 8, v68
	v_and_b32_e32 v66, -8, v66
	v_add_u32_e32 v66, s55, v66
	v_ashrrev_i32_e32 v67, 31, v66
	v_lshlrev_b64 v[66:67], 11, v[66:67]
	v_and_or_b32 v66, v68, s60, v66
	v_med3_f32 v68, v62, s61, v150
	v_max_f32_e32 v62, v63, v63
	v_med3_f32 v63, v62, s61, v150
	v_mov_b32_e32 v62, 0
	v_cvt_pk_fp8_f32 v62, v68, v63
	v_max_f32_e32 v63, v64, v64
	v_max_f32_e32 v64, v65, v65
	v_med3_f32 v63, v63, s61, v150
	v_med3_f32 v64, v64, s61, v150
	v_max_f32_e32 v58, v58, v58
	v_max_f32_e32 v59, v59, v59
	v_cvt_pk_fp8_f32 v62, v63, v64 op_sel:[0,0,1]
	v_med3_f32 v58, v58, s61, v150
	v_med3_f32 v59, v59, s61, v150
	v_mov_b32_e32 v63, 0
	v_cvt_pk_fp8_f32 v63, v58, v59
	v_max_f32_e32 v58, v60, v60
	v_max_f32_e32 v59, v61, v61
	v_med3_f32 v58, v58, s61, v150
	v_med3_f32 v59, v59, s61, v150
	v_cvt_pk_fp8_f32 v63, v58, v59 op_sel:[0,0,1]
	v_mad_u64_u32 v[58:59], s[0:1], v66, s51, v[122:123]
	v_cvt_pk_bf16_f32 v54, v54, v55
	v_cvt_pk_bf16_f32 v55, v56, v57
	v_cvt_pk_bf16_f32 v56, v50, v51
	v_lshlrev_b64 v[50:51], 8, v[66:67]
	v_mad_i32_i24 v59, v67, s51, v59
	v_lshl_add_u64 v[50:51], s[14:15], 0, v[50:51]
	v_lshl_add_u64 v[58:59], v[58:59], 0, v[142:143]
	v_cvt_pk_bf16_f32 v57, v52, v53
	v_lshl_add_u64 v[50:51], v[50:51], 0, v[114:115]
	v_add_u32_e32 v52, 0x90, v151
	global_store_dwordx2 v[58:59], v[62:63], off
	global_store_dwordx4 v[50:51], v[54:57], off
	v_max_f32_e32 v46, v46, v46
	v_ashrrev_i32_e32 v50, 8, v52
	v_and_b32_e32 v50, -8, v50
	v_add_u32_e32 v50, s55, v50
	v_ashrrev_i32_e32 v51, 31, v50
	v_lshlrev_b64 v[50:51], 11, v[50:51]
	v_and_or_b32 v50, v52, s60, v50
	v_med3_f32 v52, v46, s61, v150
	v_max_f32_e32 v46, v47, v47
	v_med3_f32 v47, v46, s61, v150
	v_mov_b32_e32 v46, 0
	v_cvt_pk_fp8_f32 v46, v52, v47
	v_max_f32_e32 v47, v48, v48
	v_max_f32_e32 v48, v49, v49
	v_med3_f32 v47, v47, s61, v150
	v_med3_f32 v48, v48, s61, v150
	v_max_f32_e32 v42, v42, v42
	v_max_f32_e32 v43, v43, v43
	v_cvt_pk_fp8_f32 v46, v47, v48 op_sel:[0,0,1]
	v_med3_f32 v42, v42, s61, v150
	v_med3_f32 v43, v43, s61, v150
	v_mov_b32_e32 v47, 0
	v_cvt_pk_fp8_f32 v47, v42, v43
	v_max_f32_e32 v42, v44, v44
	v_max_f32_e32 v43, v45, v45
	v_med3_f32 v42, v42, s61, v150
	v_med3_f32 v43, v43, s61, v150
	v_cvt_pk_fp8_f32 v47, v42, v43 op_sel:[0,0,1]
	v_mad_u64_u32 v[42:43], s[0:1], v50, s51, v[122:123]
	v_cvt_pk_bf16_f32 v38, v38, v39
	v_cvt_pk_bf16_f32 v39, v40, v41
	v_cvt_pk_bf16_f32 v40, v34, v35
	v_lshlrev_b64 v[34:35], 8, v[50:51]
	v_mad_i32_i24 v43, v51, s51, v43
	v_lshl_add_u64 v[34:35], s[14:15], 0, v[34:35]
	v_lshl_add_u64 v[42:43], v[42:43], 0, v[142:143]
	v_cvt_pk_bf16_f32 v41, v36, v37
	v_lshl_add_u64 v[34:35], v[34:35], 0, v[114:115]
	v_add_u32_e32 v36, 0xa0, v151
	global_store_dwordx2 v[42:43], v[46:47], off
	global_store_dwordx4 v[34:35], v[38:41], off
	v_max_f32_e32 v30, v30, v30
	v_ashrrev_i32_e32 v34, 8, v36
	v_and_b32_e32 v34, -8, v34
	v_add_u32_e32 v34, s55, v34
	v_ashrrev_i32_e32 v35, 31, v34
	v_lshlrev_b64 v[34:35], 11, v[34:35]
	v_and_or_b32 v34, v36, s60, v34
	v_med3_f32 v36, v30, s61, v150
	v_max_f32_e32 v30, v31, v31
	v_med3_f32 v31, v30, s61, v150
	v_mov_b32_e32 v30, 0
	v_cvt_pk_fp8_f32 v30, v36, v31
	v_max_f32_e32 v31, v32, v32
	v_max_f32_e32 v32, v33, v33
	v_med3_f32 v31, v31, s61, v150
	v_med3_f32 v32, v32, s61, v150
	v_max_f32_e32 v26, v26, v26
	v_max_f32_e32 v27, v27, v27
	v_cvt_pk_fp8_f32 v30, v31, v32 op_sel:[0,0,1]
	v_med3_f32 v26, v26, s61, v150
	v_med3_f32 v27, v27, s61, v150
	v_mov_b32_e32 v31, 0
	v_cvt_pk_fp8_f32 v31, v26, v27
	v_max_f32_e32 v26, v28, v28
	v_max_f32_e32 v27, v29, v29
	v_med3_f32 v26, v26, s61, v150
	v_med3_f32 v27, v27, s61, v150
	v_cvt_pk_fp8_f32 v31, v26, v27 op_sel:[0,0,1]
	v_mad_u64_u32 v[26:27], s[0:1], v34, s51, v[122:123]
	v_cvt_pk_bf16_f32 v22, v22, v23
	v_cvt_pk_bf16_f32 v23, v24, v25
	v_cvt_pk_bf16_f32 v24, v18, v19
	v_lshlrev_b64 v[18:19], 8, v[34:35]
	v_mad_i32_i24 v27, v35, s51, v27
	v_lshl_add_u64 v[18:19], s[14:15], 0, v[18:19]
	v_lshl_add_u64 v[26:27], v[26:27], 0, v[142:143]
	v_cvt_pk_bf16_f32 v25, v20, v21
	v_lshl_add_u64 v[18:19], v[18:19], 0, v[114:115]
	v_add_u32_e32 v20, 0xb0, v151
	global_store_dwordx2 v[26:27], v[30:31], off
	global_store_dwordx4 v[18:19], v[22:25], off
	v_max_f32_e32 v14, v14, v14
	v_ashrrev_i32_e32 v18, 8, v20
	v_and_b32_e32 v18, -8, v18
	v_add_u32_e32 v18, s55, v18
	v_ashrrev_i32_e32 v19, 31, v18
	v_lshlrev_b64 v[18:19], 11, v[18:19]
	v_and_or_b32 v18, v20, s60, v18
	v_med3_f32 v20, v14, s61, v150
	v_max_f32_e32 v14, v15, v15
	v_med3_f32 v15, v14, s61, v150
	v_mov_b32_e32 v14, 0
	v_cvt_pk_fp8_f32 v14, v20, v15
	v_max_f32_e32 v15, v16, v16
	v_max_f32_e32 v16, v17, v17
	v_med3_f32 v15, v15, s61, v150
	v_med3_f32 v16, v16, s61, v150
	v_max_f32_e32 v10, v10, v10
	v_max_f32_e32 v11, v11, v11
	v_cvt_pk_fp8_f32 v14, v15, v16 op_sel:[0,0,1]
	v_med3_f32 v10, v10, s61, v150
	v_med3_f32 v11, v11, s61, v150
	v_mov_b32_e32 v15, 0
	v_cvt_pk_fp8_f32 v15, v10, v11
	v_max_f32_e32 v10, v12, v12
	v_max_f32_e32 v11, v13, v13
	v_med3_f32 v10, v10, s61, v150
	v_med3_f32 v11, v11, s61, v150
	v_cvt_pk_fp8_f32 v15, v10, v11 op_sel:[0,0,1]
	v_mad_u64_u32 v[10:11], s[0:1], v18, s51, v[122:123]
	v_cvt_pk_bf16_f32 v6, v6, v7
	v_cvt_pk_bf16_f32 v7, v8, v9
	v_cvt_pk_bf16_f32 v8, v2, v3
	v_lshlrev_b64 v[2:3], 8, v[18:19]
	v_mad_i32_i24 v11, v19, s51, v11
	v_lshl_add_u64 v[2:3], s[14:15], 0, v[2:3]
	v_readlane_b32 s72, v254, 2
	v_lshl_add_u64 v[10:11], v[10:11], 0, v[142:143]
	v_cvt_pk_bf16_f32 v9, v4, v5
	v_lshl_add_u64 v[2:3], v[2:3], 0, v[114:115]
	s_and_b64 vcc, exec, s[10:11]
	s_mov_b32 s55, s18
	s_mov_b32 s26, s20
	s_mov_b64 s[28:29], s[24:25]
	s_mov_b64 s[30:31], s[22:23]
	v_readlane_b32 s73, v254, 3
	global_store_dwordx2 v[10:11], v[14:15], off
	global_store_dwordx4 v[2:3], v[6:9], off
	s_cbranch_vccz .LBB0_2337
	s_waitcnt vmcnt(0)
	s_cmpk_gt_u32 s5, 0xff
	s_cbranch_scc1 .LBB0_2348
	s_barrier

.LBB0_2749:
	s_add_u32 s10, s34, 0x100
	s_addc_u32 s11, s35, 0
	s_add_u32 s30, s29, s34
	s_addc_u32 s31, s55, s35
	s_cmpk_eq_i32 s34, 0x300
	s_cselect_b64 vcc, -1, 0
	s_and_b64 s[0:1], vcc, exec
	s_cselect_b32 s1, 0, s10
	s_cselect_b32 s0, 0, s11
	s_cselect_b32 s30, s27, s30
	s_cselect_b32 s31, s25, s31
	s_add_u32 s36, s14, s1
	s_addc_u32 s37, s15, s0
	s_add_i32 s1, 0, 0x10000
	v_add_u32_e32 v14, s1, v196
	ds_read_b128 v[2:5], v14
	ds_read_b128 v[6:9], v14 offset:1024
	ds_read_b128 v[10:13], v14 offset:2048
	ds_read_b128 v[14:17], v14 offset:3072
	v_cndmask_b32_e32 v162, v168, v171, vcc
	v_cndmask_b32_e32 v184, v170, v197, vcc
	v_cndmask_b32_e32 v175, v172, v198, vcc
	v_cndmask_b32_e32 v173, v174, v199, vcc
	v_lshl_add_u64 v[18:19], v[178:179], 0, s[34:35]
	s_add_i32 m0, s45, 0xc000
	ds_read_b128 v[200:203], v169
	ds_read_b128 v[204:207], v169 offset:1024
	ds_read_b128 v[208:211], v169 offset:2048
	ds_read_b128 v[212:215], v169 offset:3072
	ds_read_b128 v[216:219], v169 offset:4096
	ds_read_b128 v[220:223], v169 offset:5120
	ds_read_b128 v[224:227], v169 offset:6144
	ds_read_b128 v[228:231], v169 offset:7168
	global_load_lds_dwordx4 v[18:19], off nt
	v_lshl_add_u64 v[18:19], v[176:177], 0, s[34:35]
	s_add_i32 m0, s45, 0xe000
	s_nop 0
	global_load_lds_dwordx4 v[18:19], off nt
	s_waitcnt lgkmcnt(8)
	s_waitcnt vmcnt(10)
	s_barrier
	s_waitcnt lgkmcnt(0)
	s_waitcnt lgkmcnt(0)
	v_mfma_scale_f32_16x16x128_f8f6f4 v[158:161], v[2:9], v[200:207], v[158:161], v1, v1 op_sel_hi:[0,0,0]
	v_mfma_scale_f32_16x16x128_f8f6f4 v[150:153], v[10:17], v[200:207], v[150:153], v1, v1 op_sel_hi:[0,0,0]
	v_mfma_scale_f32_16x16x128_f8f6f4 v[142:145], v[2:9], v[208:215], v[142:145], v1, v1 op_sel_hi:[0,0,0]
	v_mfma_scale_f32_16x16x128_f8f6f4 v[134:137], v[10:17], v[208:215], v[134:137], v1, v1 op_sel_hi:[0,0,0]
	v_mfma_scale_f32_16x16x128_f8f6f4 v[126:129], v[2:9], v[216:223], v[126:129], v1, v1 op_sel_hi:[0,0,0]
	v_mfma_scale_f32_16x16x128_f8f6f4 v[118:121], v[10:17], v[216:223], v[118:121], v1, v1 op_sel_hi:[0,0,0]
	v_mfma_scale_f32_16x16x128_f8f6f4 v[110:113], v[2:9], v[224:231], v[110:113], v1, v1 op_sel_hi:[0,0,0]
	v_mfma_scale_f32_16x16x128_f8f6f4 v[102:105], v[10:17], v[224:231], v[102:105], v1, v1 op_sel_hi:[0,0,0]
	s_barrier
	s_add_i32 s0, 0, 0x14000
	s_add_i32 s1, s1, s43
	v_add_u32_e32 v30, s0, v196
	v_lshl_add_u64 v[180:181], s[30:31], 0, v[164:165]
	s_mov_b32 m0, s1
	ds_read_b128 v[18:21], v30
	ds_read_b128 v[22:25], v30 offset:1024
	ds_read_b128 v[26:29], v30 offset:2048
	ds_read_b128 v[30:33], v30 offset:3072
	global_load_lds_dwordx4 v[180:181], off
	v_lshl_add_u64 v[182:183], s[30:31], 0, v[166:167]
	s_add_i32 m0, s1, 0x2000
	s_nop 0
	global_load_lds_dwordx4 v[182:183], off
	s_waitcnt vmcnt(10)
	s_barrier
	s_waitcnt lgkmcnt(0)
	s_waitcnt lgkmcnt(0)
	v_mfma_scale_f32_16x16x128_f8f6f4 v[154:157], v[18:25], v[200:207], v[154:157], v1, v1 op_sel_hi:[0,0,0]
	v_mfma_scale_f32_16x16x128_f8f6f4 v[146:149], v[26:33], v[200:207], v[146:149], v1, v1 op_sel_hi:[0,0,0]
	v_mfma_scale_f32_16x16x128_f8f6f4 v[138:141], v[18:25], v[208:215], v[138:141], v1, v1 op_sel_hi:[0,0,0]
	v_mfma_scale_f32_16x16x128_f8f6f4 v[130:133], v[26:33], v[208:215], v[130:133], v1, v1 op_sel_hi:[0,0,0]
	v_mfma_scale_f32_16x16x128_f8f6f4 v[122:125], v[18:25], v[216:223], v[122:125], v1, v1 op_sel_hi:[0,0,0]
	v_mfma_scale_f32_16x16x128_f8f6f4 v[114:117], v[26:33], v[216:223], v[114:117], v1, v1 op_sel_hi:[0,0,0]
	v_mfma_scale_f32_16x16x128_f8f6f4 v[106:109], v[18:25], v[224:231], v[106:109], v1, v1 op_sel_hi:[0,0,0]
	v_mfma_scale_f32_16x16x128_f8f6f4 v[98:101], v[26:33], v[224:231], v[98:101], v1, v1 op_sel_hi:[0,0,0]
	s_mov_b32 m0, s45
	s_barrier
	ds_read_b128 v[200:203], v169 offset:16384
	ds_read_b128 v[204:207], v169 offset:17408
	ds_read_b128 v[208:211], v169 offset:18432
	ds_read_b128 v[212:215], v169 offset:19456
	ds_read_b128 v[216:219], v169 offset:20480
	ds_read_b128 v[220:223], v169 offset:21504
	ds_read_b128 v[224:227], v169 offset:22528
	ds_read_b128 v[228:231], v169 offset:23552
	global_load_lds_dwordx4 v162, s[36:37] nt
	s_mov_b32 m0, s46
	v_mov_b32_e32 v185, v163
	global_load_lds_dwordx4 v184, s[36:37] nt
	s_waitcnt vmcnt(10)
	s_barrier
	s_waitcnt lgkmcnt(0)
	v_lshl_add_u64 v[186:187], s[36:37], 0, v[162:163]
	v_lshl_add_u64 v[184:185], s[36:37], 0, v[184:185]
	s_waitcnt lgkmcnt(0)
	v_mfma_scale_f32_16x16x128_f8f6f4 v[94:97], v[2:9], v[200:207], v[94:97], v1, v1 op_sel_hi:[0,0,0]
	v_mfma_scale_f32_16x16x128_f8f6f4 v[86:89], v[10:17], v[200:207], v[86:89], v1, v1 op_sel_hi:[0,0,0]
	v_mfma_scale_f32_16x16x128_f8f6f4 v[78:81], v[2:9], v[208:215], v[78:81], v1, v1 op_sel_hi:[0,0,0]
	v_mfma_scale_f32_16x16x128_f8f6f4 v[70:73], v[10:17], v[208:215], v[70:73], v1, v1 op_sel_hi:[0,0,0]
	v_mfma_scale_f32_16x16x128_f8f6f4 v[62:65], v[2:9], v[216:223], v[62:65], v1, v1 op_sel_hi:[0,0,0]
	v_mfma_scale_f32_16x16x128_f8f6f4 v[54:57], v[10:17], v[216:223], v[54:57], v1, v1 op_sel_hi:[0,0,0]
	v_mfma_scale_f32_16x16x128_f8f6f4 v[46:49], v[2:9], v[224:231], v[46:49], v1, v1 op_sel_hi:[0,0,0]
	v_mfma_scale_f32_16x16x128_f8f6f4 v[38:41], v[10:17], v[224:231], v[38:41], v1, v1 op_sel_hi:[0,0,0]
	s_barrier
	s_add_u32 s34, s30, 0x20000
	s_addc_u32 s35, s31, 0
	s_add_i32 s0, s0, s43
	v_lshl_add_u64 v[2:3], s[34:35], 0, v[164:165]
	s_mov_b32 m0, s0
	s_nop 0
	global_load_lds_dwordx4 v[2:3], off
	v_lshl_add_u64 v[2:3], s[34:35], 0, v[166:167]
	s_add_i32 m0, s0, 0x2000
	s_nop 0
	global_load_lds_dwordx4 v[2:3], off
	s_waitcnt vmcnt(10)
	s_barrier
	v_mfma_scale_f32_16x16x128_f8f6f4 v[90:93], v[18:25], v[200:207], v[90:93], v1, v1 op_sel_hi:[0,0,0]
	v_mfma_scale_f32_16x16x128_f8f6f4 v[82:85], v[26:33], v[200:207], v[82:85], v1, v1 op_sel_hi:[0,0,0]
	v_mfma_scale_f32_16x16x128_f8f6f4 v[74:77], v[18:25], v[208:215], v[74:77], v1, v1 op_sel_hi:[0,0,0]
	v_mfma_scale_f32_16x16x128_f8f6f4 v[66:69], v[26:33], v[208:215], v[66:69], v1, v1 op_sel_hi:[0,0,0]
	v_mfma_scale_f32_16x16x128_f8f6f4 v[58:61], v[18:25], v[216:223], v[58:61], v1, v1 op_sel_hi:[0,0,0]
	v_mfma_scale_f32_16x16x128_f8f6f4 v[50:53], v[26:33], v[216:223], v[50:53], v1, v1 op_sel_hi:[0,0,0]
	v_mfma_scale_f32_16x16x128_f8f6f4 v[42:45], v[18:25], v[224:231], v[42:45], v1, v1 op_sel_hi:[0,0,0]
	v_mfma_scale_f32_16x16x128_f8f6f4 v[34:37], v[26:33], v[224:231], v[34:37], v1, v1 op_sel_hi:[0,0,0]
	s_add_i32 s0, 0, 0x18000
	v_add_u32_e32 v14, s0, v196
	s_barrier
	ds_read_b128 v[2:5], v14
	ds_read_b128 v[6:9], v14 offset:1024
	ds_read_b128 v[10:13], v14 offset:2048
	ds_read_b128 v[14:17], v14 offset:3072
	s_mov_b32 m0, s47
	ds_read_b128 v[18:21], v169 offset:32768
	ds_read_b128 v[22:25], v169 offset:33792
	ds_read_b128 v[26:29], v169 offset:34816
	ds_read_b128 v[30:33], v169 offset:35840
	ds_read_b128 v[200:203], v169 offset:36864
	ds_read_b128 v[204:207], v169 offset:37888
	ds_read_b128 v[208:211], v169 offset:38912
	ds_read_b128 v[212:215], v169 offset:39936
	global_load_lds_dwordx4 v175, s[36:37] nt
	s_mov_b32 m0, s48
	s_nop 0
	global_load_lds_dwordx4 v173, s[36:37] nt
	s_waitcnt lgkmcnt(8)
	s_waitcnt vmcnt(10)
	s_barrier
	s_waitcnt lgkmcnt(0)
	s_waitcnt lgkmcnt(0)
	v_mfma_scale_f32_16x16x128_f8f6f4 v[158:161], v[2:9], v[18:25], v[158:161], v1, v1 op_sel_hi:[0,0,0]
	v_mfma_scale_f32_16x16x128_f8f6f4 v[150:153], v[10:17], v[18:25], v[150:153], v1, v1 op_sel_hi:[0,0,0]
	v_mfma_scale_f32_16x16x128_f8f6f4 v[142:145], v[2:9], v[26:33], v[142:145], v1, v1 op_sel_hi:[0,0,0]
	v_mfma_scale_f32_16x16x128_f8f6f4 v[134:137], v[10:17], v[26:33], v[134:137], v1, v1 op_sel_hi:[0,0,0]
	v_mfma_scale_f32_16x16x128_f8f6f4 v[126:129], v[2:9], v[200:207], v[126:129], v1, v1 op_sel_hi:[0,0,0]
	v_mfma_scale_f32_16x16x128_f8f6f4 v[118:121], v[10:17], v[200:207], v[118:121], v1, v1 op_sel_hi:[0,0,0]
	v_mfma_scale_f32_16x16x128_f8f6f4 v[110:113], v[2:9], v[208:215], v[110:113], v1, v1 op_sel_hi:[0,0,0]
	v_mfma_scale_f32_16x16x128_f8f6f4 v[102:105], v[10:17], v[208:215], v[102:105], v1, v1 op_sel_hi:[0,0,0]
	s_barrier
	s_add_i32 s34, 0, 0x1c000
	s_add_i32 s0, s0, s43
	v_add_u32_e32 v162, s34, v196
	v_lshl_add_u64 v[180:181], v[180:181], 0, s[20:21]
	s_mov_b32 m0, s0
	ds_read_b128 v[216:219], v162
	ds_read_b128 v[220:223], v162 offset:1024
	ds_read_b128 v[224:227], v162 offset:2048
	ds_read_b128 v[228:231], v162 offset:3072
	global_load_lds_dwordx4 v[180:181], off
	v_lshl_add_u64 v[180:181], v[182:183], 0, s[20:21]
	s_add_i32 m0, s0, 0x2000
	s_nop 0
	global_load_lds_dwordx4 v[180:181], off
	s_waitcnt vmcnt(10)
	s_barrier
	s_waitcnt lgkmcnt(0)
	s_waitcnt lgkmcnt(0)
	v_mfma_scale_f32_16x16x128_f8f6f4 v[154:157], v[216:223], v[18:25], v[154:157], v1, v1 op_sel_hi:[0,0,0]
	v_mfma_scale_f32_16x16x128_f8f6f4 v[146:149], v[224:231], v[18:25], v[146:149], v1, v1 op_sel_hi:[0,0,0]
	v_mfma_scale_f32_16x16x128_f8f6f4 v[138:141], v[216:223], v[26:33], v[138:141], v1, v1 op_sel_hi:[0,0,0]
	v_mfma_scale_f32_16x16x128_f8f6f4 v[130:133], v[224:231], v[26:33], v[130:133], v1, v1 op_sel_hi:[0,0,0]
	v_mfma_scale_f32_16x16x128_f8f6f4 v[122:125], v[216:223], v[200:207], v[122:125], v1, v1 op_sel_hi:[0,0,0]
	v_mfma_scale_f32_16x16x128_f8f6f4 v[114:117], v[224:231], v[200:207], v[114:117], v1, v1 op_sel_hi:[0,0,0]
	v_mfma_scale_f32_16x16x128_f8f6f4 v[106:109], v[216:223], v[208:215], v[106:109], v1, v1 op_sel_hi:[0,0,0]
	v_mfma_scale_f32_16x16x128_f8f6f4 v[98:101], v[224:231], v[208:215], v[98:101], v1, v1 op_sel_hi:[0,0,0]
	s_mov_b32 m0, s51
	v_lshl_add_u64 v[180:181], v[186:187], 0, s[20:21]
	s_barrier
	ds_read_b128 v[18:21], v169 offset:49152
	ds_read_b128 v[22:25], v169 offset:50176
	ds_read_b128 v[26:29], v169 offset:51200
	ds_read_b128 v[30:33], v169 offset:52224
	ds_read_b128 v[200:203], v169 offset:53248
	ds_read_b128 v[204:207], v169 offset:54272
	ds_read_b128 v[208:211], v169 offset:55296
	ds_read_b128 v[212:215], v169 offset:56320
	global_load_lds_dwordx4 v[180:181], off nt
	v_lshl_add_u64 v[180:181], v[184:185], 0, s[20:21]
	s_mov_b32 m0, s52
	s_nop 0
	global_load_lds_dwordx4 v[180:181], off nt
	s_waitcnt vmcnt(10)
	s_barrier
	s_waitcnt lgkmcnt(0)
	s_waitcnt lgkmcnt(0)
	v_mfma_scale_f32_16x16x128_f8f6f4 v[94:97], v[2:9], v[18:25], v[94:97], v1, v1 op_sel_hi:[0,0,0]
	v_mfma_scale_f32_16x16x128_f8f6f4 v[86:89], v[10:17], v[18:25], v[86:89], v1, v1 op_sel_hi:[0,0,0]
	v_mfma_scale_f32_16x16x128_f8f6f4 v[78:81], v[2:9], v[26:33], v[78:81], v1, v1 op_sel_hi:[0,0,0]
	v_mfma_scale_f32_16x16x128_f8f6f4 v[70:73], v[10:17], v[26:33], v[70:73], v1, v1 op_sel_hi:[0,0,0]
	v_mfma_scale_f32_16x16x128_f8f6f4 v[62:65], v[2:9], v[200:207], v[62:65], v1, v1 op_sel_hi:[0,0,0]
	v_mfma_scale_f32_16x16x128_f8f6f4 v[54:57], v[10:17], v[200:207], v[54:57], v1, v1 op_sel_hi:[0,0,0]
	v_mfma_scale_f32_16x16x128_f8f6f4 v[46:49], v[2:9], v[208:215], v[46:49], v1, v1 op_sel_hi:[0,0,0]
	v_mfma_scale_f32_16x16x128_f8f6f4 v[38:41], v[10:17], v[208:215], v[38:41], v1, v1 op_sel_hi:[0,0,0]
	s_barrier
	s_add_u32 s0, s30, 0x20080
	s_addc_u32 s1, s31, 0
	s_add_i32 s30, s34, s43
	v_lshl_add_u64 v[2:3], s[0:1], 0, v[164:165]
	s_mov_b32 m0, s30
	s_nop 0
	global_load_lds_dwordx4 v[2:3], off
	v_lshl_add_u64 v[2:3], s[0:1], 0, v[166:167]
	s_add_i32 m0, s30, 0x2000
	s_nop 0
	global_load_lds_dwordx4 v[2:3], off
	s_waitcnt vmcnt(10)
	s_barrier
	v_mfma_scale_f32_16x16x128_f8f6f4 v[90:93], v[216:223], v[18:25], v[90:93], v1, v1 op_sel_hi:[0,0,0]
	v_mfma_scale_f32_16x16x128_f8f6f4 v[82:85], v[224:231], v[18:25], v[82:85], v1, v1 op_sel_hi:[0,0,0]
	v_mfma_scale_f32_16x16x128_f8f6f4 v[74:77], v[216:223], v[26:33], v[74:77], v1, v1 op_sel_hi:[0,0,0]
	v_mfma_scale_f32_16x16x128_f8f6f4 v[66:69], v[224:231], v[26:33], v[66:69], v1, v1 op_sel_hi:[0,0,0]
	v_mfma_scale_f32_16x16x128_f8f6f4 v[58:61], v[216:223], v[200:207], v[58:61], v1, v1 op_sel_hi:[0,0,0]
	v_mfma_scale_f32_16x16x128_f8f6f4 v[50:53], v[224:231], v[200:207], v[50:53], v1, v1 op_sel_hi:[0,0,0]
	v_mfma_scale_f32_16x16x128_f8f6f4 v[42:45], v[216:223], v[208:215], v[42:45], v1, v1 op_sel_hi:[0,0,0]
	v_mfma_scale_f32_16x16x128_f8f6f4 v[34:37], v[224:231], v[208:215], v[34:37], v1, v1 op_sel_hi:[0,0,0]
	s_add_i32 s56, s56, 2
	s_cmp_gt_u32 s56, 5
	s_mov_b64 s[34:35], s[10:11]
	s_barrier
	s_cbranch_scc0 .LBB0_2749
	v_mul_f32_e32 v5, 0x3c800000, v158
	v_mul_f32_e32 v6, 0xbfb8aa3b, v5
	v_exp_f32_e32 v6, v6
	s_ashr_i32 s29, s28, 31
	s_ashr_i32 s27, s26, 31
	s_lshl_b64 s[10:11], s[28:29], 18
	v_add_f32_e32 v6, 1.0, v6
	v_rcp_f32_e32 v6, v6
	s_lshl_b64 s[26:27], s[26:27], 15
	v_mov_b32_e32 v3, v194
	s_add_u32 s0, s8, s10
	v_mul_f32_e32 v5, v5, v6
	v_mul_f32_e32 v6, 0x3c800000, v159
	v_mul_f32_e32 v7, 0xbfb8aa3b, v6
	v_exp_f32_e32 v7, v7
	v_mul_f32_e32 v5, v5, v154
	v_mul_f32_e32 v5, 0x3e000000, v5
	v_med3_f32 v5, v5, s40, v189
	v_add_f32_e32 v7, 1.0, v7
	v_rcp_f32_e32 v7, v7
	s_nop 15
	s_nop 15
	v_mov_b32_e32 v2, v195
	v_mul_f32_e32 v6, v6, v7
	v_mul_f32_e32 v7, 0x3c800000, v160
	v_mul_f32_e32 v8, 0xbfb8aa3b, v7
	v_exp_f32_e32 v8, v8
	v_mul_f32_e32 v6, v6, v155
	v_mul_f32_e32 v6, 0x3e000000, v6
	v_add_u32_e32 v4, s49, v3
	v_add_f32_e32 v8, 1.0, v8
	v_rcp_f32_e32 v8, v8
	s_addc_u32 s1, s9, s11
	s_add_u32 s10, s0, s26
	v_mul_f32_e32 v7, v7, v8
	v_mul_f32_e32 v8, 0x3c800000, v161
	v_mul_f32_e32 v9, 0xbfb8aa3b, v8
	v_exp_f32_e32 v9, v9
	v_mul_f32_e32 v7, v7, v156
	v_mul_f32_e32 v7, 0x3e000000, v7
	v_lshl_add_u32 v2, v2, 3, s50
	v_add_f32_e32 v9, 1.0, v9
	v_rcp_f32_e32 v9, v9
	s_addc_u32 s11, s1, s27
	v_ashrrev_i32_e32 v3, 31, v2
	s_and_b64 vcc, exec, s[6:7]
	v_mul_f32_e32 v8, v8, v9
	v_mul_f32_e32 v9, 0x3c800000, v150
	v_mul_f32_e32 v10, 0xbfb8aa3b, v9
	v_exp_f32_e32 v10, v10
	v_mul_f32_e32 v8, v8, v157
	v_mul_f32_e32 v8, 0x3e000000, v8
	v_mov_b32_e32 v174, v199
	v_add_f32_e32 v10, 1.0, v10
	v_rcp_f32_e32 v10, v10
	v_mov_b32_e32 v172, v198
	v_mov_b32_e32 v170, v197
	v_mov_b32_e32 v168, v171
	v_mul_f32_e32 v9, v9, v10
	v_mul_f32_e32 v10, 0x3c800000, v151
	v_mul_f32_e32 v11, 0xbfb8aa3b, v10
	v_exp_f32_e32 v11, v11
	v_mul_f32_e32 v9, v9, v146
	v_mul_f32_e32 v9, 0x3e000000, v9
	s_mov_b32 s26, s24
	v_add_f32_e32 v11, 1.0, v11
	v_rcp_f32_e32 v11, v11
	s_mov_b32 s28, s54
	s_mov_b64 s[30:31], s[12:13]
	v_mul_f32_e32 v10, v10, v11
	v_mul_f32_e32 v11, 0x3c800000, v152
	v_mul_f32_e32 v12, 0xbfb8aa3b, v11
	v_exp_f32_e32 v12, v12
	v_mul_f32_e32 v10, v10, v147
	v_mul_f32_e32 v10, 0x3e000000, v10
	v_add_f32_e32 v12, 1.0, v12
	v_rcp_f32_e32 v12, v12
	s_nop 0
	v_mul_f32_e32 v11, v11, v12
	v_mul_f32_e32 v12, 0x3c800000, v153
	v_mul_f32_e32 v13, 0xbfb8aa3b, v12
	v_exp_f32_e32 v13, v13
	v_mul_f32_e32 v11, v11, v148
	v_mul_f32_e32 v11, 0x3e000000, v11
	v_add_f32_e32 v13, 1.0, v13
	v_rcp_f32_e32 v13, v13
	s_nop 0
	v_mul_f32_e32 v12, v12, v13
	v_med3_f32 v13, v6, s40, v189
	v_mov_b32_e32 v6, v163
	v_cvt_pk_fp8_f32 v6, v5, v13
	v_med3_f32 v5, v7, s40, v189
	v_med3_f32 v7, v8, s40, v189
	v_med3_f32 v8, v10, s40, v189
	v_cvt_pk_fp8_f32 v6, v5, v7 op_sel:[0,0,1]
	v_med3_f32 v5, v9, s40, v189
	v_mov_b32_e32 v7, v163
	v_cvt_pk_fp8_f32 v7, v5, v8
	v_mul_f32_e32 v12, v12, v149
	v_mul_f32_e32 v12, 0x3e000000, v12
	v_med3_f32 v5, v11, s40, v189
	v_med3_f32 v8, v12, s40, v189
	v_cvt_pk_fp8_f32 v7, v5, v8 op_sel:[0,0,1]
	v_ashrrev_i32_e32 v5, 31, v4
	v_lshlrev_b64 v[8:9], 7, v[4:5]
	v_lshl_add_u64 v[8:9], s[10:11], 0, v[8:9]
	v_lshl_add_u64 v[8:9], v[8:9], 0, v[2:3]
	v_mul_f32_e32 v5, 0x3c800000, v142
	global_store_dwordx2 v[8:9], v[6:7], off
	v_mul_f32_e32 v6, 0xbfb8aa3b, v5
	v_exp_f32_e32 v6, v6
	s_nop 0
	v_add_f32_e32 v6, 1.0, v6
	v_rcp_f32_e32 v6, v6
	s_nop 0
	v_mul_f32_e32 v5, v5, v6
	v_mul_f32_e32 v6, 0x3c800000, v143
	v_mul_f32_e32 v7, 0xbfb8aa3b, v6
	v_exp_f32_e32 v7, v7
	v_mul_f32_e32 v5, v5, v138
	v_mul_f32_e32 v5, 0x3e000000, v5
	v_med3_f32 v5, v5, s40, v189
	v_add_f32_e32 v7, 1.0, v7
	v_rcp_f32_e32 v7, v7
	s_nop 0
	v_mul_f32_e32 v6, v6, v7
	v_mul_f32_e32 v6, v6, v139
	v_mul_f32_e32 v7, 0x3e000000, v6
	v_mul_f32_e32 v6, 0x3c800000, v144
	v_mul_f32_e32 v8, 0xbfb8aa3b, v6
	v_exp_f32_e32 v8, v8
	v_med3_f32 v7, v7, s40, v189
	v_add_f32_e32 v8, 1.0, v8
	v_rcp_f32_e32 v8, v8
	s_nop 0
	v_mul_f32_e32 v6, v6, v8
	v_mul_f32_e32 v6, v6, v140
	v_mul_f32_e32 v9, 0x3e000000, v6
	v_mul_f32_e32 v6, 0x3c800000, v145
	v_mul_f32_e32 v8, 0xbfb8aa3b, v6
	v_exp_f32_e32 v8, v8
	s_nop 0
	v_add_f32_e32 v8, 1.0, v8
	v_rcp_f32_e32 v8, v8
	s_nop 0
	v_mul_f32_e32 v6, v6, v8
	v_mul_f32_e32 v6, v6, v141
	v_mul_f32_e32 v10, 0x3e000000, v6
	v_mul_f32_e32 v6, 0x3c800000, v134
	v_mul_f32_e32 v8, 0xbfb8aa3b, v6
	v_exp_f32_e32 v8, v8
	s_nop 0
	v_add_f32_e32 v8, 1.0, v8
	v_rcp_f32_e32 v8, v8
	s_nop 0
	v_mul_f32_e32 v6, v6, v8
	v_mul_f32_e32 v6, v6, v130
	v_mul_f32_e32 v11, 0x3e000000, v6
	v_mul_f32_e32 v6, 0x3c800000, v135
	v_mul_f32_e32 v8, 0xbfb8aa3b, v6
	v_exp_f32_e32 v8, v8
	s_nop 0
	v_add_f32_e32 v8, 1.0, v8
	v_rcp_f32_e32 v8, v8
	s_nop 0
	v_mul_f32_e32 v6, v6, v8
	v_mul_f32_e32 v6, v6, v131
	v_mul_f32_e32 v12, 0x3e000000, v6
	v_mul_f32_e32 v6, 0x3c800000, v136
	v_mul_f32_e32 v8, 0xbfb8aa3b, v6
	v_exp_f32_e32 v8, v8
	s_nop 0
	v_add_f32_e32 v8, 1.0, v8
	v_rcp_f32_e32 v8, v8
	s_nop 0
	v_mul_f32_e32 v6, v6, v8
	v_mul_f32_e32 v6, v6, v132
	v_mul_f32_e32 v13, 0x3e000000, v6
	v_mul_f32_e32 v6, 0x3c800000, v137
	v_mul_f32_e32 v8, 0xbfb8aa3b, v6
	v_exp_f32_e32 v8, v8
	s_nop 0
	v_add_f32_e32 v8, 1.0, v8
	v_rcp_f32_e32 v8, v8
	s_nop 0
	v_mul_f32_e32 v6, v6, v8
	v_mov_b32_e32 v8, v163
	v_cvt_pk_fp8_f32 v8, v5, v7
	v_med3_f32 v5, v9, s40, v189
	v_med3_f32 v7, v10, s40, v189
	v_mov_b32_e32 v9, v163
	v_cvt_pk_fp8_f32 v8, v5, v7 op_sel:[0,0,1]
	v_med3_f32 v5, v11, s40, v189
	v_med3_f32 v7, v12, s40, v189
	v_cvt_pk_fp8_f32 v9, v5, v7
	v_mul_f32_e32 v6, v6, v133
	v_mul_f32_e32 v14, 0x3e000000, v6
	v_add_u32_e32 v6, 16, v4
	v_med3_f32 v5, v13, s40, v189
	v_med3_f32 v7, v14, s40, v189
	v_cvt_pk_fp8_f32 v9, v5, v7 op_sel:[0,0,1]
	v_ashrrev_i32_e32 v7, 31, v6
	v_lshlrev_b64 v[6:7], 7, v[6:7]
	v_lshl_add_u64 v[6:7], s[10:11], 0, v[6:7]
	v_lshl_add_u64 v[6:7], v[6:7], 0, v[2:3]
	v_mul_f32_e32 v5, 0x3c800000, v126
	global_store_dwordx2 v[6:7], v[8:9], off
	v_mul_f32_e32 v6, 0xbfb8aa3b, v5
	v_exp_f32_e32 v6, v6
	s_nop 0
	v_add_f32_e32 v6, 1.0, v6
	v_rcp_f32_e32 v6, v6
	s_nop 0
	v_mul_f32_e32 v5, v5, v6
	v_mul_f32_e32 v6, 0x3c800000, v127
	v_mul_f32_e32 v7, 0xbfb8aa3b, v6
	v_exp_f32_e32 v7, v7
	v_mul_f32_e32 v5, v5, v122
	v_mul_f32_e32 v5, 0x3e000000, v5
	v_med3_f32 v5, v5, s40, v189
	v_add_f32_e32 v7, 1.0, v7
	v_rcp_f32_e32 v7, v7
	s_nop 0
	v_mul_f32_e32 v6, v6, v7
	v_mul_f32_e32 v6, v6, v123
	v_mul_f32_e32 v7, 0x3e000000, v6
	v_mul_f32_e32 v6, 0x3c800000, v128
	v_mul_f32_e32 v8, 0xbfb8aa3b, v6
	v_exp_f32_e32 v8, v8
	v_med3_f32 v7, v7, s40, v189
	v_add_f32_e32 v8, 1.0, v8
	v_rcp_f32_e32 v8, v8
	s_nop 0
	v_mul_f32_e32 v6, v6, v8
	v_mul_f32_e32 v6, v6, v124
	v_mul_f32_e32 v9, 0x3e000000, v6
	v_mul_f32_e32 v6, 0x3c800000, v129
	v_mul_f32_e32 v8, 0xbfb8aa3b, v6
	v_exp_f32_e32 v8, v8
	s_nop 0
	v_add_f32_e32 v8, 1.0, v8
	v_rcp_f32_e32 v8, v8
	s_nop 0
	v_mul_f32_e32 v6, v6, v8
	v_mul_f32_e32 v6, v6, v125
	v_mul_f32_e32 v10, 0x3e000000, v6
	v_mul_f32_e32 v6, 0x3c800000, v118
	v_mul_f32_e32 v8, 0xbfb8aa3b, v6
	v_exp_f32_e32 v8, v8
	s_nop 0
	v_add_f32_e32 v8, 1.0, v8
	v_rcp_f32_e32 v8, v8
	s_nop 0
	v_mul_f32_e32 v6, v6, v8
	v_mul_f32_e32 v6, v6, v114
	v_mul_f32_e32 v11, 0x3e000000, v6
	v_mul_f32_e32 v6, 0x3c800000, v119
	v_mul_f32_e32 v8, 0xbfb8aa3b, v6
	v_exp_f32_e32 v8, v8
	s_nop 0
	v_add_f32_e32 v8, 1.0, v8
	v_rcp_f32_e32 v8, v8
	s_nop 0
	v_mul_f32_e32 v6, v6, v8
	v_mul_f32_e32 v6, v6, v115
	v_mul_f32_e32 v12, 0x3e000000, v6
	v_mul_f32_e32 v6, 0x3c800000, v120
	v_mul_f32_e32 v8, 0xbfb8aa3b, v6
	v_exp_f32_e32 v8, v8
	s_nop 0
	v_add_f32_e32 v8, 1.0, v8
	v_rcp_f32_e32 v8, v8
	s_nop 0
	v_mul_f32_e32 v6, v6, v8
	v_mul_f32_e32 v6, v6, v116
	v_mul_f32_e32 v13, 0x3e000000, v6
	v_mul_f32_e32 v6, 0x3c800000, v121
	v_mul_f32_e32 v8, 0xbfb8aa3b, v6
	v_exp_f32_e32 v8, v8
	s_nop 0
	v_add_f32_e32 v8, 1.0, v8
	v_rcp_f32_e32 v8, v8
	s_nop 0
	v_mul_f32_e32 v6, v6, v8
	v_mov_b32_e32 v8, v163
	v_cvt_pk_fp8_f32 v8, v5, v7
	v_med3_f32 v5, v9, s40, v189
	v_med3_f32 v7, v10, s40, v189
	v_mov_b32_e32 v9, v163
	v_cvt_pk_fp8_f32 v8, v5, v7 op_sel:[0,0,1]
	v_med3_f32 v5, v11, s40, v189
	v_med3_f32 v7, v12, s40, v189
	v_cvt_pk_fp8_f32 v9, v5, v7
	v_mul_f32_e32 v6, v6, v117
	v_mul_f32_e32 v14, 0x3e000000, v6
	v_add_u32_e32 v6, 32, v4
	v_med3_f32 v5, v13, s40, v189
	v_med3_f32 v7, v14, s40, v189
	v_cvt_pk_fp8_f32 v9, v5, v7 op_sel:[0,0,1]
	v_ashrrev_i32_e32 v7, 31, v6
	v_lshlrev_b64 v[6:7], 7, v[6:7]
	v_lshl_add_u64 v[6:7], s[10:11], 0, v[6:7]
	v_lshl_add_u64 v[6:7], v[6:7], 0, v[2:3]
	v_mul_f32_e32 v5, 0x3c800000, v110
	global_store_dwordx2 v[6:7], v[8:9], off
	v_mul_f32_e32 v6, 0xbfb8aa3b, v5
	v_exp_f32_e32 v6, v6
	s_nop 0
	v_add_f32_e32 v6, 1.0, v6
	v_rcp_f32_e32 v6, v6
	s_nop 0
	v_mul_f32_e32 v5, v5, v6
	v_mul_f32_e32 v6, 0x3c800000, v111
	v_mul_f32_e32 v7, 0xbfb8aa3b, v6
	v_exp_f32_e32 v7, v7
	v_mul_f32_e32 v5, v5, v106
	v_mul_f32_e32 v5, 0x3e000000, v5
	v_med3_f32 v5, v5, s40, v189
	v_add_f32_e32 v7, 1.0, v7
	v_rcp_f32_e32 v7, v7
	s_nop 0
	v_mul_f32_e32 v6, v6, v7
	v_mul_f32_e32 v6, v6, v107
	v_mul_f32_e32 v7, 0x3e000000, v6
	v_mul_f32_e32 v6, 0x3c800000, v112
	v_mul_f32_e32 v8, 0xbfb8aa3b, v6
	v_exp_f32_e32 v8, v8
	v_med3_f32 v7, v7, s40, v189
	v_add_f32_e32 v8, 1.0, v8
	v_rcp_f32_e32 v8, v8
	s_nop 0
	v_mul_f32_e32 v6, v6, v8
	v_mul_f32_e32 v6, v6, v108
	v_mul_f32_e32 v9, 0x3e000000, v6
	v_mul_f32_e32 v6, 0x3c800000, v113
	v_mul_f32_e32 v8, 0xbfb8aa3b, v6
	v_exp_f32_e32 v8, v8
	s_nop 0
	v_add_f32_e32 v8, 1.0, v8
	v_rcp_f32_e32 v8, v8
	s_nop 0
	v_mul_f32_e32 v6, v6, v8
	v_mul_f32_e32 v6, v6, v109
	v_mul_f32_e32 v10, 0x3e000000, v6
	v_mul_f32_e32 v6, 0x3c800000, v102
	v_mul_f32_e32 v8, 0xbfb8aa3b, v6
	v_exp_f32_e32 v8, v8
	s_nop 0
	v_add_f32_e32 v8, 1.0, v8
	v_rcp_f32_e32 v8, v8
	s_nop 0
	v_mul_f32_e32 v6, v6, v8
	v_mul_f32_e32 v6, v6, v98
	v_mul_f32_e32 v11, 0x3e000000, v6
	v_mul_f32_e32 v6, 0x3c800000, v103
	v_mul_f32_e32 v8, 0xbfb8aa3b, v6
	v_exp_f32_e32 v8, v8
	s_nop 0
	v_add_f32_e32 v8, 1.0, v8
	v_rcp_f32_e32 v8, v8
	s_nop 0
	v_mul_f32_e32 v6, v6, v8
	v_mul_f32_e32 v6, v6, v99
	v_mul_f32_e32 v12, 0x3e000000, v6
	v_mul_f32_e32 v6, 0x3c800000, v104
	v_mul_f32_e32 v8, 0xbfb8aa3b, v6
	v_exp_f32_e32 v8, v8
	s_nop 0
	v_add_f32_e32 v8, 1.0, v8
	v_rcp_f32_e32 v8, v8
	s_nop 0
	v_mul_f32_e32 v6, v6, v8
	v_mul_f32_e32 v6, v6, v100
	v_mul_f32_e32 v13, 0x3e000000, v6
	v_mul_f32_e32 v6, 0x3c800000, v105
	v_mul_f32_e32 v8, 0xbfb8aa3b, v6
	v_exp_f32_e32 v8, v8
	s_nop 0
	v_add_f32_e32 v8, 1.0, v8
	v_rcp_f32_e32 v8, v8
	s_nop 0
	v_mul_f32_e32 v6, v6, v8
	v_mov_b32_e32 v8, v163
	v_cvt_pk_fp8_f32 v8, v5, v7
	v_med3_f32 v5, v9, s40, v189
	v_med3_f32 v7, v10, s40, v189
	v_mov_b32_e32 v9, v163
	v_cvt_pk_fp8_f32 v8, v5, v7 op_sel:[0,0,1]
	v_med3_f32 v5, v11, s40, v189
	v_med3_f32 v7, v12, s40, v189
	v_cvt_pk_fp8_f32 v9, v5, v7
	v_mul_f32_e32 v6, v6, v101
	v_mul_f32_e32 v14, 0x3e000000, v6
	v_add_u32_e32 v6, 48, v4
	v_med3_f32 v5, v13, s40, v189
	v_med3_f32 v7, v14, s40, v189
	v_cvt_pk_fp8_f32 v9, v5, v7 op_sel:[0,0,1]
	v_ashrrev_i32_e32 v7, 31, v6
	v_lshlrev_b64 v[6:7], 7, v[6:7]
	v_lshl_add_u64 v[6:7], s[10:11], 0, v[6:7]
	v_lshl_add_u64 v[6:7], v[6:7], 0, v[2:3]
	v_mul_f32_e32 v5, 0x3c800000, v94
	global_store_dwordx2 v[6:7], v[8:9], off
	v_mul_f32_e32 v7, 0xbfb8aa3b, v5
	v_exp_f32_e32 v7, v7
	v_add_u32_e32 v6, 0x80, v4
	v_add_f32_e32 v7, 1.0, v7
	v_rcp_f32_e32 v7, v7
	s_nop 0
	v_mul_f32_e32 v5, v5, v7
	v_mul_f32_e32 v7, 0x3c800000, v95
	v_mul_f32_e32 v8, 0xbfb8aa3b, v7
	v_exp_f32_e32 v8, v8
	v_mul_f32_e32 v5, v5, v90
	v_mul_f32_e32 v5, 0x3e000000, v5
	v_med3_f32 v5, v5, s40, v189
	v_add_f32_e32 v8, 1.0, v8
	v_rcp_f32_e32 v8, v8
	s_nop 0
	v_mul_f32_e32 v7, v7, v8
	v_mul_f32_e32 v8, 0x3c800000, v96
	v_mul_f32_e32 v9, 0xbfb8aa3b, v8
	v_exp_f32_e32 v9, v9
	v_mul_f32_e32 v7, v7, v91
	v_mul_f32_e32 v7, 0x3e000000, v7
	v_med3_f32 v7, v7, s40, v189
	v_add_f32_e32 v9, 1.0, v9
	v_rcp_f32_e32 v9, v9
	s_nop 0
	v_mul_f32_e32 v8, v8, v9
	v_mul_f32_e32 v8, v8, v92
	v_mul_f32_e32 v9, 0x3e000000, v8
	v_mul_f32_e32 v8, 0x3c800000, v97
	v_mul_f32_e32 v10, 0xbfb8aa3b, v8
	v_exp_f32_e32 v10, v10
	s_nop 0
	v_add_f32_e32 v10, 1.0, v10
	v_rcp_f32_e32 v10, v10
	s_nop 0
	v_mul_f32_e32 v8, v8, v10
	v_mul_f32_e32 v8, v8, v93
	v_mul_f32_e32 v10, 0x3e000000, v8
	v_mul_f32_e32 v8, 0x3c800000, v86
	v_mul_f32_e32 v11, 0xbfb8aa3b, v8
	v_exp_f32_e32 v11, v11
	s_nop 0
	v_add_f32_e32 v11, 1.0, v11
	v_rcp_f32_e32 v11, v11
	s_nop 0
	v_mul_f32_e32 v8, v8, v11
	v_mul_f32_e32 v8, v8, v82
	v_mul_f32_e32 v11, 0x3e000000, v8
	v_mul_f32_e32 v8, 0x3c800000, v87
	v_mul_f32_e32 v12, 0xbfb8aa3b, v8
	v_exp_f32_e32 v12, v12
	s_nop 0
	v_add_f32_e32 v12, 1.0, v12
	v_rcp_f32_e32 v12, v12
	s_nop 0
	v_mul_f32_e32 v8, v8, v12
	v_mul_f32_e32 v8, v8, v83
	v_mul_f32_e32 v12, 0x3e000000, v8
	v_mul_f32_e32 v8, 0x3c800000, v88
	v_mul_f32_e32 v13, 0xbfb8aa3b, v8
	v_exp_f32_e32 v13, v13
	s_nop 0
	v_add_f32_e32 v13, 1.0, v13
	v_rcp_f32_e32 v13, v13
	s_nop 0
	v_mul_f32_e32 v8, v8, v13
	v_mul_f32_e32 v8, v8, v84
	v_mul_f32_e32 v13, 0x3e000000, v8
	v_mul_f32_e32 v8, 0x3c800000, v89
	v_mul_f32_e32 v14, 0xbfb8aa3b, v8
	v_exp_f32_e32 v14, v14
	s_nop 0
	v_add_f32_e32 v14, 1.0, v14
	v_rcp_f32_e32 v14, v14
	s_nop 0
	v_mul_f32_e32 v8, v8, v14
	v_mul_f32_e32 v8, v8, v85
	v_mul_f32_e32 v14, 0x3e000000, v8
	v_mov_b32_e32 v8, v163
	v_cvt_pk_fp8_f32 v8, v5, v7
	v_med3_f32 v5, v9, s40, v189
	v_med3_f32 v7, v10, s40, v189
	v_mov_b32_e32 v9, v163
	v_cvt_pk_fp8_f32 v8, v5, v7 op_sel:[0,0,1]
	v_med3_f32 v5, v11, s40, v189
	v_med3_f32 v7, v12, s40, v189
	v_cvt_pk_fp8_f32 v9, v5, v7
	v_med3_f32 v5, v13, s40, v189
	v_med3_f32 v7, v14, s40, v189
	v_cvt_pk_fp8_f32 v9, v5, v7 op_sel:[0,0,1]
	v_ashrrev_i32_e32 v7, 31, v6
	v_lshlrev_b64 v[6:7], 7, v[6:7]
	v_lshl_add_u64 v[6:7], s[10:11], 0, v[6:7]
	v_lshl_add_u64 v[6:7], v[6:7], 0, v[2:3]
	v_mul_f32_e32 v5, 0x3c800000, v78
	global_store_dwordx2 v[6:7], v[8:9], off
	v_mul_f32_e32 v6, 0xbfb8aa3b, v5
	v_exp_f32_e32 v6, v6
	s_nop 0
	v_add_f32_e32 v6, 1.0, v6
	v_rcp_f32_e32 v6, v6
	s_nop 0
	v_mul_f32_e32 v5, v5, v6
	v_mul_f32_e32 v6, 0x3c800000, v79
	v_mul_f32_e32 v7, 0xbfb8aa3b, v6
	v_exp_f32_e32 v7, v7
	v_mul_f32_e32 v5, v5, v74
	v_mul_f32_e32 v5, 0x3e000000, v5
	v_med3_f32 v5, v5, s40, v189
	v_add_f32_e32 v7, 1.0, v7
	v_rcp_f32_e32 v7, v7
	s_nop 0
	v_mul_f32_e32 v6, v6, v7
	v_mul_f32_e32 v6, v6, v75
	v_mul_f32_e32 v7, 0x3e000000, v6
	v_mul_f32_e32 v6, 0x3c800000, v80
	v_mul_f32_e32 v8, 0xbfb8aa3b, v6
	v_exp_f32_e32 v8, v8
	v_med3_f32 v7, v7, s40, v189
	v_add_f32_e32 v8, 1.0, v8
	v_rcp_f32_e32 v8, v8
	s_nop 0
	v_mul_f32_e32 v6, v6, v8
	v_mul_f32_e32 v6, v6, v76
	v_mul_f32_e32 v9, 0x3e000000, v6
	v_mul_f32_e32 v6, 0x3c800000, v81
	v_mul_f32_e32 v8, 0xbfb8aa3b, v6
	v_exp_f32_e32 v8, v8
	s_nop 0
	v_add_f32_e32 v8, 1.0, v8
	v_rcp_f32_e32 v8, v8
	s_nop 0
	v_mul_f32_e32 v6, v6, v8
	v_mul_f32_e32 v6, v6, v77
	v_mul_f32_e32 v10, 0x3e000000, v6
	v_mul_f32_e32 v6, 0x3c800000, v70
	v_mul_f32_e32 v8, 0xbfb8aa3b, v6
	v_exp_f32_e32 v8, v8
	s_nop 0
	v_add_f32_e32 v8, 1.0, v8
	v_rcp_f32_e32 v8, v8
	s_nop 0
	v_mul_f32_e32 v6, v6, v8
	v_mul_f32_e32 v6, v6, v66
	v_mul_f32_e32 v11, 0x3e000000, v6
	v_mul_f32_e32 v6, 0x3c800000, v71
	v_mul_f32_e32 v8, 0xbfb8aa3b, v6
	v_exp_f32_e32 v8, v8
	s_nop 0
	v_add_f32_e32 v8, 1.0, v8
	v_rcp_f32_e32 v8, v8
	s_nop 0
	v_mul_f32_e32 v6, v6, v8
	v_mul_f32_e32 v6, v6, v67
	v_mul_f32_e32 v12, 0x3e000000, v6
	v_mul_f32_e32 v6, 0x3c800000, v72
	v_mul_f32_e32 v8, 0xbfb8aa3b, v6
	v_exp_f32_e32 v8, v8
	s_nop 0
	v_add_f32_e32 v8, 1.0, v8
	v_rcp_f32_e32 v8, v8
	s_nop 0
	v_mul_f32_e32 v6, v6, v8
	v_mul_f32_e32 v6, v6, v68
	v_mul_f32_e32 v13, 0x3e000000, v6
	v_mul_f32_e32 v6, 0x3c800000, v73
	v_mul_f32_e32 v8, 0xbfb8aa3b, v6
	v_exp_f32_e32 v8, v8
	s_nop 0
	v_add_f32_e32 v8, 1.0, v8
	v_rcp_f32_e32 v8, v8
	s_nop 0
	v_mul_f32_e32 v6, v6, v8
	v_mov_b32_e32 v8, v163
	v_cvt_pk_fp8_f32 v8, v5, v7
	v_med3_f32 v5, v9, s40, v189
	v_med3_f32 v7, v10, s40, v189
	v_mov_b32_e32 v9, v163
	v_cvt_pk_fp8_f32 v8, v5, v7 op_sel:[0,0,1]
	v_med3_f32 v5, v11, s40, v189
	v_med3_f32 v7, v12, s40, v189
	v_cvt_pk_fp8_f32 v9, v5, v7
	v_mul_f32_e32 v6, v6, v69
	v_mul_f32_e32 v14, 0x3e000000, v6
	v_add_u32_e32 v6, 0x90, v4
	v_med3_f32 v5, v13, s40, v189
	v_med3_f32 v7, v14, s40, v189
	v_cvt_pk_fp8_f32 v9, v5, v7 op_sel:[0,0,1]
	v_ashrrev_i32_e32 v7, 31, v6
	v_lshlrev_b64 v[6:7], 7, v[6:7]
	v_lshl_add_u64 v[6:7], s[10:11], 0, v[6:7]
	v_lshl_add_u64 v[6:7], v[6:7], 0, v[2:3]
	v_mul_f32_e32 v5, 0x3c800000, v62
	global_store_dwordx2 v[6:7], v[8:9], off
	v_mul_f32_e32 v6, 0xbfb8aa3b, v5
	v_exp_f32_e32 v6, v6
	s_nop 0
	v_add_f32_e32 v6, 1.0, v6
	v_rcp_f32_e32 v6, v6
	s_nop 0
	v_mul_f32_e32 v5, v5, v6
	v_mul_f32_e32 v6, 0x3c800000, v63
	v_mul_f32_e32 v7, 0xbfb8aa3b, v6
	v_exp_f32_e32 v7, v7
	v_mul_f32_e32 v5, v5, v58
	v_mul_f32_e32 v5, 0x3e000000, v5
	v_med3_f32 v5, v5, s40, v189
	v_add_f32_e32 v7, 1.0, v7
	v_rcp_f32_e32 v7, v7
	s_nop 0
	v_mul_f32_e32 v6, v6, v7
	v_mul_f32_e32 v6, v6, v59
	v_mul_f32_e32 v7, 0x3e000000, v6
	v_mul_f32_e32 v6, 0x3c800000, v64
	v_mul_f32_e32 v8, 0xbfb8aa3b, v6
	v_exp_f32_e32 v8, v8
	v_med3_f32 v7, v7, s40, v189
	v_add_f32_e32 v8, 1.0, v8
	v_rcp_f32_e32 v8, v8
	s_nop 0
	v_mul_f32_e32 v6, v6, v8
	v_mul_f32_e32 v6, v6, v60
	v_mul_f32_e32 v9, 0x3e000000, v6
	v_mul_f32_e32 v6, 0x3c800000, v65
	v_mul_f32_e32 v8, 0xbfb8aa3b, v6
	v_exp_f32_e32 v8, v8
	s_nop 0
	v_add_f32_e32 v8, 1.0, v8
	v_rcp_f32_e32 v8, v8
	s_nop 0
	v_mul_f32_e32 v6, v6, v8
	v_mul_f32_e32 v6, v6, v61
	v_mul_f32_e32 v10, 0x3e000000, v6
	v_mul_f32_e32 v6, 0x3c800000, v54
	v_mul_f32_e32 v8, 0xbfb8aa3b, v6
	v_exp_f32_e32 v8, v8
	s_nop 0
	v_add_f32_e32 v8, 1.0, v8
	v_rcp_f32_e32 v8, v8
	s_nop 0
	v_mul_f32_e32 v6, v6, v8
	v_mul_f32_e32 v6, v6, v50
	v_mul_f32_e32 v11, 0x3e000000, v6
	v_mul_f32_e32 v6, 0x3c800000, v55
	v_mul_f32_e32 v8, 0xbfb8aa3b, v6
	v_exp_f32_e32 v8, v8
	s_nop 0
	v_add_f32_e32 v8, 1.0, v8
	v_rcp_f32_e32 v8, v8
	s_nop 0
	v_mul_f32_e32 v6, v6, v8
	v_mul_f32_e32 v6, v6, v51
	v_mul_f32_e32 v12, 0x3e000000, v6
	v_mul_f32_e32 v6, 0x3c800000, v56
	v_mul_f32_e32 v8, 0xbfb8aa3b, v6
	v_exp_f32_e32 v8, v8
	s_nop 0
	v_add_f32_e32 v8, 1.0, v8
	v_rcp_f32_e32 v8, v8
	s_nop 0
	v_mul_f32_e32 v6, v6, v8
	v_mul_f32_e32 v6, v6, v52
	v_mul_f32_e32 v13, 0x3e000000, v6
	v_mul_f32_e32 v6, 0x3c800000, v57
	v_mul_f32_e32 v8, 0xbfb8aa3b, v6
	v_exp_f32_e32 v8, v8
	s_nop 0
	v_add_f32_e32 v8, 1.0, v8
	v_rcp_f32_e32 v8, v8
	s_nop 0
	v_mul_f32_e32 v6, v6, v8
	v_mov_b32_e32 v8, v163
	v_cvt_pk_fp8_f32 v8, v5, v7
	v_med3_f32 v5, v9, s40, v189
	v_med3_f32 v7, v10, s40, v189
	v_mov_b32_e32 v9, v163
	v_cvt_pk_fp8_f32 v8, v5, v7 op_sel:[0,0,1]
	v_med3_f32 v5, v11, s40, v189
	v_med3_f32 v7, v12, s40, v189
	v_cvt_pk_fp8_f32 v9, v5, v7
	v_mul_f32_e32 v6, v6, v53
	v_mul_f32_e32 v14, 0x3e000000, v6
	v_add_u32_e32 v6, 0xa0, v4
	v_med3_f32 v5, v13, s40, v189
	v_med3_f32 v7, v14, s40, v189
	v_cvt_pk_fp8_f32 v9, v5, v7 op_sel:[0,0,1]
	v_ashrrev_i32_e32 v7, 31, v6
	v_lshlrev_b64 v[6:7], 7, v[6:7]
	v_lshl_add_u64 v[6:7], s[10:11], 0, v[6:7]
	v_lshl_add_u64 v[6:7], v[6:7], 0, v[2:3]
	v_mul_f32_e32 v5, 0x3c800000, v46
	global_store_dwordx2 v[6:7], v[8:9], off
	v_mul_f32_e32 v6, 0xbfb8aa3b, v5
	v_exp_f32_e32 v6, v6
	v_add_u32_e32 v4, 0xb0, v4
	v_add_f32_e32 v6, 1.0, v6
	v_rcp_f32_e32 v6, v6
	s_nop 0
	v_mul_f32_e32 v5, v5, v6
	v_mul_f32_e32 v6, 0x3c800000, v47
	v_mul_f32_e32 v7, 0xbfb8aa3b, v6
	v_exp_f32_e32 v7, v7
	v_mul_f32_e32 v5, v5, v42
	v_mul_f32_e32 v5, 0x3e000000, v5
	v_med3_f32 v5, v5, s40, v189
	v_add_f32_e32 v7, 1.0, v7
	v_rcp_f32_e32 v7, v7
	s_nop 0
	v_mul_f32_e32 v6, v6, v7
	v_mul_f32_e32 v7, 0x3c800000, v48
	v_mul_f32_e32 v8, 0xbfb8aa3b, v7
	v_exp_f32_e32 v8, v8
	v_mul_f32_e32 v6, v6, v43
	v_mul_f32_e32 v6, 0x3e000000, v6
	v_add_f32_e32 v8, 1.0, v8
	v_rcp_f32_e32 v8, v8
	s_nop 0
	v_mul_f32_e32 v7, v7, v8
	v_mul_f32_e32 v8, 0x3c800000, v49
	v_mul_f32_e32 v9, 0xbfb8aa3b, v8
	v_exp_f32_e32 v9, v9
	v_mul_f32_e32 v7, v7, v44
	v_mul_f32_e32 v7, 0x3e000000, v7
	v_add_f32_e32 v9, 1.0, v9
	v_rcp_f32_e32 v9, v9
	s_nop 0
	v_mul_f32_e32 v8, v8, v9
	v_mul_f32_e32 v9, 0x3c800000, v38
	v_mul_f32_e32 v10, 0xbfb8aa3b, v9
	v_exp_f32_e32 v10, v10
	v_mul_f32_e32 v8, v8, v45
	v_mul_f32_e32 v8, 0x3e000000, v8
	v_add_f32_e32 v10, 1.0, v10
	v_rcp_f32_e32 v10, v10
	s_nop 0
	v_mul_f32_e32 v9, v9, v10
	v_mul_f32_e32 v10, 0x3c800000, v39
	v_mul_f32_e32 v11, 0xbfb8aa3b, v10
	v_exp_f32_e32 v11, v11
	v_mul_f32_e32 v9, v9, v34
	v_mul_f32_e32 v9, 0x3e000000, v9
	v_add_f32_e32 v11, 1.0, v11
	v_rcp_f32_e32 v11, v11
	s_nop 0
	v_mul_f32_e32 v10, v10, v11
	v_mul_f32_e32 v11, 0x3c800000, v40
	v_mul_f32_e32 v12, 0xbfb8aa3b, v11
	v_exp_f32_e32 v12, v12
	v_mul_f32_e32 v10, v10, v35
	v_mul_f32_e32 v10, 0x3e000000, v10
	v_add_f32_e32 v12, 1.0, v12
	v_rcp_f32_e32 v12, v12
	s_nop 0
	v_mul_f32_e32 v11, v11, v12
	v_mul_f32_e32 v12, 0x3c800000, v41
	v_mul_f32_e32 v13, 0xbfb8aa3b, v12
	v_exp_f32_e32 v13, v13
	v_mul_f32_e32 v11, v11, v36
	v_mul_f32_e32 v11, 0x3e000000, v11
	v_add_f32_e32 v13, 1.0, v13
	v_rcp_f32_e32 v13, v13
	s_nop 0
	v_mul_f32_e32 v12, v12, v13
	v_med3_f32 v13, v6, s40, v189
	v_mov_b32_e32 v6, v163
	v_cvt_pk_fp8_f32 v6, v5, v13
	v_med3_f32 v5, v7, s40, v189
	v_med3_f32 v7, v8, s40, v189
	v_med3_f32 v8, v10, s40, v189
	v_cvt_pk_fp8_f32 v6, v5, v7 op_sel:[0,0,1]
	v_med3_f32 v5, v9, s40, v189
	v_mov_b32_e32 v7, v163
	v_cvt_pk_fp8_f32 v7, v5, v8
	v_mul_f32_e32 v12, v12, v37
	v_mul_f32_e32 v12, 0x3e000000, v12
	v_med3_f32 v5, v11, s40, v189
	v_med3_f32 v8, v12, s40, v189
	v_cvt_pk_fp8_f32 v7, v5, v8 op_sel:[0,0,1]
	v_ashrrev_i32_e32 v5, 31, v4
	v_lshlrev_b64 v[4:5], 7, v[4:5]
	v_lshl_add_u64 v[4:5], s[10:11], 0, v[4:5]
	v_lshl_add_u64 v[2:3], v[4:5], 0, v[2:3]
	global_store_dwordx2 v[2:3], v[6:7], off
	s_cbranch_vccz .LBB0_2738
	s_waitcnt vmcnt(0)
	s_cmpk_gt_u32 s42, 0xff
	s_cbranch_scc1 .LBB0_2684
	s_barrier
	s_branch .LBB0_2684

.LBB0_2816:
	ds_read_b128 v[2:5], v168
	ds_read_b128 v[6:9], v168 offset:1024
	ds_read_b128 v[10:13], v168 offset:2048
	ds_read_b128 v[14:17], v168 offset:3072
	s_add_u32 s0, s26, 0x4000
	s_addc_u32 s1, s27, 0
	s_cmp_eq_u32 s53, 4
	s_cselect_b32 s34, s49, s0
	s_cselect_b32 s35, s19, s1
	s_cselect_b32 s28, s50, s51
	s_cselect_b32 s29, s17, s52
	s_add_u32 s30, s34, 0x8000
	s_addc_u32 s31, s35, 0
	v_lshl_add_u64 v[162:163], s[26:27], 0, v[156:157]
	s_add_i32 m0, s25, 0xc000
	ds_read_b128 v[174:177], v169
	ds_read_b128 v[178:181], v169 offset:1024
	ds_read_b128 v[182:185], v169 offset:2048
	ds_read_b128 v[186:189], v169 offset:3072
	ds_read_b128 v[190:193], v169 offset:4096
	ds_read_b128 v[194:197], v169 offset:5120
	ds_read_b128 v[198:201], v169 offset:6144
	ds_read_b128 v[202:205], v169 offset:7168
	global_load_lds_dwordx4 v[162:163], off nt
	v_lshl_add_u64 v[162:163], s[26:27], 0, v[154:155]
	s_add_i32 m0, s25, 0xe000
	s_nop 0
	global_load_lds_dwordx4 v[162:163], off nt
	s_waitcnt lgkmcnt(8)
	s_waitcnt vmcnt(10)
	s_barrier
	s_waitcnt lgkmcnt(0)
	s_waitcnt lgkmcnt(0)
	v_mfma_scale_f32_16x16x128_f8f6f4 v[142:145], v[2:9], v[174:181], v[142:145], v170, v170 op_sel_hi:[0,0,0]
	v_mfma_scale_f32_16x16x128_f8f6f4 v[138:141], v[10:17], v[174:181], v[138:141], v170, v170 op_sel_hi:[0,0,0]
	v_mfma_scale_f32_16x16x128_f8f6f4 v[126:129], v[2:9], v[182:189], v[126:129], v170, v170 op_sel_hi:[0,0,0]
	v_mfma_scale_f32_16x16x128_f8f6f4 v[122:125], v[10:17], v[182:189], v[122:125], v170, v170 op_sel_hi:[0,0,0]
	v_mfma_scale_f32_16x16x128_f8f6f4 v[110:113], v[2:9], v[190:197], v[110:113], v170, v170 op_sel_hi:[0,0,0]
	v_mfma_scale_f32_16x16x128_f8f6f4 v[106:109], v[10:17], v[190:197], v[106:109], v170, v170 op_sel_hi:[0,0,0]
	v_mfma_scale_f32_16x16x128_f8f6f4 v[94:97], v[2:9], v[198:205], v[94:97], v170, v170 op_sel_hi:[0,0,0]
	v_mfma_scale_f32_16x16x128_f8f6f4 v[90:93], v[10:17], v[198:205], v[90:93], v170, v170 op_sel_hi:[0,0,0]
	s_barrier
	s_add_i32 s0, s45, s37
	v_lshl_add_u64 v[162:163], s[28:29], 0, v[150:151]
	s_mov_b32 m0, s0
	ds_read_b128 v[206:209], v171
	ds_read_b128 v[210:213], v171 offset:1024
	ds_read_b128 v[214:217], v171 offset:2048
	ds_read_b128 v[218:221], v171 offset:3072
	global_load_lds_dwordx4 v[162:163], off
	v_lshl_add_u64 v[164:165], s[28:29], 0, v[146:147]
	s_add_i32 m0, s0, 0x2000
	s_nop 0
	global_load_lds_dwordx4 v[164:165], off
	s_waitcnt vmcnt(10)
	s_barrier
	s_waitcnt lgkmcnt(0)
	s_waitcnt lgkmcnt(0)
	v_mfma_scale_f32_16x16x128_f8f6f4 v[134:137], v[206:213], v[174:181], v[134:137], v170, v170 op_sel_hi:[0,0,0]
	v_mfma_scale_f32_16x16x128_f8f6f4 v[130:133], v[214:221], v[174:181], v[130:133], v170, v170 op_sel_hi:[0,0,0]
	v_mfma_scale_f32_16x16x128_f8f6f4 v[118:121], v[206:213], v[182:189], v[118:121], v170, v170 op_sel_hi:[0,0,0]
	v_mfma_scale_f32_16x16x128_f8f6f4 v[114:117], v[214:221], v[182:189], v[114:117], v170, v170 op_sel_hi:[0,0,0]
	v_mfma_scale_f32_16x16x128_f8f6f4 v[102:105], v[206:213], v[190:197], v[102:105], v170, v170 op_sel_hi:[0,0,0]
	v_mfma_scale_f32_16x16x128_f8f6f4 v[98:101], v[214:221], v[190:197], v[98:101], v170, v170 op_sel_hi:[0,0,0]
	v_mfma_scale_f32_16x16x128_f8f6f4 v[86:89], v[206:213], v[198:205], v[86:89], v170, v170 op_sel_hi:[0,0,0]
	v_mfma_scale_f32_16x16x128_f8f6f4 v[82:85], v[214:221], v[198:205], v[82:85], v170, v170 op_sel_hi:[0,0,0]
	s_mov_b32 m0, s25
	v_lshl_add_u64 v[222:223], s[34:35], 0, v[152:153]
	s_barrier
	ds_read_b128 v[174:177], v169 offset:16384
	ds_read_b128 v[178:181], v169 offset:17408
	ds_read_b128 v[182:185], v169 offset:18432
	ds_read_b128 v[186:189], v169 offset:19456
	ds_read_b128 v[190:193], v169 offset:20480
	ds_read_b128 v[194:197], v169 offset:21504
	ds_read_b128 v[198:201], v169 offset:22528
	ds_read_b128 v[202:205], v169 offset:23552
	global_load_lds_dwordx4 v[222:223], off nt
	v_lshl_add_u64 v[222:223], s[34:35], 0, v[148:149]
	s_mov_b32 m0, s38
	s_nop 0
	global_load_lds_dwordx4 v[222:223], off nt
	s_waitcnt vmcnt(10)
	s_barrier
	s_waitcnt lgkmcnt(0)
	s_waitcnt lgkmcnt(0)
	v_mfma_scale_f32_16x16x128_f8f6f4 v[78:81], v[2:9], v[174:181], v[78:81], v170, v170 op_sel_hi:[0,0,0]
	v_mfma_scale_f32_16x16x128_f8f6f4 v[74:77], v[10:17], v[174:181], v[74:77], v170, v170 op_sel_hi:[0,0,0]
	v_mfma_scale_f32_16x16x128_f8f6f4 v[62:65], v[2:9], v[182:189], v[62:65], v170, v170 op_sel_hi:[0,0,0]
	v_mfma_scale_f32_16x16x128_f8f6f4 v[58:61], v[10:17], v[182:189], v[58:61], v170, v170 op_sel_hi:[0,0,0]
	v_mfma_scale_f32_16x16x128_f8f6f4 v[46:49], v[2:9], v[190:197], v[46:49], v170, v170 op_sel_hi:[0,0,0]
	v_mfma_scale_f32_16x16x128_f8f6f4 v[42:45], v[10:17], v[190:197], v[42:45], v170, v170 op_sel_hi:[0,0,0]
	v_mfma_scale_f32_16x16x128_f8f6f4 v[30:33], v[2:9], v[198:205], v[30:33], v170, v170 op_sel_hi:[0,0,0]
	v_mfma_scale_f32_16x16x128_f8f6f4 v[26:29], v[10:17], v[198:205], v[26:29], v170, v170 op_sel_hi:[0,0,0]
	s_barrier
	s_add_u32 s0, s28, 0x20000
	s_addc_u32 s1, s29, 0
	s_add_i32 s54, s46, s37
	v_lshl_add_u64 v[2:3], s[0:1], 0, v[150:151]
	s_mov_b32 m0, s54
	s_nop 0
	global_load_lds_dwordx4 v[2:3], off
	v_lshl_add_u64 v[2:3], s[0:1], 0, v[146:147]
	s_add_i32 m0, s54, 0x2000
	s_nop 0
	global_load_lds_dwordx4 v[2:3], off
	s_waitcnt vmcnt(10)
	s_barrier
	v_mfma_scale_f32_16x16x128_f8f6f4 v[70:73], v[206:213], v[174:181], v[70:73], v170, v170 op_sel_hi:[0,0,0]
	v_mfma_scale_f32_16x16x128_f8f6f4 v[66:69], v[214:221], v[174:181], v[66:69], v170, v170 op_sel_hi:[0,0,0]
	v_mfma_scale_f32_16x16x128_f8f6f4 v[54:57], v[206:213], v[182:189], v[54:57], v170, v170 op_sel_hi:[0,0,0]
	v_mfma_scale_f32_16x16x128_f8f6f4 v[50:53], v[214:221], v[182:189], v[50:53], v170, v170 op_sel_hi:[0,0,0]
	v_mfma_scale_f32_16x16x128_f8f6f4 v[38:41], v[206:213], v[190:197], v[38:41], v170, v170 op_sel_hi:[0,0,0]
	v_mfma_scale_f32_16x16x128_f8f6f4 v[34:37], v[214:221], v[190:197], v[34:37], v170, v170 op_sel_hi:[0,0,0]
	v_mfma_scale_f32_16x16x128_f8f6f4 v[22:25], v[206:213], v[198:205], v[22:25], v170, v170 op_sel_hi:[0,0,0]
	v_mfma_scale_f32_16x16x128_f8f6f4 v[18:21], v[214:221], v[198:205], v[18:21], v170, v170 op_sel_hi:[0,0,0]
	s_add_i32 s54, 0, 0x18000
	v_add_u32_e32 v14, s54, v167
	s_barrier
	ds_read_b128 v[2:5], v14
	ds_read_b128 v[6:9], v14 offset:1024
	ds_read_b128 v[10:13], v14 offset:2048
	ds_read_b128 v[14:17], v14 offset:3072
	s_add_u32 s0, s34, 0x4000
	s_addc_u32 s1, s35, 0
	s_mov_b32 m0, s39
	v_lshl_add_u64 v[206:207], s[0:1], 0, v[152:153]
	ds_read_b128 v[174:177], v169 offset:32768
	ds_read_b128 v[178:181], v169 offset:33792
	ds_read_b128 v[182:185], v169 offset:34816
	ds_read_b128 v[186:189], v169 offset:35840
	ds_read_b128 v[190:193], v169 offset:36864
	ds_read_b128 v[194:197], v169 offset:37888
	ds_read_b128 v[198:201], v169 offset:38912
	ds_read_b128 v[202:205], v169 offset:39936
	global_load_lds_dwordx4 v[206:207], off nt
	v_lshl_add_u64 v[206:207], s[0:1], 0, v[148:149]
	s_mov_b32 m0, s40
	s_nop 0
	global_load_lds_dwordx4 v[206:207], off nt
	s_waitcnt lgkmcnt(8)
	s_waitcnt vmcnt(10)
	s_barrier
	s_waitcnt lgkmcnt(0)
	s_waitcnt lgkmcnt(0)
	v_mfma_scale_f32_16x16x128_f8f6f4 v[142:145], v[2:9], v[174:181], v[142:145], v170, v170 op_sel_hi:[0,0,0]
	v_mfma_scale_f32_16x16x128_f8f6f4 v[138:141], v[10:17], v[174:181], v[138:141], v170, v170 op_sel_hi:[0,0,0]
	v_mfma_scale_f32_16x16x128_f8f6f4 v[126:129], v[2:9], v[182:189], v[126:129], v170, v170 op_sel_hi:[0,0,0]
	v_mfma_scale_f32_16x16x128_f8f6f4 v[122:125], v[10:17], v[182:189], v[122:125], v170, v170 op_sel_hi:[0,0,0]
	v_mfma_scale_f32_16x16x128_f8f6f4 v[110:113], v[2:9], v[190:197], v[110:113], v170, v170 op_sel_hi:[0,0,0]
	v_mfma_scale_f32_16x16x128_f8f6f4 v[106:109], v[10:17], v[190:197], v[106:109], v170, v170 op_sel_hi:[0,0,0]
	v_mfma_scale_f32_16x16x128_f8f6f4 v[94:97], v[2:9], v[198:205], v[94:97], v170, v170 op_sel_hi:[0,0,0]
	v_mfma_scale_f32_16x16x128_f8f6f4 v[90:93], v[10:17], v[198:205], v[90:93], v170, v170 op_sel_hi:[0,0,0]
	s_barrier
	s_add_i32 s34, 0, 0x1c000
	s_add_i32 s0, s54, s37
	v_add_u32_e32 v173, s34, v167
	v_lshl_add_u64 v[162:163], v[162:163], 0, s[12:13]
	s_mov_b32 m0, s0
	ds_read_b128 v[206:209], v173
	ds_read_b128 v[210:213], v173 offset:1024
	ds_read_b128 v[214:217], v173 offset:2048
	ds_read_b128 v[218:221], v173 offset:3072
	global_load_lds_dwordx4 v[162:163], off
	v_lshl_add_u64 v[162:163], v[164:165], 0, s[12:13]
	s_add_i32 m0, s0, 0x2000
	s_nop 0
	global_load_lds_dwordx4 v[162:163], off
	s_waitcnt vmcnt(10)
	s_barrier
	s_waitcnt lgkmcnt(0)
	s_waitcnt lgkmcnt(0)
	v_mfma_scale_f32_16x16x128_f8f6f4 v[134:137], v[206:213], v[174:181], v[134:137], v170, v170 op_sel_hi:[0,0,0]
	v_mfma_scale_f32_16x16x128_f8f6f4 v[130:133], v[214:221], v[174:181], v[130:133], v170, v170 op_sel_hi:[0,0,0]
	v_mfma_scale_f32_16x16x128_f8f6f4 v[118:121], v[206:213], v[182:189], v[118:121], v170, v170 op_sel_hi:[0,0,0]
	v_mfma_scale_f32_16x16x128_f8f6f4 v[114:117], v[214:221], v[182:189], v[114:117], v170, v170 op_sel_hi:[0,0,0]
	v_mfma_scale_f32_16x16x128_f8f6f4 v[102:105], v[206:213], v[190:197], v[102:105], v170, v170 op_sel_hi:[0,0,0]
	v_mfma_scale_f32_16x16x128_f8f6f4 v[98:101], v[214:221], v[190:197], v[98:101], v170, v170 op_sel_hi:[0,0,0]
	v_mfma_scale_f32_16x16x128_f8f6f4 v[86:89], v[206:213], v[198:205], v[86:89], v170, v170 op_sel_hi:[0,0,0]
	v_mfma_scale_f32_16x16x128_f8f6f4 v[82:85], v[214:221], v[198:205], v[82:85], v170, v170 op_sel_hi:[0,0,0]
	s_mov_b32 m0, s43
	v_lshl_add_u64 v[162:163], s[30:31], 0, v[152:153]
	s_barrier
	ds_read_b128 v[174:177], v169 offset:49152
	ds_read_b128 v[178:181], v169 offset:50176
	ds_read_b128 v[182:185], v169 offset:51200
	ds_read_b128 v[186:189], v169 offset:52224
	ds_read_b128 v[190:193], v169 offset:53248
	ds_read_b128 v[194:197], v169 offset:54272
	ds_read_b128 v[198:201], v169 offset:55296
	ds_read_b128 v[202:205], v169 offset:56320
	global_load_lds_dwordx4 v[162:163], off nt
	v_lshl_add_u64 v[162:163], s[30:31], 0, v[148:149]
	s_mov_b32 m0, s44
	s_nop 0
	global_load_lds_dwordx4 v[162:163], off nt
	s_waitcnt vmcnt(10)
	s_barrier
	s_waitcnt lgkmcnt(0)
	s_waitcnt lgkmcnt(0)
	v_mfma_scale_f32_16x16x128_f8f6f4 v[78:81], v[2:9], v[174:181], v[78:81], v170, v170 op_sel_hi:[0,0,0]
	v_mfma_scale_f32_16x16x128_f8f6f4 v[74:77], v[10:17], v[174:181], v[74:77], v170, v170 op_sel_hi:[0,0,0]
	v_mfma_scale_f32_16x16x128_f8f6f4 v[62:65], v[2:9], v[182:189], v[62:65], v170, v170 op_sel_hi:[0,0,0]
	v_mfma_scale_f32_16x16x128_f8f6f4 v[58:61], v[10:17], v[182:189], v[58:61], v170, v170 op_sel_hi:[0,0,0]
	v_mfma_scale_f32_16x16x128_f8f6f4 v[46:49], v[2:9], v[190:197], v[46:49], v170, v170 op_sel_hi:[0,0,0]
	v_mfma_scale_f32_16x16x128_f8f6f4 v[42:45], v[10:17], v[190:197], v[42:45], v170, v170 op_sel_hi:[0,0,0]
	v_mfma_scale_f32_16x16x128_f8f6f4 v[30:33], v[2:9], v[198:205], v[30:33], v170, v170 op_sel_hi:[0,0,0]
	v_mfma_scale_f32_16x16x128_f8f6f4 v[26:29], v[10:17], v[198:205], v[26:29], v170, v170 op_sel_hi:[0,0,0]
	s_barrier
	s_add_u32 s0, s28, 0x20080
	s_addc_u32 s1, s29, 0
	s_add_i32 s28, s34, s37
	v_lshl_add_u64 v[2:3], s[0:1], 0, v[150:151]
	s_mov_b32 m0, s28
	s_nop 0
	global_load_lds_dwordx4 v[2:3], off
	v_lshl_add_u64 v[2:3], s[0:1], 0, v[146:147]
	s_add_i32 m0, s28, 0x2000
	s_nop 0
	global_load_lds_dwordx4 v[2:3], off
	s_waitcnt vmcnt(10)
	s_barrier
	v_mfma_scale_f32_16x16x128_f8f6f4 v[70:73], v[206:213], v[174:181], v[70:73], v170, v170 op_sel_hi:[0,0,0]
	v_mfma_scale_f32_16x16x128_f8f6f4 v[66:69], v[214:221], v[174:181], v[66:69], v170, v170 op_sel_hi:[0,0,0]
	v_mfma_scale_f32_16x16x128_f8f6f4 v[54:57], v[206:213], v[182:189], v[54:57], v170, v170 op_sel_hi:[0,0,0]
	v_mfma_scale_f32_16x16x128_f8f6f4 v[50:53], v[214:221], v[182:189], v[50:53], v170, v170 op_sel_hi:[0,0,0]
	v_mfma_scale_f32_16x16x128_f8f6f4 v[38:41], v[206:213], v[190:197], v[38:41], v170, v170 op_sel_hi:[0,0,0]
	v_mfma_scale_f32_16x16x128_f8f6f4 v[34:37], v[214:221], v[190:197], v[34:37], v170, v170 op_sel_hi:[0,0,0]
	v_mfma_scale_f32_16x16x128_f8f6f4 v[22:25], v[206:213], v[198:205], v[22:25], v170, v170 op_sel_hi:[0,0,0]
	v_mfma_scale_f32_16x16x128_f8f6f4 v[18:21], v[214:221], v[198:205], v[18:21], v170, v170 op_sel_hi:[0,0,0]
	s_add_i32 s53, s53, 2
	s_add_u32 s51, s51, 0x100
	s_addc_u32 s52, s52, 0
	s_add_u32 s26, s26, 0x10000
	s_addc_u32 s27, s27, 0
	s_cmp_gt_u32 s53, 5
	s_barrier
	s_cbranch_scc0 .LBB0_2816
	v_pk_mul_f32 v[8:9], v[142:143], s[14:15] op_sel_hi:[1,0]
	v_pk_mul_f32 v[6:7], v[144:145], s[14:15] op_sel_hi:[1,0]
	v_med3_f32 v14, v8, s47, v172
	v_med3_f32 v9, v9, s47, v172
	v_mov_b32_e32 v8, 0
	v_cvt_pk_fp8_f32 v8, v14, v9
	v_pk_mul_f32 v[12:13], v[138:139], s[14:15] op_sel_hi:[1,0]
	v_pk_mul_f32 v[10:11], v[140:141], s[14:15] op_sel_hi:[1,0]
	v_med3_f32 v6, v6, s47, v172
	v_med3_f32 v7, v7, s47, v172
	v_med3_f32 v12, v12, s47, v172
	v_med3_f32 v13, v13, s47, v172
	v_mov_b32_e32 v9, 0
	v_mov_b32_e32 v3, v1
	v_mov_b32_e32 v2, v166
	s_lshl_b32 s0, s48, 8
	v_cvt_pk_fp8_f32 v9, v12, v13
	v_cvt_pk_fp8_f32 v8, v6, v7 op_sel:[0,0,1]
	v_med3_f32 v6, v10, s47, v172
	v_med3_f32 v7, v11, s47, v172
	v_pk_mul_f32 v[10:11], v[134:135], s[14:15] op_sel_hi:[1,0]
	s_nop 15
	s_nop 15
	s_or_b32 s0, s0, s42
	v_pk_mul_f32 v[14:15], v[130:131], s[14:15] op_sel_hi:[1,0]
	v_med3_f32 v17, v10, s47, v172
	v_med3_f32 v11, v11, s47, v172
	v_mov_b32_e32 v10, 0
	v_lshl_add_u32 v2, v2, 3, s0
	s_lshl_b32 s0, s24, 8
	v_cvt_pk_fp8_f32 v10, v17, v11
	v_med3_f32 v14, v14, s47, v172
	v_med3_f32 v15, v15, s47, v172
	v_mov_b32_e32 v11, 0
	s_add_i32 s0, s0, s15
	v_cvt_pk_fp8_f32 v11, v14, v15
	v_add_u32_e32 v16, s0, v3
	v_cvt_pk_fp8_f32 v9, v6, v7 op_sel:[0,0,1]
	v_pk_mul_f32 v[6:7], v[136:137], s[14:15] op_sel_hi:[1,0]
	v_mov_b32_e32 v4, v16
	v_pk_mul_f32 v[12:13], v[132:133], s[14:15] op_sel_hi:[1,0]
	v_med3_f32 v6, v6, s47, v172
	v_med3_f32 v7, v7, s47, v172
	v_cvt_pk_fp8_f32 v10, v6, v7 op_sel:[0,0,1]
	v_ashrrev_i32_e32 v5, 31, v4
	v_med3_f32 v6, v12, s47, v172
	v_med3_f32 v7, v13, s47, v172
	v_lshlrev_b64 v[4:5], 10, v[4:5]
	v_cvt_pk_fp8_f32 v11, v6, v7 op_sel:[0,0,1]
	v_ashrrev_i32_e32 v3, 31, v2
	v_lshl_add_u64 v[4:5], s[10:11], 0, v[4:5]
	v_lshl_add_u64 v[4:5], v[4:5], 0, v[2:3]
	global_store_dwordx2 v[4:5], v[8:9], off
	global_store_dwordx2 v[4:5], v[10:11], off offset:128
	v_pk_mul_f32 v[8:9], v[126:127], s[14:15] op_sel_hi:[1,0]
	v_pk_mul_f32 v[6:7], v[128:129], s[14:15] op_sel_hi:[1,0]
	v_med3_f32 v14, v8, s47, v172
	v_med3_f32 v9, v9, s47, v172
	v_mov_b32_e32 v8, 0
	v_cvt_pk_fp8_f32 v8, v14, v9
	v_pk_mul_f32 v[12:13], v[122:123], s[14:15] op_sel_hi:[1,0]
	v_pk_mul_f32 v[10:11], v[124:125], s[14:15] op_sel_hi:[1,0]
	v_med3_f32 v6, v6, s47, v172
	v_med3_f32 v7, v7, s47, v172
	v_med3_f32 v12, v12, s47, v172
	v_med3_f32 v13, v13, s47, v172
	v_mov_b32_e32 v9, 0
	v_cvt_pk_fp8_f32 v9, v12, v13
	v_cvt_pk_fp8_f32 v8, v6, v7 op_sel:[0,0,1]
	v_med3_f32 v6, v10, s47, v172
	v_med3_f32 v7, v11, s47, v172
	v_pk_mul_f32 v[10:11], v[118:119], s[14:15] op_sel_hi:[1,0]
	v_pk_mul_f32 v[14:15], v[114:115], s[14:15] op_sel_hi:[1,0]
	v_med3_f32 v17, v10, s47, v172
	v_med3_f32 v11, v11, s47, v172
	v_mov_b32_e32 v10, 0
	v_cvt_pk_fp8_f32 v10, v17, v11
	v_med3_f32 v14, v14, s47, v172
	v_med3_f32 v15, v15, s47, v172
	v_mov_b32_e32 v11, 0
	v_cvt_pk_fp8_f32 v11, v14, v15
	v_cvt_pk_fp8_f32 v9, v6, v7 op_sel:[0,0,1]
	v_pk_mul_f32 v[6:7], v[120:121], s[14:15] op_sel_hi:[1,0]
	v_add_u32_e32 v4, 16, v16
	v_pk_mul_f32 v[12:13], v[116:117], s[14:15] op_sel_hi:[1,0]
	v_med3_f32 v6, v6, s47, v172
	v_med3_f32 v7, v7, s47, v172
	v_cvt_pk_fp8_f32 v10, v6, v7 op_sel:[0,0,1]
	v_ashrrev_i32_e32 v5, 31, v4
	v_med3_f32 v6, v12, s47, v172
	v_med3_f32 v7, v13, s47, v172
	v_lshlrev_b64 v[4:5], 10, v[4:5]
	v_cvt_pk_fp8_f32 v11, v6, v7 op_sel:[0,0,1]
	v_lshl_add_u64 v[4:5], s[10:11], 0, v[4:5]
	v_lshl_add_u64 v[4:5], v[4:5], 0, v[2:3]
	global_store_dwordx2 v[4:5], v[8:9], off
	global_store_dwordx2 v[4:5], v[10:11], off offset:128
	v_pk_mul_f32 v[8:9], v[110:111], s[14:15] op_sel_hi:[1,0]
	v_pk_mul_f32 v[6:7], v[112:113], s[14:15] op_sel_hi:[1,0]
	v_med3_f32 v14, v8, s47, v172
	v_med3_f32 v9, v9, s47, v172
	v_mov_b32_e32 v8, 0
	v_cvt_pk_fp8_f32 v8, v14, v9
	v_pk_mul_f32 v[12:13], v[106:107], s[14:15] op_sel_hi:[1,0]
	v_pk_mul_f32 v[10:11], v[108:109], s[14:15] op_sel_hi:[1,0]
	v_med3_f32 v6, v6, s47, v172
	v_med3_f32 v7, v7, s47, v172
	v_med3_f32 v12, v12, s47, v172
	v_med3_f32 v13, v13, s47, v172
	v_mov_b32_e32 v9, 0
	v_cvt_pk_fp8_f32 v9, v12, v13
	v_cvt_pk_fp8_f32 v8, v6, v7 op_sel:[0,0,1]
	v_med3_f32 v6, v10, s47, v172
	v_med3_f32 v7, v11, s47, v172
	v_pk_mul_f32 v[10:11], v[102:103], s[14:15] op_sel_hi:[1,0]
	v_pk_mul_f32 v[14:15], v[98:99], s[14:15] op_sel_hi:[1,0]
	v_med3_f32 v17, v10, s47, v172
	v_med3_f32 v11, v11, s47, v172
	v_mov_b32_e32 v10, 0
	v_cvt_pk_fp8_f32 v10, v17, v11
	v_med3_f32 v14, v14, s47, v172
	v_med3_f32 v15, v15, s47, v172
	v_mov_b32_e32 v11, 0
	v_cvt_pk_fp8_f32 v11, v14, v15
	v_cvt_pk_fp8_f32 v9, v6, v7 op_sel:[0,0,1]
	v_pk_mul_f32 v[6:7], v[104:105], s[14:15] op_sel_hi:[1,0]
	v_add_u32_e32 v4, 32, v16
	v_pk_mul_f32 v[12:13], v[100:101], s[14:15] op_sel_hi:[1,0]
	v_med3_f32 v6, v6, s47, v172
	v_med3_f32 v7, v7, s47, v172
	v_cvt_pk_fp8_f32 v10, v6, v7 op_sel:[0,0,1]
	v_ashrrev_i32_e32 v5, 31, v4
	v_med3_f32 v6, v12, s47, v172
	v_med3_f32 v7, v13, s47, v172
	v_lshlrev_b64 v[4:5], 10, v[4:5]
	v_cvt_pk_fp8_f32 v11, v6, v7 op_sel:[0,0,1]
	v_lshl_add_u64 v[4:5], s[10:11], 0, v[4:5]
	v_lshl_add_u64 v[4:5], v[4:5], 0, v[2:3]
	global_store_dwordx2 v[4:5], v[8:9], off
	global_store_dwordx2 v[4:5], v[10:11], off offset:128
	v_pk_mul_f32 v[8:9], v[94:95], s[14:15] op_sel_hi:[1,0]
	v_pk_mul_f32 v[6:7], v[96:97], s[14:15] op_sel_hi:[1,0]
	v_med3_f32 v14, v8, s47, v172
	v_med3_f32 v9, v9, s47, v172
	v_mov_b32_e32 v8, 0
	v_cvt_pk_fp8_f32 v8, v14, v9
	v_pk_mul_f32 v[12:13], v[90:91], s[14:15] op_sel_hi:[1,0]
	v_pk_mul_f32 v[10:11], v[92:93], s[14:15] op_sel_hi:[1,0]
	v_med3_f32 v6, v6, s47, v172
	v_med3_f32 v7, v7, s47, v172
	v_med3_f32 v12, v12, s47, v172
	v_med3_f32 v13, v13, s47, v172
	v_mov_b32_e32 v9, 0
	v_cvt_pk_fp8_f32 v9, v12, v13
	v_cvt_pk_fp8_f32 v8, v6, v7 op_sel:[0,0,1]
	v_med3_f32 v6, v10, s47, v172
	v_med3_f32 v7, v11, s47, v172
	v_pk_mul_f32 v[10:11], v[86:87], s[14:15] op_sel_hi:[1,0]
	v_pk_mul_f32 v[14:15], v[82:83], s[14:15] op_sel_hi:[1,0]
	v_med3_f32 v17, v10, s47, v172
	v_med3_f32 v11, v11, s47, v172
	v_mov_b32_e32 v10, 0
	v_cvt_pk_fp8_f32 v10, v17, v11
	v_med3_f32 v14, v14, s47, v172
	v_med3_f32 v15, v15, s47, v172
	v_mov_b32_e32 v11, 0
	v_cvt_pk_fp8_f32 v11, v14, v15
	v_cvt_pk_fp8_f32 v9, v6, v7 op_sel:[0,0,1]
	v_pk_mul_f32 v[6:7], v[88:89], s[14:15] op_sel_hi:[1,0]
	v_add_u32_e32 v4, 48, v16
	v_pk_mul_f32 v[12:13], v[84:85], s[14:15] op_sel_hi:[1,0]
	v_med3_f32 v6, v6, s47, v172
	v_med3_f32 v7, v7, s47, v172
	v_cvt_pk_fp8_f32 v10, v6, v7 op_sel:[0,0,1]
	v_ashrrev_i32_e32 v5, 31, v4
	v_med3_f32 v6, v12, s47, v172
	v_med3_f32 v7, v13, s47, v172
	v_lshlrev_b64 v[4:5], 10, v[4:5]
	v_cvt_pk_fp8_f32 v11, v6, v7 op_sel:[0,0,1]
	v_lshl_add_u64 v[4:5], s[10:11], 0, v[4:5]
	v_lshl_add_u64 v[4:5], v[4:5], 0, v[2:3]
	global_store_dwordx2 v[4:5], v[8:9], off
	global_store_dwordx2 v[4:5], v[10:11], off offset:128
	v_pk_mul_f32 v[8:9], v[78:79], s[14:15] op_sel_hi:[1,0]
	v_pk_mul_f32 v[6:7], v[80:81], s[14:15] op_sel_hi:[1,0]
	v_med3_f32 v14, v8, s47, v172
	v_med3_f32 v9, v9, s47, v172
	v_mov_b32_e32 v8, 0
	v_cvt_pk_fp8_f32 v8, v14, v9
	v_pk_mul_f32 v[12:13], v[74:75], s[14:15] op_sel_hi:[1,0]
	v_pk_mul_f32 v[10:11], v[76:77], s[14:15] op_sel_hi:[1,0]
	v_med3_f32 v6, v6, s47, v172
	v_med3_f32 v7, v7, s47, v172
	v_med3_f32 v12, v12, s47, v172
	v_med3_f32 v13, v13, s47, v172
	v_mov_b32_e32 v9, 0
	v_cvt_pk_fp8_f32 v9, v12, v13
	v_cvt_pk_fp8_f32 v8, v6, v7 op_sel:[0,0,1]
	v_med3_f32 v6, v10, s47, v172
	v_med3_f32 v7, v11, s47, v172
	v_pk_mul_f32 v[10:11], v[70:71], s[14:15] op_sel_hi:[1,0]
	v_pk_mul_f32 v[14:15], v[66:67], s[14:15] op_sel_hi:[1,0]
	v_med3_f32 v17, v10, s47, v172
	v_med3_f32 v11, v11, s47, v172
	v_mov_b32_e32 v10, 0
	v_cvt_pk_fp8_f32 v10, v17, v11
	v_med3_f32 v14, v14, s47, v172
	v_med3_f32 v15, v15, s47, v172
	v_mov_b32_e32 v11, 0
	v_cvt_pk_fp8_f32 v11, v14, v15
	v_cvt_pk_fp8_f32 v9, v6, v7 op_sel:[0,0,1]
	v_pk_mul_f32 v[6:7], v[72:73], s[14:15] op_sel_hi:[1,0]
	v_add_u32_e32 v4, 0x80, v16
	v_pk_mul_f32 v[12:13], v[68:69], s[14:15] op_sel_hi:[1,0]
	v_med3_f32 v6, v6, s47, v172
	v_med3_f32 v7, v7, s47, v172
	v_cvt_pk_fp8_f32 v10, v6, v7 op_sel:[0,0,1]
	v_ashrrev_i32_e32 v5, 31, v4
	v_med3_f32 v6, v12, s47, v172
	v_med3_f32 v7, v13, s47, v172
	v_lshlrev_b64 v[4:5], 10, v[4:5]
	v_cvt_pk_fp8_f32 v11, v6, v7 op_sel:[0,0,1]
	v_lshl_add_u64 v[4:5], s[10:11], 0, v[4:5]
	v_lshl_add_u64 v[4:5], v[4:5], 0, v[2:3]
	global_store_dwordx2 v[4:5], v[8:9], off
	global_store_dwordx2 v[4:5], v[10:11], off offset:128
	v_pk_mul_f32 v[8:9], v[62:63], s[14:15] op_sel_hi:[1,0]
	v_pk_mul_f32 v[6:7], v[64:65], s[14:15] op_sel_hi:[1,0]
	v_med3_f32 v14, v8, s47, v172
	v_med3_f32 v9, v9, s47, v172
	v_mov_b32_e32 v8, 0
	v_cvt_pk_fp8_f32 v8, v14, v9
	v_pk_mul_f32 v[12:13], v[58:59], s[14:15] op_sel_hi:[1,0]
	v_pk_mul_f32 v[10:11], v[60:61], s[14:15] op_sel_hi:[1,0]
	v_med3_f32 v6, v6, s47, v172
	v_med3_f32 v7, v7, s47, v172
	v_med3_f32 v12, v12, s47, v172
	v_med3_f32 v13, v13, s47, v172
	v_mov_b32_e32 v9, 0
	v_cvt_pk_fp8_f32 v9, v12, v13
	v_cvt_pk_fp8_f32 v8, v6, v7 op_sel:[0,0,1]
	v_med3_f32 v6, v10, s47, v172
	v_med3_f32 v7, v11, s47, v172
	v_pk_mul_f32 v[10:11], v[54:55], s[14:15] op_sel_hi:[1,0]
	v_pk_mul_f32 v[14:15], v[50:51], s[14:15] op_sel_hi:[1,0]
	v_med3_f32 v17, v10, s47, v172
	v_med3_f32 v11, v11, s47, v172
	v_mov_b32_e32 v10, 0
	v_cvt_pk_fp8_f32 v10, v17, v11
	v_med3_f32 v14, v14, s47, v172
	v_med3_f32 v15, v15, s47, v172
	v_mov_b32_e32 v11, 0
	v_cvt_pk_fp8_f32 v11, v14, v15
	v_cvt_pk_fp8_f32 v9, v6, v7 op_sel:[0,0,1]
	v_pk_mul_f32 v[6:7], v[56:57], s[14:15] op_sel_hi:[1,0]
	v_add_u32_e32 v4, 0x90, v16
	v_pk_mul_f32 v[12:13], v[52:53], s[14:15] op_sel_hi:[1,0]
	v_med3_f32 v6, v6, s47, v172
	v_med3_f32 v7, v7, s47, v172
	v_cvt_pk_fp8_f32 v10, v6, v7 op_sel:[0,0,1]
	v_ashrrev_i32_e32 v5, 31, v4
	v_med3_f32 v6, v12, s47, v172
	v_med3_f32 v7, v13, s47, v172
	v_lshlrev_b64 v[4:5], 10, v[4:5]
	v_cvt_pk_fp8_f32 v11, v6, v7 op_sel:[0,0,1]
	v_lshl_add_u64 v[4:5], s[10:11], 0, v[4:5]
	v_lshl_add_u64 v[4:5], v[4:5], 0, v[2:3]
	global_store_dwordx2 v[4:5], v[8:9], off
	global_store_dwordx2 v[4:5], v[10:11], off offset:128
	v_pk_mul_f32 v[8:9], v[46:47], s[14:15] op_sel_hi:[1,0]
	v_pk_mul_f32 v[6:7], v[48:49], s[14:15] op_sel_hi:[1,0]
	v_med3_f32 v14, v8, s47, v172
	v_med3_f32 v9, v9, s47, v172
	v_mov_b32_e32 v8, 0
	v_cvt_pk_fp8_f32 v8, v14, v9
	v_pk_mul_f32 v[12:13], v[42:43], s[14:15] op_sel_hi:[1,0]
	v_pk_mul_f32 v[10:11], v[44:45], s[14:15] op_sel_hi:[1,0]
	v_med3_f32 v6, v6, s47, v172
	v_med3_f32 v7, v7, s47, v172
	v_med3_f32 v12, v12, s47, v172
	v_med3_f32 v13, v13, s47, v172
	v_mov_b32_e32 v9, 0
	v_cvt_pk_fp8_f32 v9, v12, v13
	v_cvt_pk_fp8_f32 v8, v6, v7 op_sel:[0,0,1]
	v_med3_f32 v6, v10, s47, v172
	v_med3_f32 v7, v11, s47, v172
	v_pk_mul_f32 v[10:11], v[38:39], s[14:15] op_sel_hi:[1,0]
	v_pk_mul_f32 v[14:15], v[34:35], s[14:15] op_sel_hi:[1,0]
	v_med3_f32 v17, v10, s47, v172
	v_med3_f32 v11, v11, s47, v172
	v_mov_b32_e32 v10, 0
	v_cvt_pk_fp8_f32 v10, v17, v11
	v_med3_f32 v14, v14, s47, v172
	v_med3_f32 v15, v15, s47, v172
	v_mov_b32_e32 v11, 0
	v_cvt_pk_fp8_f32 v11, v14, v15
	v_cvt_pk_fp8_f32 v9, v6, v7 op_sel:[0,0,1]
	v_pk_mul_f32 v[6:7], v[40:41], s[14:15] op_sel_hi:[1,0]
	v_add_u32_e32 v4, 0xa0, v16
	v_pk_mul_f32 v[12:13], v[36:37], s[14:15] op_sel_hi:[1,0]
	v_med3_f32 v6, v6, s47, v172
	v_med3_f32 v7, v7, s47, v172
	v_cvt_pk_fp8_f32 v10, v6, v7 op_sel:[0,0,1]
	v_ashrrev_i32_e32 v5, 31, v4
	v_med3_f32 v6, v12, s47, v172
	v_med3_f32 v7, v13, s47, v172
	v_lshlrev_b64 v[4:5], 10, v[4:5]
	v_cvt_pk_fp8_f32 v11, v6, v7 op_sel:[0,0,1]
	v_lshl_add_u64 v[4:5], s[10:11], 0, v[4:5]
	v_lshl_add_u64 v[4:5], v[4:5], 0, v[2:3]
	global_store_dwordx2 v[4:5], v[8:9], off
	global_store_dwordx2 v[4:5], v[10:11], off offset:128
	v_pk_mul_f32 v[8:9], v[30:31], s[14:15] op_sel_hi:[1,0]
	v_pk_mul_f32 v[6:7], v[32:33], s[14:15] op_sel_hi:[1,0]
	v_med3_f32 v14, v8, s47, v172
	v_med3_f32 v9, v9, s47, v172
	v_mov_b32_e32 v8, 0
	v_cvt_pk_fp8_f32 v8, v14, v9
	v_pk_mul_f32 v[12:13], v[26:27], s[14:15] op_sel_hi:[1,0]
	v_pk_mul_f32 v[10:11], v[28:29], s[14:15] op_sel_hi:[1,0]
	v_med3_f32 v6, v6, s47, v172
	v_med3_f32 v7, v7, s47, v172
	v_med3_f32 v12, v12, s47, v172
	v_med3_f32 v13, v13, s47, v172
	v_mov_b32_e32 v9, 0
	v_cvt_pk_fp8_f32 v9, v12, v13
	v_cvt_pk_fp8_f32 v8, v6, v7 op_sel:[0,0,1]
	v_med3_f32 v6, v10, s47, v172
	v_med3_f32 v7, v11, s47, v172
	v_pk_mul_f32 v[10:11], v[22:23], s[14:15] op_sel_hi:[1,0]
	v_add_u32_e32 v4, 0xb0, v16
	v_pk_mul_f32 v[14:15], v[18:19], s[14:15] op_sel_hi:[1,0]
	v_med3_f32 v16, v10, s47, v172
	v_med3_f32 v11, v11, s47, v172
	v_mov_b32_e32 v10, 0
	v_cvt_pk_fp8_f32 v10, v16, v11
	v_med3_f32 v14, v14, s47, v172
	v_med3_f32 v15, v15, s47, v172
	v_mov_b32_e32 v11, 0
	v_cvt_pk_fp8_f32 v11, v14, v15
	v_cvt_pk_fp8_f32 v9, v6, v7 op_sel:[0,0,1]
	v_pk_mul_f32 v[6:7], v[24:25], s[14:15] op_sel_hi:[1,0]
	v_pk_mul_f32 v[12:13], v[20:21], s[14:15] op_sel_hi:[1,0]
	v_med3_f32 v6, v6, s47, v172
	v_med3_f32 v7, v7, s47, v172
	v_cvt_pk_fp8_f32 v10, v6, v7 op_sel:[0,0,1]
	v_ashrrev_i32_e32 v5, 31, v4
	v_med3_f32 v6, v12, s47, v172
	v_med3_f32 v7, v13, s47, v172
	v_lshlrev_b64 v[4:5], 10, v[4:5]
	v_cvt_pk_fp8_f32 v11, v6, v7 op_sel:[0,0,1]
	v_lshl_add_u64 v[4:5], s[10:11], 0, v[4:5]
	v_lshl_add_u64 v[2:3], v[4:5], 0, v[2:3]
	s_and_b64 vcc, exec, s[6:7]
	s_mov_b32 s48, s16
	s_mov_b32 s24, s18
	s_mov_b64 s[26:27], s[22:23]
	s_mov_b64 s[28:29], s[20:21]
	global_store_dwordx2 v[2:3], v[8:9], off
	global_store_dwordx2 v[2:3], v[10:11], off offset:128
	s_cbranch_vccz .LBB0_2809
	s_waitcnt vmcnt(0)
	s_cmpk_gt_u32 s4, 0xff
	s_cbranch_scc1 .LBB0_2820
	s_barrier
